# v39
# speedup vs baseline: 1.0062x; 1.0016x over previous
.LBB0_189:
	v_add_u32_e32 v141, 0x10000, v161
	s_add_u32 s36, s34, 0xfffc0080
	s_addc_u32 s37, s35, -1
	s_add_i32 s75, 0, 0x10000
	ds_read_b128 v[164:167], v141
	ds_read_b128 v[168:171], v141 offset:1024
	ds_read_b128 v[172:175], v141 offset:2048
	ds_read_b128 v[176:179], v141 offset:3072
	s_cmp_eq_u32 s74, 12
	s_cselect_b32 s39, s25, s37
	s_cselect_b32 s38, s69, s36
	s_cselect_b32 s37, s23, s73
	s_cselect_b32 s36, s70, s71
	s_add_i32 m0, s31, 0xc000
	ds_read_b128 v[180:183], v163
	ds_read_b128 v[184:187], v163 offset:1024
	ds_read_b128 v[188:191], v163 offset:2048
	ds_read_b128 v[192:195], v163 offset:3072
	ds_read_b128 v[196:199], v163 offset:4096
	ds_read_b128 v[200:203], v163 offset:5120
	ds_read_b128 v[204:207], v163 offset:6144
	ds_read_b128 v[208:211], v163 offset:7168
	global_load_lds_dwordx4 v136, s[34:35]
	s_add_i32 m0, s31, 0xe000
	s_nop 0
	global_load_lds_dwordx4 v138, s[34:35]
	s_waitcnt lgkmcnt(8)
	s_barrier
	s_waitcnt lgkmcnt(0)
	v_mfma_f32_16x16x32_bf16 v[124:127], v[164:167], v[180:183], v[124:127]
	v_mfma_f32_16x16x32_bf16 v[120:123], v[172:175], v[180:183], v[120:123]
	v_mfma_f32_16x16x32_bf16 v[116:119], v[164:167], v[188:191], v[116:119]
	v_mfma_f32_16x16x32_bf16 v[108:111], v[172:175], v[188:191], v[108:111]
	v_mfma_f32_16x16x32_bf16 v[100:103], v[164:167], v[196:199], v[100:103]
	v_mfma_f32_16x16x32_bf16 v[92:95], v[172:175], v[196:199], v[92:95]
	v_mfma_f32_16x16x32_bf16 v[84:87], v[164:167], v[204:207], v[84:87]
	v_mfma_f32_16x16x32_bf16 v[76:79], v[172:175], v[204:207], v[76:79]
	v_mfma_f32_16x16x32_bf16 v[124:127], v[168:171], v[184:187], v[124:127]
	v_mfma_f32_16x16x32_bf16 v[120:123], v[176:179], v[184:187], v[120:123]
	v_mfma_f32_16x16x32_bf16 v[116:119], v[168:171], v[192:195], v[116:119]
	v_mfma_f32_16x16x32_bf16 v[108:111], v[176:179], v[192:195], v[108:111]
	v_mfma_f32_16x16x32_bf16 v[100:103], v[168:171], v[200:203], v[100:103]
	v_mfma_f32_16x16x32_bf16 v[92:95], v[176:179], v[200:203], v[92:95]
	v_mfma_f32_16x16x32_bf16 v[84:87], v[168:171], v[208:211], v[84:87]
	v_mfma_f32_16x16x32_bf16 v[76:79], v[176:179], v[208:211], v[76:79]
	s_barrier
	s_add_i32 s78, 0, 0x14000
	s_add_i32 s75, s75, s57
	ds_read_b128 v[212:215], v141 offset:16384
	ds_read_b128 v[216:219], v141 offset:17408
	ds_read_b128 v[220:223], v141 offset:18432
	ds_read_b128 v[224:227], v141 offset:19456
	s_add_u32 s98, s36, s14
	s_addc_u32 s99, s37, s15
	s_mov_b32 m0, s75
	s_nop 0
	global_load_lds_dwordx4 v128, s[36:37]
	s_add_i32 m0, s75, 0x2000
	s_nop 0
	global_load_lds_dwordx4 v130, s[36:37]
	s_barrier
	s_waitcnt lgkmcnt(0)
	v_mfma_f32_16x16x32_bf16 v[112:115], v[212:215], v[180:183], v[112:115]
	v_mfma_f32_16x16x32_bf16 v[104:107], v[220:223], v[180:183], v[104:107]
	v_mfma_f32_16x16x32_bf16 v[96:99], v[212:215], v[188:191], v[96:99]
	v_mfma_f32_16x16x32_bf16 v[88:91], v[220:223], v[188:191], v[88:91]
	v_mfma_f32_16x16x32_bf16 v[80:83], v[212:215], v[196:199], v[80:83]
	v_mfma_f32_16x16x32_bf16 v[72:75], v[220:223], v[196:199], v[72:75]
	v_mfma_f32_16x16x32_bf16 v[68:71], v[212:215], v[204:207], v[68:71]
	v_mfma_f32_16x16x32_bf16 v[64:67], v[220:223], v[204:207], v[64:67]
	v_mfma_f32_16x16x32_bf16 v[112:115], v[216:219], v[184:187], v[112:115]
	v_mfma_f32_16x16x32_bf16 v[104:107], v[224:227], v[184:187], v[104:107]
	v_mfma_f32_16x16x32_bf16 v[96:99], v[216:219], v[192:195], v[96:99]
	v_mfma_f32_16x16x32_bf16 v[88:91], v[224:227], v[192:195], v[88:91]
	v_mfma_f32_16x16x32_bf16 v[80:83], v[216:219], v[200:203], v[80:83]
	v_mfma_f32_16x16x32_bf16 v[72:75], v[224:227], v[200:203], v[72:75]
	v_mfma_f32_16x16x32_bf16 v[68:71], v[216:219], v[208:211], v[68:71]
	v_mfma_f32_16x16x32_bf16 v[64:67], v[224:227], v[208:211], v[64:67]
	s_mov_b32 m0, s31
	s_add_u32 s100, s38, s14
	s_addc_u32 s101, s39, s15
	s_barrier
	ds_read_b128 v[180:183], v163 offset:16384
	ds_read_b128 v[184:187], v163 offset:17408
	ds_read_b128 v[188:191], v163 offset:18432
	ds_read_b128 v[192:195], v163 offset:19456
	ds_read_b128 v[196:199], v163 offset:20480
	ds_read_b128 v[200:203], v163 offset:21504
	ds_read_b128 v[204:207], v163 offset:22528
	ds_read_b128 v[208:211], v163 offset:23552
	global_load_lds_dwordx4 v134, s[38:39]
	s_mov_b32 m0, s60
	s_nop 0
	global_load_lds_dwordx4 v132, s[38:39]
	s_barrier
	s_waitcnt lgkmcnt(0)
	v_mfma_f32_16x16x32_bf16 v[60:63], v[164:167], v[180:183], v[60:63]
	v_mfma_f32_16x16x32_bf16 v[56:59], v[172:175], v[180:183], v[56:59]
	v_mfma_f32_16x16x32_bf16 v[52:55], v[164:167], v[188:191], v[52:55]
	v_mfma_f32_16x16x32_bf16 v[44:47], v[172:175], v[188:191], v[44:47]
	v_mfma_f32_16x16x32_bf16 v[36:39], v[164:167], v[196:199], v[36:39]
	v_mfma_f32_16x16x32_bf16 v[28:31], v[172:175], v[196:199], v[28:31]
	v_mfma_f32_16x16x32_bf16 v[20:23], v[164:167], v[204:207], v[20:23]
	v_mfma_f32_16x16x32_bf16 v[12:15], v[172:175], v[204:207], v[12:15]
	v_mfma_f32_16x16x32_bf16 v[60:63], v[168:171], v[184:187], v[60:63]
	v_mfma_f32_16x16x32_bf16 v[56:59], v[176:179], v[184:187], v[56:59]
	v_mfma_f32_16x16x32_bf16 v[52:55], v[168:171], v[192:195], v[52:55]
	v_mfma_f32_16x16x32_bf16 v[44:47], v[176:179], v[192:195], v[44:47]
	v_mfma_f32_16x16x32_bf16 v[36:39], v[168:171], v[200:203], v[36:39]
	v_mfma_f32_16x16x32_bf16 v[28:31], v[176:179], v[200:203], v[28:31]
	v_mfma_f32_16x16x32_bf16 v[20:23], v[168:171], v[208:211], v[20:23]
	v_mfma_f32_16x16x32_bf16 v[12:15], v[176:179], v[208:211], v[12:15]
	s_barrier
	s_add_u32 s76, s36, 0x40000
	s_addc_u32 s77, s37, 0
	s_add_i32 s75, s78, s57
	s_mov_b32 m0, s75
	s_nop 0
	global_load_lds_dwordx4 v128, s[76:77]
	s_add_i32 m0, s75, 0x2000
	s_nop 0
	global_load_lds_dwordx4 v130, s[76:77]
	s_waitcnt vmcnt(6)
	s_barrier
	v_mfma_f32_16x16x32_bf16 v[48:51], v[212:215], v[180:183], v[48:51]
	v_mfma_f32_16x16x32_bf16 v[40:43], v[220:223], v[180:183], v[40:43]
	v_mfma_f32_16x16x32_bf16 v[32:35], v[212:215], v[188:191], v[32:35]
	v_mfma_f32_16x16x32_bf16 v[24:27], v[220:223], v[188:191], v[24:27]
	v_mfma_f32_16x16x32_bf16 v[16:19], v[212:215], v[196:199], v[16:19]
	v_mfma_f32_16x16x32_bf16 v[8:11], v[220:223], v[196:199], v[8:11]
	v_mfma_f32_16x16x32_bf16 v[4:7], v[212:215], v[204:207], v[4:7]
	v_mfma_f32_16x16x32_bf16 v[0:3], v[220:223], v[204:207], v[0:3]
	v_mfma_f32_16x16x32_bf16 v[48:51], v[216:219], v[184:187], v[48:51]
	v_mfma_f32_16x16x32_bf16 v[40:43], v[224:227], v[184:187], v[40:43]
	v_mfma_f32_16x16x32_bf16 v[32:35], v[216:219], v[192:195], v[32:35]
	v_mfma_f32_16x16x32_bf16 v[24:27], v[224:227], v[192:195], v[24:27]
	v_mfma_f32_16x16x32_bf16 v[16:19], v[216:219], v[200:203], v[16:19]
	v_mfma_f32_16x16x32_bf16 v[8:11], v[224:227], v[200:203], v[8:11]
	v_mfma_f32_16x16x32_bf16 v[4:7], v[216:219], v[208:211], v[4:7]
	v_mfma_f32_16x16x32_bf16 v[0:3], v[224:227], v[208:211], v[0:3]
	s_add_i32 s75, 0, 0x18000
	s_barrier
	ds_read_b128 v[164:167], v141 offset:32768
	ds_read_b128 v[168:171], v141 offset:33792
	ds_read_b128 v[172:175], v141 offset:34816
	ds_read_b128 v[176:179], v141 offset:35840
	s_add_u32 s38, s38, 0x40000
	s_addc_u32 s39, s39, 0
	s_mov_b32 m0, s61
	ds_read_b128 v[180:183], v163 offset:32768
	ds_read_b128 v[184:187], v163 offset:33792
	ds_read_b128 v[188:191], v163 offset:34816
	ds_read_b128 v[192:195], v163 offset:35840
	ds_read_b128 v[196:199], v163 offset:36864
	ds_read_b128 v[200:203], v163 offset:37888
	ds_read_b128 v[204:207], v163 offset:38912
	ds_read_b128 v[208:211], v163 offset:39936
	global_load_lds_dwordx4 v134, s[38:39]
	s_mov_b32 m0, s62
	s_nop 0
	global_load_lds_dwordx4 v132, s[38:39]
	s_waitcnt lgkmcnt(8)
	s_barrier
	s_waitcnt lgkmcnt(0)
	v_mfma_f32_16x16x32_bf16 v[124:127], v[164:167], v[180:183], v[124:127]
	v_mfma_f32_16x16x32_bf16 v[120:123], v[172:175], v[180:183], v[120:123]
	v_mfma_f32_16x16x32_bf16 v[116:119], v[164:167], v[188:191], v[116:119]
	v_mfma_f32_16x16x32_bf16 v[108:111], v[172:175], v[188:191], v[108:111]
	v_mfma_f32_16x16x32_bf16 v[100:103], v[164:167], v[196:199], v[100:103]
	v_mfma_f32_16x16x32_bf16 v[92:95], v[172:175], v[196:199], v[92:95]
	v_mfma_f32_16x16x32_bf16 v[84:87], v[164:167], v[204:207], v[84:87]
	v_mfma_f32_16x16x32_bf16 v[76:79], v[172:175], v[204:207], v[76:79]
	v_mfma_f32_16x16x32_bf16 v[124:127], v[168:171], v[184:187], v[124:127]
	v_mfma_f32_16x16x32_bf16 v[120:123], v[176:179], v[184:187], v[120:123]
	v_mfma_f32_16x16x32_bf16 v[116:119], v[168:171], v[192:195], v[116:119]
	v_mfma_f32_16x16x32_bf16 v[108:111], v[176:179], v[192:195], v[108:111]
	v_mfma_f32_16x16x32_bf16 v[100:103], v[168:171], v[200:203], v[100:103]
	v_mfma_f32_16x16x32_bf16 v[92:95], v[176:179], v[200:203], v[92:95]
	v_mfma_f32_16x16x32_bf16 v[84:87], v[168:171], v[208:211], v[84:87]
	v_mfma_f32_16x16x32_bf16 v[76:79], v[176:179], v[208:211], v[76:79]
	s_barrier
	s_add_i32 s38, 0, 0x1c000
	s_add_i32 s39, s75, s57
	s_mov_b32 m0, s39
	ds_read_b128 v[212:215], v141 offset:49152
	ds_read_b128 v[216:219], v141 offset:50176
	ds_read_b128 v[220:223], v141 offset:51200
	ds_read_b128 v[224:227], v141 offset:52224
	global_load_lds_dwordx4 v128, s[98:99]
	s_add_i32 m0, s39, 0x2000
	s_nop 0
	global_load_lds_dwordx4 v130, s[98:99]
	s_barrier
	s_waitcnt lgkmcnt(0)
	v_mfma_f32_16x16x32_bf16 v[112:115], v[212:215], v[180:183], v[112:115]
	v_mfma_f32_16x16x32_bf16 v[104:107], v[220:223], v[180:183], v[104:107]
	v_mfma_f32_16x16x32_bf16 v[96:99], v[212:215], v[188:191], v[96:99]
	v_mfma_f32_16x16x32_bf16 v[88:91], v[220:223], v[188:191], v[88:91]
	v_mfma_f32_16x16x32_bf16 v[80:83], v[212:215], v[196:199], v[80:83]
	v_mfma_f32_16x16x32_bf16 v[72:75], v[220:223], v[196:199], v[72:75]
	v_mfma_f32_16x16x32_bf16 v[68:71], v[212:215], v[204:207], v[68:71]
	v_mfma_f32_16x16x32_bf16 v[64:67], v[220:223], v[204:207], v[64:67]
	v_mfma_f32_16x16x32_bf16 v[112:115], v[216:219], v[184:187], v[112:115]
	v_mfma_f32_16x16x32_bf16 v[104:107], v[224:227], v[184:187], v[104:107]
	v_mfma_f32_16x16x32_bf16 v[96:99], v[216:219], v[192:195], v[96:99]
	v_mfma_f32_16x16x32_bf16 v[88:91], v[224:227], v[192:195], v[88:91]
	v_mfma_f32_16x16x32_bf16 v[80:83], v[216:219], v[200:203], v[80:83]
	v_mfma_f32_16x16x32_bf16 v[72:75], v[224:227], v[200:203], v[72:75]
	v_mfma_f32_16x16x32_bf16 v[68:71], v[216:219], v[208:211], v[68:71]
	v_mfma_f32_16x16x32_bf16 v[64:67], v[224:227], v[208:211], v[64:67]
	s_mov_b32 m0, s63
	s_barrier
	ds_read_b128 v[180:183], v163 offset:49152
	ds_read_b128 v[184:187], v163 offset:50176
	ds_read_b128 v[188:191], v163 offset:51200
	ds_read_b128 v[192:195], v163 offset:52224
	ds_read_b128 v[196:199], v163 offset:53248
	ds_read_b128 v[200:203], v163 offset:54272
	ds_read_b128 v[204:207], v163 offset:55296
	ds_read_b128 v[208:211], v163 offset:56320
	global_load_lds_dwordx4 v134, s[100:101]
	s_mov_b32 m0, s64
	s_nop 0
	global_load_lds_dwordx4 v132, s[100:101]
	s_barrier
	s_waitcnt lgkmcnt(0)
	v_mfma_f32_16x16x32_bf16 v[60:63], v[164:167], v[180:183], v[60:63]
	v_mfma_f32_16x16x32_bf16 v[56:59], v[172:175], v[180:183], v[56:59]
	v_mfma_f32_16x16x32_bf16 v[52:55], v[164:167], v[188:191], v[52:55]
	v_mfma_f32_16x16x32_bf16 v[44:47], v[172:175], v[188:191], v[44:47]
	v_mfma_f32_16x16x32_bf16 v[36:39], v[164:167], v[196:199], v[36:39]
	v_mfma_f32_16x16x32_bf16 v[28:31], v[172:175], v[196:199], v[28:31]
	v_mfma_f32_16x16x32_bf16 v[20:23], v[164:167], v[204:207], v[20:23]
	v_mfma_f32_16x16x32_bf16 v[12:15], v[172:175], v[204:207], v[12:15]
	v_mfma_f32_16x16x32_bf16 v[60:63], v[168:171], v[184:187], v[60:63]
	v_mfma_f32_16x16x32_bf16 v[56:59], v[176:179], v[184:187], v[56:59]
	v_mfma_f32_16x16x32_bf16 v[52:55], v[168:171], v[192:195], v[52:55]
	v_mfma_f32_16x16x32_bf16 v[44:47], v[176:179], v[192:195], v[44:47]
	v_mfma_f32_16x16x32_bf16 v[36:39], v[168:171], v[200:203], v[36:39]
	v_mfma_f32_16x16x32_bf16 v[28:31], v[176:179], v[200:203], v[28:31]
	v_mfma_f32_16x16x32_bf16 v[20:23], v[168:171], v[208:211], v[20:23]
	v_mfma_f32_16x16x32_bf16 v[12:15], v[176:179], v[208:211], v[12:15]
	s_barrier
	s_add_u32 s36, s36, 0x40080
	s_addc_u32 s37, s37, 0
	s_add_i32 s38, s38, s57
	s_mov_b32 m0, s38
	s_nop 0
	global_load_lds_dwordx4 v128, s[36:37]
	s_add_i32 m0, s38, 0x2000
	s_nop 0
	global_load_lds_dwordx4 v130, s[36:37]
	s_waitcnt vmcnt(6)
	s_barrier
	v_mfma_f32_16x16x32_bf16 v[48:51], v[212:215], v[180:183], v[48:51]
	v_mfma_f32_16x16x32_bf16 v[40:43], v[220:223], v[180:183], v[40:43]
	v_mfma_f32_16x16x32_bf16 v[32:35], v[212:215], v[188:191], v[32:35]
	v_mfma_f32_16x16x32_bf16 v[24:27], v[220:223], v[188:191], v[24:27]
	v_mfma_f32_16x16x32_bf16 v[16:19], v[212:215], v[196:199], v[16:19]
	v_mfma_f32_16x16x32_bf16 v[8:11], v[220:223], v[196:199], v[8:11]
	v_mfma_f32_16x16x32_bf16 v[4:7], v[212:215], v[204:207], v[4:7]
	v_mfma_f32_16x16x32_bf16 v[0:3], v[220:223], v[204:207], v[0:3]
	v_mfma_f32_16x16x32_bf16 v[48:51], v[216:219], v[184:187], v[48:51]
	v_mfma_f32_16x16x32_bf16 v[40:43], v[224:227], v[184:187], v[40:43]
	v_mfma_f32_16x16x32_bf16 v[32:35], v[216:219], v[192:195], v[32:35]
	v_mfma_f32_16x16x32_bf16 v[24:27], v[224:227], v[192:195], v[24:27]
	v_mfma_f32_16x16x32_bf16 v[16:19], v[216:219], v[200:203], v[16:19]
	v_mfma_f32_16x16x32_bf16 v[8:11], v[224:227], v[200:203], v[8:11]
	v_mfma_f32_16x16x32_bf16 v[4:7], v[216:219], v[208:211], v[4:7]
	v_mfma_f32_16x16x32_bf16 v[0:3], v[224:227], v[208:211], v[0:3]
	s_add_i32 s74, s74, 2
	s_add_u32 s34, s34, 0x100
	s_addc_u32 s35, s35, 0
	s_add_u32 s71, s71, 0x100
	s_addc_u32 s73, s73, 0
	s_cmp_gt_u32 s74, 13
	s_barrier
	s_cbranch_scc0 .LBB0_189
	v_lshl_or_b32 v140, s68, 8, v162
	v_lshl_add_u32 v166, s30, 8, v159
	v_ashrrev_i32_e32 v141, 31, v140
	v_lshl_add_u64 v[140:141], v[140:141], 1, s[20:21]
	v_mad_i64_i32 v[164:165], s[34:35], v166, s52, 0
	v_lshl_add_u64 v[164:165], v[164:165], 1, v[140:141]
	v_cvt_pk_bf16_f32 v124, v124, v125
	v_cvt_pk_bf16_f32 v125, v126, v127
	v_cvt_pk_bf16_f32 v126, v120, v121
	v_cvt_pk_bf16_f32 v127, v122, v123
	global_store_dwordx4 v[164:165], v[124:127], off
	v_cvt_pk_bf16_f32 v112, v112, v113
	v_cvt_pk_bf16_f32 v113, v114, v115
	v_cvt_pk_bf16_f32 v114, v104, v105
	v_or_b32_e32 v104, 16, v166
	v_mad_i64_i32 v[104:105], s[34:35], v104, s52, 0
	v_cvt_pk_bf16_f32 v115, v106, v107
	global_store_dwordx4 v[164:165], v[112:115], off offset:256
	s_and_b64 vcc, exec, s[4:5]
	s_mov_b32 s68, s22
	v_lshl_add_u64 v[112:113], v[104:105], 1, v[140:141]
	v_cvt_pk_bf16_f32 v104, v116, v117
	v_cvt_pk_bf16_f32 v105, v118, v119
	v_cvt_pk_bf16_f32 v106, v108, v109
	v_cvt_pk_bf16_f32 v107, v110, v111
	global_store_dwordx4 v[112:113], v[104:107], off
	v_cvt_pk_bf16_f32 v96, v96, v97
	v_cvt_pk_bf16_f32 v97, v98, v99
	v_cvt_pk_bf16_f32 v98, v88, v89
	v_or_b32_e32 v88, 32, v166
	v_mad_i64_i32 v[88:89], s[34:35], v88, s52, 0
	v_cvt_pk_bf16_f32 v99, v90, v91
	global_store_dwordx4 v[112:113], v[96:99], off offset:256
	s_mov_b32 s30, s24
	s_mov_b64 s[36:37], s[28:29]
	v_lshl_add_u64 v[96:97], v[88:89], 1, v[140:141]
	v_cvt_pk_bf16_f32 v88, v100, v101
	v_cvt_pk_bf16_f32 v89, v102, v103
	v_cvt_pk_bf16_f32 v90, v92, v93
	v_cvt_pk_bf16_f32 v91, v94, v95
	global_store_dwordx4 v[96:97], v[88:91], off
	v_cvt_pk_bf16_f32 v80, v80, v81
	v_cvt_pk_bf16_f32 v81, v82, v83
	v_cvt_pk_bf16_f32 v82, v72, v73
	v_or_b32_e32 v72, 48, v166
	v_mad_i64_i32 v[72:73], s[34:35], v72, s52, 0
	v_cvt_pk_bf16_f32 v83, v74, v75
	global_store_dwordx4 v[96:97], v[80:83], off offset:256
	s_nop 1
	v_lshl_add_u64 v[80:81], v[72:73], 1, v[140:141]
	v_cvt_pk_bf16_f32 v72, v84, v85
	v_cvt_pk_bf16_f32 v73, v86, v87
	v_cvt_pk_bf16_f32 v74, v76, v77
	v_cvt_pk_bf16_f32 v75, v78, v79
	global_store_dwordx4 v[80:81], v[72:75], off
	v_cvt_pk_bf16_f32 v68, v68, v69
	v_cvt_pk_bf16_f32 v69, v70, v71
	v_cvt_pk_bf16_f32 v70, v64, v65
	v_add_u32_e32 v64, 0x80, v166
	v_mad_i64_i32 v[64:65], s[34:35], v64, s52, 0
	v_lshl_add_u64 v[64:65], v[64:65], 1, v[140:141]
	v_cvt_pk_bf16_f32 v71, v66, v67
	global_store_dwordx4 v[80:81], v[68:71], off offset:256
	v_cvt_pk_bf16_f32 v60, v60, v61
	v_cvt_pk_bf16_f32 v61, v62, v63
	v_cvt_pk_bf16_f32 v62, v56, v57
	v_cvt_pk_bf16_f32 v63, v58, v59
	global_store_dwordx4 v[64:65], v[60:63], off
	v_cvt_pk_bf16_f32 v48, v48, v49
	v_cvt_pk_bf16_f32 v49, v50, v51
	v_cvt_pk_bf16_f32 v50, v40, v41
	v_add_u32_e32 v40, 0x90, v166
	v_mad_i64_i32 v[40:41], s[34:35], v40, s52, 0
	v_cvt_pk_bf16_f32 v51, v42, v43
	global_store_dwordx4 v[64:65], v[48:51], off offset:256
	s_nop 1
	v_lshl_add_u64 v[48:49], v[40:41], 1, v[140:141]
	v_cvt_pk_bf16_f32 v40, v52, v53
	v_cvt_pk_bf16_f32 v41, v54, v55
	v_cvt_pk_bf16_f32 v42, v44, v45
	v_cvt_pk_bf16_f32 v43, v46, v47
	global_store_dwordx4 v[48:49], v[40:43], off
	v_cvt_pk_bf16_f32 v32, v32, v33
	v_cvt_pk_bf16_f32 v33, v34, v35
	v_cvt_pk_bf16_f32 v34, v24, v25
	v_add_u32_e32 v24, 0xa0, v166
	v_mad_i64_i32 v[24:25], s[34:35], v24, s52, 0
	v_cvt_pk_bf16_f32 v35, v26, v27
	global_store_dwordx4 v[48:49], v[32:35], off offset:256
	s_nop 1
	v_lshl_add_u64 v[32:33], v[24:25], 1, v[140:141]
	v_cvt_pk_bf16_f32 v24, v36, v37
	v_cvt_pk_bf16_f32 v25, v38, v39
	v_cvt_pk_bf16_f32 v26, v28, v29
	v_cvt_pk_bf16_f32 v27, v30, v31
	global_store_dwordx4 v[32:33], v[24:27], off
	v_cvt_pk_bf16_f32 v16, v16, v17
	v_cvt_pk_bf16_f32 v17, v18, v19
	v_cvt_pk_bf16_f32 v18, v8, v9
	v_add_u32_e32 v8, 0xb0, v166
	v_mad_i64_i32 v[8:9], s[34:35], v8, s52, 0
	v_cvt_pk_bf16_f32 v19, v10, v11
	global_store_dwordx4 v[32:33], v[16:19], off offset:256
	s_mov_b64 s[34:35], s[26:27]
	s_nop 0
	v_lshl_add_u64 v[16:17], v[8:9], 1, v[140:141]
	v_cvt_pk_bf16_f32 v8, v20, v21
	v_cvt_pk_bf16_f32 v9, v22, v23
	v_cvt_pk_bf16_f32 v10, v12, v13
	v_cvt_pk_bf16_f32 v11, v14, v15
	global_store_dwordx4 v[16:17], v[8:11], off
	v_cvt_pk_bf16_f32 v4, v4, v5
	v_cvt_pk_bf16_f32 v5, v6, v7
	v_cvt_pk_bf16_f32 v6, v0, v1
	v_cvt_pk_bf16_f32 v7, v2, v3
	global_store_dwordx4 v[16:17], v[4:7], off offset:256
	s_cbranch_vccz .LBB0_186
	s_waitcnt vmcnt(0)
	s_cmpk_gt_u32 s56, 0xff
	s_cbranch_scc1 .LBB0_174
	s_barrier
	s_branch .LBB0_174

.LBB0_203:
	v_add_u32_e32 v148, 0x10000, v151
	ds_read_b128 v[144:147], v153
	ds_read_b128 v[156:159], v153 offset:1024
	ds_read_b128 v[162:165], v153 offset:2048
	ds_read_b128 v[166:169], v153 offset:3072
	s_add_u32 s26, s24, 0xfffc0080
	s_addc_u32 s27, s25, -1
	s_cmp_eq_u32 s54, 12
	s_cselect_b32 s29, s5, s27
	s_cselect_b32 s28, s17, s26
	s_cselect_b32 s27, s15, s53
	s_cselect_b32 s26, s23, s52
	s_add_i32 m0, s36, 0xc000
	ds_read_b128 v[170:173], v154
	ds_read_b128 v[174:177], v154 offset:1024
	ds_read_b128 v[178:181], v154 offset:2048
	ds_read_b128 v[182:185], v154 offset:3072
	ds_read_b128 v[186:189], v154 offset:4096
	ds_read_b128 v[190:193], v154 offset:5120
	ds_read_b128 v[194:197], v154 offset:6144
	ds_read_b128 v[198:201], v154 offset:7168
	global_load_lds_dwordx4 v136, s[24:25]
	s_add_i32 m0, s36, 0xe000
	s_nop 0
	global_load_lds_dwordx4 v138, s[24:25]
	s_waitcnt lgkmcnt(8)
	s_barrier
	s_waitcnt lgkmcnt(0)
	v_mfma_f32_16x16x32_bf16 v[124:127], v[144:147], v[170:173], v[124:127]
	v_mfma_f32_16x16x32_bf16 v[120:123], v[162:165], v[170:173], v[120:123]
	v_mfma_f32_16x16x32_bf16 v[108:111], v[144:147], v[178:181], v[108:111]
	v_mfma_f32_16x16x32_bf16 v[104:107], v[162:165], v[178:181], v[104:107]
	v_mfma_f32_16x16x32_bf16 v[92:95], v[144:147], v[186:189], v[92:95]
	v_mfma_f32_16x16x32_bf16 v[88:91], v[162:165], v[186:189], v[88:91]
	v_mfma_f32_16x16x32_bf16 v[76:79], v[144:147], v[194:197], v[76:79]
	v_mfma_f32_16x16x32_bf16 v[72:75], v[162:165], v[194:197], v[72:75]
	v_mfma_f32_16x16x32_bf16 v[124:127], v[156:159], v[174:177], v[124:127]
	v_mfma_f32_16x16x32_bf16 v[120:123], v[166:169], v[174:177], v[120:123]
	v_mfma_f32_16x16x32_bf16 v[108:111], v[156:159], v[182:185], v[108:111]
	v_mfma_f32_16x16x32_bf16 v[104:107], v[166:169], v[182:185], v[104:107]
	v_mfma_f32_16x16x32_bf16 v[92:95], v[156:159], v[190:193], v[92:95]
	v_mfma_f32_16x16x32_bf16 v[88:91], v[166:169], v[190:193], v[88:91]
	v_mfma_f32_16x16x32_bf16 v[76:79], v[156:159], v[198:201], v[76:79]
	v_mfma_f32_16x16x32_bf16 v[72:75], v[166:169], v[198:201], v[72:75]
	s_barrier
	s_add_i32 s55, s48, s35
	s_add_u32 s98, s26, s12
	s_addc_u32 s99, s27, s13
	s_mov_b32 m0, s55
	ds_read_b128 v[202:205], v155
	ds_read_b128 v[206:209], v155 offset:1024
	ds_read_b128 v[210:213], v155 offset:2048
	ds_read_b128 v[214:217], v155 offset:3072
	global_load_lds_dwordx4 v130, s[26:27]
	s_add_i32 m0, s55, 0x2000
	s_nop 0
	global_load_lds_dwordx4 v134, s[26:27]
	s_barrier
	s_waitcnt lgkmcnt(0)
	v_mfma_f32_16x16x32_bf16 v[116:119], v[202:205], v[170:173], v[116:119]
	v_mfma_f32_16x16x32_bf16 v[112:115], v[210:213], v[170:173], v[112:115]
	v_mfma_f32_16x16x32_bf16 v[100:103], v[202:205], v[178:181], v[100:103]
	v_mfma_f32_16x16x32_bf16 v[96:99], v[210:213], v[178:181], v[96:99]
	v_mfma_f32_16x16x32_bf16 v[84:87], v[202:205], v[186:189], v[84:87]
	v_mfma_f32_16x16x32_bf16 v[80:83], v[210:213], v[186:189], v[80:83]
	v_mfma_f32_16x16x32_bf16 v[68:71], v[202:205], v[194:197], v[68:71]
	v_mfma_f32_16x16x32_bf16 v[64:67], v[210:213], v[194:197], v[64:67]
	v_mfma_f32_16x16x32_bf16 v[116:119], v[206:209], v[174:177], v[116:119]
	v_mfma_f32_16x16x32_bf16 v[112:115], v[214:217], v[174:177], v[112:115]
	v_mfma_f32_16x16x32_bf16 v[100:103], v[206:209], v[182:185], v[100:103]
	v_mfma_f32_16x16x32_bf16 v[96:99], v[214:217], v[182:185], v[96:99]
	v_mfma_f32_16x16x32_bf16 v[84:87], v[206:209], v[190:193], v[84:87]
	v_mfma_f32_16x16x32_bf16 v[80:83], v[214:217], v[190:193], v[80:83]
	v_mfma_f32_16x16x32_bf16 v[68:71], v[206:209], v[198:201], v[68:71]
	v_mfma_f32_16x16x32_bf16 v[64:67], v[214:217], v[198:201], v[64:67]
	s_mov_b32 m0, s36
	s_add_u32 s100, s28, s12
	s_addc_u32 s101, s29, s13
	s_barrier
	ds_read_b128 v[170:173], v154 offset:16384
	ds_read_b128 v[174:177], v154 offset:17408
	ds_read_b128 v[178:181], v154 offset:18432
	ds_read_b128 v[182:185], v154 offset:19456
	ds_read_b128 v[186:189], v154 offset:20480
	ds_read_b128 v[190:193], v154 offset:21504
	ds_read_b128 v[194:197], v154 offset:22528
	ds_read_b128 v[198:201], v154 offset:23552
	global_load_lds_dwordx4 v128, s[28:29]
	s_mov_b32 m0, s37
	s_nop 0
	global_load_lds_dwordx4 v132, s[28:29]
	s_barrier
	s_waitcnt lgkmcnt(0)
	v_mfma_f32_16x16x32_bf16 v[60:63], v[144:147], v[170:173], v[60:63]
	v_mfma_f32_16x16x32_bf16 v[56:59], v[162:165], v[170:173], v[56:59]
	v_mfma_f32_16x16x32_bf16 v[44:47], v[144:147], v[178:181], v[44:47]
	v_mfma_f32_16x16x32_bf16 v[40:43], v[162:165], v[178:181], v[40:43]
	v_mfma_f32_16x16x32_bf16 v[28:31], v[144:147], v[186:189], v[28:31]
	v_mfma_f32_16x16x32_bf16 v[24:27], v[162:165], v[186:189], v[24:27]
	v_mfma_f32_16x16x32_bf16 v[12:15], v[144:147], v[194:197], v[12:15]
	v_mfma_f32_16x16x32_bf16 v[8:11], v[162:165], v[194:197], v[8:11]
	v_mfma_f32_16x16x32_bf16 v[60:63], v[156:159], v[174:177], v[60:63]
	v_mfma_f32_16x16x32_bf16 v[56:59], v[166:169], v[174:177], v[56:59]
	v_mfma_f32_16x16x32_bf16 v[44:47], v[156:159], v[182:185], v[44:47]
	v_mfma_f32_16x16x32_bf16 v[40:43], v[166:169], v[182:185], v[40:43]
	v_mfma_f32_16x16x32_bf16 v[28:31], v[156:159], v[190:193], v[28:31]
	v_mfma_f32_16x16x32_bf16 v[24:27], v[166:169], v[190:193], v[24:27]
	v_mfma_f32_16x16x32_bf16 v[12:15], v[156:159], v[198:201], v[12:15]
	v_mfma_f32_16x16x32_bf16 v[8:11], v[166:169], v[198:201], v[8:11]
	s_barrier
	s_add_u32 s56, s26, 0x40000
	s_addc_u32 s57, s27, 0
	s_add_i32 s55, s49, s35
	s_mov_b32 m0, s55
	s_nop 0
	global_load_lds_dwordx4 v130, s[56:57]
	s_add_i32 m0, s55, 0x2000
	s_nop 0
	global_load_lds_dwordx4 v134, s[56:57]
	s_waitcnt vmcnt(6)
	s_barrier
	v_mfma_f32_16x16x32_bf16 v[52:55], v[202:205], v[170:173], v[52:55]
	v_mfma_f32_16x16x32_bf16 v[48:51], v[210:213], v[170:173], v[48:51]
	v_mfma_f32_16x16x32_bf16 v[36:39], v[202:205], v[178:181], v[36:39]
	v_mfma_f32_16x16x32_bf16 v[32:35], v[210:213], v[178:181], v[32:35]
	v_mfma_f32_16x16x32_bf16 v[20:23], v[202:205], v[186:189], v[20:23]
	v_mfma_f32_16x16x32_bf16 v[16:19], v[210:213], v[186:189], v[16:19]
	v_mfma_f32_16x16x32_bf16 v[4:7], v[202:205], v[194:197], v[4:7]
	v_mfma_f32_16x16x32_bf16 v[0:3], v[210:213], v[194:197], v[0:3]
	v_mfma_f32_16x16x32_bf16 v[52:55], v[206:209], v[174:177], v[52:55]
	v_mfma_f32_16x16x32_bf16 v[48:51], v[214:217], v[174:177], v[48:51]
	v_mfma_f32_16x16x32_bf16 v[36:39], v[206:209], v[182:185], v[36:39]
	v_mfma_f32_16x16x32_bf16 v[32:35], v[214:217], v[182:185], v[32:35]
	v_mfma_f32_16x16x32_bf16 v[20:23], v[206:209], v[190:193], v[20:23]
	v_mfma_f32_16x16x32_bf16 v[16:19], v[214:217], v[190:193], v[16:19]
	v_mfma_f32_16x16x32_bf16 v[4:7], v[206:209], v[198:201], v[4:7]
	v_mfma_f32_16x16x32_bf16 v[0:3], v[214:217], v[198:201], v[0:3]
	s_add_i32 s55, 0, 0x18000
	s_barrier
	ds_read_b128 v[144:147], v148 offset:32768
	ds_read_b128 v[156:159], v148 offset:33792
	ds_read_b128 v[162:165], v148 offset:34816
	ds_read_b128 v[166:169], v148 offset:35840
	s_add_u32 s28, s28, 0x40000
	s_addc_u32 s29, s29, 0
	s_mov_b32 m0, s38
	ds_read_b128 v[170:173], v154 offset:32768
	ds_read_b128 v[174:177], v154 offset:33792
	ds_read_b128 v[178:181], v154 offset:34816
	ds_read_b128 v[182:185], v154 offset:35840
	ds_read_b128 v[186:189], v154 offset:36864
	ds_read_b128 v[190:193], v154 offset:37888
	ds_read_b128 v[194:197], v154 offset:38912
	ds_read_b128 v[198:201], v154 offset:39936
	global_load_lds_dwordx4 v128, s[28:29]
	s_mov_b32 m0, s39
	s_nop 0
	global_load_lds_dwordx4 v132, s[28:29]
	s_waitcnt lgkmcnt(8)
	s_barrier
	s_waitcnt lgkmcnt(0)
	v_mfma_f32_16x16x32_bf16 v[124:127], v[144:147], v[170:173], v[124:127]
	v_mfma_f32_16x16x32_bf16 v[120:123], v[162:165], v[170:173], v[120:123]
	v_mfma_f32_16x16x32_bf16 v[108:111], v[144:147], v[178:181], v[108:111]
	v_mfma_f32_16x16x32_bf16 v[104:107], v[162:165], v[178:181], v[104:107]
	v_mfma_f32_16x16x32_bf16 v[92:95], v[144:147], v[186:189], v[92:95]
	v_mfma_f32_16x16x32_bf16 v[88:91], v[162:165], v[186:189], v[88:91]
	v_mfma_f32_16x16x32_bf16 v[76:79], v[144:147], v[194:197], v[76:79]
	v_mfma_f32_16x16x32_bf16 v[72:75], v[162:165], v[194:197], v[72:75]
	v_mfma_f32_16x16x32_bf16 v[124:127], v[156:159], v[174:177], v[124:127]
	v_mfma_f32_16x16x32_bf16 v[120:123], v[166:169], v[174:177], v[120:123]
	v_mfma_f32_16x16x32_bf16 v[108:111], v[156:159], v[182:185], v[108:111]
	v_mfma_f32_16x16x32_bf16 v[104:107], v[166:169], v[182:185], v[104:107]
	v_mfma_f32_16x16x32_bf16 v[92:95], v[156:159], v[190:193], v[92:95]
	v_mfma_f32_16x16x32_bf16 v[88:91], v[166:169], v[190:193], v[88:91]
	v_mfma_f32_16x16x32_bf16 v[76:79], v[156:159], v[198:201], v[76:79]
	v_mfma_f32_16x16x32_bf16 v[72:75], v[166:169], v[198:201], v[72:75]
	s_barrier
	s_add_i32 s28, 0, 0x1c000
	s_add_i32 s29, s55, s35
	s_mov_b32 m0, s29
	ds_read_b128 v[202:205], v148 offset:49152
	ds_read_b128 v[206:209], v148 offset:50176
	ds_read_b128 v[210:213], v148 offset:51200
	ds_read_b128 v[214:217], v148 offset:52224
	global_load_lds_dwordx4 v130, s[98:99]
	s_add_i32 m0, s29, 0x2000
	s_nop 0
	global_load_lds_dwordx4 v134, s[98:99]
	s_barrier
	s_waitcnt lgkmcnt(0)
	v_mfma_f32_16x16x32_bf16 v[116:119], v[202:205], v[170:173], v[116:119]
	v_mfma_f32_16x16x32_bf16 v[112:115], v[210:213], v[170:173], v[112:115]
	v_mfma_f32_16x16x32_bf16 v[100:103], v[202:205], v[178:181], v[100:103]
	v_mfma_f32_16x16x32_bf16 v[96:99], v[210:213], v[178:181], v[96:99]
	v_mfma_f32_16x16x32_bf16 v[84:87], v[202:205], v[186:189], v[84:87]
	v_mfma_f32_16x16x32_bf16 v[80:83], v[210:213], v[186:189], v[80:83]
	v_mfma_f32_16x16x32_bf16 v[68:71], v[202:205], v[194:197], v[68:71]
	v_mfma_f32_16x16x32_bf16 v[64:67], v[210:213], v[194:197], v[64:67]
	v_mfma_f32_16x16x32_bf16 v[116:119], v[206:209], v[174:177], v[116:119]
	v_mfma_f32_16x16x32_bf16 v[112:115], v[214:217], v[174:177], v[112:115]
	v_mfma_f32_16x16x32_bf16 v[100:103], v[206:209], v[182:185], v[100:103]
	v_mfma_f32_16x16x32_bf16 v[96:99], v[214:217], v[182:185], v[96:99]
	v_mfma_f32_16x16x32_bf16 v[84:87], v[206:209], v[190:193], v[84:87]
	v_mfma_f32_16x16x32_bf16 v[80:83], v[214:217], v[190:193], v[80:83]
	v_mfma_f32_16x16x32_bf16 v[68:71], v[206:209], v[198:201], v[68:71]
	v_mfma_f32_16x16x32_bf16 v[64:67], v[214:217], v[198:201], v[64:67]
	s_mov_b32 m0, s44
	s_barrier
	ds_read_b128 v[170:173], v154 offset:49152
	ds_read_b128 v[174:177], v154 offset:50176
	ds_read_b128 v[178:181], v154 offset:51200
	ds_read_b128 v[182:185], v154 offset:52224
	ds_read_b128 v[186:189], v154 offset:53248
	ds_read_b128 v[190:193], v154 offset:54272
	ds_read_b128 v[194:197], v154 offset:55296
	ds_read_b128 v[198:201], v154 offset:56320
	global_load_lds_dwordx4 v128, s[100:101]
	s_mov_b32 m0, s46
	s_nop 0
	global_load_lds_dwordx4 v132, s[100:101]
	s_barrier
	s_waitcnt lgkmcnt(0)
	v_mfma_f32_16x16x32_bf16 v[60:63], v[144:147], v[170:173], v[60:63]
	v_mfma_f32_16x16x32_bf16 v[56:59], v[162:165], v[170:173], v[56:59]
	v_mfma_f32_16x16x32_bf16 v[44:47], v[144:147], v[178:181], v[44:47]
	v_mfma_f32_16x16x32_bf16 v[40:43], v[162:165], v[178:181], v[40:43]
	v_mfma_f32_16x16x32_bf16 v[28:31], v[144:147], v[186:189], v[28:31]
	v_mfma_f32_16x16x32_bf16 v[24:27], v[162:165], v[186:189], v[24:27]
	v_mfma_f32_16x16x32_bf16 v[12:15], v[144:147], v[194:197], v[12:15]
	v_mfma_f32_16x16x32_bf16 v[8:11], v[162:165], v[194:197], v[8:11]
	v_mfma_f32_16x16x32_bf16 v[60:63], v[156:159], v[174:177], v[60:63]
	v_mfma_f32_16x16x32_bf16 v[56:59], v[166:169], v[174:177], v[56:59]
	v_mfma_f32_16x16x32_bf16 v[44:47], v[156:159], v[182:185], v[44:47]
	v_mfma_f32_16x16x32_bf16 v[40:43], v[166:169], v[182:185], v[40:43]
	v_mfma_f32_16x16x32_bf16 v[28:31], v[156:159], v[190:193], v[28:31]
	v_mfma_f32_16x16x32_bf16 v[24:27], v[166:169], v[190:193], v[24:27]
	v_mfma_f32_16x16x32_bf16 v[12:15], v[156:159], v[198:201], v[12:15]
	v_mfma_f32_16x16x32_bf16 v[8:11], v[166:169], v[198:201], v[8:11]
	s_barrier
	s_add_u32 s26, s26, 0x40080
	s_addc_u32 s27, s27, 0
	s_add_i32 s28, s28, s35
	s_mov_b32 m0, s28
	s_nop 0
	global_load_lds_dwordx4 v130, s[26:27]
	s_add_i32 m0, s28, 0x2000
	s_nop 0
	global_load_lds_dwordx4 v134, s[26:27]
	s_waitcnt vmcnt(6)
	s_barrier
	v_mfma_f32_16x16x32_bf16 v[52:55], v[202:205], v[170:173], v[52:55]
	v_mfma_f32_16x16x32_bf16 v[48:51], v[210:213], v[170:173], v[48:51]
	v_mfma_f32_16x16x32_bf16 v[36:39], v[202:205], v[178:181], v[36:39]
	v_mfma_f32_16x16x32_bf16 v[32:35], v[210:213], v[178:181], v[32:35]
	v_mfma_f32_16x16x32_bf16 v[20:23], v[202:205], v[186:189], v[20:23]
	v_mfma_f32_16x16x32_bf16 v[16:19], v[210:213], v[186:189], v[16:19]
	v_mfma_f32_16x16x32_bf16 v[4:7], v[202:205], v[194:197], v[4:7]
	v_mfma_f32_16x16x32_bf16 v[0:3], v[210:213], v[194:197], v[0:3]
	v_mfma_f32_16x16x32_bf16 v[52:55], v[206:209], v[174:177], v[52:55]
	v_mfma_f32_16x16x32_bf16 v[48:51], v[214:217], v[174:177], v[48:51]
	v_mfma_f32_16x16x32_bf16 v[36:39], v[206:209], v[182:185], v[36:39]
	v_mfma_f32_16x16x32_bf16 v[32:35], v[214:217], v[182:185], v[32:35]
	v_mfma_f32_16x16x32_bf16 v[20:23], v[206:209], v[190:193], v[20:23]
	v_mfma_f32_16x16x32_bf16 v[16:19], v[214:217], v[190:193], v[16:19]
	v_mfma_f32_16x16x32_bf16 v[4:7], v[206:209], v[198:201], v[4:7]
	v_mfma_f32_16x16x32_bf16 v[0:3], v[214:217], v[198:201], v[0:3]
	s_add_i32 s54, s54, 2
	s_add_u32 s24, s24, 0x100
	s_addc_u32 s25, s25, 0
	s_add_u32 s52, s52, 0x100
	s_addc_u32 s53, s53, 0
	s_cmp_gt_u32 s54, 13
	s_barrier
	s_cbranch_scc0 .LBB0_203
	v_lshl_or_b32 v148, s22, 8, v152
	v_cmp_lt_i32_e32 vcc, s50, v148
	s_and_saveexec_b64 s[22:23], vcc
	s_cbranch_execz .LBB0_206
	v_mul_f32_e32 v149, 0x3d372713, v126
	v_mul_f32_e32 v145, 0x3d372713, v120
	v_mul_f32_e32 v149, v126, v149
	v_mul_f32_e32 v156, 0x3d372713, v122
	v_mul_f32_e32 v145, v120, v145
	v_mul_f32_e32 v146, 0x3d372713, v125
	v_fma_f32 v149, v126, v149, v126
	v_mul_f32_e32 v156, v122, v156
	v_fma_f32 v145, v120, v145, v120
	v_mul_f32_e32 v146, v125, v146
	v_mul_f32_e32 v149, 0xc0135761, v149
	v_fma_f32 v156, v122, v156, v122
	v_mul_f32_e32 v145, 0xc0135761, v145
	v_fma_f32 v146, v125, v146, v125
	v_exp_f32_e32 v149, v149
	v_mul_f32_e32 v156, 0xc0135761, v156
	v_exp_f32_e32 v145, v145
	v_mul_f32_e32 v146, 0xc0135761, v146
	v_exp_f32_e32 v157, v156
	v_exp_f32_e32 v147, v146
	v_add_f32_e32 v149, 1.0, v149
	v_add_f32_e32 v145, 1.0, v145
	v_rcp_f32_e32 v156, v149
	v_add_f32_e32 v149, 1.0, v157
	v_mul_f32_e32 v157, 0x3d372713, v127
	v_mul_f32_e32 v144, 0x3d372713, v124
	v_rcp_f32_e32 v146, v145
	v_add_f32_e32 v145, 1.0, v147
	v_mul_f32_e32 v147, 0x3d372713, v121
	v_mul_f32_e32 v157, v127, v157
	v_mul_f32_e32 v158, 0x3d372713, v123
	v_mul_f32_e32 v144, v124, v144
	v_mul_f32_e32 v147, v121, v147
	v_fma_f32 v157, v127, v157, v127
	v_mul_f32_e32 v158, v123, v158
	v_fma_f32 v144, v124, v144, v124
	v_fma_f32 v147, v121, v147, v121
	v_mul_f32_e32 v157, 0xc0135761, v157
	v_fma_f32 v158, v123, v158, v123
	v_mul_f32_e32 v144, 0xc0135761, v144
	v_mul_f32_e32 v147, 0xc0135761, v147
	v_exp_f32_e32 v157, v157
	v_mul_f32_e32 v158, 0xc0135761, v158
	v_exp_f32_e32 v144, v144
	v_exp_f32_e32 v147, v147
	v_exp_f32_e32 v159, v158
	v_rcp_f32_e32 v158, v149
	v_add_f32_e32 v149, 1.0, v157
	v_add_f32_e32 v144, 1.0, v144
	v_add_f32_e32 v147, 1.0, v147
	v_rcp_f32_e32 v157, v149
	v_add_f32_e32 v149, 1.0, v159
	v_rcp_f32_e32 v144, v144
	v_rcp_f32_e32 v145, v145
	v_rcp_f32_e32 v159, v149
	v_rcp_f32_e32 v147, v147
	v_pk_mul_f32 v[126:127], v[126:127], v[156:157]
	v_pk_mul_f32 v[124:125], v[124:125], v[144:145]
	v_pk_mul_f32 v[122:123], v[122:123], v[158:159]
	v_pk_mul_f32 v[120:121], v[120:121], v[146:147]

.LBB0_321:
	v_add_u32_e32 v152, 0x10000, v155
	ds_read_b128 v[144:147], v157
	ds_read_b128 v[148:151], v157 offset:1024
	ds_read_b128 v[164:167], v157 offset:2048
	ds_read_b128 v[168:171], v157 offset:3072
	s_add_u32 s4, s8, 0x100
	s_addc_u32 s5, s9, 0
	s_cmp_eq_u32 s60, 2
	s_cselect_b32 s11, s29, s5
	s_cselect_b32 s10, s28, s4
	s_cselect_b32 s7, s31, s37
	s_cselect_b32 s6, s30, s35
	s_add_i32 m0, s46, 0xc000
	ds_read_b128 v[172:175], v158
	ds_read_b128 v[176:179], v158 offset:1024
	ds_read_b128 v[180:183], v158 offset:2048
	ds_read_b128 v[184:187], v158 offset:3072
	ds_read_b128 v[188:191], v158 offset:4096
	ds_read_b128 v[192:195], v158 offset:5120
	ds_read_b128 v[196:199], v158 offset:6144
	ds_read_b128 v[200:203], v158 offset:7168
	global_load_lds_dwordx4 v136, s[8:9]
	s_add_i32 m0, s46, 0xe000
	s_nop 0
	global_load_lds_dwordx4 v138, s[8:9]
	s_waitcnt lgkmcnt(8)
	s_barrier
	s_waitcnt lgkmcnt(0)
	v_mfma_f32_16x16x32_bf16 v[124:127], v[144:147], v[172:175], v[124:127]
	v_mfma_f32_16x16x32_bf16 v[120:123], v[164:167], v[172:175], v[120:123]
	v_mfma_f32_16x16x32_bf16 v[116:119], v[144:147], v[180:183], v[116:119]
	v_mfma_f32_16x16x32_bf16 v[112:115], v[164:167], v[180:183], v[112:115]
	v_mfma_f32_16x16x32_bf16 v[108:111], v[144:147], v[188:191], v[108:111]
	v_mfma_f32_16x16x32_bf16 v[104:107], v[164:167], v[188:191], v[104:107]
	v_mfma_f32_16x16x32_bf16 v[100:103], v[144:147], v[196:199], v[100:103]
	v_mfma_f32_16x16x32_bf16 v[96:99], v[164:167], v[196:199], v[96:99]
	v_mfma_f32_16x16x32_bf16 v[124:127], v[148:151], v[176:179], v[124:127]
	v_mfma_f32_16x16x32_bf16 v[120:123], v[168:171], v[176:179], v[120:123]
	v_mfma_f32_16x16x32_bf16 v[116:119], v[148:151], v[184:187], v[116:119]
	v_mfma_f32_16x16x32_bf16 v[112:115], v[168:171], v[184:187], v[112:115]
	v_mfma_f32_16x16x32_bf16 v[108:111], v[148:151], v[192:195], v[108:111]
	v_mfma_f32_16x16x32_bf16 v[104:107], v[168:171], v[192:195], v[104:107]
	v_mfma_f32_16x16x32_bf16 v[100:103], v[148:151], v[200:203], v[100:103]
	v_mfma_f32_16x16x32_bf16 v[96:99], v[168:171], v[200:203], v[96:99]
	s_barrier
	s_add_i32 s8, s54, s44
	s_add_u32 s98, s6, s26
	s_addc_u32 s99, s7, s27
	s_mov_b32 m0, s8
	ds_read_b128 v[204:207], v159
	ds_read_b128 v[208:211], v159 offset:1024
	ds_read_b128 v[212:215], v159 offset:2048
	ds_read_b128 v[216:219], v159 offset:3072
	global_load_lds_dwordx4 v130, s[6:7]
	s_add_i32 m0, s8, 0x2000
	s_nop 0
	global_load_lds_dwordx4 v134, s[6:7]
	s_barrier
	s_waitcnt lgkmcnt(0)
	v_mfma_f32_16x16x32_bf16 v[60:63], v[204:207], v[172:175], v[60:63]
	v_mfma_f32_16x16x32_bf16 v[56:59], v[212:215], v[172:175], v[56:59]
	v_mfma_f32_16x16x32_bf16 v[52:55], v[204:207], v[180:183], v[52:55]
	v_mfma_f32_16x16x32_bf16 v[48:51], v[212:215], v[180:183], v[48:51]
	v_mfma_f32_16x16x32_bf16 v[44:47], v[204:207], v[188:191], v[44:47]
	v_mfma_f32_16x16x32_bf16 v[40:43], v[212:215], v[188:191], v[40:43]
	v_mfma_f32_16x16x32_bf16 v[36:39], v[204:207], v[196:199], v[36:39]
	v_mfma_f32_16x16x32_bf16 v[32:35], v[212:215], v[196:199], v[32:35]
	v_mfma_f32_16x16x32_bf16 v[60:63], v[208:211], v[176:179], v[60:63]
	v_mfma_f32_16x16x32_bf16 v[56:59], v[216:219], v[176:179], v[56:59]
	v_mfma_f32_16x16x32_bf16 v[52:55], v[208:211], v[184:187], v[52:55]
	v_mfma_f32_16x16x32_bf16 v[48:51], v[216:219], v[184:187], v[48:51]
	v_mfma_f32_16x16x32_bf16 v[44:47], v[208:211], v[192:195], v[44:47]
	v_mfma_f32_16x16x32_bf16 v[40:43], v[216:219], v[192:195], v[40:43]
	v_mfma_f32_16x16x32_bf16 v[36:39], v[208:211], v[200:203], v[36:39]
	v_mfma_f32_16x16x32_bf16 v[32:35], v[216:219], v[200:203], v[32:35]
	s_mov_b32 m0, s46
	s_add_u32 s100, s10, s26
	s_addc_u32 s101, s11, s27
	s_barrier
	ds_read_b128 v[172:175], v158 offset:16384
	ds_read_b128 v[176:179], v158 offset:17408
	ds_read_b128 v[180:183], v158 offset:18432
	ds_read_b128 v[184:187], v158 offset:19456
	ds_read_b128 v[188:191], v158 offset:20480
	ds_read_b128 v[192:195], v158 offset:21504
	ds_read_b128 v[196:199], v158 offset:22528
	ds_read_b128 v[200:203], v158 offset:23552
	global_load_lds_dwordx4 v128, s[10:11]
	s_mov_b32 m0, s47
	s_nop 0
	global_load_lds_dwordx4 v132, s[10:11]
	s_barrier
	s_waitcnt lgkmcnt(0)
	v_mfma_f32_16x16x32_bf16 v[92:95], v[144:147], v[172:175], v[92:95]
	v_mfma_f32_16x16x32_bf16 v[88:91], v[164:167], v[172:175], v[88:91]
	v_mfma_f32_16x16x32_bf16 v[84:87], v[144:147], v[180:183], v[84:87]
	v_mfma_f32_16x16x32_bf16 v[80:83], v[164:167], v[180:183], v[80:83]
	v_mfma_f32_16x16x32_bf16 v[76:79], v[144:147], v[188:191], v[76:79]
	v_mfma_f32_16x16x32_bf16 v[72:75], v[164:167], v[188:191], v[72:75]
	v_mfma_f32_16x16x32_bf16 v[68:71], v[144:147], v[196:199], v[68:71]
	v_mfma_f32_16x16x32_bf16 v[64:67], v[164:167], v[196:199], v[64:67]
	v_mfma_f32_16x16x32_bf16 v[92:95], v[148:151], v[176:179], v[92:95]
	v_mfma_f32_16x16x32_bf16 v[88:91], v[168:171], v[176:179], v[88:91]
	v_mfma_f32_16x16x32_bf16 v[84:87], v[148:151], v[184:187], v[84:87]
	v_mfma_f32_16x16x32_bf16 v[80:83], v[168:171], v[184:187], v[80:83]
	v_mfma_f32_16x16x32_bf16 v[76:79], v[148:151], v[192:195], v[76:79]
	v_mfma_f32_16x16x32_bf16 v[72:75], v[168:171], v[192:195], v[72:75]
	v_mfma_f32_16x16x32_bf16 v[68:71], v[148:151], v[200:203], v[68:71]
	v_mfma_f32_16x16x32_bf16 v[64:67], v[168:171], v[200:203], v[64:67]
	s_barrier
	s_add_u32 s8, s6, 0x18000
	s_addc_u32 s9, s7, 0
	s_add_i32 s61, s55, s44
	s_mov_b32 m0, s61
	s_nop 0
	global_load_lds_dwordx4 v130, s[8:9]
	s_add_i32 m0, s61, 0x2000
	s_nop 0
	global_load_lds_dwordx4 v134, s[8:9]
	s_waitcnt vmcnt(6)
	s_barrier
	v_mfma_f32_16x16x32_bf16 v[28:31], v[204:207], v[172:175], v[28:31]
	v_mfma_f32_16x16x32_bf16 v[24:27], v[212:215], v[172:175], v[24:27]
	v_mfma_f32_16x16x32_bf16 v[20:23], v[204:207], v[180:183], v[20:23]
	v_mfma_f32_16x16x32_bf16 v[16:19], v[212:215], v[180:183], v[16:19]
	v_mfma_f32_16x16x32_bf16 v[12:15], v[204:207], v[188:191], v[12:15]
	v_mfma_f32_16x16x32_bf16 v[8:11], v[212:215], v[188:191], v[8:11]
	v_mfma_f32_16x16x32_bf16 v[4:7], v[204:207], v[196:199], v[4:7]
	v_mfma_f32_16x16x32_bf16 v[0:3], v[212:215], v[196:199], v[0:3]
	v_mfma_f32_16x16x32_bf16 v[28:31], v[208:211], v[176:179], v[28:31]
	v_mfma_f32_16x16x32_bf16 v[24:27], v[216:219], v[176:179], v[24:27]
	v_mfma_f32_16x16x32_bf16 v[20:23], v[208:211], v[184:187], v[20:23]
	v_mfma_f32_16x16x32_bf16 v[16:19], v[216:219], v[184:187], v[16:19]
	v_mfma_f32_16x16x32_bf16 v[12:15], v[208:211], v[192:195], v[12:15]
	v_mfma_f32_16x16x32_bf16 v[8:11], v[216:219], v[192:195], v[8:11]
	v_mfma_f32_16x16x32_bf16 v[4:7], v[208:211], v[200:203], v[4:7]
	v_mfma_f32_16x16x32_bf16 v[0:3], v[216:219], v[200:203], v[0:3]
	s_add_i32 s61, 0, 0x18000
	s_barrier
	ds_read_b128 v[144:147], v152 offset:32768
	ds_read_b128 v[148:151], v152 offset:33792
	ds_read_b128 v[164:167], v152 offset:34816
	ds_read_b128 v[168:171], v152 offset:35840
	s_add_u32 s8, s10, 0x18000
	s_addc_u32 s9, s11, 0
	s_mov_b32 m0, s48
	ds_read_b128 v[172:175], v158 offset:32768
	ds_read_b128 v[176:179], v158 offset:33792
	ds_read_b128 v[180:183], v158 offset:34816
	ds_read_b128 v[184:187], v158 offset:35840
	ds_read_b128 v[188:191], v158 offset:36864
	ds_read_b128 v[192:195], v158 offset:37888
	ds_read_b128 v[196:199], v158 offset:38912
	ds_read_b128 v[200:203], v158 offset:39936
	global_load_lds_dwordx4 v128, s[8:9]
	s_mov_b32 m0, s49
	s_nop 0
	global_load_lds_dwordx4 v132, s[8:9]
	s_waitcnt lgkmcnt(8)
	s_barrier
	s_waitcnt lgkmcnt(0)
	v_mfma_f32_16x16x32_bf16 v[124:127], v[144:147], v[172:175], v[124:127]
	v_mfma_f32_16x16x32_bf16 v[120:123], v[164:167], v[172:175], v[120:123]
	v_mfma_f32_16x16x32_bf16 v[116:119], v[144:147], v[180:183], v[116:119]
	v_mfma_f32_16x16x32_bf16 v[112:115], v[164:167], v[180:183], v[112:115]
	v_mfma_f32_16x16x32_bf16 v[108:111], v[144:147], v[188:191], v[108:111]
	v_mfma_f32_16x16x32_bf16 v[104:107], v[164:167], v[188:191], v[104:107]
	v_mfma_f32_16x16x32_bf16 v[100:103], v[144:147], v[196:199], v[100:103]
	v_mfma_f32_16x16x32_bf16 v[96:99], v[164:167], v[196:199], v[96:99]
	v_mfma_f32_16x16x32_bf16 v[124:127], v[148:151], v[176:179], v[124:127]
	v_mfma_f32_16x16x32_bf16 v[120:123], v[168:171], v[176:179], v[120:123]
	v_mfma_f32_16x16x32_bf16 v[116:119], v[148:151], v[184:187], v[116:119]
	v_mfma_f32_16x16x32_bf16 v[112:115], v[168:171], v[184:187], v[112:115]
	v_mfma_f32_16x16x32_bf16 v[108:111], v[148:151], v[192:195], v[108:111]
	v_mfma_f32_16x16x32_bf16 v[104:107], v[168:171], v[192:195], v[104:107]
	v_mfma_f32_16x16x32_bf16 v[100:103], v[148:151], v[200:203], v[100:103]
	v_mfma_f32_16x16x32_bf16 v[96:99], v[168:171], v[200:203], v[96:99]
	s_barrier
	s_add_i32 s8, 0, 0x1c000
	s_add_i32 s9, s61, s44
	s_mov_b32 m0, s9
	ds_read_b128 v[204:207], v152 offset:49152
	ds_read_b128 v[208:211], v152 offset:50176
	ds_read_b128 v[212:215], v152 offset:51200
	ds_read_b128 v[216:219], v152 offset:52224
	global_load_lds_dwordx4 v130, s[98:99]
	s_add_i32 m0, s9, 0x2000
	s_nop 0
	global_load_lds_dwordx4 v134, s[98:99]
	s_barrier
	s_waitcnt lgkmcnt(0)
	v_mfma_f32_16x16x32_bf16 v[60:63], v[204:207], v[172:175], v[60:63]
	v_mfma_f32_16x16x32_bf16 v[56:59], v[212:215], v[172:175], v[56:59]
	v_mfma_f32_16x16x32_bf16 v[52:55], v[204:207], v[180:183], v[52:55]
	v_mfma_f32_16x16x32_bf16 v[48:51], v[212:215], v[180:183], v[48:51]
	v_mfma_f32_16x16x32_bf16 v[44:47], v[204:207], v[188:191], v[44:47]
	v_mfma_f32_16x16x32_bf16 v[40:43], v[212:215], v[188:191], v[40:43]
	v_mfma_f32_16x16x32_bf16 v[36:39], v[204:207], v[196:199], v[36:39]
	v_mfma_f32_16x16x32_bf16 v[32:35], v[212:215], v[196:199], v[32:35]
	v_mfma_f32_16x16x32_bf16 v[60:63], v[208:211], v[176:179], v[60:63]
	v_mfma_f32_16x16x32_bf16 v[56:59], v[216:219], v[176:179], v[56:59]
	v_mfma_f32_16x16x32_bf16 v[52:55], v[208:211], v[184:187], v[52:55]
	v_mfma_f32_16x16x32_bf16 v[48:51], v[216:219], v[184:187], v[48:51]
	v_mfma_f32_16x16x32_bf16 v[44:47], v[208:211], v[192:195], v[44:47]
	v_mfma_f32_16x16x32_bf16 v[40:43], v[216:219], v[192:195], v[40:43]
	v_mfma_f32_16x16x32_bf16 v[36:39], v[208:211], v[200:203], v[36:39]
	v_mfma_f32_16x16x32_bf16 v[32:35], v[216:219], v[200:203], v[32:35]
	s_mov_b32 m0, s51
	s_barrier
	ds_read_b128 v[172:175], v158 offset:49152
	ds_read_b128 v[176:179], v158 offset:50176
	ds_read_b128 v[180:183], v158 offset:51200
	ds_read_b128 v[184:187], v158 offset:52224
	ds_read_b128 v[188:191], v158 offset:53248
	ds_read_b128 v[192:195], v158 offset:54272
	ds_read_b128 v[196:199], v158 offset:55296
	ds_read_b128 v[200:203], v158 offset:56320
	global_load_lds_dwordx4 v128, s[100:101]
	s_mov_b32 m0, s52
	s_nop 0
	global_load_lds_dwordx4 v132, s[100:101]
	s_barrier
	s_waitcnt lgkmcnt(0)
	v_mfma_f32_16x16x32_bf16 v[92:95], v[144:147], v[172:175], v[92:95]
	v_mfma_f32_16x16x32_bf16 v[88:91], v[164:167], v[172:175], v[88:91]
	v_mfma_f32_16x16x32_bf16 v[84:87], v[144:147], v[180:183], v[84:87]
	v_mfma_f32_16x16x32_bf16 v[80:83], v[164:167], v[180:183], v[80:83]
	v_mfma_f32_16x16x32_bf16 v[76:79], v[144:147], v[188:191], v[76:79]
	v_mfma_f32_16x16x32_bf16 v[72:75], v[164:167], v[188:191], v[72:75]
	v_mfma_f32_16x16x32_bf16 v[68:71], v[144:147], v[196:199], v[68:71]
	v_mfma_f32_16x16x32_bf16 v[64:67], v[164:167], v[196:199], v[64:67]
	v_mfma_f32_16x16x32_bf16 v[92:95], v[148:151], v[176:179], v[92:95]
	v_mfma_f32_16x16x32_bf16 v[88:91], v[168:171], v[176:179], v[88:91]
	v_mfma_f32_16x16x32_bf16 v[84:87], v[148:151], v[184:187], v[84:87]
	v_mfma_f32_16x16x32_bf16 v[80:83], v[168:171], v[184:187], v[80:83]
	v_mfma_f32_16x16x32_bf16 v[76:79], v[148:151], v[192:195], v[76:79]
	v_mfma_f32_16x16x32_bf16 v[72:75], v[168:171], v[192:195], v[72:75]
	v_mfma_f32_16x16x32_bf16 v[68:71], v[148:151], v[200:203], v[68:71]
	v_mfma_f32_16x16x32_bf16 v[64:67], v[168:171], v[200:203], v[64:67]
	s_barrier
	s_add_u32 s6, s6, 0x18080
	s_addc_u32 s7, s7, 0
	s_add_i32 s8, s8, s44
	s_mov_b32 m0, s8
	s_nop 0
	global_load_lds_dwordx4 v130, s[6:7]
	s_add_i32 m0, s8, 0x2000
	s_nop 0
	global_load_lds_dwordx4 v134, s[6:7]
	s_waitcnt vmcnt(6)
	s_barrier
	v_mfma_f32_16x16x32_bf16 v[28:31], v[204:207], v[172:175], v[28:31]
	v_mfma_f32_16x16x32_bf16 v[24:27], v[212:215], v[172:175], v[24:27]
	v_mfma_f32_16x16x32_bf16 v[20:23], v[204:207], v[180:183], v[20:23]
	v_mfma_f32_16x16x32_bf16 v[16:19], v[212:215], v[180:183], v[16:19]
	v_mfma_f32_16x16x32_bf16 v[12:15], v[204:207], v[188:191], v[12:15]
	v_mfma_f32_16x16x32_bf16 v[8:11], v[212:215], v[188:191], v[8:11]
	v_mfma_f32_16x16x32_bf16 v[4:7], v[204:207], v[196:199], v[4:7]
	v_mfma_f32_16x16x32_bf16 v[0:3], v[212:215], v[196:199], v[0:3]
	v_mfma_f32_16x16x32_bf16 v[28:31], v[208:211], v[176:179], v[28:31]
	v_mfma_f32_16x16x32_bf16 v[24:27], v[216:219], v[176:179], v[24:27]
	v_mfma_f32_16x16x32_bf16 v[20:23], v[208:211], v[184:187], v[20:23]
	v_mfma_f32_16x16x32_bf16 v[16:19], v[216:219], v[184:187], v[16:19]
	v_mfma_f32_16x16x32_bf16 v[12:15], v[208:211], v[192:195], v[12:15]
	v_mfma_f32_16x16x32_bf16 v[8:11], v[216:219], v[192:195], v[8:11]
	v_mfma_f32_16x16x32_bf16 v[4:7], v[208:211], v[200:203], v[4:7]
	v_mfma_f32_16x16x32_bf16 v[0:3], v[216:219], v[200:203], v[0:3]
	s_add_i32 s60, s60, 2
	s_add_u32 s35, s35, 0x100
	s_addc_u32 s37, s37, 0
	s_cmp_gt_u32 s60, 3
	s_mov_b64 s[8:9], s[4:5]
	s_barrier
	s_cbranch_scc0 .LBB0_321
	s_lshl_b32 s37, s34, 8
	s_ashr_i32 s6, s34, 1
	s_cmp_lt_i32 s6, 2
	s_cselect_b64 s[8:9], -1, 0
	s_cmp_gt_i32 s6, 1
	s_cselect_b64 s[34:35], -1, 0
	s_lshl_b32 s60, s6, 9
	s_add_i32 s61, s60, 0xfffffc00
	v_bitop3_b32 v144, s37, v161, v156 bitop3:0xc8
	v_or_b32_e32 v146, s61, v144
	v_or_b32_e32 v144, s60, v144
	v_mov_b32_e32 v145, 0
	s_cmp_lt_i32 s6, 4
	v_cndmask_b32_e64 v152, v146, v144, s[8:9]
	s_cselect_b64 s[4:5], -1, 0
	s_cmp_gt_i32 s6, 3
	v_ashrrev_i32_e32 v153, 31, v152
	v_mov_b32_e32 v144, v145
	s_cbranch_scc1 .LBB0_330
	s_and_b64 s[10:11], s[8:9], exec
	s_cselect_b32 s7, s21, s23
	s_cselect_b32 s10, s20, s22
	v_mov_b32_e32 v146, s10
	v_mov_b32_e32 v147, s7
	v_lshl_add_u64 v[146:147], v[152:153], 2, v[146:147]
	global_load_dword v144, v[146:147], off
	v_cndmask_b32_e64 v146, 0, 1, s[4:5]
	v_cmp_ne_u32_e64 s[10:11], 1, v146
	s_andn2_b64 vcc, exec, s[4:5]
	s_cbranch_vccz .LBB0_331

.LBB0_583:
	v_add_u32_e32 v216, 0x10000, v162
	ds_read_b128 v[128:131], v164
	ds_read_b128 v[132:135], v164 offset:1024
	ds_read_b128 v[152:155], v164 offset:2048
	ds_read_b128 v[156:159], v164 offset:3072
	s_add_u32 s38, s36, 0xfffc0080
	s_addc_u32 s39, s37, -1
	s_cmp_eq_u32 s63, 12
	s_cselect_b32 s41, s9, s39
	s_cselect_b32 s40, s29, s38
	s_cselect_b32 s39, s27, s62
	s_cselect_b32 s38, s60, s61
	s_add_i32 m0, s50, 0xc000
	ds_read_b128 v[168:171], v165
	ds_read_b128 v[172:175], v165 offset:1024
	ds_read_b128 v[176:179], v165 offset:2048
	ds_read_b128 v[180:183], v165 offset:3072
	ds_read_b128 v[184:187], v165 offset:4096
	ds_read_b128 v[188:191], v165 offset:5120
	ds_read_b128 v[192:195], v165 offset:6144
	ds_read_b128 v[196:199], v165 offset:7168
	global_load_lds_dwordx4 v144, s[36:37]
	s_add_i32 m0, s50, 0xe000
	s_nop 0
	global_load_lds_dwordx4 v146, s[36:37]
	s_waitcnt lgkmcnt(8)
	s_barrier
	s_waitcnt lgkmcnt(0)
	v_mfma_f32_16x16x32_bf16 v[120:123], v[128:131], v[168:171], v[120:123]
	v_mfma_f32_16x16x32_bf16 v[124:127], v[152:155], v[168:171], v[124:127]
	v_mfma_f32_16x16x32_bf16 v[104:107], v[128:131], v[176:179], v[104:107]
	v_mfma_f32_16x16x32_bf16 v[108:111], v[152:155], v[176:179], v[108:111]
	v_mfma_f32_16x16x32_bf16 v[88:91], v[128:131], v[184:187], v[88:91]
	v_mfma_f32_16x16x32_bf16 v[92:95], v[152:155], v[184:187], v[92:95]
	v_mfma_f32_16x16x32_bf16 v[72:75], v[128:131], v[192:195], v[72:75]
	v_mfma_f32_16x16x32_bf16 v[76:79], v[152:155], v[192:195], v[76:79]
	v_mfma_f32_16x16x32_bf16 v[120:123], v[132:135], v[172:175], v[120:123]
	v_mfma_f32_16x16x32_bf16 v[124:127], v[156:159], v[172:175], v[124:127]
	v_mfma_f32_16x16x32_bf16 v[104:107], v[132:135], v[180:183], v[104:107]
	v_mfma_f32_16x16x32_bf16 v[108:111], v[156:159], v[180:183], v[108:111]
	v_mfma_f32_16x16x32_bf16 v[88:91], v[132:135], v[188:191], v[88:91]
	v_mfma_f32_16x16x32_bf16 v[92:95], v[156:159], v[188:191], v[92:95]
	v_mfma_f32_16x16x32_bf16 v[72:75], v[132:135], v[196:199], v[72:75]
	v_mfma_f32_16x16x32_bf16 v[76:79], v[156:159], v[196:199], v[76:79]
	s_barrier
	s_add_i32 s64, s57, s49
	s_add_u32 s98, s38, s22
	s_addc_u32 s99, s39, s23
	s_mov_b32 m0, s64
	ds_read_b128 v[200:203], v166
	ds_read_b128 v[204:207], v166 offset:1024
	ds_read_b128 v[208:211], v166 offset:2048
	ds_read_b128 v[212:215], v166 offset:3072
	global_load_lds_dwordx4 v138, s[38:39]
	s_add_i32 m0, s64, 0x2000
	s_nop 0
	global_load_lds_dwordx4 v142, s[38:39]
	s_barrier
	s_waitcnt lgkmcnt(0)
	v_mfma_f32_16x16x32_bf16 v[112:115], v[200:203], v[168:171], v[112:115]
	v_mfma_f32_16x16x32_bf16 v[116:119], v[208:211], v[168:171], v[116:119]
	v_mfma_f32_16x16x32_bf16 v[96:99], v[200:203], v[176:179], v[96:99]
	v_mfma_f32_16x16x32_bf16 v[100:103], v[208:211], v[176:179], v[100:103]
	v_mfma_f32_16x16x32_bf16 v[80:83], v[200:203], v[184:187], v[80:83]
	v_mfma_f32_16x16x32_bf16 v[84:87], v[208:211], v[184:187], v[84:87]
	v_mfma_f32_16x16x32_bf16 v[64:67], v[200:203], v[192:195], v[64:67]
	v_mfma_f32_16x16x32_bf16 v[68:71], v[208:211], v[192:195], v[68:71]
	v_mfma_f32_16x16x32_bf16 v[112:115], v[204:207], v[172:175], v[112:115]
	v_mfma_f32_16x16x32_bf16 v[116:119], v[212:215], v[172:175], v[116:119]
	v_mfma_f32_16x16x32_bf16 v[96:99], v[204:207], v[180:183], v[96:99]
	v_mfma_f32_16x16x32_bf16 v[100:103], v[212:215], v[180:183], v[100:103]
	v_mfma_f32_16x16x32_bf16 v[80:83], v[204:207], v[188:191], v[80:83]
	v_mfma_f32_16x16x32_bf16 v[84:87], v[212:215], v[188:191], v[84:87]
	v_mfma_f32_16x16x32_bf16 v[64:67], v[204:207], v[196:199], v[64:67]
	v_mfma_f32_16x16x32_bf16 v[68:71], v[212:215], v[196:199], v[68:71]
	s_mov_b32 m0, s50
	s_add_u32 s100, s40, s22
	s_addc_u32 s101, s41, s23
	s_barrier
	ds_read_b128 v[168:171], v165 offset:16384
	ds_read_b128 v[172:175], v165 offset:17408
	ds_read_b128 v[176:179], v165 offset:18432
	ds_read_b128 v[180:183], v165 offset:19456
	ds_read_b128 v[184:187], v165 offset:20480
	ds_read_b128 v[188:191], v165 offset:21504
	ds_read_b128 v[192:195], v165 offset:22528
	ds_read_b128 v[196:199], v165 offset:23552
	global_load_lds_dwordx4 v136, s[40:41]
	s_mov_b32 m0, s51
	s_nop 0
	global_load_lds_dwordx4 v140, s[40:41]
	s_barrier
	s_waitcnt lgkmcnt(0)
	v_mfma_f32_16x16x32_bf16 v[56:59], v[128:131], v[168:171], v[56:59]
	v_mfma_f32_16x16x32_bf16 v[60:63], v[152:155], v[168:171], v[60:63]
	v_mfma_f32_16x16x32_bf16 v[40:43], v[128:131], v[176:179], v[40:43]
	v_mfma_f32_16x16x32_bf16 v[44:47], v[152:155], v[176:179], v[44:47]
	v_mfma_f32_16x16x32_bf16 v[24:27], v[128:131], v[184:187], v[24:27]
	v_mfma_f32_16x16x32_bf16 v[28:31], v[152:155], v[184:187], v[28:31]
	v_mfma_f32_16x16x32_bf16 v[8:11], v[128:131], v[192:195], v[8:11]
	v_mfma_f32_16x16x32_bf16 v[12:15], v[152:155], v[192:195], v[12:15]
	v_mfma_f32_16x16x32_bf16 v[56:59], v[132:135], v[172:175], v[56:59]
	v_mfma_f32_16x16x32_bf16 v[60:63], v[156:159], v[172:175], v[60:63]
	v_mfma_f32_16x16x32_bf16 v[40:43], v[132:135], v[180:183], v[40:43]
	v_mfma_f32_16x16x32_bf16 v[44:47], v[156:159], v[180:183], v[44:47]
	v_mfma_f32_16x16x32_bf16 v[24:27], v[132:135], v[188:191], v[24:27]
	v_mfma_f32_16x16x32_bf16 v[28:31], v[156:159], v[188:191], v[28:31]
	v_mfma_f32_16x16x32_bf16 v[8:11], v[132:135], v[196:199], v[8:11]
	v_mfma_f32_16x16x32_bf16 v[12:15], v[156:159], v[196:199], v[12:15]
	s_barrier
	s_add_u32 s64, s38, 0x40000
	s_addc_u32 s65, s39, 0
	s_add_i32 s66, s58, s49
	s_mov_b32 m0, s66
	s_nop 0
	global_load_lds_dwordx4 v138, s[64:65]
	s_add_i32 m0, s66, 0x2000
	s_nop 0
	global_load_lds_dwordx4 v142, s[64:65]
	s_waitcnt vmcnt(6)
	s_barrier
	v_mfma_f32_16x16x32_bf16 v[48:51], v[200:203], v[168:171], v[48:51]
	v_mfma_f32_16x16x32_bf16 v[52:55], v[208:211], v[168:171], v[52:55]
	v_mfma_f32_16x16x32_bf16 v[32:35], v[200:203], v[176:179], v[32:35]
	v_mfma_f32_16x16x32_bf16 v[36:39], v[208:211], v[176:179], v[36:39]
	v_mfma_f32_16x16x32_bf16 v[16:19], v[200:203], v[184:187], v[16:19]
	v_mfma_f32_16x16x32_bf16 v[20:23], v[208:211], v[184:187], v[20:23]
	v_mfma_f32_16x16x32_bf16 v[4:7], v[200:203], v[192:195], v[4:7]
	v_mfma_f32_16x16x32_bf16 v[0:3], v[208:211], v[192:195], v[0:3]
	v_mfma_f32_16x16x32_bf16 v[48:51], v[204:207], v[172:175], v[48:51]
	v_mfma_f32_16x16x32_bf16 v[52:55], v[212:215], v[172:175], v[52:55]
	v_mfma_f32_16x16x32_bf16 v[32:35], v[204:207], v[180:183], v[32:35]
	v_mfma_f32_16x16x32_bf16 v[36:39], v[212:215], v[180:183], v[36:39]
	v_mfma_f32_16x16x32_bf16 v[16:19], v[204:207], v[188:191], v[16:19]
	v_mfma_f32_16x16x32_bf16 v[20:23], v[212:215], v[188:191], v[20:23]
	v_mfma_f32_16x16x32_bf16 v[4:7], v[204:207], v[196:199], v[4:7]
	v_mfma_f32_16x16x32_bf16 v[0:3], v[212:215], v[196:199], v[0:3]
	s_add_i32 s64, 0, 0x18000
	s_barrier
	ds_read_b128 v[128:131], v216 offset:32768
	ds_read_b128 v[132:135], v216 offset:33792
	ds_read_b128 v[152:155], v216 offset:34816
	ds_read_b128 v[156:159], v216 offset:35840
	s_add_u32 s40, s40, 0x40000
	s_addc_u32 s41, s41, 0
	s_mov_b32 m0, s52
	ds_read_b128 v[168:171], v165 offset:32768
	ds_read_b128 v[172:175], v165 offset:33792
	ds_read_b128 v[176:179], v165 offset:34816
	ds_read_b128 v[180:183], v165 offset:35840
	ds_read_b128 v[184:187], v165 offset:36864
	ds_read_b128 v[188:191], v165 offset:37888
	ds_read_b128 v[192:195], v165 offset:38912
	ds_read_b128 v[196:199], v165 offset:39936
	global_load_lds_dwordx4 v136, s[40:41]
	s_mov_b32 m0, s53
	s_nop 0
	global_load_lds_dwordx4 v140, s[40:41]
	s_waitcnt lgkmcnt(8)
	s_barrier
	s_waitcnt lgkmcnt(0)
	v_mfma_f32_16x16x32_bf16 v[120:123], v[128:131], v[168:171], v[120:123]
	v_mfma_f32_16x16x32_bf16 v[124:127], v[152:155], v[168:171], v[124:127]
	v_mfma_f32_16x16x32_bf16 v[104:107], v[128:131], v[176:179], v[104:107]
	v_mfma_f32_16x16x32_bf16 v[108:111], v[152:155], v[176:179], v[108:111]
	v_mfma_f32_16x16x32_bf16 v[88:91], v[128:131], v[184:187], v[88:91]
	v_mfma_f32_16x16x32_bf16 v[92:95], v[152:155], v[184:187], v[92:95]
	v_mfma_f32_16x16x32_bf16 v[72:75], v[128:131], v[192:195], v[72:75]
	v_mfma_f32_16x16x32_bf16 v[76:79], v[152:155], v[192:195], v[76:79]
	v_mfma_f32_16x16x32_bf16 v[120:123], v[132:135], v[172:175], v[120:123]
	v_mfma_f32_16x16x32_bf16 v[124:127], v[156:159], v[172:175], v[124:127]
	v_mfma_f32_16x16x32_bf16 v[104:107], v[132:135], v[180:183], v[104:107]
	v_mfma_f32_16x16x32_bf16 v[108:111], v[156:159], v[180:183], v[108:111]
	v_mfma_f32_16x16x32_bf16 v[88:91], v[132:135], v[188:191], v[88:91]
	v_mfma_f32_16x16x32_bf16 v[92:95], v[156:159], v[188:191], v[92:95]
	v_mfma_f32_16x16x32_bf16 v[72:75], v[132:135], v[196:199], v[72:75]
	v_mfma_f32_16x16x32_bf16 v[76:79], v[156:159], v[196:199], v[76:79]
	s_barrier
	s_add_i32 s40, 0, 0x1c000
	s_add_i32 s41, s64, s49
	s_mov_b32 m0, s41
	ds_read_b128 v[200:203], v216 offset:49152
	ds_read_b128 v[204:207], v216 offset:50176
	ds_read_b128 v[208:211], v216 offset:51200
	ds_read_b128 v[212:215], v216 offset:52224
	global_load_lds_dwordx4 v138, s[98:99]
	s_add_i32 m0, s41, 0x2000
	s_nop 0
	global_load_lds_dwordx4 v142, s[98:99]
	s_barrier
	s_waitcnt lgkmcnt(0)
	v_mfma_f32_16x16x32_bf16 v[112:115], v[200:203], v[168:171], v[112:115]
	v_mfma_f32_16x16x32_bf16 v[116:119], v[208:211], v[168:171], v[116:119]
	v_mfma_f32_16x16x32_bf16 v[96:99], v[200:203], v[176:179], v[96:99]
	v_mfma_f32_16x16x32_bf16 v[100:103], v[208:211], v[176:179], v[100:103]
	v_mfma_f32_16x16x32_bf16 v[80:83], v[200:203], v[184:187], v[80:83]
	v_mfma_f32_16x16x32_bf16 v[84:87], v[208:211], v[184:187], v[84:87]
	v_mfma_f32_16x16x32_bf16 v[64:67], v[200:203], v[192:195], v[64:67]
	v_mfma_f32_16x16x32_bf16 v[68:71], v[208:211], v[192:195], v[68:71]
	v_mfma_f32_16x16x32_bf16 v[112:115], v[204:207], v[172:175], v[112:115]
	v_mfma_f32_16x16x32_bf16 v[116:119], v[212:215], v[172:175], v[116:119]
	v_mfma_f32_16x16x32_bf16 v[96:99], v[204:207], v[180:183], v[96:99]
	v_mfma_f32_16x16x32_bf16 v[100:103], v[212:215], v[180:183], v[100:103]
	v_mfma_f32_16x16x32_bf16 v[80:83], v[204:207], v[188:191], v[80:83]
	v_mfma_f32_16x16x32_bf16 v[84:87], v[212:215], v[188:191], v[84:87]
	v_mfma_f32_16x16x32_bf16 v[64:67], v[204:207], v[196:199], v[64:67]
	v_mfma_f32_16x16x32_bf16 v[68:71], v[212:215], v[196:199], v[68:71]
	s_mov_b32 m0, s55
	s_barrier
	ds_read_b128 v[168:171], v165 offset:49152
	ds_read_b128 v[172:175], v165 offset:50176
	ds_read_b128 v[176:179], v165 offset:51200
	ds_read_b128 v[180:183], v165 offset:52224
	ds_read_b128 v[184:187], v165 offset:53248
	ds_read_b128 v[188:191], v165 offset:54272
	ds_read_b128 v[192:195], v165 offset:55296
	ds_read_b128 v[196:199], v165 offset:56320
	global_load_lds_dwordx4 v136, s[100:101]
	s_mov_b32 m0, s56
	s_nop 0
	global_load_lds_dwordx4 v140, s[100:101]
	s_barrier
	s_waitcnt lgkmcnt(0)
	v_mfma_f32_16x16x32_bf16 v[56:59], v[128:131], v[168:171], v[56:59]
	v_mfma_f32_16x16x32_bf16 v[60:63], v[152:155], v[168:171], v[60:63]
	v_mfma_f32_16x16x32_bf16 v[40:43], v[128:131], v[176:179], v[40:43]
	v_mfma_f32_16x16x32_bf16 v[44:47], v[152:155], v[176:179], v[44:47]
	v_mfma_f32_16x16x32_bf16 v[24:27], v[128:131], v[184:187], v[24:27]
	v_mfma_f32_16x16x32_bf16 v[28:31], v[152:155], v[184:187], v[28:31]
	v_mfma_f32_16x16x32_bf16 v[8:11], v[128:131], v[192:195], v[8:11]
	v_mfma_f32_16x16x32_bf16 v[12:15], v[152:155], v[192:195], v[12:15]
	v_mfma_f32_16x16x32_bf16 v[56:59], v[132:135], v[172:175], v[56:59]
	v_mfma_f32_16x16x32_bf16 v[60:63], v[156:159], v[172:175], v[60:63]
	v_mfma_f32_16x16x32_bf16 v[40:43], v[132:135], v[180:183], v[40:43]
	v_mfma_f32_16x16x32_bf16 v[44:47], v[156:159], v[180:183], v[44:47]
	v_mfma_f32_16x16x32_bf16 v[24:27], v[132:135], v[188:191], v[24:27]
	v_mfma_f32_16x16x32_bf16 v[28:31], v[156:159], v[188:191], v[28:31]
	v_mfma_f32_16x16x32_bf16 v[8:11], v[132:135], v[196:199], v[8:11]
	v_mfma_f32_16x16x32_bf16 v[12:15], v[156:159], v[196:199], v[12:15]
	s_barrier
	s_add_u32 s38, s38, 0x40080
	s_addc_u32 s39, s39, 0
	s_add_i32 s40, s40, s49
	s_mov_b32 m0, s40
	s_nop 0
	global_load_lds_dwordx4 v138, s[38:39]
	s_add_i32 m0, s40, 0x2000
	s_nop 0
	global_load_lds_dwordx4 v142, s[38:39]
	s_waitcnt vmcnt(6)
	s_barrier
	v_mfma_f32_16x16x32_bf16 v[48:51], v[200:203], v[168:171], v[48:51]
	v_mfma_f32_16x16x32_bf16 v[52:55], v[208:211], v[168:171], v[52:55]
	v_mfma_f32_16x16x32_bf16 v[32:35], v[200:203], v[176:179], v[32:35]
	v_mfma_f32_16x16x32_bf16 v[36:39], v[208:211], v[176:179], v[36:39]
	v_mfma_f32_16x16x32_bf16 v[16:19], v[200:203], v[184:187], v[16:19]
	v_mfma_f32_16x16x32_bf16 v[20:23], v[208:211], v[184:187], v[20:23]
	v_mfma_f32_16x16x32_bf16 v[4:7], v[200:203], v[192:195], v[4:7]
	v_mfma_f32_16x16x32_bf16 v[0:3], v[208:211], v[192:195], v[0:3]
	v_mfma_f32_16x16x32_bf16 v[48:51], v[204:207], v[172:175], v[48:51]
	v_mfma_f32_16x16x32_bf16 v[52:55], v[212:215], v[172:175], v[52:55]
	v_mfma_f32_16x16x32_bf16 v[32:35], v[204:207], v[180:183], v[32:35]
	v_mfma_f32_16x16x32_bf16 v[36:39], v[212:215], v[180:183], v[36:39]
	v_mfma_f32_16x16x32_bf16 v[16:19], v[204:207], v[188:191], v[16:19]
	v_mfma_f32_16x16x32_bf16 v[20:23], v[212:215], v[188:191], v[20:23]
	v_mfma_f32_16x16x32_bf16 v[4:7], v[204:207], v[196:199], v[4:7]
	v_mfma_f32_16x16x32_bf16 v[0:3], v[212:215], v[196:199], v[0:3]
	s_add_i32 s63, s63, 2
	s_add_u32 s36, s36, 0x100
	s_addc_u32 s37, s37, 0
	s_add_u32 s61, s61, 0x100
	s_addc_u32 s62, s62, 0
	s_cmp_gt_u32 s63, 13
	s_barrier
	s_cbranch_scc0 .LBB0_583
	v_lshl_add_u32 v152, s8, 8, v161
	v_lshl_or_b32 v153, s16, 8, v163
	s_lshl_b32 s36, s16, 2
	s_ashr_i32 s37, s36, 31
	s_lshl_b32 s16, s54, 2
	v_lshl_add_u32 v154, v152, 10, v153
	v_lshl_add_u32 v156, v152, 6, s16
	v_lshl_add_u32 v156, s36, 2, v156
	v_lshlrev_b32_e32 v155, 1, v154
	v_lshlrev_b32_e32 v154, 2, v154
	global_load_dwordx4 v[168:171], v154, s[14:15]
	global_load_dwordx4 v[172:175], v154, s[14:15] offset:16
	global_load_dwordx4 v[176:179], v154, s[14:15] offset:512
	global_load_dwordx4 v[180:183], v154, s[14:15] offset:528
	v_add_u32_e32 v154, 0x10000, v154
	global_load_dwordx4 v[184:187], v154, s[14:15]
	global_load_dwordx4 v[188:191], v154, s[14:15] offset:16
	global_load_dwordx4 v[192:195], v154, s[14:15] offset:512
	global_load_dwordx4 v[196:199], v154, s[14:15] offset:528
	v_add_u32_e32 v154, 0x10000, v154
	global_load_dwordx4 v[200:203], v154, s[14:15]
	global_load_dwordx4 v[204:207], v154, s[14:15] offset:16
	global_load_dwordx4 v[208:211], v154, s[14:15] offset:512
	global_load_dwordx4 v[212:215], v154, s[14:15] offset:528
	v_add_u32_e32 v154, 0x10000, v154
	global_load_dwordx4 v[216:219], v154, s[14:15]
	global_load_dwordx4 v[220:223], v154, s[14:15] offset:16
	global_load_dwordx4 v[128:131], v154, s[14:15] offset:512
	global_load_dwordx4 v[132:135], v154, s[14:15] offset:528
	v_add_u32_e32 v154, 0x50000, v154
	s_waitcnt vmcnt(12)
	v_pk_add_f32 v[120:121], v[120:121], v[168:169]
	v_pk_add_f32 v[122:123], v[122:123], v[170:171]
	v_pk_add_f32 v[124:125], v[124:125], v[172:173]
	v_pk_add_f32 v[126:127], v[126:127], v[174:175]
	v_cvt_pk_bf16_f32 v168, v120, v121
	v_cvt_pk_bf16_f32 v169, v122, v123
	v_cvt_pk_bf16_f32 v170, v124, v125
	v_cvt_pk_bf16_f32 v171, v126, v127
	v_pk_mul_f32 v[172:173], v[120:121], v[120:121]
	global_store_dwordx4 v155, v[168:171], s[18:19]
	v_pk_fma_f32 v[172:173], v[122:123], v[122:123], v[172:173]
	v_pk_fma_f32 v[172:173], v[124:125], v[124:125], v[172:173]
	v_pk_fma_f32 v[172:173], v[126:127], v[126:127], v[172:173]
	v_pk_add_f32 v[112:113], v[112:113], v[176:177]
	v_pk_add_f32 v[114:115], v[114:115], v[178:179]
	v_pk_add_f32 v[116:117], v[116:117], v[180:181]
	v_pk_add_f32 v[118:119], v[118:119], v[182:183]
	v_cvt_pk_bf16_f32 v176, v112, v113
	v_cvt_pk_bf16_f32 v177, v114, v115
	v_cvt_pk_bf16_f32 v178, v116, v117
	v_cvt_pk_bf16_f32 v179, v118, v119
	v_pk_fma_f32 v[172:173], v[112:113], v[112:113], v[172:173]
	global_store_dwordx4 v155, v[176:179], s[18:19] offset:256
	v_pk_fma_f32 v[172:173], v[114:115], v[114:115], v[172:173]
	v_pk_fma_f32 v[172:173], v[116:117], v[116:117], v[172:173]
	v_pk_fma_f32 v[172:173], v[118:119], v[118:119], v[172:173]
	v_add_f32_e32 v157, v172, v173
	v_add_u32_e32 v155, 0x8000, v155
	v_mov_b32_e32 v158, v157
	s_nop 1
	v_permlane16_swap_b32_e32 v157, v158
	s_nop 0
	v_add_f32_e32 v157, v157, v158
	v_mov_b32_e32 v158, v157
	s_nop 1
	v_permlane32_swap_b32_e32 v157, v158
	s_nop 0
	v_add_f32_e32 v157, v157, v158
	s_and_saveexec_b64 s[38:39], s[4:5]
	global_store_dword v156, v157, s[20:21]
	s_mov_b64 exec, s[38:39]
	global_load_dwordx4 v[168:171], v154, s[14:15]
	global_load_dwordx4 v[172:175], v154, s[14:15] offset:16
	global_load_dwordx4 v[176:179], v154, s[14:15] offset:512
	global_load_dwordx4 v[180:183], v154, s[14:15] offset:528
	v_add_u32_e32 v154, 0x10000, v154
	s_waitcnt vmcnt(15)
	v_pk_add_f32 v[104:105], v[104:105], v[184:185]
	v_pk_add_f32 v[106:107], v[106:107], v[186:187]
	v_pk_add_f32 v[108:109], v[108:109], v[188:189]
	v_pk_add_f32 v[110:111], v[110:111], v[190:191]
	v_cvt_pk_bf16_f32 v184, v104, v105
	v_cvt_pk_bf16_f32 v185, v106, v107
	v_cvt_pk_bf16_f32 v186, v108, v109
	v_cvt_pk_bf16_f32 v187, v110, v111
	v_pk_mul_f32 v[188:189], v[104:105], v[104:105]
	global_store_dwordx4 v155, v[184:187], s[18:19]
	v_pk_fma_f32 v[188:189], v[106:107], v[106:107], v[188:189]
	v_pk_fma_f32 v[188:189], v[108:109], v[108:109], v[188:189]
	v_pk_fma_f32 v[188:189], v[110:111], v[110:111], v[188:189]
	v_pk_add_f32 v[96:97], v[96:97], v[192:193]
	v_pk_add_f32 v[98:99], v[98:99], v[194:195]
	v_pk_add_f32 v[100:101], v[100:101], v[196:197]
	v_pk_add_f32 v[102:103], v[102:103], v[198:199]
	v_cvt_pk_bf16_f32 v192, v96, v97
	v_cvt_pk_bf16_f32 v193, v98, v99
	v_cvt_pk_bf16_f32 v194, v100, v101
	v_cvt_pk_bf16_f32 v195, v102, v103
	v_pk_fma_f32 v[188:189], v[96:97], v[96:97], v[188:189]
	global_store_dwordx4 v155, v[192:195], s[18:19] offset:256
	v_pk_fma_f32 v[188:189], v[98:99], v[98:99], v[188:189]
	v_pk_fma_f32 v[188:189], v[100:101], v[100:101], v[188:189]
	v_pk_fma_f32 v[188:189], v[102:103], v[102:103], v[188:189]
	v_add_f32_e32 v157, v188, v189
	v_add_u32_e32 v155, 0x8000, v155
	v_mov_b32_e32 v158, v157
	s_nop 1
	v_permlane16_swap_b32_e32 v157, v158
	s_nop 0
	v_add_f32_e32 v157, v157, v158
	v_mov_b32_e32 v158, v157
	s_nop 1
	v_permlane32_swap_b32_e32 v157, v158
	s_nop 0
	v_add_f32_e32 v157, v157, v158
	s_and_saveexec_b64 s[38:39], s[4:5]
	global_store_dword v156, v157, s[20:21] offset:1024
	s_mov_b64 exec, s[38:39]
	global_load_dwordx4 v[184:187], v154, s[14:15]
	global_load_dwordx4 v[188:191], v154, s[14:15] offset:16
	global_load_dwordx4 v[192:195], v154, s[14:15] offset:512
	global_load_dwordx4 v[196:199], v154, s[14:15] offset:528
	v_add_u32_e32 v154, 0x10000, v154
	s_waitcnt vmcnt(18)
	v_pk_add_f32 v[88:89], v[88:89], v[200:201]
	v_pk_add_f32 v[90:91], v[90:91], v[202:203]
	v_pk_add_f32 v[92:93], v[92:93], v[204:205]
	v_pk_add_f32 v[94:95], v[94:95], v[206:207]
	v_cvt_pk_bf16_f32 v200, v88, v89
	v_cvt_pk_bf16_f32 v201, v90, v91
	v_cvt_pk_bf16_f32 v202, v92, v93
	v_cvt_pk_bf16_f32 v203, v94, v95
	v_pk_mul_f32 v[204:205], v[88:89], v[88:89]
	global_store_dwordx4 v155, v[200:203], s[18:19]
	v_pk_fma_f32 v[204:205], v[90:91], v[90:91], v[204:205]
	v_pk_fma_f32 v[204:205], v[92:93], v[92:93], v[204:205]
	v_pk_fma_f32 v[204:205], v[94:95], v[94:95], v[204:205]
	v_pk_add_f32 v[80:81], v[80:81], v[208:209]
	v_pk_add_f32 v[82:83], v[82:83], v[210:211]
	v_pk_add_f32 v[84:85], v[84:85], v[212:213]
	v_pk_add_f32 v[86:87], v[86:87], v[214:215]
	v_cvt_pk_bf16_f32 v208, v80, v81
	v_cvt_pk_bf16_f32 v209, v82, v83
	v_cvt_pk_bf16_f32 v210, v84, v85
	v_cvt_pk_bf16_f32 v211, v86, v87
	v_pk_fma_f32 v[204:205], v[80:81], v[80:81], v[204:205]
	global_store_dwordx4 v155, v[208:211], s[18:19] offset:256
	v_pk_fma_f32 v[204:205], v[82:83], v[82:83], v[204:205]
	v_pk_fma_f32 v[204:205], v[84:85], v[84:85], v[204:205]
	v_pk_fma_f32 v[204:205], v[86:87], v[86:87], v[204:205]
	v_add_f32_e32 v157, v204, v205
	v_add_u32_e32 v155, 0x8000, v155
	v_mov_b32_e32 v158, v157
	s_nop 1
	v_permlane16_swap_b32_e32 v157, v158
	s_nop 0
	v_add_f32_e32 v157, v157, v158
	v_mov_b32_e32 v158, v157
	s_nop 1
	v_permlane32_swap_b32_e32 v157, v158
	s_nop 0
	v_add_f32_e32 v157, v157, v158
	s_and_saveexec_b64 s[38:39], s[4:5]
	global_store_dword v156, v157, s[20:21] offset:2048
	s_mov_b64 exec, s[38:39]
	global_load_dwordx4 v[200:203], v154, s[14:15]
	global_load_dwordx4 v[204:207], v154, s[14:15] offset:16
	global_load_dwordx4 v[208:211], v154, s[14:15] offset:512
	global_load_dwordx4 v[212:215], v154, s[14:15] offset:528
	v_add_u32_e32 v154, 0x10000, v154
	s_waitcnt vmcnt(21)
	v_pk_add_f32 v[72:73], v[72:73], v[216:217]
	v_pk_add_f32 v[74:75], v[74:75], v[218:219]
	v_pk_add_f32 v[76:77], v[76:77], v[220:221]
	v_pk_add_f32 v[78:79], v[78:79], v[222:223]
	v_cvt_pk_bf16_f32 v216, v72, v73
	v_cvt_pk_bf16_f32 v217, v74, v75
	v_cvt_pk_bf16_f32 v218, v76, v77
	v_cvt_pk_bf16_f32 v219, v78, v79
	v_pk_mul_f32 v[220:221], v[72:73], v[72:73]
	global_store_dwordx4 v155, v[216:219], s[18:19]
	v_pk_fma_f32 v[220:221], v[74:75], v[74:75], v[220:221]
	v_pk_fma_f32 v[220:221], v[76:77], v[76:77], v[220:221]
	v_pk_fma_f32 v[220:221], v[78:79], v[78:79], v[220:221]
	v_pk_add_f32 v[64:65], v[64:65], v[128:129]
	v_pk_add_f32 v[66:67], v[66:67], v[130:131]
	v_pk_add_f32 v[68:69], v[68:69], v[132:133]
	v_pk_add_f32 v[70:71], v[70:71], v[134:135]
	v_cvt_pk_bf16_f32 v128, v64, v65
	v_cvt_pk_bf16_f32 v129, v66, v67
	v_cvt_pk_bf16_f32 v130, v68, v69
	v_cvt_pk_bf16_f32 v131, v70, v71
	v_pk_fma_f32 v[220:221], v[64:65], v[64:65], v[220:221]
	global_store_dwordx4 v155, v[128:131], s[18:19] offset:256
	v_pk_fma_f32 v[220:221], v[66:67], v[66:67], v[220:221]
	v_pk_fma_f32 v[220:221], v[68:69], v[68:69], v[220:221]
	v_pk_fma_f32 v[220:221], v[70:71], v[70:71], v[220:221]
	v_add_f32_e32 v157, v220, v221
	v_add_u32_e32 v155, 0x28000, v155
	v_mov_b32_e32 v158, v157
	s_nop 1
	v_permlane16_swap_b32_e32 v157, v158
	s_nop 0
	v_add_f32_e32 v157, v157, v158
	v_mov_b32_e32 v158, v157
	s_nop 1
	v_permlane32_swap_b32_e32 v157, v158
	s_nop 0
	v_add_f32_e32 v157, v157, v158
	s_and_saveexec_b64 s[38:39], s[4:5]
	global_store_dword v156, v157, s[20:21] offset:3072
	s_mov_b64 exec, s[38:39]
	v_add_u32_e32 v156, 0x2000, v156
	global_load_dwordx4 v[216:219], v154, s[14:15]
	global_load_dwordx4 v[220:223], v154, s[14:15] offset:16
	global_load_dwordx4 v[128:131], v154, s[14:15] offset:512
	global_load_dwordx4 v[132:135], v154, s[14:15] offset:528
	s_waitcnt vmcnt(21)
	v_pk_add_f32 v[56:57], v[56:57], v[168:169]
	v_pk_add_f32 v[58:59], v[58:59], v[170:171]
	v_pk_add_f32 v[60:61], v[60:61], v[172:173]
	v_pk_add_f32 v[62:63], v[62:63], v[174:175]
	v_cvt_pk_bf16_f32 v168, v56, v57
	v_cvt_pk_bf16_f32 v169, v58, v59
	v_cvt_pk_bf16_f32 v170, v60, v61
	v_cvt_pk_bf16_f32 v171, v62, v63
	v_pk_mul_f32 v[172:173], v[56:57], v[56:57]
	global_store_dwordx4 v155, v[168:171], s[18:19]
	v_pk_fma_f32 v[172:173], v[58:59], v[58:59], v[172:173]
	v_pk_fma_f32 v[172:173], v[60:61], v[60:61], v[172:173]
	v_pk_fma_f32 v[172:173], v[62:63], v[62:63], v[172:173]
	v_pk_add_f32 v[48:49], v[48:49], v[176:177]
	v_pk_add_f32 v[50:51], v[50:51], v[178:179]
	v_pk_add_f32 v[52:53], v[52:53], v[180:181]
	v_pk_add_f32 v[54:55], v[54:55], v[182:183]
	v_cvt_pk_bf16_f32 v176, v48, v49
	v_cvt_pk_bf16_f32 v177, v50, v51
	v_cvt_pk_bf16_f32 v178, v52, v53
	v_cvt_pk_bf16_f32 v179, v54, v55
	v_pk_fma_f32 v[172:173], v[48:49], v[48:49], v[172:173]
	global_store_dwordx4 v155, v[176:179], s[18:19] offset:256
	v_pk_fma_f32 v[172:173], v[50:51], v[50:51], v[172:173]
	v_pk_fma_f32 v[172:173], v[52:53], v[52:53], v[172:173]
	v_pk_fma_f32 v[172:173], v[54:55], v[54:55], v[172:173]
	v_add_f32_e32 v157, v172, v173
	v_add_u32_e32 v155, 0x8000, v155
	v_mov_b32_e32 v158, v157
	s_nop 1
	v_permlane16_swap_b32_e32 v157, v158
	s_nop 0
	v_add_f32_e32 v157, v157, v158
	v_mov_b32_e32 v158, v157
	s_nop 1
	v_permlane32_swap_b32_e32 v157, v158
	s_nop 0
	v_add_f32_e32 v157, v157, v158
	s_and_saveexec_b64 s[38:39], s[4:5]
	global_store_dword v156, v157, s[20:21]
	s_mov_b64 exec, s[38:39]
	s_waitcnt vmcnt(17)
	v_pk_add_f32 v[40:41], v[40:41], v[184:185]
	v_pk_add_f32 v[42:43], v[42:43], v[186:187]
	v_pk_add_f32 v[44:45], v[44:45], v[188:189]
	v_pk_add_f32 v[46:47], v[46:47], v[190:191]
	v_cvt_pk_bf16_f32 v184, v40, v41
	v_cvt_pk_bf16_f32 v185, v42, v43
	v_cvt_pk_bf16_f32 v186, v44, v45
	v_cvt_pk_bf16_f32 v187, v46, v47
	v_pk_mul_f32 v[188:189], v[40:41], v[40:41]
	global_store_dwordx4 v155, v[184:187], s[18:19]
	v_pk_fma_f32 v[188:189], v[42:43], v[42:43], v[188:189]
	v_pk_fma_f32 v[188:189], v[44:45], v[44:45], v[188:189]
	v_pk_fma_f32 v[188:189], v[46:47], v[46:47], v[188:189]
	v_pk_add_f32 v[32:33], v[32:33], v[192:193]
	v_pk_add_f32 v[34:35], v[34:35], v[194:195]
	v_pk_add_f32 v[36:37], v[36:37], v[196:197]
	v_pk_add_f32 v[38:39], v[38:39], v[198:199]
	v_cvt_pk_bf16_f32 v192, v32, v33
	v_cvt_pk_bf16_f32 v193, v34, v35
	v_cvt_pk_bf16_f32 v194, v36, v37
	v_cvt_pk_bf16_f32 v195, v38, v39
	v_pk_fma_f32 v[188:189], v[32:33], v[32:33], v[188:189]
	global_store_dwordx4 v155, v[192:195], s[18:19] offset:256
	v_pk_fma_f32 v[188:189], v[34:35], v[34:35], v[188:189]
	v_pk_fma_f32 v[188:189], v[36:37], v[36:37], v[188:189]
	v_pk_fma_f32 v[188:189], v[38:39], v[38:39], v[188:189]
	v_add_f32_e32 v157, v188, v189
	v_add_u32_e32 v155, 0x8000, v155
	v_mov_b32_e32 v158, v157
	s_nop 1
	v_permlane16_swap_b32_e32 v157, v158
	s_nop 0
	v_add_f32_e32 v157, v157, v158
	v_mov_b32_e32 v158, v157
	s_nop 1
	v_permlane32_swap_b32_e32 v157, v158
	s_nop 0
	v_add_f32_e32 v157, v157, v158
	s_and_saveexec_b64 s[38:39], s[4:5]
	global_store_dword v156, v157, s[20:21] offset:1024
	s_mov_b64 exec, s[38:39]
	s_waitcnt vmcnt(13)
	v_pk_add_f32 v[24:25], v[24:25], v[200:201]
	v_pk_add_f32 v[26:27], v[26:27], v[202:203]
	v_pk_add_f32 v[28:29], v[28:29], v[204:205]
	v_pk_add_f32 v[30:31], v[30:31], v[206:207]
	v_cvt_pk_bf16_f32 v200, v24, v25
	v_cvt_pk_bf16_f32 v201, v26, v27
	v_cvt_pk_bf16_f32 v202, v28, v29
	v_cvt_pk_bf16_f32 v203, v30, v31
	v_pk_mul_f32 v[204:205], v[24:25], v[24:25]
	global_store_dwordx4 v155, v[200:203], s[18:19]
	v_pk_fma_f32 v[204:205], v[26:27], v[26:27], v[204:205]
	v_pk_fma_f32 v[204:205], v[28:29], v[28:29], v[204:205]
	v_pk_fma_f32 v[204:205], v[30:31], v[30:31], v[204:205]
	v_pk_add_f32 v[16:17], v[16:17], v[208:209]
	v_pk_add_f32 v[18:19], v[18:19], v[210:211]
	v_pk_add_f32 v[20:21], v[20:21], v[212:213]
	v_pk_add_f32 v[22:23], v[22:23], v[214:215]
	v_cvt_pk_bf16_f32 v208, v16, v17
	v_cvt_pk_bf16_f32 v209, v18, v19
	v_cvt_pk_bf16_f32 v210, v20, v21
	v_cvt_pk_bf16_f32 v211, v22, v23
	v_pk_fma_f32 v[204:205], v[16:17], v[16:17], v[204:205]
	global_store_dwordx4 v155, v[208:211], s[18:19] offset:256
	v_pk_fma_f32 v[204:205], v[18:19], v[18:19], v[204:205]
	v_pk_fma_f32 v[204:205], v[20:21], v[20:21], v[204:205]
	v_pk_fma_f32 v[204:205], v[22:23], v[22:23], v[204:205]
	v_add_f32_e32 v157, v204, v205
	v_add_u32_e32 v155, 0x8000, v155
	v_mov_b32_e32 v158, v157
	s_nop 1
	v_permlane16_swap_b32_e32 v157, v158
	s_nop 0
	v_add_f32_e32 v157, v157, v158
	v_mov_b32_e32 v158, v157
	s_nop 1
	v_permlane32_swap_b32_e32 v157, v158
	s_nop 0
	v_add_f32_e32 v157, v157, v158
	s_and_saveexec_b64 s[38:39], s[4:5]
	global_store_dword v156, v157, s[20:21] offset:2048
	s_mov_b64 exec, s[38:39]
	s_waitcnt vmcnt(9)
	v_pk_add_f32 v[8:9], v[8:9], v[216:217]
	v_pk_add_f32 v[10:11], v[10:11], v[218:219]
	v_pk_add_f32 v[12:13], v[12:13], v[220:221]
	v_pk_add_f32 v[14:15], v[14:15], v[222:223]
	v_cvt_pk_bf16_f32 v216, v8, v9
	v_cvt_pk_bf16_f32 v217, v10, v11
	v_cvt_pk_bf16_f32 v218, v12, v13
	v_cvt_pk_bf16_f32 v219, v14, v15
	v_pk_mul_f32 v[220:221], v[8:9], v[8:9]
	global_store_dwordx4 v155, v[216:219], s[18:19]
	v_pk_fma_f32 v[220:221], v[10:11], v[10:11], v[220:221]
	v_pk_fma_f32 v[220:221], v[12:13], v[12:13], v[220:221]
	v_pk_fma_f32 v[220:221], v[14:15], v[14:15], v[220:221]
	v_pk_add_f32 v[4:5], v[4:5], v[128:129]
	v_pk_add_f32 v[6:7], v[6:7], v[130:131]
	v_pk_add_f32 v[0:1], v[0:1], v[132:133]
	v_pk_add_f32 v[2:3], v[2:3], v[134:135]
	v_cvt_pk_bf16_f32 v128, v4, v5
	v_cvt_pk_bf16_f32 v129, v6, v7
	v_cvt_pk_bf16_f32 v130, v0, v1
	v_cvt_pk_bf16_f32 v131, v2, v3
	v_pk_fma_f32 v[220:221], v[4:5], v[4:5], v[220:221]
	global_store_dwordx4 v155, v[128:131], s[18:19] offset:256
	v_pk_fma_f32 v[220:221], v[6:7], v[6:7], v[220:221]
	v_pk_fma_f32 v[220:221], v[0:1], v[0:1], v[220:221]
	v_pk_fma_f32 v[220:221], v[2:3], v[2:3], v[220:221]
	v_add_f32_e32 v157, v220, v221
	v_add_u32_e32 v155, 0x8000, v155
	v_mov_b32_e32 v158, v157
	s_nop 1
	v_permlane16_swap_b32_e32 v157, v158
	s_nop 0
	v_add_f32_e32 v157, v157, v158
	v_mov_b32_e32 v158, v157
	s_nop 1
	v_permlane32_swap_b32_e32 v157, v158
	s_nop 0
	v_add_f32_e32 v157, v157, v158
	s_and_saveexec_b64 s[38:39], s[4:5]
	global_store_dword v156, v157, s[20:21] offset:3072
	s_mov_b64 exec, s[38:39]
	s_branch .LBB0_575

.LBB0_698:
	v_add_u32_e32 v210, 0x10000, v153
	s_add_u32 s28, s26, 0xfffc0080
	s_addc_u32 s29, s27, -1
	s_add_i32 s68, 0, 0x10000
	ds_read_b128 v[138:141], v210
	ds_read_b128 v[142:145], v210 offset:1024
	ds_read_b128 v[146:149], v210 offset:2048
	ds_read_b128 v[156:159], v210 offset:3072
	s_cmp_eq_u32 s51, 12
	s_cselect_b32 s31, s21, s29
	s_cselect_b32 s30, s38, s28
	s_cselect_b32 s29, s7, s50
	s_cselect_b32 s28, s39, s46
	s_add_i32 m0, s58, 0xc000
	ds_read_b128 v[160:163], v154
	ds_read_b128 v[164:167], v154 offset:1024
	ds_read_b128 v[168:171], v154 offset:2048
	ds_read_b128 v[172:175], v154 offset:3072
	ds_read_b128 v[176:179], v154 offset:4096
	ds_read_b128 v[180:183], v154 offset:5120
	ds_read_b128 v[184:187], v154 offset:6144
	ds_read_b128 v[188:191], v154 offset:7168
	global_load_lds_dwordx4 v134, s[26:27]
	s_add_i32 m0, s58, 0xe000
	s_nop 0
	global_load_lds_dwordx4 v136, s[26:27]
	s_waitcnt lgkmcnt(8)
	s_barrier
	s_waitcnt lgkmcnt(0)
	v_mfma_f32_16x16x32_bf16 v[124:127], v[138:141], v[160:163], v[124:127]
	v_mfma_f32_16x16x32_bf16 v[120:123], v[146:149], v[160:163], v[120:123]
	v_mfma_f32_16x16x32_bf16 v[108:111], v[138:141], v[168:171], v[108:111]
	v_mfma_f32_16x16x32_bf16 v[104:107], v[146:149], v[168:171], v[104:107]
	v_mfma_f32_16x16x32_bf16 v[92:95], v[138:141], v[176:179], v[92:95]
	v_mfma_f32_16x16x32_bf16 v[88:91], v[146:149], v[176:179], v[88:91]
	v_mfma_f32_16x16x32_bf16 v[76:79], v[138:141], v[184:187], v[76:79]
	v_mfma_f32_16x16x32_bf16 v[72:75], v[146:149], v[184:187], v[72:75]
	v_mfma_f32_16x16x32_bf16 v[124:127], v[142:145], v[164:167], v[124:127]
	v_mfma_f32_16x16x32_bf16 v[120:123], v[156:159], v[164:167], v[120:123]
	v_mfma_f32_16x16x32_bf16 v[108:111], v[142:145], v[172:175], v[108:111]
	v_mfma_f32_16x16x32_bf16 v[104:107], v[156:159], v[172:175], v[104:107]
	v_mfma_f32_16x16x32_bf16 v[92:95], v[142:145], v[180:183], v[92:95]
	v_mfma_f32_16x16x32_bf16 v[88:91], v[156:159], v[180:183], v[88:91]
	v_mfma_f32_16x16x32_bf16 v[76:79], v[142:145], v[188:191], v[76:79]
	v_mfma_f32_16x16x32_bf16 v[72:75], v[156:159], v[188:191], v[72:75]
	s_barrier
	s_add_i32 s70, 0, 0x14000
	s_add_i32 s68, s68, s57
	s_add_u32 s98, s28, s40
	s_addc_u32 s99, s29, s41
	s_mov_b32 m0, s68
	ds_read_b128 v[192:195], v210 offset:16384
	ds_read_b128 v[196:199], v210 offset:17408
	ds_read_b128 v[200:203], v210 offset:18432
	ds_read_b128 v[204:207], v210 offset:19456
	global_load_lds_dwordx4 v208, s[28:29]
	s_add_i32 m0, s68, 0x2000
	s_nop 0
	global_load_lds_dwordx4 v128, s[28:29]
	s_barrier
	s_waitcnt lgkmcnt(0)
	v_mfma_f32_16x16x32_bf16 v[116:119], v[192:195], v[160:163], v[116:119]
	v_mfma_f32_16x16x32_bf16 v[112:115], v[200:203], v[160:163], v[112:115]
	v_mfma_f32_16x16x32_bf16 v[100:103], v[192:195], v[168:171], v[100:103]
	v_mfma_f32_16x16x32_bf16 v[96:99], v[200:203], v[168:171], v[96:99]
	v_mfma_f32_16x16x32_bf16 v[84:87], v[192:195], v[176:179], v[84:87]
	v_mfma_f32_16x16x32_bf16 v[80:83], v[200:203], v[176:179], v[80:83]
	v_mfma_f32_16x16x32_bf16 v[68:71], v[192:195], v[184:187], v[68:71]
	v_mfma_f32_16x16x32_bf16 v[64:67], v[200:203], v[184:187], v[64:67]
	v_mfma_f32_16x16x32_bf16 v[116:119], v[196:199], v[164:167], v[116:119]
	v_mfma_f32_16x16x32_bf16 v[112:115], v[204:207], v[164:167], v[112:115]
	v_mfma_f32_16x16x32_bf16 v[100:103], v[196:199], v[172:175], v[100:103]
	v_mfma_f32_16x16x32_bf16 v[96:99], v[204:207], v[172:175], v[96:99]
	v_mfma_f32_16x16x32_bf16 v[84:87], v[196:199], v[180:183], v[84:87]
	v_mfma_f32_16x16x32_bf16 v[80:83], v[204:207], v[180:183], v[80:83]
	v_mfma_f32_16x16x32_bf16 v[68:71], v[196:199], v[188:191], v[68:71]
	v_mfma_f32_16x16x32_bf16 v[64:67], v[204:207], v[188:191], v[64:67]
	s_mov_b32 m0, s58
	s_add_u32 s100, s30, s40
	s_addc_u32 s101, s31, s41
	s_barrier
	ds_read_b128 v[160:163], v154 offset:16384
	ds_read_b128 v[164:167], v154 offset:17408
	ds_read_b128 v[168:171], v154 offset:18432
	ds_read_b128 v[172:175], v154 offset:19456
	ds_read_b128 v[176:179], v154 offset:20480
	ds_read_b128 v[180:183], v154 offset:21504
	ds_read_b128 v[184:187], v154 offset:22528
	ds_read_b128 v[188:191], v154 offset:23552
	global_load_lds_dwordx4 v132, s[30:31]
	s_mov_b32 m0, s59
	s_nop 0
	global_load_lds_dwordx4 v130, s[30:31]
	s_barrier
	s_waitcnt lgkmcnt(0)
	v_mfma_f32_16x16x32_bf16 v[60:63], v[138:141], v[160:163], v[60:63]
	v_mfma_f32_16x16x32_bf16 v[56:59], v[146:149], v[160:163], v[56:59]
	v_mfma_f32_16x16x32_bf16 v[44:47], v[138:141], v[168:171], v[44:47]
	v_mfma_f32_16x16x32_bf16 v[40:43], v[146:149], v[168:171], v[40:43]
	v_mfma_f32_16x16x32_bf16 v[28:31], v[138:141], v[176:179], v[28:31]
	v_mfma_f32_16x16x32_bf16 v[24:27], v[146:149], v[176:179], v[24:27]
	v_mfma_f32_16x16x32_bf16 v[12:15], v[138:141], v[184:187], v[12:15]
	v_mfma_f32_16x16x32_bf16 v[8:11], v[146:149], v[184:187], v[8:11]
	v_mfma_f32_16x16x32_bf16 v[60:63], v[142:145], v[164:167], v[60:63]
	v_mfma_f32_16x16x32_bf16 v[56:59], v[156:159], v[164:167], v[56:59]
	v_mfma_f32_16x16x32_bf16 v[44:47], v[142:145], v[172:175], v[44:47]
	v_mfma_f32_16x16x32_bf16 v[40:43], v[156:159], v[172:175], v[40:43]
	v_mfma_f32_16x16x32_bf16 v[28:31], v[142:145], v[180:183], v[28:31]
	v_mfma_f32_16x16x32_bf16 v[24:27], v[156:159], v[180:183], v[24:27]
	v_mfma_f32_16x16x32_bf16 v[12:15], v[142:145], v[188:191], v[12:15]
	v_mfma_f32_16x16x32_bf16 v[8:11], v[156:159], v[188:191], v[8:11]
	s_barrier
	s_add_u32 s68, s28, 0x40000
	s_addc_u32 s69, s29, 0
	s_add_i32 s70, s70, s57
	s_mov_b32 m0, s70
	s_nop 0
	global_load_lds_dwordx4 v208, s[68:69]
	s_add_i32 m0, s70, 0x2000
	s_nop 0
	global_load_lds_dwordx4 v128, s[68:69]
	s_waitcnt vmcnt(6)
	s_barrier
	v_mfma_f32_16x16x32_bf16 v[52:55], v[192:195], v[160:163], v[52:55]
	v_mfma_f32_16x16x32_bf16 v[48:51], v[200:203], v[160:163], v[48:51]
	v_mfma_f32_16x16x32_bf16 v[36:39], v[192:195], v[168:171], v[36:39]
	v_mfma_f32_16x16x32_bf16 v[32:35], v[200:203], v[168:171], v[32:35]
	v_mfma_f32_16x16x32_bf16 v[20:23], v[192:195], v[176:179], v[20:23]
	v_mfma_f32_16x16x32_bf16 v[16:19], v[200:203], v[176:179], v[16:19]
	v_mfma_f32_16x16x32_bf16 v[4:7], v[192:195], v[184:187], v[4:7]
	v_mfma_f32_16x16x32_bf16 v[0:3], v[200:203], v[184:187], v[0:3]
	v_mfma_f32_16x16x32_bf16 v[52:55], v[196:199], v[164:167], v[52:55]
	v_mfma_f32_16x16x32_bf16 v[48:51], v[204:207], v[164:167], v[48:51]
	v_mfma_f32_16x16x32_bf16 v[36:39], v[196:199], v[172:175], v[36:39]
	v_mfma_f32_16x16x32_bf16 v[32:35], v[204:207], v[172:175], v[32:35]
	v_mfma_f32_16x16x32_bf16 v[20:23], v[196:199], v[180:183], v[20:23]
	v_mfma_f32_16x16x32_bf16 v[16:19], v[204:207], v[180:183], v[16:19]
	v_mfma_f32_16x16x32_bf16 v[4:7], v[196:199], v[188:191], v[4:7]
	v_mfma_f32_16x16x32_bf16 v[0:3], v[204:207], v[188:191], v[0:3]
	s_add_i32 s68, 0, 0x18000
	s_barrier
	ds_read_b128 v[138:141], v210 offset:32768
	ds_read_b128 v[142:145], v210 offset:33792
	ds_read_b128 v[146:149], v210 offset:34816
	ds_read_b128 v[156:159], v210 offset:35840
	s_add_u32 s30, s30, 0x40000
	s_addc_u32 s31, s31, 0
	s_mov_b32 m0, s60
	ds_read_b128 v[160:163], v154 offset:32768
	ds_read_b128 v[164:167], v154 offset:33792
	ds_read_b128 v[168:171], v154 offset:34816
	ds_read_b128 v[172:175], v154 offset:35840
	ds_read_b128 v[176:179], v154 offset:36864
	ds_read_b128 v[180:183], v154 offset:37888
	ds_read_b128 v[184:187], v154 offset:38912
	ds_read_b128 v[188:191], v154 offset:39936
	global_load_lds_dwordx4 v132, s[30:31]
	s_mov_b32 m0, s61
	s_nop 0
	global_load_lds_dwordx4 v130, s[30:31]
	s_waitcnt lgkmcnt(8)
	s_barrier
	s_waitcnt lgkmcnt(0)
	v_mfma_f32_16x16x32_bf16 v[124:127], v[138:141], v[160:163], v[124:127]
	v_mfma_f32_16x16x32_bf16 v[120:123], v[146:149], v[160:163], v[120:123]
	v_mfma_f32_16x16x32_bf16 v[108:111], v[138:141], v[168:171], v[108:111]
	v_mfma_f32_16x16x32_bf16 v[104:107], v[146:149], v[168:171], v[104:107]
	v_mfma_f32_16x16x32_bf16 v[92:95], v[138:141], v[176:179], v[92:95]
	v_mfma_f32_16x16x32_bf16 v[88:91], v[146:149], v[176:179], v[88:91]
	v_mfma_f32_16x16x32_bf16 v[76:79], v[138:141], v[184:187], v[76:79]
	v_mfma_f32_16x16x32_bf16 v[72:75], v[146:149], v[184:187], v[72:75]
	v_mfma_f32_16x16x32_bf16 v[124:127], v[142:145], v[164:167], v[124:127]
	v_mfma_f32_16x16x32_bf16 v[120:123], v[156:159], v[164:167], v[120:123]
	v_mfma_f32_16x16x32_bf16 v[108:111], v[142:145], v[172:175], v[108:111]
	v_mfma_f32_16x16x32_bf16 v[104:107], v[156:159], v[172:175], v[104:107]
	v_mfma_f32_16x16x32_bf16 v[92:95], v[142:145], v[180:183], v[92:95]
	v_mfma_f32_16x16x32_bf16 v[88:91], v[156:159], v[180:183], v[88:91]
	v_mfma_f32_16x16x32_bf16 v[76:79], v[142:145], v[188:191], v[76:79]
	v_mfma_f32_16x16x32_bf16 v[72:75], v[156:159], v[188:191], v[72:75]
	s_barrier
	s_add_i32 s30, 0, 0x1c000
	s_add_i32 s31, s68, s57
	s_mov_b32 m0, s31
	ds_read_b128 v[192:195], v210 offset:49152
	ds_read_b128 v[196:199], v210 offset:50176
	ds_read_b128 v[200:203], v210 offset:51200
	ds_read_b128 v[204:207], v210 offset:52224
	global_load_lds_dwordx4 v208, s[98:99]
	s_add_i32 m0, s31, 0x2000
	s_nop 0
	global_load_lds_dwordx4 v128, s[98:99]
	s_barrier
	s_waitcnt lgkmcnt(0)
	v_mfma_f32_16x16x32_bf16 v[116:119], v[192:195], v[160:163], v[116:119]
	v_mfma_f32_16x16x32_bf16 v[112:115], v[200:203], v[160:163], v[112:115]
	v_mfma_f32_16x16x32_bf16 v[100:103], v[192:195], v[168:171], v[100:103]
	v_mfma_f32_16x16x32_bf16 v[96:99], v[200:203], v[168:171], v[96:99]
	v_mfma_f32_16x16x32_bf16 v[84:87], v[192:195], v[176:179], v[84:87]
	v_mfma_f32_16x16x32_bf16 v[80:83], v[200:203], v[176:179], v[80:83]
	v_mfma_f32_16x16x32_bf16 v[68:71], v[192:195], v[184:187], v[68:71]
	v_mfma_f32_16x16x32_bf16 v[64:67], v[200:203], v[184:187], v[64:67]
	v_mfma_f32_16x16x32_bf16 v[116:119], v[196:199], v[164:167], v[116:119]
	v_mfma_f32_16x16x32_bf16 v[112:115], v[204:207], v[164:167], v[112:115]
	v_mfma_f32_16x16x32_bf16 v[100:103], v[196:199], v[172:175], v[100:103]
	v_mfma_f32_16x16x32_bf16 v[96:99], v[204:207], v[172:175], v[96:99]
	v_mfma_f32_16x16x32_bf16 v[84:87], v[196:199], v[180:183], v[84:87]
	v_mfma_f32_16x16x32_bf16 v[80:83], v[204:207], v[180:183], v[80:83]
	v_mfma_f32_16x16x32_bf16 v[68:71], v[196:199], v[188:191], v[68:71]
	v_mfma_f32_16x16x32_bf16 v[64:67], v[204:207], v[188:191], v[64:67]
	s_mov_b32 m0, s64
	s_barrier
	ds_read_b128 v[160:163], v154 offset:49152
	ds_read_b128 v[164:167], v154 offset:50176
	ds_read_b128 v[168:171], v154 offset:51200
	ds_read_b128 v[172:175], v154 offset:52224
	ds_read_b128 v[176:179], v154 offset:53248
	ds_read_b128 v[180:183], v154 offset:54272
	ds_read_b128 v[184:187], v154 offset:55296
	ds_read_b128 v[188:191], v154 offset:56320
	global_load_lds_dwordx4 v132, s[100:101]
	s_mov_b32 m0, s65
	s_nop 0
	global_load_lds_dwordx4 v130, s[100:101]
	s_barrier
	s_waitcnt lgkmcnt(0)
	v_mfma_f32_16x16x32_bf16 v[60:63], v[138:141], v[160:163], v[60:63]
	v_mfma_f32_16x16x32_bf16 v[56:59], v[146:149], v[160:163], v[56:59]
	v_mfma_f32_16x16x32_bf16 v[44:47], v[138:141], v[168:171], v[44:47]
	v_mfma_f32_16x16x32_bf16 v[40:43], v[146:149], v[168:171], v[40:43]
	v_mfma_f32_16x16x32_bf16 v[28:31], v[138:141], v[176:179], v[28:31]
	v_mfma_f32_16x16x32_bf16 v[24:27], v[146:149], v[176:179], v[24:27]
	v_mfma_f32_16x16x32_bf16 v[12:15], v[138:141], v[184:187], v[12:15]
	v_mfma_f32_16x16x32_bf16 v[8:11], v[146:149], v[184:187], v[8:11]
	v_mfma_f32_16x16x32_bf16 v[60:63], v[142:145], v[164:167], v[60:63]
	v_mfma_f32_16x16x32_bf16 v[56:59], v[156:159], v[164:167], v[56:59]
	v_mfma_f32_16x16x32_bf16 v[44:47], v[142:145], v[172:175], v[44:47]
	v_mfma_f32_16x16x32_bf16 v[40:43], v[156:159], v[172:175], v[40:43]
	v_mfma_f32_16x16x32_bf16 v[28:31], v[142:145], v[180:183], v[28:31]
	v_mfma_f32_16x16x32_bf16 v[24:27], v[156:159], v[180:183], v[24:27]
	v_mfma_f32_16x16x32_bf16 v[12:15], v[142:145], v[188:191], v[12:15]
	v_mfma_f32_16x16x32_bf16 v[8:11], v[156:159], v[188:191], v[8:11]
	s_barrier
	s_add_u32 s28, s28, 0x40080
	s_addc_u32 s29, s29, 0
	s_add_i32 s30, s30, s57
	s_mov_b32 m0, s30
	s_nop 0
	global_load_lds_dwordx4 v208, s[28:29]
	s_add_i32 m0, s30, 0x2000
	s_nop 0
	global_load_lds_dwordx4 v128, s[28:29]
	s_waitcnt vmcnt(6)
	s_barrier
	v_mfma_f32_16x16x32_bf16 v[52:55], v[192:195], v[160:163], v[52:55]
	v_mfma_f32_16x16x32_bf16 v[48:51], v[200:203], v[160:163], v[48:51]
	v_mfma_f32_16x16x32_bf16 v[36:39], v[192:195], v[168:171], v[36:39]
	v_mfma_f32_16x16x32_bf16 v[32:35], v[200:203], v[168:171], v[32:35]
	v_mfma_f32_16x16x32_bf16 v[20:23], v[192:195], v[176:179], v[20:23]
	v_mfma_f32_16x16x32_bf16 v[16:19], v[200:203], v[176:179], v[16:19]
	v_mfma_f32_16x16x32_bf16 v[4:7], v[192:195], v[184:187], v[4:7]
	v_mfma_f32_16x16x32_bf16 v[0:3], v[200:203], v[184:187], v[0:3]
	v_mfma_f32_16x16x32_bf16 v[52:55], v[196:199], v[164:167], v[52:55]
	v_mfma_f32_16x16x32_bf16 v[48:51], v[204:207], v[164:167], v[48:51]
	v_mfma_f32_16x16x32_bf16 v[36:39], v[196:199], v[172:175], v[36:39]
	v_mfma_f32_16x16x32_bf16 v[32:35], v[204:207], v[172:175], v[32:35]
	v_mfma_f32_16x16x32_bf16 v[20:23], v[196:199], v[180:183], v[20:23]
	v_mfma_f32_16x16x32_bf16 v[16:19], v[204:207], v[180:183], v[16:19]
	v_mfma_f32_16x16x32_bf16 v[4:7], v[196:199], v[188:191], v[4:7]
	v_mfma_f32_16x16x32_bf16 v[0:3], v[204:207], v[188:191], v[0:3]
	s_add_i32 s51, s51, 2
	s_add_u32 s26, s26, 0x100
	s_addc_u32 s27, s27, 0
	s_add_u32 s46, s46, 0x100
	s_addc_u32 s50, s50, 0
	s_cmp_gt_u32 s51, 13
	s_barrier
	s_cbranch_scc0 .LBB0_698
	s_cmp_lt_i32 s34, 4
	s_cselect_b64 vcc, -1, 0
	v_mov_b32_e32 v138, 0x3e38aa3b
	s_nop 0
	v_cndmask_b32_e32 v155, 1.0, v138, vcc
	s_and_b64 s[26:27], vcc, exec
	v_lshl_add_u32 v140, s35, 8, v152
	s_cselect_b32 s7, s9, s11
	s_cselect_b32 s21, s8, s10
	v_mov_b32_e32 v138, s21
	v_mov_b32_e32 v139, s7
	v_lshlrev_b32_e32 v142, 3, v151
	v_mov_b32_e32 v143, 0
	v_lshl_add_u64 v[138:139], v[142:143], 2, v[138:139]
	global_load_dwordx4 v[188:191], v[138:139], off
	global_load_dwordx4 v[192:195], v[138:139], off offset:16
	global_load_dwordx4 v[196:199], v[138:139], off offset:128
	global_load_dwordx4 v[200:203], v[138:139], off offset:144
	s_lshl_b32 s7, s34, 8
	s_or_b32 s26, s7, s66
	s_ashr_i32 s27, s26, 31
	s_lshl_b64 s[26:27], s[26:27], 1
	s_add_u32 s26, s62, s26
	s_addc_u32 s27, s63, s27
	s_mov_b32 s34, s6
	s_mov_b32 s35, s20
	s_mov_b64 s[28:29], s[24:25]
	v_mbcnt_lo_u32_b32 v210, -1, 0
	v_mbcnt_hi_u32_b32 v210, -1, v210
	v_and_b32_e32 v210, 48, v210
	v_lshl_add_u32 v210, v140, 6, v210
	v_lshlrev_b32_e32 v211, 12, v140
	v_lshl_add_u32 v211, v151, 4, v211
	global_load_dwordx4 v[156:159], v210, s[18:19]
	global_load_dwordx4 v[160:163], v210, s[18:19] offset:1024
	global_load_dwordx4 v[164:167], v210, s[18:19] offset:2048
	global_load_dwordx4 v[168:171], v210, s[18:19] offset:3072
	v_add_u32_e32 v210, 0x2000, v210
	global_load_dwordx4 v[172:175], v210, s[18:19]
	global_load_dwordx4 v[176:179], v210, s[18:19] offset:1024
	global_load_dwordx4 v[180:183], v210, s[18:19] offset:2048
	global_load_dwordx4 v[184:187], v210, s[18:19] offset:3072
	s_waitcnt vmcnt(7)
	v_pk_add_f32 v[156:157], v[156:157], v[158:159]
	s_nop 0
	v_add_f32_e32 v214, v156, v157
	v_mov_b32_e32 v215, v214
	s_nop 1
	v_permlane16_swap_b32_e32 v214, v215
	s_nop 0
	v_add_f32_e32 v214, v214, v215
	v_mov_b32_e32 v215, v214
	s_nop 1
	v_permlane32_swap_b32_e32 v214, v215
	s_nop 0
	v_add_f32_e32 v214, v214, v215
	v_fmamk_f32 v214, v214, 0x3a800000, v248
	v_rsq_f32_e32 v216, v214
	s_nop 0
	v_pk_mul_f32 v[124:125], v[124:125], v[216:217] op_sel_hi:[1,0]
	v_pk_mul_f32 v[126:127], v[126:127], v[216:217] op_sel_hi:[1,0]
	v_pk_mul_f32 v[120:121], v[120:121], v[216:217] op_sel_hi:[1,0]
	v_pk_mul_f32 v[122:123], v[122:123], v[216:217] op_sel_hi:[1,0]
	v_pk_mul_f32 v[116:117], v[116:117], v[216:217] op_sel_hi:[1,0]
	v_pk_mul_f32 v[118:119], v[118:119], v[216:217] op_sel_hi:[1,0]
	v_pk_mul_f32 v[112:113], v[112:113], v[216:217] op_sel_hi:[1,0]
	v_pk_mul_f32 v[114:115], v[114:115], v[216:217] op_sel_hi:[1,0]
	v_pk_mul_f32 v[148:149], v[124:125], v[124:125]
	v_pk_fma_f32 v[148:149], v[126:127], v[126:127], v[148:149]
	v_pk_fma_f32 v[148:149], v[120:121], v[120:121], v[148:149]
	v_pk_fma_f32 v[148:149], v[122:123], v[122:123], v[148:149]
	v_pk_fma_f32 v[148:149], v[116:117], v[116:117], v[148:149]
	v_pk_fma_f32 v[148:149], v[118:119], v[118:119], v[148:149]
	v_pk_fma_f32 v[148:149], v[112:113], v[112:113], v[148:149]
	v_pk_fma_f32 v[148:149], v[114:115], v[114:115], v[148:149]
	v_add_f32_e32 v214, v148, v149
	v_mov_b32_e32 v215, v214
	s_nop 1
	v_permlane16_swap_b32_e32 v214, v215
	s_nop 0
	v_add_f32_e32 v214, v214, v215
	v_mov_b32_e32 v215, v214
	s_nop 1
	v_permlane32_swap_b32_e32 v214, v215
	s_nop 0
	v_add_f32_e32 v214, v214, v215
	v_fmamk_f32 v214, v214, 0x3c800000, v248
	v_rsq_f32_e32 v214, v214
	s_nop 0
	v_mul_f32_e32 v218, v155, v214
	v_pk_mul_f32 v[156:157], v[188:189], v[218:219] op_sel_hi:[1,0]
	v_pk_mul_f32 v[124:125], v[124:125], v[156:157]
	v_pk_mul_f32 v[156:157], v[190:191], v[218:219] op_sel_hi:[1,0]
	v_pk_mul_f32 v[126:127], v[126:127], v[156:157]
	v_pk_mul_f32 v[156:157], v[192:193], v[218:219] op_sel_hi:[1,0]
	v_pk_mul_f32 v[120:121], v[120:121], v[156:157]
	v_pk_mul_f32 v[156:157], v[194:195], v[218:219] op_sel_hi:[1,0]
	v_pk_mul_f32 v[122:123], v[122:123], v[156:157]
	v_cvt_pk_bf16_f32 v204, v124, v125
	v_cvt_pk_bf16_f32 v205, v126, v127
	v_cvt_pk_bf16_f32 v206, v120, v121
	v_cvt_pk_bf16_f32 v207, v122, v123
	global_store_dwordx4 v211, v[204:207], s[26:27]
	v_pk_mul_f32 v[156:157], v[196:197], v[218:219] op_sel_hi:[1,0]
	v_pk_mul_f32 v[116:117], v[116:117], v[156:157]
	v_pk_mul_f32 v[156:157], v[198:199], v[218:219] op_sel_hi:[1,0]
	v_pk_mul_f32 v[118:119], v[118:119], v[156:157]
	v_pk_mul_f32 v[156:157], v[200:201], v[218:219] op_sel_hi:[1,0]
	v_pk_mul_f32 v[112:113], v[112:113], v[156:157]
	v_pk_mul_f32 v[156:157], v[202:203], v[218:219] op_sel_hi:[1,0]
	v_pk_mul_f32 v[114:115], v[114:115], v[156:157]
	v_cvt_pk_bf16_f32 v144, v116, v117
	v_cvt_pk_bf16_f32 v145, v118, v119
	v_cvt_pk_bf16_f32 v146, v112, v113
	v_cvt_pk_bf16_f32 v147, v114, v115
	global_store_dwordx4 v211, v[144:147], s[26:27] offset:64
	v_add_u32_e32 v211, 0x10000, v211
	s_waitcnt vmcnt(8)
	v_pk_add_f32 v[160:161], v[160:161], v[162:163]
	s_nop 0
	v_add_f32_e32 v214, v160, v161
	v_mov_b32_e32 v215, v214
	s_nop 1
	v_permlane16_swap_b32_e32 v214, v215
	s_nop 0
	v_add_f32_e32 v214, v214, v215
	v_mov_b32_e32 v215, v214
	s_nop 1
	v_permlane32_swap_b32_e32 v214, v215
	s_nop 0
	v_add_f32_e32 v214, v214, v215
	v_fmamk_f32 v214, v214, 0x3a800000, v248
	v_rsq_f32_e32 v216, v214
	s_nop 0
	v_pk_mul_f32 v[108:109], v[108:109], v[216:217] op_sel_hi:[1,0]
	v_pk_mul_f32 v[110:111], v[110:111], v[216:217] op_sel_hi:[1,0]
	v_pk_mul_f32 v[104:105], v[104:105], v[216:217] op_sel_hi:[1,0]
	v_pk_mul_f32 v[106:107], v[106:107], v[216:217] op_sel_hi:[1,0]
	v_pk_mul_f32 v[100:101], v[100:101], v[216:217] op_sel_hi:[1,0]
	v_pk_mul_f32 v[102:103], v[102:103], v[216:217] op_sel_hi:[1,0]
	v_pk_mul_f32 v[96:97], v[96:97], v[216:217] op_sel_hi:[1,0]
	v_pk_mul_f32 v[98:99], v[98:99], v[216:217] op_sel_hi:[1,0]
	v_pk_mul_f32 v[148:149], v[108:109], v[108:109]
	v_pk_fma_f32 v[148:149], v[110:111], v[110:111], v[148:149]
	v_pk_fma_f32 v[148:149], v[104:105], v[104:105], v[148:149]
	v_pk_fma_f32 v[148:149], v[106:107], v[106:107], v[148:149]
	v_pk_fma_f32 v[148:149], v[100:101], v[100:101], v[148:149]
	v_pk_fma_f32 v[148:149], v[102:103], v[102:103], v[148:149]
	v_pk_fma_f32 v[148:149], v[96:97], v[96:97], v[148:149]
	v_pk_fma_f32 v[148:149], v[98:99], v[98:99], v[148:149]
	v_add_f32_e32 v214, v148, v149
	v_mov_b32_e32 v215, v214
	s_nop 1
	v_permlane16_swap_b32_e32 v214, v215
	s_nop 0
	v_add_f32_e32 v214, v214, v215
	v_mov_b32_e32 v215, v214
	s_nop 1
	v_permlane32_swap_b32_e32 v214, v215
	s_nop 0
	v_add_f32_e32 v214, v214, v215
	v_fmamk_f32 v214, v214, 0x3c800000, v248
	v_rsq_f32_e32 v214, v214
	s_nop 0
	v_mul_f32_e32 v218, v155, v214
	v_pk_mul_f32 v[160:161], v[188:189], v[218:219] op_sel_hi:[1,0]
	v_pk_mul_f32 v[108:109], v[108:109], v[160:161]
	v_pk_mul_f32 v[160:161], v[190:191], v[218:219] op_sel_hi:[1,0]
	v_pk_mul_f32 v[110:111], v[110:111], v[160:161]
	v_pk_mul_f32 v[160:161], v[192:193], v[218:219] op_sel_hi:[1,0]
	v_pk_mul_f32 v[104:105], v[104:105], v[160:161]
	v_pk_mul_f32 v[160:161], v[194:195], v[218:219] op_sel_hi:[1,0]
	v_pk_mul_f32 v[106:107], v[106:107], v[160:161]
	v_cvt_pk_bf16_f32 v204, v108, v109
	v_cvt_pk_bf16_f32 v205, v110, v111
	v_cvt_pk_bf16_f32 v206, v104, v105
	v_cvt_pk_bf16_f32 v207, v106, v107
	global_store_dwordx4 v211, v[204:207], s[26:27]
	v_pk_mul_f32 v[160:161], v[196:197], v[218:219] op_sel_hi:[1,0]
	v_pk_mul_f32 v[100:101], v[100:101], v[160:161]
	v_pk_mul_f32 v[160:161], v[198:199], v[218:219] op_sel_hi:[1,0]
	v_pk_mul_f32 v[102:103], v[102:103], v[160:161]
	v_pk_mul_f32 v[160:161], v[200:201], v[218:219] op_sel_hi:[1,0]
	v_pk_mul_f32 v[96:97], v[96:97], v[160:161]
	v_pk_mul_f32 v[160:161], v[202:203], v[218:219] op_sel_hi:[1,0]
	v_pk_mul_f32 v[98:99], v[98:99], v[160:161]
	v_cvt_pk_bf16_f32 v144, v100, v101
	v_cvt_pk_bf16_f32 v145, v102, v103
	v_cvt_pk_bf16_f32 v146, v96, v97
	v_cvt_pk_bf16_f32 v147, v98, v99
	global_store_dwordx4 v211, v[144:147], s[26:27] offset:64
	v_add_u32_e32 v211, 0x10000, v211
	s_waitcnt vmcnt(9)
	v_pk_add_f32 v[164:165], v[164:165], v[166:167]
	s_nop 0
	v_add_f32_e32 v214, v164, v165
	v_mov_b32_e32 v215, v214
	s_nop 1
	v_permlane16_swap_b32_e32 v214, v215
	s_nop 0
	v_add_f32_e32 v214, v214, v215
	v_mov_b32_e32 v215, v214
	s_nop 1
	v_permlane32_swap_b32_e32 v214, v215
	s_nop 0
	v_add_f32_e32 v214, v214, v215
	v_fmamk_f32 v214, v214, 0x3a800000, v248
	v_rsq_f32_e32 v216, v214
	s_nop 0
	v_pk_mul_f32 v[92:93], v[92:93], v[216:217] op_sel_hi:[1,0]
	v_pk_mul_f32 v[94:95], v[94:95], v[216:217] op_sel_hi:[1,0]
	v_pk_mul_f32 v[88:89], v[88:89], v[216:217] op_sel_hi:[1,0]
	v_pk_mul_f32 v[90:91], v[90:91], v[216:217] op_sel_hi:[1,0]
	v_pk_mul_f32 v[84:85], v[84:85], v[216:217] op_sel_hi:[1,0]
	v_pk_mul_f32 v[86:87], v[86:87], v[216:217] op_sel_hi:[1,0]
	v_pk_mul_f32 v[80:81], v[80:81], v[216:217] op_sel_hi:[1,0]
	v_pk_mul_f32 v[82:83], v[82:83], v[216:217] op_sel_hi:[1,0]
	v_pk_mul_f32 v[148:149], v[92:93], v[92:93]
	v_pk_fma_f32 v[148:149], v[94:95], v[94:95], v[148:149]
	v_pk_fma_f32 v[148:149], v[88:89], v[88:89], v[148:149]
	v_pk_fma_f32 v[148:149], v[90:91], v[90:91], v[148:149]
	v_pk_fma_f32 v[148:149], v[84:85], v[84:85], v[148:149]
	v_pk_fma_f32 v[148:149], v[86:87], v[86:87], v[148:149]
	v_pk_fma_f32 v[148:149], v[80:81], v[80:81], v[148:149]
	v_pk_fma_f32 v[148:149], v[82:83], v[82:83], v[148:149]
	v_add_f32_e32 v214, v148, v149
	v_mov_b32_e32 v215, v214
	s_nop 1
	v_permlane16_swap_b32_e32 v214, v215
	s_nop 0
	v_add_f32_e32 v214, v214, v215
	v_mov_b32_e32 v215, v214
	s_nop 1
	v_permlane32_swap_b32_e32 v214, v215
	s_nop 0
	v_add_f32_e32 v214, v214, v215
	v_fmamk_f32 v214, v214, 0x3c800000, v248
	v_rsq_f32_e32 v214, v214
	s_nop 0
	v_mul_f32_e32 v218, v155, v214
	v_pk_mul_f32 v[164:165], v[188:189], v[218:219] op_sel_hi:[1,0]
	v_pk_mul_f32 v[92:93], v[92:93], v[164:165]
	v_pk_mul_f32 v[164:165], v[190:191], v[218:219] op_sel_hi:[1,0]
	v_pk_mul_f32 v[94:95], v[94:95], v[164:165]
	v_pk_mul_f32 v[164:165], v[192:193], v[218:219] op_sel_hi:[1,0]
	v_pk_mul_f32 v[88:89], v[88:89], v[164:165]
	v_pk_mul_f32 v[164:165], v[194:195], v[218:219] op_sel_hi:[1,0]
	v_pk_mul_f32 v[90:91], v[90:91], v[164:165]
	v_cvt_pk_bf16_f32 v204, v92, v93
	v_cvt_pk_bf16_f32 v205, v94, v95
	v_cvt_pk_bf16_f32 v206, v88, v89
	v_cvt_pk_bf16_f32 v207, v90, v91
	global_store_dwordx4 v211, v[204:207], s[26:27]
	v_pk_mul_f32 v[164:165], v[196:197], v[218:219] op_sel_hi:[1,0]
	v_pk_mul_f32 v[84:85], v[84:85], v[164:165]
	v_pk_mul_f32 v[164:165], v[198:199], v[218:219] op_sel_hi:[1,0]
	v_pk_mul_f32 v[86:87], v[86:87], v[164:165]
	v_pk_mul_f32 v[164:165], v[200:201], v[218:219] op_sel_hi:[1,0]
	v_pk_mul_f32 v[80:81], v[80:81], v[164:165]
	v_pk_mul_f32 v[164:165], v[202:203], v[218:219] op_sel_hi:[1,0]
	v_pk_mul_f32 v[82:83], v[82:83], v[164:165]
	v_cvt_pk_bf16_f32 v144, v84, v85
	v_cvt_pk_bf16_f32 v145, v86, v87
	v_cvt_pk_bf16_f32 v146, v80, v81
	v_cvt_pk_bf16_f32 v147, v82, v83
	global_store_dwordx4 v211, v[144:147], s[26:27] offset:64
	v_add_u32_e32 v211, 0x10000, v211
	s_waitcnt vmcnt(10)
	v_pk_add_f32 v[168:169], v[168:169], v[170:171]
	s_nop 0
	v_add_f32_e32 v214, v168, v169
	v_mov_b32_e32 v215, v214
	s_nop 1
	v_permlane16_swap_b32_e32 v214, v215
	s_nop 0
	v_add_f32_e32 v214, v214, v215
	v_mov_b32_e32 v215, v214
	s_nop 1
	v_permlane32_swap_b32_e32 v214, v215
	s_nop 0
	v_add_f32_e32 v214, v214, v215
	v_fmamk_f32 v214, v214, 0x3a800000, v248
	v_rsq_f32_e32 v216, v214
	s_nop 0
	v_pk_mul_f32 v[76:77], v[76:77], v[216:217] op_sel_hi:[1,0]
	v_pk_mul_f32 v[78:79], v[78:79], v[216:217] op_sel_hi:[1,0]
	v_pk_mul_f32 v[72:73], v[72:73], v[216:217] op_sel_hi:[1,0]
	v_pk_mul_f32 v[74:75], v[74:75], v[216:217] op_sel_hi:[1,0]
	v_pk_mul_f32 v[68:69], v[68:69], v[216:217] op_sel_hi:[1,0]
	v_pk_mul_f32 v[70:71], v[70:71], v[216:217] op_sel_hi:[1,0]
	v_pk_mul_f32 v[64:65], v[64:65], v[216:217] op_sel_hi:[1,0]
	v_pk_mul_f32 v[66:67], v[66:67], v[216:217] op_sel_hi:[1,0]
	v_pk_mul_f32 v[148:149], v[76:77], v[76:77]
	v_pk_fma_f32 v[148:149], v[78:79], v[78:79], v[148:149]
	v_pk_fma_f32 v[148:149], v[72:73], v[72:73], v[148:149]
	v_pk_fma_f32 v[148:149], v[74:75], v[74:75], v[148:149]
	v_pk_fma_f32 v[148:149], v[68:69], v[68:69], v[148:149]
	v_pk_fma_f32 v[148:149], v[70:71], v[70:71], v[148:149]
	v_pk_fma_f32 v[148:149], v[64:65], v[64:65], v[148:149]
	v_pk_fma_f32 v[148:149], v[66:67], v[66:67], v[148:149]
	v_add_f32_e32 v214, v148, v149
	v_mov_b32_e32 v215, v214
	s_nop 1
	v_permlane16_swap_b32_e32 v214, v215
	s_nop 0
	v_add_f32_e32 v214, v214, v215
	v_mov_b32_e32 v215, v214
	s_nop 1
	v_permlane32_swap_b32_e32 v214, v215
	s_nop 0
	v_add_f32_e32 v214, v214, v215
	v_fmamk_f32 v214, v214, 0x3c800000, v248
	v_rsq_f32_e32 v214, v214
	s_nop 0
	v_mul_f32_e32 v218, v155, v214
	v_pk_mul_f32 v[168:169], v[188:189], v[218:219] op_sel_hi:[1,0]
	v_pk_mul_f32 v[76:77], v[76:77], v[168:169]
	v_pk_mul_f32 v[168:169], v[190:191], v[218:219] op_sel_hi:[1,0]
	v_pk_mul_f32 v[78:79], v[78:79], v[168:169]
	v_pk_mul_f32 v[168:169], v[192:193], v[218:219] op_sel_hi:[1,0]
	v_pk_mul_f32 v[72:73], v[72:73], v[168:169]
	v_pk_mul_f32 v[168:169], v[194:195], v[218:219] op_sel_hi:[1,0]
	v_pk_mul_f32 v[74:75], v[74:75], v[168:169]
	v_cvt_pk_bf16_f32 v204, v76, v77
	v_cvt_pk_bf16_f32 v205, v78, v79
	v_cvt_pk_bf16_f32 v206, v72, v73
	v_cvt_pk_bf16_f32 v207, v74, v75
	global_store_dwordx4 v211, v[204:207], s[26:27]
	v_pk_mul_f32 v[168:169], v[196:197], v[218:219] op_sel_hi:[1,0]
	v_pk_mul_f32 v[68:69], v[68:69], v[168:169]
	v_pk_mul_f32 v[168:169], v[198:199], v[218:219] op_sel_hi:[1,0]
	v_pk_mul_f32 v[70:71], v[70:71], v[168:169]
	v_pk_mul_f32 v[168:169], v[200:201], v[218:219] op_sel_hi:[1,0]
	v_pk_mul_f32 v[64:65], v[64:65], v[168:169]
	v_pk_mul_f32 v[168:169], v[202:203], v[218:219] op_sel_hi:[1,0]
	v_pk_mul_f32 v[66:67], v[66:67], v[168:169]
	v_cvt_pk_bf16_f32 v144, v68, v69
	v_cvt_pk_bf16_f32 v145, v70, v71
	v_cvt_pk_bf16_f32 v146, v64, v65
	v_cvt_pk_bf16_f32 v147, v66, v67
	global_store_dwordx4 v211, v[144:147], s[26:27] offset:64
	v_add_u32_e32 v211, 0x50000, v211
	s_waitcnt vmcnt(11)
	v_pk_add_f32 v[172:173], v[172:173], v[174:175]
	s_nop 0
	v_add_f32_e32 v214, v172, v173
	v_mov_b32_e32 v215, v214
	s_nop 1
	v_permlane16_swap_b32_e32 v214, v215
	s_nop 0
	v_add_f32_e32 v214, v214, v215
	v_mov_b32_e32 v215, v214
	s_nop 1
	v_permlane32_swap_b32_e32 v214, v215
	s_nop 0
	v_add_f32_e32 v214, v214, v215
	v_fmamk_f32 v214, v214, 0x3a800000, v248
	v_rsq_f32_e32 v216, v214
	s_nop 0
	v_pk_mul_f32 v[60:61], v[60:61], v[216:217] op_sel_hi:[1,0]
	v_pk_mul_f32 v[62:63], v[62:63], v[216:217] op_sel_hi:[1,0]
	v_pk_mul_f32 v[56:57], v[56:57], v[216:217] op_sel_hi:[1,0]
	v_pk_mul_f32 v[58:59], v[58:59], v[216:217] op_sel_hi:[1,0]
	v_pk_mul_f32 v[52:53], v[52:53], v[216:217] op_sel_hi:[1,0]
	v_pk_mul_f32 v[54:55], v[54:55], v[216:217] op_sel_hi:[1,0]
	v_pk_mul_f32 v[48:49], v[48:49], v[216:217] op_sel_hi:[1,0]
	v_pk_mul_f32 v[50:51], v[50:51], v[216:217] op_sel_hi:[1,0]
	v_pk_mul_f32 v[148:149], v[60:61], v[60:61]
	v_pk_fma_f32 v[148:149], v[62:63], v[62:63], v[148:149]
	v_pk_fma_f32 v[148:149], v[56:57], v[56:57], v[148:149]
	v_pk_fma_f32 v[148:149], v[58:59], v[58:59], v[148:149]
	v_pk_fma_f32 v[148:149], v[52:53], v[52:53], v[148:149]
	v_pk_fma_f32 v[148:149], v[54:55], v[54:55], v[148:149]
	v_pk_fma_f32 v[148:149], v[48:49], v[48:49], v[148:149]
	v_pk_fma_f32 v[148:149], v[50:51], v[50:51], v[148:149]
	v_add_f32_e32 v214, v148, v149
	v_mov_b32_e32 v215, v214
	s_nop 1
	v_permlane16_swap_b32_e32 v214, v215
	s_nop 0
	v_add_f32_e32 v214, v214, v215
	v_mov_b32_e32 v215, v214
	s_nop 1
	v_permlane32_swap_b32_e32 v214, v215
	s_nop 0
	v_add_f32_e32 v214, v214, v215
	v_fmamk_f32 v214, v214, 0x3c800000, v248
	v_rsq_f32_e32 v214, v214
	s_nop 0
	v_mul_f32_e32 v218, v155, v214
	v_pk_mul_f32 v[172:173], v[188:189], v[218:219] op_sel_hi:[1,0]
	v_pk_mul_f32 v[60:61], v[60:61], v[172:173]
	v_pk_mul_f32 v[172:173], v[190:191], v[218:219] op_sel_hi:[1,0]
	v_pk_mul_f32 v[62:63], v[62:63], v[172:173]
	v_pk_mul_f32 v[172:173], v[192:193], v[218:219] op_sel_hi:[1,0]
	v_pk_mul_f32 v[56:57], v[56:57], v[172:173]
	v_pk_mul_f32 v[172:173], v[194:195], v[218:219] op_sel_hi:[1,0]
	v_pk_mul_f32 v[58:59], v[58:59], v[172:173]
	v_cvt_pk_bf16_f32 v204, v60, v61
	v_cvt_pk_bf16_f32 v205, v62, v63
	v_cvt_pk_bf16_f32 v206, v56, v57
	v_cvt_pk_bf16_f32 v207, v58, v59
	global_store_dwordx4 v211, v[204:207], s[26:27]
	v_pk_mul_f32 v[172:173], v[196:197], v[218:219] op_sel_hi:[1,0]
	v_pk_mul_f32 v[52:53], v[52:53], v[172:173]
	v_pk_mul_f32 v[172:173], v[198:199], v[218:219] op_sel_hi:[1,0]
	v_pk_mul_f32 v[54:55], v[54:55], v[172:173]
	v_pk_mul_f32 v[172:173], v[200:201], v[218:219] op_sel_hi:[1,0]
	v_pk_mul_f32 v[48:49], v[48:49], v[172:173]
	v_pk_mul_f32 v[172:173], v[202:203], v[218:219] op_sel_hi:[1,0]
	v_pk_mul_f32 v[50:51], v[50:51], v[172:173]
	v_cvt_pk_bf16_f32 v144, v52, v53
	v_cvt_pk_bf16_f32 v145, v54, v55
	v_cvt_pk_bf16_f32 v146, v48, v49
	v_cvt_pk_bf16_f32 v147, v50, v51
	global_store_dwordx4 v211, v[144:147], s[26:27] offset:64
	v_add_u32_e32 v211, 0x10000, v211
	s_waitcnt vmcnt(12)
	v_pk_add_f32 v[176:177], v[176:177], v[178:179]
	s_nop 0
	v_add_f32_e32 v214, v176, v177
	v_mov_b32_e32 v215, v214
	s_nop 1
	v_permlane16_swap_b32_e32 v214, v215
	s_nop 0
	v_add_f32_e32 v214, v214, v215
	v_mov_b32_e32 v215, v214
	s_nop 1
	v_permlane32_swap_b32_e32 v214, v215
	s_nop 0
	v_add_f32_e32 v214, v214, v215
	v_fmamk_f32 v214, v214, 0x3a800000, v248
	v_rsq_f32_e32 v216, v214
	s_nop 0
	v_pk_mul_f32 v[44:45], v[44:45], v[216:217] op_sel_hi:[1,0]
	v_pk_mul_f32 v[46:47], v[46:47], v[216:217] op_sel_hi:[1,0]
	v_pk_mul_f32 v[40:41], v[40:41], v[216:217] op_sel_hi:[1,0]
	v_pk_mul_f32 v[42:43], v[42:43], v[216:217] op_sel_hi:[1,0]
	v_pk_mul_f32 v[36:37], v[36:37], v[216:217] op_sel_hi:[1,0]
	v_pk_mul_f32 v[38:39], v[38:39], v[216:217] op_sel_hi:[1,0]
	v_pk_mul_f32 v[32:33], v[32:33], v[216:217] op_sel_hi:[1,0]
	v_pk_mul_f32 v[34:35], v[34:35], v[216:217] op_sel_hi:[1,0]
	v_pk_mul_f32 v[148:149], v[44:45], v[44:45]
	v_pk_fma_f32 v[148:149], v[46:47], v[46:47], v[148:149]
	v_pk_fma_f32 v[148:149], v[40:41], v[40:41], v[148:149]
	v_pk_fma_f32 v[148:149], v[42:43], v[42:43], v[148:149]
	v_pk_fma_f32 v[148:149], v[36:37], v[36:37], v[148:149]
	v_pk_fma_f32 v[148:149], v[38:39], v[38:39], v[148:149]
	v_pk_fma_f32 v[148:149], v[32:33], v[32:33], v[148:149]
	v_pk_fma_f32 v[148:149], v[34:35], v[34:35], v[148:149]
	v_add_f32_e32 v214, v148, v149
	v_mov_b32_e32 v215, v214
	s_nop 1
	v_permlane16_swap_b32_e32 v214, v215
	s_nop 0
	v_add_f32_e32 v214, v214, v215
	v_mov_b32_e32 v215, v214
	s_nop 1
	v_permlane32_swap_b32_e32 v214, v215
	s_nop 0
	v_add_f32_e32 v214, v214, v215
	v_fmamk_f32 v214, v214, 0x3c800000, v248
	v_rsq_f32_e32 v214, v214
	s_nop 0
	v_mul_f32_e32 v218, v155, v214
	v_pk_mul_f32 v[176:177], v[188:189], v[218:219] op_sel_hi:[1,0]
	v_pk_mul_f32 v[44:45], v[44:45], v[176:177]
	v_pk_mul_f32 v[176:177], v[190:191], v[218:219] op_sel_hi:[1,0]
	v_pk_mul_f32 v[46:47], v[46:47], v[176:177]
	v_pk_mul_f32 v[176:177], v[192:193], v[218:219] op_sel_hi:[1,0]
	v_pk_mul_f32 v[40:41], v[40:41], v[176:177]
	v_pk_mul_f32 v[176:177], v[194:195], v[218:219] op_sel_hi:[1,0]
	v_pk_mul_f32 v[42:43], v[42:43], v[176:177]
	v_cvt_pk_bf16_f32 v204, v44, v45
	v_cvt_pk_bf16_f32 v205, v46, v47
	v_cvt_pk_bf16_f32 v206, v40, v41
	v_cvt_pk_bf16_f32 v207, v42, v43
	global_store_dwordx4 v211, v[204:207], s[26:27]
	v_pk_mul_f32 v[176:177], v[196:197], v[218:219] op_sel_hi:[1,0]
	v_pk_mul_f32 v[36:37], v[36:37], v[176:177]
	v_pk_mul_f32 v[176:177], v[198:199], v[218:219] op_sel_hi:[1,0]
	v_pk_mul_f32 v[38:39], v[38:39], v[176:177]
	v_pk_mul_f32 v[176:177], v[200:201], v[218:219] op_sel_hi:[1,0]
	v_pk_mul_f32 v[32:33], v[32:33], v[176:177]
	v_pk_mul_f32 v[176:177], v[202:203], v[218:219] op_sel_hi:[1,0]
	v_pk_mul_f32 v[34:35], v[34:35], v[176:177]
	v_cvt_pk_bf16_f32 v144, v36, v37
	v_cvt_pk_bf16_f32 v145, v38, v39
	v_cvt_pk_bf16_f32 v146, v32, v33
	v_cvt_pk_bf16_f32 v147, v34, v35
	global_store_dwordx4 v211, v[144:147], s[26:27] offset:64
	v_add_u32_e32 v211, 0x10000, v211
	s_waitcnt vmcnt(13)
	v_pk_add_f32 v[180:181], v[180:181], v[182:183]
	s_nop 0
	v_add_f32_e32 v214, v180, v181
	v_mov_b32_e32 v215, v214
	s_nop 1
	v_permlane16_swap_b32_e32 v214, v215
	s_nop 0
	v_add_f32_e32 v214, v214, v215
	v_mov_b32_e32 v215, v214
	s_nop 1
	v_permlane32_swap_b32_e32 v214, v215
	s_nop 0
	v_add_f32_e32 v214, v214, v215
	v_fmamk_f32 v214, v214, 0x3a800000, v248
	v_rsq_f32_e32 v216, v214
	s_nop 0
	v_pk_mul_f32 v[28:29], v[28:29], v[216:217] op_sel_hi:[1,0]
	v_pk_mul_f32 v[30:31], v[30:31], v[216:217] op_sel_hi:[1,0]
	v_pk_mul_f32 v[24:25], v[24:25], v[216:217] op_sel_hi:[1,0]
	v_pk_mul_f32 v[26:27], v[26:27], v[216:217] op_sel_hi:[1,0]
	v_pk_mul_f32 v[20:21], v[20:21], v[216:217] op_sel_hi:[1,0]
	v_pk_mul_f32 v[22:23], v[22:23], v[216:217] op_sel_hi:[1,0]
	v_pk_mul_f32 v[16:17], v[16:17], v[216:217] op_sel_hi:[1,0]
	v_pk_mul_f32 v[18:19], v[18:19], v[216:217] op_sel_hi:[1,0]
	v_pk_mul_f32 v[148:149], v[28:29], v[28:29]
	v_pk_fma_f32 v[148:149], v[30:31], v[30:31], v[148:149]
	v_pk_fma_f32 v[148:149], v[24:25], v[24:25], v[148:149]
	v_pk_fma_f32 v[148:149], v[26:27], v[26:27], v[148:149]
	v_pk_fma_f32 v[148:149], v[20:21], v[20:21], v[148:149]
	v_pk_fma_f32 v[148:149], v[22:23], v[22:23], v[148:149]
	v_pk_fma_f32 v[148:149], v[16:17], v[16:17], v[148:149]
	v_pk_fma_f32 v[148:149], v[18:19], v[18:19], v[148:149]
	v_add_f32_e32 v214, v148, v149
	v_mov_b32_e32 v215, v214
	s_nop 1
	v_permlane16_swap_b32_e32 v214, v215
	s_nop 0
	v_add_f32_e32 v214, v214, v215
	v_mov_b32_e32 v215, v214
	s_nop 1
	v_permlane32_swap_b32_e32 v214, v215
	s_nop 0
	v_add_f32_e32 v214, v214, v215
	v_fmamk_f32 v214, v214, 0x3c800000, v248
	v_rsq_f32_e32 v214, v214
	s_nop 0
	v_mul_f32_e32 v218, v155, v214
	v_pk_mul_f32 v[180:181], v[188:189], v[218:219] op_sel_hi:[1,0]
	v_pk_mul_f32 v[28:29], v[28:29], v[180:181]
	v_pk_mul_f32 v[180:181], v[190:191], v[218:219] op_sel_hi:[1,0]
	v_pk_mul_f32 v[30:31], v[30:31], v[180:181]
	v_pk_mul_f32 v[180:181], v[192:193], v[218:219] op_sel_hi:[1,0]
	v_pk_mul_f32 v[24:25], v[24:25], v[180:181]
	v_pk_mul_f32 v[180:181], v[194:195], v[218:219] op_sel_hi:[1,0]
	v_pk_mul_f32 v[26:27], v[26:27], v[180:181]
	v_cvt_pk_bf16_f32 v204, v28, v29
	v_cvt_pk_bf16_f32 v205, v30, v31
	v_cvt_pk_bf16_f32 v206, v24, v25
	v_cvt_pk_bf16_f32 v207, v26, v27
	global_store_dwordx4 v211, v[204:207], s[26:27]
	v_pk_mul_f32 v[180:181], v[196:197], v[218:219] op_sel_hi:[1,0]
	v_pk_mul_f32 v[20:21], v[20:21], v[180:181]
	v_pk_mul_f32 v[180:181], v[198:199], v[218:219] op_sel_hi:[1,0]
	v_pk_mul_f32 v[22:23], v[22:23], v[180:181]
	v_pk_mul_f32 v[180:181], v[200:201], v[218:219] op_sel_hi:[1,0]
	v_pk_mul_f32 v[16:17], v[16:17], v[180:181]
	v_pk_mul_f32 v[180:181], v[202:203], v[218:219] op_sel_hi:[1,0]
	v_pk_mul_f32 v[18:19], v[18:19], v[180:181]
	v_cvt_pk_bf16_f32 v144, v20, v21
	v_cvt_pk_bf16_f32 v145, v22, v23
	v_cvt_pk_bf16_f32 v146, v16, v17
	v_cvt_pk_bf16_f32 v147, v18, v19
	global_store_dwordx4 v211, v[144:147], s[26:27] offset:64
	v_add_u32_e32 v211, 0x10000, v211
	s_waitcnt vmcnt(14)
	v_pk_add_f32 v[184:185], v[184:185], v[186:187]
	s_nop 0
	v_add_f32_e32 v214, v184, v185
	v_mov_b32_e32 v215, v214
	s_nop 1
	v_permlane16_swap_b32_e32 v214, v215
	s_nop 0
	v_add_f32_e32 v214, v214, v215
	v_mov_b32_e32 v215, v214
	s_nop 1
	v_permlane32_swap_b32_e32 v214, v215
	s_nop 0
	v_add_f32_e32 v214, v214, v215
	v_fmamk_f32 v214, v214, 0x3a800000, v248
	v_rsq_f32_e32 v216, v214
	s_nop 0
	v_pk_mul_f32 v[12:13], v[12:13], v[216:217] op_sel_hi:[1,0]
	v_pk_mul_f32 v[14:15], v[14:15], v[216:217] op_sel_hi:[1,0]
	v_pk_mul_f32 v[8:9], v[8:9], v[216:217] op_sel_hi:[1,0]
	v_pk_mul_f32 v[10:11], v[10:11], v[216:217] op_sel_hi:[1,0]
	v_pk_mul_f32 v[4:5], v[4:5], v[216:217] op_sel_hi:[1,0]
	v_pk_mul_f32 v[6:7], v[6:7], v[216:217] op_sel_hi:[1,0]
	v_pk_mul_f32 v[0:1], v[0:1], v[216:217] op_sel_hi:[1,0]
	v_pk_mul_f32 v[2:3], v[2:3], v[216:217] op_sel_hi:[1,0]
	v_pk_mul_f32 v[148:149], v[12:13], v[12:13]
	v_pk_fma_f32 v[148:149], v[14:15], v[14:15], v[148:149]
	v_pk_fma_f32 v[148:149], v[8:9], v[8:9], v[148:149]
	v_pk_fma_f32 v[148:149], v[10:11], v[10:11], v[148:149]
	v_pk_fma_f32 v[148:149], v[4:5], v[4:5], v[148:149]
	v_pk_fma_f32 v[148:149], v[6:7], v[6:7], v[148:149]
	v_pk_fma_f32 v[148:149], v[0:1], v[0:1], v[148:149]
	v_pk_fma_f32 v[148:149], v[2:3], v[2:3], v[148:149]
	v_add_f32_e32 v214, v148, v149
	v_mov_b32_e32 v215, v214
	s_nop 1
	v_permlane16_swap_b32_e32 v214, v215
	s_nop 0
	v_add_f32_e32 v214, v214, v215
	v_mov_b32_e32 v215, v214
	s_nop 1
	v_permlane32_swap_b32_e32 v214, v215
	s_nop 0
	v_add_f32_e32 v214, v214, v215
	v_fmamk_f32 v214, v214, 0x3c800000, v248
	v_rsq_f32_e32 v214, v214
	s_nop 0
	v_mul_f32_e32 v218, v155, v214
	v_pk_mul_f32 v[184:185], v[188:189], v[218:219] op_sel_hi:[1,0]
	v_pk_mul_f32 v[12:13], v[12:13], v[184:185]
	v_pk_mul_f32 v[184:185], v[190:191], v[218:219] op_sel_hi:[1,0]
	v_pk_mul_f32 v[14:15], v[14:15], v[184:185]
	v_pk_mul_f32 v[184:185], v[192:193], v[218:219] op_sel_hi:[1,0]
	v_pk_mul_f32 v[8:9], v[8:9], v[184:185]
	v_pk_mul_f32 v[184:185], v[194:195], v[218:219] op_sel_hi:[1,0]
	v_pk_mul_f32 v[10:11], v[10:11], v[184:185]
	v_cvt_pk_bf16_f32 v204, v12, v13
	v_cvt_pk_bf16_f32 v205, v14, v15
	v_cvt_pk_bf16_f32 v206, v8, v9
	v_cvt_pk_bf16_f32 v207, v10, v11
	global_store_dwordx4 v211, v[204:207], s[26:27]
	v_pk_mul_f32 v[184:185], v[196:197], v[218:219] op_sel_hi:[1,0]
	v_pk_mul_f32 v[4:5], v[4:5], v[184:185]
	v_pk_mul_f32 v[184:185], v[198:199], v[218:219] op_sel_hi:[1,0]
	v_pk_mul_f32 v[6:7], v[6:7], v[184:185]
	v_pk_mul_f32 v[184:185], v[200:201], v[218:219] op_sel_hi:[1,0]
	v_pk_mul_f32 v[0:1], v[0:1], v[184:185]
	v_pk_mul_f32 v[184:185], v[202:203], v[218:219] op_sel_hi:[1,0]
	v_pk_mul_f32 v[2:3], v[2:3], v[184:185]
	v_cvt_pk_bf16_f32 v144, v4, v5
	v_cvt_pk_bf16_f32 v145, v6, v7
	v_cvt_pk_bf16_f32 v146, v0, v1
	v_cvt_pk_bf16_f32 v147, v2, v3
	global_store_dwordx4 v211, v[144:147], s[26:27] offset:64
	s_and_b64 vcc, exec, s[4:5]
	s_mov_b64 s[26:27], s[22:23]
	s_cbranch_vccz .LBB0_691
	s_waitcnt vmcnt(0)
	s_cmpk_gt_u32 s54, 0xff
	s_cbranch_scc1 .LBB0_702
	s_barrier

.LBB0_714:
	v_add_u32_e32 v163, 0x10000, v165
	s_add_u32 s26, s6, 0xfffc0080
	s_addc_u32 s27, s7, -1
	s_add_i32 s63, 0, 0x10000
	ds_read_b128 v[128:131], v163
	ds_read_b128 v[132:135], v163 offset:1024
	ds_read_b128 v[136:139], v163 offset:2048
	ds_read_b128 v[140:143], v163 offset:3072
	s_cmp_eq_u32 s51, 12
	s_cselect_b32 s29, s21, s27
	s_cselect_b32 s28, s38, s26
	s_cselect_b32 s27, s11, s50
	s_cselect_b32 s26, s39, s46
	s_add_i32 m0, s56, 0xc000
	ds_read_b128 v[154:157], v167
	ds_read_b128 v[158:161], v167 offset:1024
	ds_read_b128 v[168:171], v167 offset:2048
	ds_read_b128 v[172:175], v167 offset:3072
	ds_read_b128 v[176:179], v167 offset:4096
	ds_read_b128 v[180:183], v167 offset:5120
	ds_read_b128 v[184:187], v167 offset:6144
	ds_read_b128 v[188:191], v167 offset:7168
	global_load_lds_dwordx4 v150, s[6:7]
	s_add_i32 m0, s56, 0xe000
	s_nop 0
	global_load_lds_dwordx4 v152, s[6:7]
	s_waitcnt lgkmcnt(8)
	s_barrier
	s_waitcnt lgkmcnt(0)
	v_mfma_f32_16x16x32_bf16 v[124:127], v[128:131], v[154:157], v[124:127]
	v_mfma_f32_16x16x32_bf16 v[120:123], v[136:139], v[154:157], v[120:123]
	v_mfma_f32_16x16x32_bf16 v[116:119], v[128:131], v[168:171], v[116:119]
	v_mfma_f32_16x16x32_bf16 v[112:115], v[136:139], v[168:171], v[112:115]
	v_mfma_f32_16x16x32_bf16 v[108:111], v[128:131], v[176:179], v[108:111]
	v_mfma_f32_16x16x32_bf16 v[104:107], v[136:139], v[176:179], v[104:107]
	v_mfma_f32_16x16x32_bf16 v[100:103], v[128:131], v[184:187], v[100:103]
	v_mfma_f32_16x16x32_bf16 v[96:99], v[136:139], v[184:187], v[96:99]
	v_mfma_f32_16x16x32_bf16 v[124:127], v[132:135], v[158:161], v[124:127]
	v_mfma_f32_16x16x32_bf16 v[120:123], v[140:143], v[158:161], v[120:123]
	v_mfma_f32_16x16x32_bf16 v[116:119], v[132:135], v[172:175], v[116:119]
	v_mfma_f32_16x16x32_bf16 v[112:115], v[140:143], v[172:175], v[112:115]
	v_mfma_f32_16x16x32_bf16 v[108:111], v[132:135], v[180:183], v[108:111]
	v_mfma_f32_16x16x32_bf16 v[104:107], v[140:143], v[180:183], v[104:107]
	v_mfma_f32_16x16x32_bf16 v[100:103], v[132:135], v[188:191], v[100:103]
	v_mfma_f32_16x16x32_bf16 v[96:99], v[140:143], v[188:191], v[96:99]
	s_barrier
	s_add_i32 s66, 0, 0x14000
	s_add_i32 s63, s63, s55
	ds_read_b128 v[192:195], v163 offset:16384
	ds_read_b128 v[196:199], v163 offset:17408
	ds_read_b128 v[200:203], v163 offset:18432
	ds_read_b128 v[204:207], v163 offset:19456
	s_add_u32 s98, s26, s40
	s_addc_u32 s99, s27, s41
	s_mov_b32 m0, s63
	s_nop 0
	global_load_lds_dwordx4 v208, s[26:27]
	s_add_i32 m0, s63, 0x2000
	s_nop 0
	global_load_lds_dwordx4 v144, s[26:27]
	s_barrier
	s_waitcnt lgkmcnt(0)
	v_mfma_f32_16x16x32_bf16 v[60:63], v[192:195], v[154:157], v[60:63]
	v_mfma_f32_16x16x32_bf16 v[56:59], v[200:203], v[154:157], v[56:59]
	v_mfma_f32_16x16x32_bf16 v[52:55], v[192:195], v[168:171], v[52:55]
	v_mfma_f32_16x16x32_bf16 v[48:51], v[200:203], v[168:171], v[48:51]
	v_mfma_f32_16x16x32_bf16 v[44:47], v[192:195], v[176:179], v[44:47]
	v_mfma_f32_16x16x32_bf16 v[40:43], v[200:203], v[176:179], v[40:43]
	v_mfma_f32_16x16x32_bf16 v[36:39], v[192:195], v[184:187], v[36:39]
	v_mfma_f32_16x16x32_bf16 v[32:35], v[200:203], v[184:187], v[32:35]
	v_mfma_f32_16x16x32_bf16 v[60:63], v[196:199], v[158:161], v[60:63]
	v_mfma_f32_16x16x32_bf16 v[56:59], v[204:207], v[158:161], v[56:59]
	v_mfma_f32_16x16x32_bf16 v[52:55], v[196:199], v[172:175], v[52:55]
	v_mfma_f32_16x16x32_bf16 v[48:51], v[204:207], v[172:175], v[48:51]
	v_mfma_f32_16x16x32_bf16 v[44:47], v[196:199], v[180:183], v[44:47]
	v_mfma_f32_16x16x32_bf16 v[40:43], v[204:207], v[180:183], v[40:43]
	v_mfma_f32_16x16x32_bf16 v[36:39], v[196:199], v[188:191], v[36:39]
	v_mfma_f32_16x16x32_bf16 v[32:35], v[204:207], v[188:191], v[32:35]
	s_mov_b32 m0, s56
	s_add_u32 s100, s28, s40
	s_addc_u32 s101, s29, s41
	s_barrier
	ds_read_b128 v[154:157], v167 offset:16384
	ds_read_b128 v[158:161], v167 offset:17408
	ds_read_b128 v[168:171], v167 offset:18432
	ds_read_b128 v[172:175], v167 offset:19456
	ds_read_b128 v[176:179], v167 offset:20480
	ds_read_b128 v[180:183], v167 offset:21504
	ds_read_b128 v[184:187], v167 offset:22528
	ds_read_b128 v[188:191], v167 offset:23552
	global_load_lds_dwordx4 v148, s[28:29]
	s_mov_b32 m0, s57
	s_nop 0
	global_load_lds_dwordx4 v146, s[28:29]
	s_barrier
	s_waitcnt lgkmcnt(0)
	v_mfma_f32_16x16x32_bf16 v[92:95], v[128:131], v[154:157], v[92:95]
	v_mfma_f32_16x16x32_bf16 v[88:91], v[136:139], v[154:157], v[88:91]
	v_mfma_f32_16x16x32_bf16 v[84:87], v[128:131], v[168:171], v[84:87]
	v_mfma_f32_16x16x32_bf16 v[80:83], v[136:139], v[168:171], v[80:83]
	v_mfma_f32_16x16x32_bf16 v[76:79], v[128:131], v[176:179], v[76:79]
	v_mfma_f32_16x16x32_bf16 v[72:75], v[136:139], v[176:179], v[72:75]
	v_mfma_f32_16x16x32_bf16 v[68:71], v[128:131], v[184:187], v[68:71]
	v_mfma_f32_16x16x32_bf16 v[64:67], v[136:139], v[184:187], v[64:67]
	v_mfma_f32_16x16x32_bf16 v[92:95], v[132:135], v[158:161], v[92:95]
	v_mfma_f32_16x16x32_bf16 v[88:91], v[140:143], v[158:161], v[88:91]
	v_mfma_f32_16x16x32_bf16 v[84:87], v[132:135], v[172:175], v[84:87]
	v_mfma_f32_16x16x32_bf16 v[80:83], v[140:143], v[172:175], v[80:83]
	v_mfma_f32_16x16x32_bf16 v[76:79], v[132:135], v[180:183], v[76:79]
	v_mfma_f32_16x16x32_bf16 v[72:75], v[140:143], v[180:183], v[72:75]
	v_mfma_f32_16x16x32_bf16 v[68:71], v[132:135], v[188:191], v[68:71]
	v_mfma_f32_16x16x32_bf16 v[64:67], v[140:143], v[188:191], v[64:67]
	s_barrier
	s_add_u32 s64, s26, 0x40000
	s_addc_u32 s65, s27, 0
	s_add_i32 s63, s66, s55
	s_mov_b32 m0, s63
	s_nop 0
	global_load_lds_dwordx4 v208, s[64:65]
	s_add_i32 m0, s63, 0x2000
	s_nop 0
	global_load_lds_dwordx4 v144, s[64:65]
	s_waitcnt vmcnt(6)
	s_barrier
	v_mfma_f32_16x16x32_bf16 v[28:31], v[192:195], v[154:157], v[28:31]
	v_mfma_f32_16x16x32_bf16 v[24:27], v[200:203], v[154:157], v[24:27]
	v_mfma_f32_16x16x32_bf16 v[20:23], v[192:195], v[168:171], v[20:23]
	v_mfma_f32_16x16x32_bf16 v[16:19], v[200:203], v[168:171], v[16:19]
	v_mfma_f32_16x16x32_bf16 v[12:15], v[192:195], v[176:179], v[12:15]
	v_mfma_f32_16x16x32_bf16 v[8:11], v[200:203], v[176:179], v[8:11]
	v_mfma_f32_16x16x32_bf16 v[4:7], v[192:195], v[184:187], v[4:7]
	v_mfma_f32_16x16x32_bf16 v[0:3], v[200:203], v[184:187], v[0:3]
	v_mfma_f32_16x16x32_bf16 v[28:31], v[196:199], v[158:161], v[28:31]
	v_mfma_f32_16x16x32_bf16 v[24:27], v[204:207], v[158:161], v[24:27]
	v_mfma_f32_16x16x32_bf16 v[20:23], v[196:199], v[172:175], v[20:23]
	v_mfma_f32_16x16x32_bf16 v[16:19], v[204:207], v[172:175], v[16:19]
	v_mfma_f32_16x16x32_bf16 v[12:15], v[196:199], v[180:183], v[12:15]
	v_mfma_f32_16x16x32_bf16 v[8:11], v[204:207], v[180:183], v[8:11]
	v_mfma_f32_16x16x32_bf16 v[4:7], v[196:199], v[188:191], v[4:7]
	v_mfma_f32_16x16x32_bf16 v[0:3], v[204:207], v[188:191], v[0:3]
	s_add_i32 s63, 0, 0x18000
	s_barrier
	ds_read_b128 v[128:131], v163 offset:32768
	ds_read_b128 v[132:135], v163 offset:33792
	ds_read_b128 v[136:139], v163 offset:34816
	ds_read_b128 v[140:143], v163 offset:35840
	s_add_u32 s28, s28, 0x40000
	s_addc_u32 s29, s29, 0
	s_mov_b32 m0, s58
	ds_read_b128 v[154:157], v167 offset:32768
	ds_read_b128 v[158:161], v167 offset:33792
	ds_read_b128 v[168:171], v167 offset:34816
	ds_read_b128 v[172:175], v167 offset:35840
	ds_read_b128 v[176:179], v167 offset:36864
	ds_read_b128 v[180:183], v167 offset:37888
	ds_read_b128 v[184:187], v167 offset:38912
	ds_read_b128 v[188:191], v167 offset:39936
	global_load_lds_dwordx4 v148, s[28:29]
	s_mov_b32 m0, s59
	s_nop 0
	global_load_lds_dwordx4 v146, s[28:29]
	s_waitcnt lgkmcnt(8)
	s_barrier
	s_waitcnt lgkmcnt(0)
	v_mfma_f32_16x16x32_bf16 v[124:127], v[128:131], v[154:157], v[124:127]
	v_mfma_f32_16x16x32_bf16 v[120:123], v[136:139], v[154:157], v[120:123]
	v_mfma_f32_16x16x32_bf16 v[116:119], v[128:131], v[168:171], v[116:119]
	v_mfma_f32_16x16x32_bf16 v[112:115], v[136:139], v[168:171], v[112:115]
	v_mfma_f32_16x16x32_bf16 v[108:111], v[128:131], v[176:179], v[108:111]
	v_mfma_f32_16x16x32_bf16 v[104:107], v[136:139], v[176:179], v[104:107]
	v_mfma_f32_16x16x32_bf16 v[100:103], v[128:131], v[184:187], v[100:103]
	v_mfma_f32_16x16x32_bf16 v[96:99], v[136:139], v[184:187], v[96:99]
	v_mfma_f32_16x16x32_bf16 v[124:127], v[132:135], v[158:161], v[124:127]
	v_mfma_f32_16x16x32_bf16 v[120:123], v[140:143], v[158:161], v[120:123]
	v_mfma_f32_16x16x32_bf16 v[116:119], v[132:135], v[172:175], v[116:119]
	v_mfma_f32_16x16x32_bf16 v[112:115], v[140:143], v[172:175], v[112:115]
	v_mfma_f32_16x16x32_bf16 v[108:111], v[132:135], v[180:183], v[108:111]
	v_mfma_f32_16x16x32_bf16 v[104:107], v[140:143], v[180:183], v[104:107]
	v_mfma_f32_16x16x32_bf16 v[100:103], v[132:135], v[188:191], v[100:103]
	v_mfma_f32_16x16x32_bf16 v[96:99], v[140:143], v[188:191], v[96:99]
	s_barrier
	s_add_i32 s28, 0, 0x1c000
	s_add_i32 s29, s63, s55
	s_mov_b32 m0, s29
	ds_read_b128 v[192:195], v163 offset:49152
	ds_read_b128 v[196:199], v163 offset:50176
	ds_read_b128 v[200:203], v163 offset:51200
	ds_read_b128 v[204:207], v163 offset:52224
	global_load_lds_dwordx4 v208, s[98:99]
	s_add_i32 m0, s29, 0x2000
	s_nop 0
	global_load_lds_dwordx4 v144, s[98:99]
	s_barrier
	s_waitcnt lgkmcnt(0)
	v_mfma_f32_16x16x32_bf16 v[60:63], v[192:195], v[154:157], v[60:63]
	v_mfma_f32_16x16x32_bf16 v[56:59], v[200:203], v[154:157], v[56:59]
	v_mfma_f32_16x16x32_bf16 v[52:55], v[192:195], v[168:171], v[52:55]
	v_mfma_f32_16x16x32_bf16 v[48:51], v[200:203], v[168:171], v[48:51]
	v_mfma_f32_16x16x32_bf16 v[44:47], v[192:195], v[176:179], v[44:47]
	v_mfma_f32_16x16x32_bf16 v[40:43], v[200:203], v[176:179], v[40:43]
	v_mfma_f32_16x16x32_bf16 v[36:39], v[192:195], v[184:187], v[36:39]
	v_mfma_f32_16x16x32_bf16 v[32:35], v[200:203], v[184:187], v[32:35]
	v_mfma_f32_16x16x32_bf16 v[60:63], v[196:199], v[158:161], v[60:63]
	v_mfma_f32_16x16x32_bf16 v[56:59], v[204:207], v[158:161], v[56:59]
	v_mfma_f32_16x16x32_bf16 v[52:55], v[196:199], v[172:175], v[52:55]
	v_mfma_f32_16x16x32_bf16 v[48:51], v[204:207], v[172:175], v[48:51]
	v_mfma_f32_16x16x32_bf16 v[44:47], v[196:199], v[180:183], v[44:47]
	v_mfma_f32_16x16x32_bf16 v[40:43], v[204:207], v[180:183], v[40:43]
	v_mfma_f32_16x16x32_bf16 v[36:39], v[196:199], v[188:191], v[36:39]
	v_mfma_f32_16x16x32_bf16 v[32:35], v[204:207], v[188:191], v[32:35]
	s_mov_b32 m0, s60
	s_barrier
	ds_read_b128 v[154:157], v167 offset:49152
	ds_read_b128 v[158:161], v167 offset:50176
	ds_read_b128 v[168:171], v167 offset:51200
	ds_read_b128 v[172:175], v167 offset:52224
	ds_read_b128 v[176:179], v167 offset:53248
	ds_read_b128 v[180:183], v167 offset:54272
	ds_read_b128 v[184:187], v167 offset:55296
	ds_read_b128 v[188:191], v167 offset:56320
	global_load_lds_dwordx4 v148, s[100:101]
	s_mov_b32 m0, s61
	s_nop 0
	global_load_lds_dwordx4 v146, s[100:101]
	s_barrier
	s_waitcnt lgkmcnt(0)
	v_mfma_f32_16x16x32_bf16 v[92:95], v[128:131], v[154:157], v[92:95]
	v_mfma_f32_16x16x32_bf16 v[88:91], v[136:139], v[154:157], v[88:91]
	v_mfma_f32_16x16x32_bf16 v[84:87], v[128:131], v[168:171], v[84:87]
	v_mfma_f32_16x16x32_bf16 v[80:83], v[136:139], v[168:171], v[80:83]
	v_mfma_f32_16x16x32_bf16 v[76:79], v[128:131], v[176:179], v[76:79]
	v_mfma_f32_16x16x32_bf16 v[72:75], v[136:139], v[176:179], v[72:75]
	v_mfma_f32_16x16x32_bf16 v[68:71], v[128:131], v[184:187], v[68:71]
	v_mfma_f32_16x16x32_bf16 v[64:67], v[136:139], v[184:187], v[64:67]
	v_mfma_f32_16x16x32_bf16 v[92:95], v[132:135], v[158:161], v[92:95]
	v_mfma_f32_16x16x32_bf16 v[88:91], v[140:143], v[158:161], v[88:91]
	v_mfma_f32_16x16x32_bf16 v[84:87], v[132:135], v[172:175], v[84:87]
	v_mfma_f32_16x16x32_bf16 v[80:83], v[140:143], v[172:175], v[80:83]
	v_mfma_f32_16x16x32_bf16 v[76:79], v[132:135], v[180:183], v[76:79]
	v_mfma_f32_16x16x32_bf16 v[72:75], v[140:143], v[180:183], v[72:75]
	v_mfma_f32_16x16x32_bf16 v[68:71], v[132:135], v[188:191], v[68:71]
	v_mfma_f32_16x16x32_bf16 v[64:67], v[140:143], v[188:191], v[64:67]
	s_barrier
	s_add_u32 s26, s26, 0x40080
	s_addc_u32 s27, s27, 0
	s_add_i32 s28, s28, s55
	s_mov_b32 m0, s28
	s_nop 0
	global_load_lds_dwordx4 v208, s[26:27]
	s_add_i32 m0, s28, 0x2000
	s_nop 0
	global_load_lds_dwordx4 v144, s[26:27]
	s_waitcnt vmcnt(6)
	s_barrier
	v_mfma_f32_16x16x32_bf16 v[28:31], v[192:195], v[154:157], v[28:31]
	v_mfma_f32_16x16x32_bf16 v[24:27], v[200:203], v[154:157], v[24:27]
	v_mfma_f32_16x16x32_bf16 v[20:23], v[192:195], v[168:171], v[20:23]
	v_mfma_f32_16x16x32_bf16 v[16:19], v[200:203], v[168:171], v[16:19]
	v_mfma_f32_16x16x32_bf16 v[12:15], v[192:195], v[176:179], v[12:15]
	v_mfma_f32_16x16x32_bf16 v[8:11], v[200:203], v[176:179], v[8:11]
	v_mfma_f32_16x16x32_bf16 v[4:7], v[192:195], v[184:187], v[4:7]
	v_mfma_f32_16x16x32_bf16 v[0:3], v[200:203], v[184:187], v[0:3]
	v_mfma_f32_16x16x32_bf16 v[28:31], v[196:199], v[158:161], v[28:31]
	v_mfma_f32_16x16x32_bf16 v[24:27], v[204:207], v[158:161], v[24:27]
	v_mfma_f32_16x16x32_bf16 v[20:23], v[196:199], v[172:175], v[20:23]
	v_mfma_f32_16x16x32_bf16 v[16:19], v[204:207], v[172:175], v[16:19]
	v_mfma_f32_16x16x32_bf16 v[12:15], v[196:199], v[180:183], v[12:15]
	v_mfma_f32_16x16x32_bf16 v[8:11], v[204:207], v[180:183], v[8:11]
	v_mfma_f32_16x16x32_bf16 v[4:7], v[196:199], v[188:191], v[4:7]
	v_mfma_f32_16x16x32_bf16 v[0:3], v[204:207], v[188:191], v[0:3]
	s_add_i32 s51, s51, 2
	s_add_u32 s6, s6, 0x100
	s_addc_u32 s7, s7, 0
	s_add_u32 s46, s46, 0x100
	s_addc_u32 s50, s50, 0
	s_cmp_gt_u32 s51, 13
	s_barrier
	s_cbranch_scc0 .LBB0_714
	v_lshl_or_b32 v158, s34, 8, v166
	v_lshl_add_u32 v159, s35, 8, v164
	s_mov_b32 s34, s10
	s_mov_b32 s35, s20
	s_mov_b64 s[26:27], s[24:25]
	v_mbcnt_lo_u32_b32 v160, -1, 0
	v_mbcnt_hi_u32_b32 v160, -1, v160
	v_and_b32_e32 v157, 7, v160
	v_and_b32_e32 v160, 8, v160
	v_add_u32_e32 v157, v158, v157
	v_lshlrev_b32_e32 v157, 6, v157
	v_lshl_add_u32 v157, v160, 2, v157
	v_add_u32_e32 v161, 0x2000, v157
	global_load_dwordx4 v[128:131], v157, s[18:19]
	global_load_dwordx4 v[132:135], v157, s[18:19] offset:16
	global_load_dwordx4 v[136:139], v161, s[18:19]
	global_load_dwordx4 v[140:143], v161, s[18:19] offset:16
	v_mov_b32_e32 v155, 0x358637bd
	v_lshlrev_b32_e32 v156, 17, v159
	v_lshl_add_u32 v156, v158, 1, v156
	s_waitcnt vmcnt(0)
	v_pk_add_f32 v[128:129], v[128:129], v[130:131]
	v_pk_add_f32 v[132:133], v[132:133], v[134:135]
	v_pk_add_f32 v[128:129], v[128:129], v[132:133]
	s_nop 0
	v_add_f32_e32 v154, v128, v129
	s_nop 1
	v_add_f32_dpp v154, v154, v154 row_ror:8 row_mask:0xf bank_mask:0xf
	s_nop 0
	v_fmamk_f32 v154, v154, 0x3a800000, v155
	v_rsq_f32_e32 v154, v154
	s_nop 1
	v_mov_b32_dpp v168, v154 row_newbcast:0 row_mask:0xf bank_mask:0xf
	v_mov_b32_dpp v169, v154 row_newbcast:1 row_mask:0xf bank_mask:0xf
	v_mov_b32_dpp v170, v154 row_newbcast:2 row_mask:0xf bank_mask:0xf
	v_mov_b32_dpp v171, v154 row_newbcast:3 row_mask:0xf bank_mask:0xf
	v_mov_b32_dpp v172, v154 row_newbcast:4 row_mask:0xf bank_mask:0xf
	v_mov_b32_dpp v173, v154 row_newbcast:5 row_mask:0xf bank_mask:0xf
	v_mov_b32_dpp v174, v154 row_newbcast:6 row_mask:0xf bank_mask:0xf
	v_mov_b32_dpp v175, v154 row_newbcast:7 row_mask:0xf bank_mask:0xf
	v_pk_add_f32 v[136:137], v[136:137], v[138:139]
	v_pk_add_f32 v[140:141], v[140:141], v[142:143]
	v_pk_add_f32 v[136:137], v[136:137], v[140:141]
	s_nop 0
	v_add_f32_e32 v154, v136, v137
	s_nop 1
	v_add_f32_dpp v154, v154, v154 row_ror:8 row_mask:0xf bank_mask:0xf
	s_nop 0
	v_fmamk_f32 v154, v154, 0x3a800000, v155
	v_rsq_f32_e32 v154, v154
	s_nop 1
	v_mov_b32_dpp v176, v154 row_newbcast:0 row_mask:0xf bank_mask:0xf
	v_mov_b32_dpp v177, v154 row_newbcast:1 row_mask:0xf bank_mask:0xf
	v_mov_b32_dpp v178, v154 row_newbcast:2 row_mask:0xf bank_mask:0xf
	v_mov_b32_dpp v179, v154 row_newbcast:3 row_mask:0xf bank_mask:0xf
	v_mov_b32_dpp v180, v154 row_newbcast:4 row_mask:0xf bank_mask:0xf
	v_mov_b32_dpp v181, v154 row_newbcast:5 row_mask:0xf bank_mask:0xf
	v_mov_b32_dpp v182, v154 row_newbcast:6 row_mask:0xf bank_mask:0xf
	v_mov_b32_dpp v183, v154 row_newbcast:7 row_mask:0xf bank_mask:0xf
	v_pk_mul_f32 v[124:125], v[124:125], v[168:169]
	v_pk_mul_f32 v[126:127], v[126:127], v[170:171]
	v_pk_mul_f32 v[120:121], v[120:121], v[172:173]
	v_pk_mul_f32 v[122:123], v[122:123], v[174:175]
	v_cvt_pk_bf16_f32 v184, v124, v125
	v_cvt_pk_bf16_f32 v185, v126, v127
	v_cvt_pk_bf16_f32 v186, v120, v121
	v_cvt_pk_bf16_f32 v187, v122, v123
	global_store_dwordx4 v156, v[184:187], s[8:9]
	v_pk_mul_f32 v[60:61], v[60:61], v[176:177]
	v_pk_mul_f32 v[62:63], v[62:63], v[178:179]
	v_pk_mul_f32 v[56:57], v[56:57], v[180:181]
	v_pk_mul_f32 v[58:59], v[58:59], v[182:183]
	v_cvt_pk_bf16_f32 v188, v60, v61
	v_cvt_pk_bf16_f32 v189, v62, v63
	v_cvt_pk_bf16_f32 v190, v56, v57
	v_cvt_pk_bf16_f32 v191, v58, v59
	global_store_dwordx4 v156, v[188:191], s[8:9] offset:256
	v_add_u32_e32 v156, 0x200000, v156
	v_pk_mul_f32 v[116:117], v[116:117], v[168:169]
	v_pk_mul_f32 v[118:119], v[118:119], v[170:171]
	v_pk_mul_f32 v[112:113], v[112:113], v[172:173]
	v_pk_mul_f32 v[114:115], v[114:115], v[174:175]
	v_cvt_pk_bf16_f32 v184, v116, v117
	v_cvt_pk_bf16_f32 v185, v118, v119
	v_cvt_pk_bf16_f32 v186, v112, v113
	v_cvt_pk_bf16_f32 v187, v114, v115
	global_store_dwordx4 v156, v[184:187], s[8:9]
	v_pk_mul_f32 v[52:53], v[52:53], v[176:177]
	v_pk_mul_f32 v[54:55], v[54:55], v[178:179]
	v_pk_mul_f32 v[48:49], v[48:49], v[180:181]
	v_pk_mul_f32 v[50:51], v[50:51], v[182:183]
	v_cvt_pk_bf16_f32 v188, v52, v53
	v_cvt_pk_bf16_f32 v189, v54, v55
	v_cvt_pk_bf16_f32 v190, v48, v49
	v_cvt_pk_bf16_f32 v191, v50, v51
	global_store_dwordx4 v156, v[188:191], s[8:9] offset:256
	v_add_u32_e32 v156, 0x200000, v156
	v_pk_mul_f32 v[108:109], v[108:109], v[168:169]
	v_pk_mul_f32 v[110:111], v[110:111], v[170:171]
	v_pk_mul_f32 v[104:105], v[104:105], v[172:173]
	v_pk_mul_f32 v[106:107], v[106:107], v[174:175]
	v_cvt_pk_bf16_f32 v184, v108, v109
	v_cvt_pk_bf16_f32 v185, v110, v111
	v_cvt_pk_bf16_f32 v186, v104, v105
	v_cvt_pk_bf16_f32 v187, v106, v107
	global_store_dwordx4 v156, v[184:187], s[8:9]
	v_pk_mul_f32 v[44:45], v[44:45], v[176:177]
	v_pk_mul_f32 v[46:47], v[46:47], v[178:179]
	v_pk_mul_f32 v[40:41], v[40:41], v[180:181]
	v_pk_mul_f32 v[42:43], v[42:43], v[182:183]
	v_cvt_pk_bf16_f32 v188, v44, v45
	v_cvt_pk_bf16_f32 v189, v46, v47
	v_cvt_pk_bf16_f32 v190, v40, v41
	v_cvt_pk_bf16_f32 v191, v42, v43
	global_store_dwordx4 v156, v[188:191], s[8:9] offset:256
	v_add_u32_e32 v156, 0x200000, v156
	v_pk_mul_f32 v[100:101], v[100:101], v[168:169]
	v_pk_mul_f32 v[102:103], v[102:103], v[170:171]
	v_pk_mul_f32 v[96:97], v[96:97], v[172:173]
	v_pk_mul_f32 v[98:99], v[98:99], v[174:175]
	v_cvt_pk_bf16_f32 v184, v100, v101
	v_cvt_pk_bf16_f32 v185, v102, v103
	v_cvt_pk_bf16_f32 v186, v96, v97
	v_cvt_pk_bf16_f32 v187, v98, v99
	global_store_dwordx4 v156, v[184:187], s[8:9]
	v_pk_mul_f32 v[36:37], v[36:37], v[176:177]
	v_pk_mul_f32 v[38:39], v[38:39], v[178:179]
	v_pk_mul_f32 v[32:33], v[32:33], v[180:181]
	v_pk_mul_f32 v[34:35], v[34:35], v[182:183]
	v_cvt_pk_bf16_f32 v188, v36, v37
	v_cvt_pk_bf16_f32 v189, v38, v39
	v_cvt_pk_bf16_f32 v190, v32, v33
	v_cvt_pk_bf16_f32 v191, v34, v35
	global_store_dwordx4 v156, v[188:191], s[8:9] offset:256
	v_add_u32_e32 v156, 0xa00000, v156
	v_pk_mul_f32 v[92:93], v[92:93], v[168:169]
	v_pk_mul_f32 v[94:95], v[94:95], v[170:171]
	v_pk_mul_f32 v[88:89], v[88:89], v[172:173]
	v_pk_mul_f32 v[90:91], v[90:91], v[174:175]
	v_cvt_pk_bf16_f32 v184, v92, v93
	v_cvt_pk_bf16_f32 v185, v94, v95
	v_cvt_pk_bf16_f32 v186, v88, v89
	v_cvt_pk_bf16_f32 v187, v90, v91
	global_store_dwordx4 v156, v[184:187], s[8:9]
	v_pk_mul_f32 v[28:29], v[28:29], v[176:177]
	v_pk_mul_f32 v[30:31], v[30:31], v[178:179]
	v_pk_mul_f32 v[24:25], v[24:25], v[180:181]
	v_pk_mul_f32 v[26:27], v[26:27], v[182:183]
	v_cvt_pk_bf16_f32 v188, v28, v29
	v_cvt_pk_bf16_f32 v189, v30, v31
	v_cvt_pk_bf16_f32 v190, v24, v25
	v_cvt_pk_bf16_f32 v191, v26, v27
	global_store_dwordx4 v156, v[188:191], s[8:9] offset:256
	v_add_u32_e32 v156, 0x200000, v156
	v_pk_mul_f32 v[84:85], v[84:85], v[168:169]
	v_pk_mul_f32 v[86:87], v[86:87], v[170:171]
	v_pk_mul_f32 v[80:81], v[80:81], v[172:173]
	v_pk_mul_f32 v[82:83], v[82:83], v[174:175]
	v_cvt_pk_bf16_f32 v184, v84, v85
	v_cvt_pk_bf16_f32 v185, v86, v87
	v_cvt_pk_bf16_f32 v186, v80, v81
	v_cvt_pk_bf16_f32 v187, v82, v83
	global_store_dwordx4 v156, v[184:187], s[8:9]
	v_pk_mul_f32 v[20:21], v[20:21], v[176:177]
	v_pk_mul_f32 v[22:23], v[22:23], v[178:179]
	v_pk_mul_f32 v[16:17], v[16:17], v[180:181]
	v_pk_mul_f32 v[18:19], v[18:19], v[182:183]
	v_cvt_pk_bf16_f32 v188, v20, v21
	v_cvt_pk_bf16_f32 v189, v22, v23
	v_cvt_pk_bf16_f32 v190, v16, v17
	v_cvt_pk_bf16_f32 v191, v18, v19
	global_store_dwordx4 v156, v[188:191], s[8:9] offset:256
	v_add_u32_e32 v156, 0x200000, v156
	v_pk_mul_f32 v[76:77], v[76:77], v[168:169]
	v_pk_mul_f32 v[78:79], v[78:79], v[170:171]
	v_pk_mul_f32 v[72:73], v[72:73], v[172:173]
	v_pk_mul_f32 v[74:75], v[74:75], v[174:175]
	v_cvt_pk_bf16_f32 v184, v76, v77
	v_cvt_pk_bf16_f32 v185, v78, v79
	v_cvt_pk_bf16_f32 v186, v72, v73
	v_cvt_pk_bf16_f32 v187, v74, v75
	global_store_dwordx4 v156, v[184:187], s[8:9]
	v_pk_mul_f32 v[12:13], v[12:13], v[176:177]
	v_pk_mul_f32 v[14:15], v[14:15], v[178:179]
	v_pk_mul_f32 v[8:9], v[8:9], v[180:181]
	v_pk_mul_f32 v[10:11], v[10:11], v[182:183]
	v_cvt_pk_bf16_f32 v188, v12, v13
	v_cvt_pk_bf16_f32 v189, v14, v15
	v_cvt_pk_bf16_f32 v190, v8, v9
	v_cvt_pk_bf16_f32 v191, v10, v11
	global_store_dwordx4 v156, v[188:191], s[8:9] offset:256
	v_add_u32_e32 v156, 0x200000, v156
	v_pk_mul_f32 v[68:69], v[68:69], v[168:169]
	v_pk_mul_f32 v[70:71], v[70:71], v[170:171]
	v_pk_mul_f32 v[64:65], v[64:65], v[172:173]
	v_pk_mul_f32 v[66:67], v[66:67], v[174:175]
	v_cvt_pk_bf16_f32 v184, v68, v69
	v_cvt_pk_bf16_f32 v185, v70, v71
	v_cvt_pk_bf16_f32 v186, v64, v65
	v_cvt_pk_bf16_f32 v187, v66, v67
	global_store_dwordx4 v156, v[184:187], s[8:9]
	v_pk_mul_f32 v[4:5], v[4:5], v[176:177]
	v_pk_mul_f32 v[6:7], v[6:7], v[178:179]
	v_pk_mul_f32 v[0:1], v[0:1], v[180:181]
	v_pk_mul_f32 v[2:3], v[2:3], v[182:183]
	v_cvt_pk_bf16_f32 v188, v4, v5
	v_cvt_pk_bf16_f32 v189, v6, v7
	v_cvt_pk_bf16_f32 v190, v0, v1
	v_cvt_pk_bf16_f32 v191, v2, v3
	global_store_dwordx4 v156, v[188:191], s[8:9] offset:256
	s_mov_b64 s[6:7], s[22:23]
	s_and_b64 vcc, exec, s[4:5]
	s_cbranch_vccz .LBB0_707
	s_waitcnt vmcnt(0)
	s_cmpk_gt_u32 s30, 0xff
	s_cbranch_scc1 .LBB0_718
	s_barrier

.LBB0_776:
	v_add_u32_e32 v206, 0x10000, v143
	s_add_u32 s28, s26, 0xfffc0080
	s_addc_u32 s29, s27, -1
	s_add_i32 s66, 0, 0x10000
	ds_read_b128 v[138:141], v206
	ds_read_b128 v[146:149], v206 offset:1024
	ds_read_b128 v[150:153], v206 offset:2048
	ds_read_b128 v[154:157], v206 offset:3072
	s_cmp_eq_u32 s65, 12
	s_cselect_b32 s31, s21, s29
	s_cselect_b32 s30, s39, s28
	s_cselect_b32 s29, s19, s64
	s_cselect_b32 s28, s62, s63
	s_add_i32 m0, s54, 0xc000
	ds_read_b128 v[158:161], v145
	ds_read_b128 v[162:165], v145 offset:1024
	ds_read_b128 v[166:169], v145 offset:2048
	ds_read_b128 v[170:173], v145 offset:3072
	ds_read_b128 v[174:177], v145 offset:4096
	ds_read_b128 v[178:181], v145 offset:5120
	ds_read_b128 v[182:185], v145 offset:6144
	ds_read_b128 v[186:189], v145 offset:7168
	global_load_lds_dwordx4 v134, s[26:27]
	s_add_i32 m0, s54, 0xe000
	s_nop 0
	global_load_lds_dwordx4 v136, s[26:27]
	s_waitcnt lgkmcnt(8)
	s_barrier
	s_waitcnt lgkmcnt(0)
	v_mfma_f32_16x16x32_bf16 v[124:127], v[138:141], v[158:161], v[124:127]
	v_mfma_f32_16x16x32_bf16 v[120:123], v[150:153], v[158:161], v[120:123]
	v_mfma_f32_16x16x32_bf16 v[108:111], v[138:141], v[166:169], v[108:111]
	v_mfma_f32_16x16x32_bf16 v[104:107], v[150:153], v[166:169], v[104:107]
	v_mfma_f32_16x16x32_bf16 v[92:95], v[138:141], v[174:177], v[92:95]
	v_mfma_f32_16x16x32_bf16 v[88:91], v[150:153], v[174:177], v[88:91]
	v_mfma_f32_16x16x32_bf16 v[76:79], v[138:141], v[182:185], v[76:79]
	v_mfma_f32_16x16x32_bf16 v[72:75], v[150:153], v[182:185], v[72:75]
	v_mfma_f32_16x16x32_bf16 v[124:127], v[146:149], v[162:165], v[124:127]
	v_mfma_f32_16x16x32_bf16 v[120:123], v[154:157], v[162:165], v[120:123]
	v_mfma_f32_16x16x32_bf16 v[108:111], v[146:149], v[170:173], v[108:111]
	v_mfma_f32_16x16x32_bf16 v[104:107], v[154:157], v[170:173], v[104:107]
	v_mfma_f32_16x16x32_bf16 v[92:95], v[146:149], v[178:181], v[92:95]
	v_mfma_f32_16x16x32_bf16 v[88:91], v[154:157], v[178:181], v[88:91]
	v_mfma_f32_16x16x32_bf16 v[76:79], v[146:149], v[186:189], v[76:79]
	v_mfma_f32_16x16x32_bf16 v[72:75], v[154:157], v[186:189], v[72:75]
	s_barrier
	s_add_i32 s68, 0, 0x14000
	s_add_i32 s66, s66, s53
	s_add_u32 s98, s28, s40
	s_addc_u32 s99, s29, s41
	s_mov_b32 m0, s66
	ds_read_b128 v[190:193], v206 offset:16384
	ds_read_b128 v[194:197], v206 offset:17408
	ds_read_b128 v[198:201], v206 offset:18432
	ds_read_b128 v[202:205], v206 offset:19456
	global_load_lds_dwordx4 v208, s[28:29]
	s_add_i32 m0, s66, 0x2000
	s_nop 0
	global_load_lds_dwordx4 v128, s[28:29]
	s_barrier
	s_waitcnt lgkmcnt(0)
	v_mfma_f32_16x16x32_bf16 v[116:119], v[190:193], v[158:161], v[116:119]
	v_mfma_f32_16x16x32_bf16 v[112:115], v[198:201], v[158:161], v[112:115]
	v_mfma_f32_16x16x32_bf16 v[100:103], v[190:193], v[166:169], v[100:103]
	v_mfma_f32_16x16x32_bf16 v[96:99], v[198:201], v[166:169], v[96:99]
	v_mfma_f32_16x16x32_bf16 v[84:87], v[190:193], v[174:177], v[84:87]
	v_mfma_f32_16x16x32_bf16 v[80:83], v[198:201], v[174:177], v[80:83]
	v_mfma_f32_16x16x32_bf16 v[68:71], v[190:193], v[182:185], v[68:71]
	v_mfma_f32_16x16x32_bf16 v[64:67], v[198:201], v[182:185], v[64:67]
	v_mfma_f32_16x16x32_bf16 v[116:119], v[194:197], v[162:165], v[116:119]
	v_mfma_f32_16x16x32_bf16 v[112:115], v[202:205], v[162:165], v[112:115]
	v_mfma_f32_16x16x32_bf16 v[100:103], v[194:197], v[170:173], v[100:103]
	v_mfma_f32_16x16x32_bf16 v[96:99], v[202:205], v[170:173], v[96:99]
	v_mfma_f32_16x16x32_bf16 v[84:87], v[194:197], v[178:181], v[84:87]
	v_mfma_f32_16x16x32_bf16 v[80:83], v[202:205], v[178:181], v[80:83]
	v_mfma_f32_16x16x32_bf16 v[68:71], v[194:197], v[186:189], v[68:71]
	v_mfma_f32_16x16x32_bf16 v[64:67], v[202:205], v[186:189], v[64:67]
	s_mov_b32 m0, s54
	s_add_u32 s100, s30, s40
	s_addc_u32 s101, s31, s41
	s_barrier
	ds_read_b128 v[158:161], v145 offset:16384
	ds_read_b128 v[162:165], v145 offset:17408
	ds_read_b128 v[166:169], v145 offset:18432
	ds_read_b128 v[170:173], v145 offset:19456
	ds_read_b128 v[174:177], v145 offset:20480
	ds_read_b128 v[178:181], v145 offset:21504
	ds_read_b128 v[182:185], v145 offset:22528
	ds_read_b128 v[186:189], v145 offset:23552
	global_load_lds_dwordx4 v132, s[30:31]
	s_mov_b32 m0, s55
	s_nop 0
	global_load_lds_dwordx4 v130, s[30:31]
	s_barrier
	s_waitcnt lgkmcnt(0)
	v_mfma_f32_16x16x32_bf16 v[60:63], v[138:141], v[158:161], v[60:63]
	v_mfma_f32_16x16x32_bf16 v[56:59], v[150:153], v[158:161], v[56:59]
	v_mfma_f32_16x16x32_bf16 v[44:47], v[138:141], v[166:169], v[44:47]
	v_mfma_f32_16x16x32_bf16 v[40:43], v[150:153], v[166:169], v[40:43]
	v_mfma_f32_16x16x32_bf16 v[28:31], v[138:141], v[174:177], v[28:31]
	v_mfma_f32_16x16x32_bf16 v[24:27], v[150:153], v[174:177], v[24:27]
	v_mfma_f32_16x16x32_bf16 v[12:15], v[138:141], v[182:185], v[12:15]
	v_mfma_f32_16x16x32_bf16 v[8:11], v[150:153], v[182:185], v[8:11]
	v_mfma_f32_16x16x32_bf16 v[60:63], v[146:149], v[162:165], v[60:63]
	v_mfma_f32_16x16x32_bf16 v[56:59], v[154:157], v[162:165], v[56:59]
	v_mfma_f32_16x16x32_bf16 v[44:47], v[146:149], v[170:173], v[44:47]
	v_mfma_f32_16x16x32_bf16 v[40:43], v[154:157], v[170:173], v[40:43]
	v_mfma_f32_16x16x32_bf16 v[28:31], v[146:149], v[178:181], v[28:31]
	v_mfma_f32_16x16x32_bf16 v[24:27], v[154:157], v[178:181], v[24:27]
	v_mfma_f32_16x16x32_bf16 v[12:15], v[146:149], v[186:189], v[12:15]
	v_mfma_f32_16x16x32_bf16 v[8:11], v[154:157], v[186:189], v[8:11]
	s_barrier
	s_add_u32 s66, s28, 0x40000
	s_addc_u32 s67, s29, 0
	s_add_i32 s68, s68, s53
	s_mov_b32 m0, s68
	s_nop 0
	global_load_lds_dwordx4 v208, s[66:67]
	s_add_i32 m0, s68, 0x2000
	s_nop 0
	global_load_lds_dwordx4 v128, s[66:67]
	s_waitcnt vmcnt(6)
	s_barrier
	v_mfma_f32_16x16x32_bf16 v[52:55], v[190:193], v[158:161], v[52:55]
	v_mfma_f32_16x16x32_bf16 v[48:51], v[198:201], v[158:161], v[48:51]
	v_mfma_f32_16x16x32_bf16 v[36:39], v[190:193], v[166:169], v[36:39]
	v_mfma_f32_16x16x32_bf16 v[32:35], v[198:201], v[166:169], v[32:35]
	v_mfma_f32_16x16x32_bf16 v[20:23], v[190:193], v[174:177], v[20:23]
	v_mfma_f32_16x16x32_bf16 v[16:19], v[198:201], v[174:177], v[16:19]
	v_mfma_f32_16x16x32_bf16 v[4:7], v[190:193], v[182:185], v[4:7]
	v_mfma_f32_16x16x32_bf16 v[0:3], v[198:201], v[182:185], v[0:3]
	v_mfma_f32_16x16x32_bf16 v[52:55], v[194:197], v[162:165], v[52:55]
	v_mfma_f32_16x16x32_bf16 v[48:51], v[202:205], v[162:165], v[48:51]
	v_mfma_f32_16x16x32_bf16 v[36:39], v[194:197], v[170:173], v[36:39]
	v_mfma_f32_16x16x32_bf16 v[32:35], v[202:205], v[170:173], v[32:35]
	v_mfma_f32_16x16x32_bf16 v[20:23], v[194:197], v[178:181], v[20:23]
	v_mfma_f32_16x16x32_bf16 v[16:19], v[202:205], v[178:181], v[16:19]
	v_mfma_f32_16x16x32_bf16 v[4:7], v[194:197], v[186:189], v[4:7]
	v_mfma_f32_16x16x32_bf16 v[0:3], v[202:205], v[186:189], v[0:3]
	s_add_i32 s66, 0, 0x18000
	s_barrier
	ds_read_b128 v[138:141], v206 offset:32768
	ds_read_b128 v[146:149], v206 offset:33792
	ds_read_b128 v[150:153], v206 offset:34816
	ds_read_b128 v[154:157], v206 offset:35840
	s_add_u32 s30, s30, 0x40000
	s_addc_u32 s31, s31, 0
	s_mov_b32 m0, s56
	ds_read_b128 v[158:161], v145 offset:32768
	ds_read_b128 v[162:165], v145 offset:33792
	ds_read_b128 v[166:169], v145 offset:34816
	ds_read_b128 v[170:173], v145 offset:35840
	ds_read_b128 v[174:177], v145 offset:36864
	ds_read_b128 v[178:181], v145 offset:37888
	ds_read_b128 v[182:185], v145 offset:38912
	ds_read_b128 v[186:189], v145 offset:39936
	global_load_lds_dwordx4 v132, s[30:31]
	s_mov_b32 m0, s57
	s_nop 0
	global_load_lds_dwordx4 v130, s[30:31]
	s_waitcnt lgkmcnt(8)
	s_barrier
	s_waitcnt lgkmcnt(0)
	v_mfma_f32_16x16x32_bf16 v[124:127], v[138:141], v[158:161], v[124:127]
	v_mfma_f32_16x16x32_bf16 v[120:123], v[150:153], v[158:161], v[120:123]
	v_mfma_f32_16x16x32_bf16 v[108:111], v[138:141], v[166:169], v[108:111]
	v_mfma_f32_16x16x32_bf16 v[104:107], v[150:153], v[166:169], v[104:107]
	v_mfma_f32_16x16x32_bf16 v[92:95], v[138:141], v[174:177], v[92:95]
	v_mfma_f32_16x16x32_bf16 v[88:91], v[150:153], v[174:177], v[88:91]
	v_mfma_f32_16x16x32_bf16 v[76:79], v[138:141], v[182:185], v[76:79]
	v_mfma_f32_16x16x32_bf16 v[72:75], v[150:153], v[182:185], v[72:75]
	v_mfma_f32_16x16x32_bf16 v[124:127], v[146:149], v[162:165], v[124:127]
	v_mfma_f32_16x16x32_bf16 v[120:123], v[154:157], v[162:165], v[120:123]
	v_mfma_f32_16x16x32_bf16 v[108:111], v[146:149], v[170:173], v[108:111]
	v_mfma_f32_16x16x32_bf16 v[104:107], v[154:157], v[170:173], v[104:107]
	v_mfma_f32_16x16x32_bf16 v[92:95], v[146:149], v[178:181], v[92:95]
	v_mfma_f32_16x16x32_bf16 v[88:91], v[154:157], v[178:181], v[88:91]
	v_mfma_f32_16x16x32_bf16 v[76:79], v[146:149], v[186:189], v[76:79]
	v_mfma_f32_16x16x32_bf16 v[72:75], v[154:157], v[186:189], v[72:75]
	s_barrier
	s_add_i32 s30, 0, 0x1c000
	s_add_i32 s31, s66, s53
	s_mov_b32 m0, s31
	ds_read_b128 v[190:193], v206 offset:49152
	ds_read_b128 v[194:197], v206 offset:50176
	ds_read_b128 v[198:201], v206 offset:51200
	ds_read_b128 v[202:205], v206 offset:52224
	global_load_lds_dwordx4 v208, s[98:99]
	s_add_i32 m0, s31, 0x2000
	s_nop 0
	global_load_lds_dwordx4 v128, s[98:99]
	s_barrier
	s_waitcnt lgkmcnt(0)
	v_mfma_f32_16x16x32_bf16 v[116:119], v[190:193], v[158:161], v[116:119]
	v_mfma_f32_16x16x32_bf16 v[112:115], v[198:201], v[158:161], v[112:115]
	v_mfma_f32_16x16x32_bf16 v[100:103], v[190:193], v[166:169], v[100:103]
	v_mfma_f32_16x16x32_bf16 v[96:99], v[198:201], v[166:169], v[96:99]
	v_mfma_f32_16x16x32_bf16 v[84:87], v[190:193], v[174:177], v[84:87]
	v_mfma_f32_16x16x32_bf16 v[80:83], v[198:201], v[174:177], v[80:83]
	v_mfma_f32_16x16x32_bf16 v[68:71], v[190:193], v[182:185], v[68:71]
	v_mfma_f32_16x16x32_bf16 v[64:67], v[198:201], v[182:185], v[64:67]
	v_mfma_f32_16x16x32_bf16 v[116:119], v[194:197], v[162:165], v[116:119]
	v_mfma_f32_16x16x32_bf16 v[112:115], v[202:205], v[162:165], v[112:115]
	v_mfma_f32_16x16x32_bf16 v[100:103], v[194:197], v[170:173], v[100:103]
	v_mfma_f32_16x16x32_bf16 v[96:99], v[202:205], v[170:173], v[96:99]
	v_mfma_f32_16x16x32_bf16 v[84:87], v[194:197], v[178:181], v[84:87]
	v_mfma_f32_16x16x32_bf16 v[80:83], v[202:205], v[178:181], v[80:83]
	v_mfma_f32_16x16x32_bf16 v[68:71], v[194:197], v[186:189], v[68:71]
	v_mfma_f32_16x16x32_bf16 v[64:67], v[202:205], v[186:189], v[64:67]
	s_mov_b32 m0, s59
	s_barrier
	ds_read_b128 v[158:161], v145 offset:49152
	ds_read_b128 v[162:165], v145 offset:50176
	ds_read_b128 v[166:169], v145 offset:51200
	ds_read_b128 v[170:173], v145 offset:52224
	ds_read_b128 v[174:177], v145 offset:53248
	ds_read_b128 v[178:181], v145 offset:54272
	ds_read_b128 v[182:185], v145 offset:55296
	ds_read_b128 v[186:189], v145 offset:56320
	global_load_lds_dwordx4 v132, s[100:101]
	s_mov_b32 m0, s60
	s_nop 0
	global_load_lds_dwordx4 v130, s[100:101]
	s_barrier
	s_waitcnt lgkmcnt(0)
	v_mfma_f32_16x16x32_bf16 v[60:63], v[138:141], v[158:161], v[60:63]
	v_mfma_f32_16x16x32_bf16 v[56:59], v[150:153], v[158:161], v[56:59]
	v_mfma_f32_16x16x32_bf16 v[44:47], v[138:141], v[166:169], v[44:47]
	v_mfma_f32_16x16x32_bf16 v[40:43], v[150:153], v[166:169], v[40:43]
	v_mfma_f32_16x16x32_bf16 v[28:31], v[138:141], v[174:177], v[28:31]
	v_mfma_f32_16x16x32_bf16 v[24:27], v[150:153], v[174:177], v[24:27]
	v_mfma_f32_16x16x32_bf16 v[12:15], v[138:141], v[182:185], v[12:15]
	v_mfma_f32_16x16x32_bf16 v[8:11], v[150:153], v[182:185], v[8:11]
	v_mfma_f32_16x16x32_bf16 v[60:63], v[146:149], v[162:165], v[60:63]
	v_mfma_f32_16x16x32_bf16 v[56:59], v[154:157], v[162:165], v[56:59]
	v_mfma_f32_16x16x32_bf16 v[44:47], v[146:149], v[170:173], v[44:47]
	v_mfma_f32_16x16x32_bf16 v[40:43], v[154:157], v[170:173], v[40:43]
	v_mfma_f32_16x16x32_bf16 v[28:31], v[146:149], v[178:181], v[28:31]
	v_mfma_f32_16x16x32_bf16 v[24:27], v[154:157], v[178:181], v[24:27]
	v_mfma_f32_16x16x32_bf16 v[12:15], v[146:149], v[186:189], v[12:15]
	v_mfma_f32_16x16x32_bf16 v[8:11], v[154:157], v[186:189], v[8:11]
	s_barrier
	s_add_u32 s28, s28, 0x40080
	s_addc_u32 s29, s29, 0
	s_add_i32 s30, s30, s53
	s_mov_b32 m0, s30
	s_nop 0
	global_load_lds_dwordx4 v208, s[28:29]
	s_add_i32 m0, s30, 0x2000
	s_nop 0
	global_load_lds_dwordx4 v128, s[28:29]
	s_waitcnt vmcnt(6)
	s_barrier
	v_mfma_f32_16x16x32_bf16 v[52:55], v[190:193], v[158:161], v[52:55]
	v_mfma_f32_16x16x32_bf16 v[48:51], v[198:201], v[158:161], v[48:51]
	v_mfma_f32_16x16x32_bf16 v[36:39], v[190:193], v[166:169], v[36:39]
	v_mfma_f32_16x16x32_bf16 v[32:35], v[198:201], v[166:169], v[32:35]
	v_mfma_f32_16x16x32_bf16 v[20:23], v[190:193], v[174:177], v[20:23]
	v_mfma_f32_16x16x32_bf16 v[16:19], v[198:201], v[174:177], v[16:19]
	v_mfma_f32_16x16x32_bf16 v[4:7], v[190:193], v[182:185], v[4:7]
	v_mfma_f32_16x16x32_bf16 v[0:3], v[198:201], v[182:185], v[0:3]
	v_mfma_f32_16x16x32_bf16 v[52:55], v[194:197], v[162:165], v[52:55]
	v_mfma_f32_16x16x32_bf16 v[48:51], v[202:205], v[162:165], v[48:51]
	v_mfma_f32_16x16x32_bf16 v[36:39], v[194:197], v[170:173], v[36:39]
	v_mfma_f32_16x16x32_bf16 v[32:35], v[202:205], v[170:173], v[32:35]
	v_mfma_f32_16x16x32_bf16 v[20:23], v[194:197], v[178:181], v[20:23]
	v_mfma_f32_16x16x32_bf16 v[16:19], v[202:205], v[178:181], v[16:19]
	v_mfma_f32_16x16x32_bf16 v[4:7], v[194:197], v[186:189], v[4:7]
	v_mfma_f32_16x16x32_bf16 v[0:3], v[202:205], v[186:189], v[0:3]
	s_add_i32 s65, s65, 2
	s_add_u32 s26, s26, 0x100
	s_addc_u32 s27, s27, 0
	s_add_u32 s63, s63, 0x100
	s_addc_u32 s64, s64, 0
	s_cmp_gt_u32 s65, 13
	s_barrier
	s_cbranch_scc0 .LBB0_776
	v_lshl_add_u32 v140, s38, 8, v142
	v_lshl_or_b32 v141, s36, 8, v144
	s_lshl_b32 s26, s36, 2
	s_ashr_i32 s27, s26, 31
	s_lshl_b32 s36, s58, 2
	v_lshlrev_b32_e32 v206, 11, v140
	v_lshl_add_u32 v206, v141, 1, v206
	v_lshl_add_u32 v210, v140, 6, s36
	v_lshl_add_u32 v210, s26, 2, v210
	v_mov_b32_e32 v207, v206
	global_load_dwordx4 v[146:149], v206, s[10:11]
	global_load_dwordx4 v[150:153], v206, s[10:11] offset:256
	v_add_u32_e32 v206, 0x8000, v206
	global_load_dwordx4 v[154:157], v206, s[10:11]
	global_load_dwordx4 v[158:161], v206, s[10:11] offset:256
	v_add_u32_e32 v206, 0x8000, v206
	global_load_dwordx4 v[162:165], v206, s[10:11]
	global_load_dwordx4 v[166:169], v206, s[10:11] offset:256
	v_add_u32_e32 v206, 0x8000, v206
	global_load_dwordx4 v[170:173], v206, s[10:11]
	global_load_dwordx4 v[174:177], v206, s[10:11] offset:256
	v_add_u32_e32 v206, 0x28000, v206
	global_load_dwordx4 v[178:181], v206, s[10:11]
	global_load_dwordx4 v[182:185], v206, s[10:11] offset:256
	v_add_u32_e32 v206, 0x8000, v206
	global_load_dwordx4 v[186:189], v206, s[10:11]
	global_load_dwordx4 v[190:193], v206, s[10:11] offset:256
	v_add_u32_e32 v206, 0x8000, v206
	global_load_dwordx4 v[194:197], v206, s[10:11]
	global_load_dwordx4 v[198:201], v206, s[10:11] offset:256
	v_add_u32_e32 v206, 0x8000, v206
	s_waitcnt vmcnt(12)
	v_lshlrev_b32_e32 v202, 16, v146
	v_and_b32_e32 v203, 0xffff0000, v146
	v_lshlrev_b32_e32 v204, 16, v147
	v_and_b32_e32 v205, 0xffff0000, v147
	v_pk_add_f32 v[124:125], v[124:125], v[202:203]
	v_pk_add_f32 v[126:127], v[126:127], v[204:205]
	v_lshlrev_b32_e32 v202, 16, v148
	v_and_b32_e32 v203, 0xffff0000, v148
	v_lshlrev_b32_e32 v204, 16, v149
	v_and_b32_e32 v205, 0xffff0000, v149
	v_pk_add_f32 v[120:121], v[120:121], v[202:203]
	v_pk_add_f32 v[122:123], v[122:123], v[204:205]
	v_cvt_pk_bf16_f32 v146, v124, v125
	v_cvt_pk_bf16_f32 v147, v126, v127
	v_cvt_pk_bf16_f32 v148, v120, v121
	v_cvt_pk_bf16_f32 v149, v122, v123
	v_pk_mul_f32 v[138:139], v[124:125], v[124:125]
	global_store_dwordx4 v207, v[146:149], s[10:11]
	v_pk_fma_f32 v[138:139], v[126:127], v[126:127], v[138:139]
	v_pk_fma_f32 v[138:139], v[120:121], v[120:121], v[138:139]
	v_pk_fma_f32 v[138:139], v[122:123], v[122:123], v[138:139]
	v_lshlrev_b32_e32 v202, 16, v150
	v_and_b32_e32 v203, 0xffff0000, v150
	v_lshlrev_b32_e32 v204, 16, v151
	v_and_b32_e32 v205, 0xffff0000, v151
	v_pk_add_f32 v[116:117], v[116:117], v[202:203]
	v_pk_add_f32 v[118:119], v[118:119], v[204:205]
	v_lshlrev_b32_e32 v202, 16, v152
	v_and_b32_e32 v203, 0xffff0000, v152
	v_lshlrev_b32_e32 v204, 16, v153
	v_and_b32_e32 v205, 0xffff0000, v153
	v_pk_add_f32 v[112:113], v[112:113], v[202:203]
	v_pk_add_f32 v[114:115], v[114:115], v[204:205]
	v_cvt_pk_bf16_f32 v150, v116, v117
	v_cvt_pk_bf16_f32 v151, v118, v119
	v_cvt_pk_bf16_f32 v152, v112, v113
	v_cvt_pk_bf16_f32 v153, v114, v115
	v_pk_fma_f32 v[138:139], v[116:117], v[116:117], v[138:139]
	global_store_dwordx4 v207, v[150:153], s[10:11] offset:256
	v_pk_fma_f32 v[138:139], v[118:119], v[118:119], v[138:139]
	v_pk_fma_f32 v[138:139], v[112:113], v[112:113], v[138:139]
	v_pk_fma_f32 v[138:139], v[114:115], v[114:115], v[138:139]
	v_add_f32_e32 v214, v138, v139
	v_add_u32_e32 v207, 0x8000, v207
	v_mov_b32_e32 v215, v214
	s_nop 1
	v_permlane16_swap_b32_e32 v214, v215
	s_nop 0
	v_add_f32_e32 v214, v214, v215
	v_mov_b32_e32 v215, v214
	s_nop 1
	v_permlane32_swap_b32_e32 v214, v215
	s_nop 0
	v_add_f32_e32 v214, v214, v215
	s_and_saveexec_b64 s[28:29], s[4:5]
	global_store_dword v210, v214, s[16:17]
	s_mov_b64 exec, s[28:29]
	global_load_dwordx4 v[146:149], v206, s[10:11]
	global_load_dwordx4 v[150:153], v206, s[10:11] offset:256
	s_waitcnt vmcnt(15)
	v_lshlrev_b32_e32 v202, 16, v154
	v_and_b32_e32 v203, 0xffff0000, v154
	v_lshlrev_b32_e32 v204, 16, v155
	v_and_b32_e32 v205, 0xffff0000, v155
	v_pk_add_f32 v[108:109], v[108:109], v[202:203]
	v_pk_add_f32 v[110:111], v[110:111], v[204:205]
	v_lshlrev_b32_e32 v202, 16, v156
	v_and_b32_e32 v203, 0xffff0000, v156
	v_lshlrev_b32_e32 v204, 16, v157
	v_and_b32_e32 v205, 0xffff0000, v157
	v_pk_add_f32 v[104:105], v[104:105], v[202:203]
	v_pk_add_f32 v[106:107], v[106:107], v[204:205]
	v_cvt_pk_bf16_f32 v154, v108, v109
	v_cvt_pk_bf16_f32 v155, v110, v111
	v_cvt_pk_bf16_f32 v156, v104, v105
	v_cvt_pk_bf16_f32 v157, v106, v107
	v_pk_mul_f32 v[138:139], v[108:109], v[108:109]
	global_store_dwordx4 v207, v[154:157], s[10:11]
	v_pk_fma_f32 v[138:139], v[110:111], v[110:111], v[138:139]
	v_pk_fma_f32 v[138:139], v[104:105], v[104:105], v[138:139]
	v_pk_fma_f32 v[138:139], v[106:107], v[106:107], v[138:139]
	v_lshlrev_b32_e32 v202, 16, v158
	v_and_b32_e32 v203, 0xffff0000, v158
	v_lshlrev_b32_e32 v204, 16, v159
	v_and_b32_e32 v205, 0xffff0000, v159
	v_pk_add_f32 v[100:101], v[100:101], v[202:203]
	v_pk_add_f32 v[102:103], v[102:103], v[204:205]
	v_lshlrev_b32_e32 v202, 16, v160
	v_and_b32_e32 v203, 0xffff0000, v160
	v_lshlrev_b32_e32 v204, 16, v161
	v_and_b32_e32 v205, 0xffff0000, v161
	v_pk_add_f32 v[96:97], v[96:97], v[202:203]
	v_pk_add_f32 v[98:99], v[98:99], v[204:205]
	v_cvt_pk_bf16_f32 v158, v100, v101
	v_cvt_pk_bf16_f32 v159, v102, v103
	v_cvt_pk_bf16_f32 v160, v96, v97
	v_cvt_pk_bf16_f32 v161, v98, v99
	v_pk_fma_f32 v[138:139], v[100:101], v[100:101], v[138:139]
	global_store_dwordx4 v207, v[158:161], s[10:11] offset:256
	v_pk_fma_f32 v[138:139], v[102:103], v[102:103], v[138:139]
	v_pk_fma_f32 v[138:139], v[96:97], v[96:97], v[138:139]
	v_pk_fma_f32 v[138:139], v[98:99], v[98:99], v[138:139]
	v_add_f32_e32 v214, v138, v139
	v_add_u32_e32 v207, 0x8000, v207
	v_mov_b32_e32 v215, v214
	s_nop 1
	v_permlane16_swap_b32_e32 v214, v215
	s_nop 0
	v_add_f32_e32 v214, v214, v215
	v_mov_b32_e32 v215, v214
	s_nop 1
	v_permlane32_swap_b32_e32 v214, v215
	s_nop 0
	v_add_f32_e32 v214, v214, v215
	s_and_saveexec_b64 s[28:29], s[4:5]
	global_store_dword v210, v214, s[16:17] offset:1024
	s_mov_b64 exec, s[28:29]
	s_waitcnt vmcnt(16)
	v_lshlrev_b32_e32 v202, 16, v162
	v_and_b32_e32 v203, 0xffff0000, v162
	v_lshlrev_b32_e32 v204, 16, v163
	v_and_b32_e32 v205, 0xffff0000, v163
	v_pk_add_f32 v[92:93], v[92:93], v[202:203]
	v_pk_add_f32 v[94:95], v[94:95], v[204:205]
	v_lshlrev_b32_e32 v202, 16, v164
	v_and_b32_e32 v203, 0xffff0000, v164
	v_lshlrev_b32_e32 v204, 16, v165
	v_and_b32_e32 v205, 0xffff0000, v165
	v_pk_add_f32 v[88:89], v[88:89], v[202:203]
	v_pk_add_f32 v[90:91], v[90:91], v[204:205]
	v_cvt_pk_bf16_f32 v162, v92, v93
	v_cvt_pk_bf16_f32 v163, v94, v95
	v_cvt_pk_bf16_f32 v164, v88, v89
	v_cvt_pk_bf16_f32 v165, v90, v91
	v_pk_mul_f32 v[138:139], v[92:93], v[92:93]
	global_store_dwordx4 v207, v[162:165], s[10:11]
	v_pk_fma_f32 v[138:139], v[94:95], v[94:95], v[138:139]
	v_pk_fma_f32 v[138:139], v[88:89], v[88:89], v[138:139]
	v_pk_fma_f32 v[138:139], v[90:91], v[90:91], v[138:139]
	v_lshlrev_b32_e32 v202, 16, v166
	v_and_b32_e32 v203, 0xffff0000, v166
	v_lshlrev_b32_e32 v204, 16, v167
	v_and_b32_e32 v205, 0xffff0000, v167
	v_pk_add_f32 v[84:85], v[84:85], v[202:203]
	v_pk_add_f32 v[86:87], v[86:87], v[204:205]
	v_lshlrev_b32_e32 v202, 16, v168
	v_and_b32_e32 v203, 0xffff0000, v168
	v_lshlrev_b32_e32 v204, 16, v169
	v_and_b32_e32 v205, 0xffff0000, v169
	v_pk_add_f32 v[80:81], v[80:81], v[202:203]
	v_pk_add_f32 v[82:83], v[82:83], v[204:205]
	v_cvt_pk_bf16_f32 v166, v84, v85
	v_cvt_pk_bf16_f32 v167, v86, v87
	v_cvt_pk_bf16_f32 v168, v80, v81
	v_cvt_pk_bf16_f32 v169, v82, v83
	v_pk_fma_f32 v[138:139], v[84:85], v[84:85], v[138:139]
	global_store_dwordx4 v207, v[166:169], s[10:11] offset:256
	v_pk_fma_f32 v[138:139], v[86:87], v[86:87], v[138:139]
	v_pk_fma_f32 v[138:139], v[80:81], v[80:81], v[138:139]
	v_pk_fma_f32 v[138:139], v[82:83], v[82:83], v[138:139]
	v_add_f32_e32 v214, v138, v139
	v_add_u32_e32 v207, 0x8000, v207
	v_mov_b32_e32 v215, v214
	s_nop 1
	v_permlane16_swap_b32_e32 v214, v215
	s_nop 0
	v_add_f32_e32 v214, v214, v215
	v_mov_b32_e32 v215, v214
	s_nop 1
	v_permlane32_swap_b32_e32 v214, v215
	s_nop 0
	v_add_f32_e32 v214, v214, v215
	s_and_saveexec_b64 s[28:29], s[4:5]
	global_store_dword v210, v214, s[16:17] offset:2048
	s_mov_b64 exec, s[28:29]
	s_waitcnt vmcnt(17)
	v_lshlrev_b32_e32 v202, 16, v170
	v_and_b32_e32 v203, 0xffff0000, v170
	v_lshlrev_b32_e32 v204, 16, v171
	v_and_b32_e32 v205, 0xffff0000, v171
	v_pk_add_f32 v[76:77], v[76:77], v[202:203]
	v_pk_add_f32 v[78:79], v[78:79], v[204:205]
	v_lshlrev_b32_e32 v202, 16, v172
	v_and_b32_e32 v203, 0xffff0000, v172
	v_lshlrev_b32_e32 v204, 16, v173
	v_and_b32_e32 v205, 0xffff0000, v173
	v_pk_add_f32 v[72:73], v[72:73], v[202:203]
	v_pk_add_f32 v[74:75], v[74:75], v[204:205]
	v_cvt_pk_bf16_f32 v170, v76, v77
	v_cvt_pk_bf16_f32 v171, v78, v79
	v_cvt_pk_bf16_f32 v172, v72, v73
	v_cvt_pk_bf16_f32 v173, v74, v75
	v_pk_mul_f32 v[138:139], v[76:77], v[76:77]
	global_store_dwordx4 v207, v[170:173], s[10:11]
	v_pk_fma_f32 v[138:139], v[78:79], v[78:79], v[138:139]
	v_pk_fma_f32 v[138:139], v[72:73], v[72:73], v[138:139]
	v_pk_fma_f32 v[138:139], v[74:75], v[74:75], v[138:139]
	v_lshlrev_b32_e32 v202, 16, v174
	v_and_b32_e32 v203, 0xffff0000, v174
	v_lshlrev_b32_e32 v204, 16, v175
	v_and_b32_e32 v205, 0xffff0000, v175
	v_pk_add_f32 v[68:69], v[68:69], v[202:203]
	v_pk_add_f32 v[70:71], v[70:71], v[204:205]
	v_lshlrev_b32_e32 v202, 16, v176
	v_and_b32_e32 v203, 0xffff0000, v176
	v_lshlrev_b32_e32 v204, 16, v177
	v_and_b32_e32 v205, 0xffff0000, v177
	v_pk_add_f32 v[64:65], v[64:65], v[202:203]
	v_pk_add_f32 v[66:67], v[66:67], v[204:205]
	v_cvt_pk_bf16_f32 v174, v68, v69
	v_cvt_pk_bf16_f32 v175, v70, v71
	v_cvt_pk_bf16_f32 v176, v64, v65
	v_cvt_pk_bf16_f32 v177, v66, v67
	v_pk_fma_f32 v[138:139], v[68:69], v[68:69], v[138:139]
	global_store_dwordx4 v207, v[174:177], s[10:11] offset:256
	v_pk_fma_f32 v[138:139], v[70:71], v[70:71], v[138:139]
	v_pk_fma_f32 v[138:139], v[64:65], v[64:65], v[138:139]
	v_pk_fma_f32 v[138:139], v[66:67], v[66:67], v[138:139]
	v_add_f32_e32 v214, v138, v139
	v_add_u32_e32 v207, 0x28000, v207
	v_mov_b32_e32 v215, v214
	s_nop 1
	v_permlane16_swap_b32_e32 v214, v215
	s_nop 0
	v_add_f32_e32 v214, v214, v215
	v_mov_b32_e32 v215, v214
	s_nop 1
	v_permlane32_swap_b32_e32 v214, v215
	s_nop 0
	v_add_f32_e32 v214, v214, v215
	s_and_saveexec_b64 s[28:29], s[4:5]
	global_store_dword v210, v214, s[16:17] offset:3072
	s_mov_b64 exec, s[28:29]
	v_add_u32_e32 v210, 0x2000, v210
	s_waitcnt vmcnt(18)
	v_lshlrev_b32_e32 v202, 16, v178
	v_and_b32_e32 v203, 0xffff0000, v178
	v_lshlrev_b32_e32 v204, 16, v179
	v_and_b32_e32 v205, 0xffff0000, v179
	v_pk_add_f32 v[60:61], v[60:61], v[202:203]
	v_pk_add_f32 v[62:63], v[62:63], v[204:205]
	v_lshlrev_b32_e32 v202, 16, v180
	v_and_b32_e32 v203, 0xffff0000, v180
	v_lshlrev_b32_e32 v204, 16, v181
	v_and_b32_e32 v205, 0xffff0000, v181
	v_pk_add_f32 v[56:57], v[56:57], v[202:203]
	v_pk_add_f32 v[58:59], v[58:59], v[204:205]
	v_cvt_pk_bf16_f32 v178, v60, v61
	v_cvt_pk_bf16_f32 v179, v62, v63
	v_cvt_pk_bf16_f32 v180, v56, v57
	v_cvt_pk_bf16_f32 v181, v58, v59
	v_pk_mul_f32 v[138:139], v[60:61], v[60:61]
	global_store_dwordx4 v207, v[178:181], s[10:11]
	v_pk_fma_f32 v[138:139], v[62:63], v[62:63], v[138:139]
	v_pk_fma_f32 v[138:139], v[56:57], v[56:57], v[138:139]
	v_pk_fma_f32 v[138:139], v[58:59], v[58:59], v[138:139]
	v_lshlrev_b32_e32 v202, 16, v182
	v_and_b32_e32 v203, 0xffff0000, v182
	v_lshlrev_b32_e32 v204, 16, v183
	v_and_b32_e32 v205, 0xffff0000, v183
	v_pk_add_f32 v[52:53], v[52:53], v[202:203]
	v_pk_add_f32 v[54:55], v[54:55], v[204:205]
	v_lshlrev_b32_e32 v202, 16, v184
	v_and_b32_e32 v203, 0xffff0000, v184
	v_lshlrev_b32_e32 v204, 16, v185
	v_and_b32_e32 v205, 0xffff0000, v185
	v_pk_add_f32 v[48:49], v[48:49], v[202:203]
	v_pk_add_f32 v[50:51], v[50:51], v[204:205]
	v_cvt_pk_bf16_f32 v182, v52, v53
	v_cvt_pk_bf16_f32 v183, v54, v55
	v_cvt_pk_bf16_f32 v184, v48, v49
	v_cvt_pk_bf16_f32 v185, v50, v51
	v_pk_fma_f32 v[138:139], v[52:53], v[52:53], v[138:139]
	global_store_dwordx4 v207, v[182:185], s[10:11] offset:256
	v_pk_fma_f32 v[138:139], v[54:55], v[54:55], v[138:139]
	v_pk_fma_f32 v[138:139], v[48:49], v[48:49], v[138:139]
	v_pk_fma_f32 v[138:139], v[50:51], v[50:51], v[138:139]
	v_add_f32_e32 v214, v138, v139
	v_add_u32_e32 v207, 0x8000, v207
	v_mov_b32_e32 v215, v214
	s_nop 1
	v_permlane16_swap_b32_e32 v214, v215
	s_nop 0
	v_add_f32_e32 v214, v214, v215
	v_mov_b32_e32 v215, v214
	s_nop 1
	v_permlane32_swap_b32_e32 v214, v215
	s_nop 0
	v_add_f32_e32 v214, v214, v215
	s_and_saveexec_b64 s[28:29], s[4:5]
	global_store_dword v210, v214, s[16:17]
	s_mov_b64 exec, s[28:29]
	s_waitcnt vmcnt(19)
	v_lshlrev_b32_e32 v202, 16, v186
	v_and_b32_e32 v203, 0xffff0000, v186
	v_lshlrev_b32_e32 v204, 16, v187
	v_and_b32_e32 v205, 0xffff0000, v187
	v_pk_add_f32 v[44:45], v[44:45], v[202:203]
	v_pk_add_f32 v[46:47], v[46:47], v[204:205]
	v_lshlrev_b32_e32 v202, 16, v188
	v_and_b32_e32 v203, 0xffff0000, v188
	v_lshlrev_b32_e32 v204, 16, v189
	v_and_b32_e32 v205, 0xffff0000, v189
	v_pk_add_f32 v[40:41], v[40:41], v[202:203]
	v_pk_add_f32 v[42:43], v[42:43], v[204:205]
	v_cvt_pk_bf16_f32 v186, v44, v45
	v_cvt_pk_bf16_f32 v187, v46, v47
	v_cvt_pk_bf16_f32 v188, v40, v41
	v_cvt_pk_bf16_f32 v189, v42, v43
	v_pk_mul_f32 v[138:139], v[44:45], v[44:45]
	global_store_dwordx4 v207, v[186:189], s[10:11]
	v_pk_fma_f32 v[138:139], v[46:47], v[46:47], v[138:139]
	v_pk_fma_f32 v[138:139], v[40:41], v[40:41], v[138:139]
	v_pk_fma_f32 v[138:139], v[42:43], v[42:43], v[138:139]
	v_lshlrev_b32_e32 v202, 16, v190
	v_and_b32_e32 v203, 0xffff0000, v190
	v_lshlrev_b32_e32 v204, 16, v191
	v_and_b32_e32 v205, 0xffff0000, v191
	v_pk_add_f32 v[36:37], v[36:37], v[202:203]
	v_pk_add_f32 v[38:39], v[38:39], v[204:205]
	v_lshlrev_b32_e32 v202, 16, v192
	v_and_b32_e32 v203, 0xffff0000, v192
	v_lshlrev_b32_e32 v204, 16, v193
	v_and_b32_e32 v205, 0xffff0000, v193
	v_pk_add_f32 v[32:33], v[32:33], v[202:203]
	v_pk_add_f32 v[34:35], v[34:35], v[204:205]
	v_cvt_pk_bf16_f32 v190, v36, v37
	v_cvt_pk_bf16_f32 v191, v38, v39
	v_cvt_pk_bf16_f32 v192, v32, v33
	v_cvt_pk_bf16_f32 v193, v34, v35
	v_pk_fma_f32 v[138:139], v[36:37], v[36:37], v[138:139]
	global_store_dwordx4 v207, v[190:193], s[10:11] offset:256
	v_pk_fma_f32 v[138:139], v[38:39], v[38:39], v[138:139]
	v_pk_fma_f32 v[138:139], v[32:33], v[32:33], v[138:139]
	v_pk_fma_f32 v[138:139], v[34:35], v[34:35], v[138:139]
	v_add_f32_e32 v214, v138, v139
	v_add_u32_e32 v207, 0x8000, v207
	v_mov_b32_e32 v215, v214
	s_nop 1
	v_permlane16_swap_b32_e32 v214, v215
	s_nop 0
	v_add_f32_e32 v214, v214, v215
	v_mov_b32_e32 v215, v214
	s_nop 1
	v_permlane32_swap_b32_e32 v214, v215
	s_nop 0
	v_add_f32_e32 v214, v214, v215
	s_and_saveexec_b64 s[28:29], s[4:5]
	global_store_dword v210, v214, s[16:17] offset:1024
	s_mov_b64 exec, s[28:29]
	s_waitcnt vmcnt(20)
	v_lshlrev_b32_e32 v202, 16, v194
	v_and_b32_e32 v203, 0xffff0000, v194
	v_lshlrev_b32_e32 v204, 16, v195
	v_and_b32_e32 v205, 0xffff0000, v195
	v_pk_add_f32 v[28:29], v[28:29], v[202:203]
	v_pk_add_f32 v[30:31], v[30:31], v[204:205]
	v_lshlrev_b32_e32 v202, 16, v196
	v_and_b32_e32 v203, 0xffff0000, v196
	v_lshlrev_b32_e32 v204, 16, v197
	v_and_b32_e32 v205, 0xffff0000, v197
	v_pk_add_f32 v[24:25], v[24:25], v[202:203]
	v_pk_add_f32 v[26:27], v[26:27], v[204:205]
	v_cvt_pk_bf16_f32 v194, v28, v29
	v_cvt_pk_bf16_f32 v195, v30, v31
	v_cvt_pk_bf16_f32 v196, v24, v25
	v_cvt_pk_bf16_f32 v197, v26, v27
	v_pk_mul_f32 v[138:139], v[28:29], v[28:29]
	global_store_dwordx4 v207, v[194:197], s[10:11]
	v_pk_fma_f32 v[138:139], v[30:31], v[30:31], v[138:139]
	v_pk_fma_f32 v[138:139], v[24:25], v[24:25], v[138:139]
	v_pk_fma_f32 v[138:139], v[26:27], v[26:27], v[138:139]
	v_lshlrev_b32_e32 v202, 16, v198
	v_and_b32_e32 v203, 0xffff0000, v198
	v_lshlrev_b32_e32 v204, 16, v199
	v_and_b32_e32 v205, 0xffff0000, v199
	v_pk_add_f32 v[20:21], v[20:21], v[202:203]
	v_pk_add_f32 v[22:23], v[22:23], v[204:205]
	v_lshlrev_b32_e32 v202, 16, v200
	v_and_b32_e32 v203, 0xffff0000, v200
	v_lshlrev_b32_e32 v204, 16, v201
	v_and_b32_e32 v205, 0xffff0000, v201
	v_pk_add_f32 v[16:17], v[16:17], v[202:203]
	v_pk_add_f32 v[18:19], v[18:19], v[204:205]
	v_cvt_pk_bf16_f32 v198, v20, v21
	v_cvt_pk_bf16_f32 v199, v22, v23
	v_cvt_pk_bf16_f32 v200, v16, v17
	v_cvt_pk_bf16_f32 v201, v18, v19
	v_pk_fma_f32 v[138:139], v[20:21], v[20:21], v[138:139]
	global_store_dwordx4 v207, v[198:201], s[10:11] offset:256
	v_pk_fma_f32 v[138:139], v[22:23], v[22:23], v[138:139]
	v_pk_fma_f32 v[138:139], v[16:17], v[16:17], v[138:139]
	v_pk_fma_f32 v[138:139], v[18:19], v[18:19], v[138:139]
	v_add_f32_e32 v214, v138, v139
	v_add_u32_e32 v207, 0x8000, v207
	v_mov_b32_e32 v215, v214
	s_nop 1
	v_permlane16_swap_b32_e32 v214, v215
	s_nop 0
	v_add_f32_e32 v214, v214, v215
	v_mov_b32_e32 v215, v214
	s_nop 1
	v_permlane32_swap_b32_e32 v214, v215
	s_nop 0
	v_add_f32_e32 v214, v214, v215
	s_and_saveexec_b64 s[28:29], s[4:5]
	global_store_dword v210, v214, s[16:17] offset:2048
	s_mov_b64 exec, s[28:29]
	s_waitcnt vmcnt(18)
	v_lshlrev_b32_e32 v202, 16, v146
	v_and_b32_e32 v203, 0xffff0000, v146
	v_lshlrev_b32_e32 v204, 16, v147
	v_and_b32_e32 v205, 0xffff0000, v147
	v_pk_add_f32 v[12:13], v[12:13], v[202:203]
	v_pk_add_f32 v[14:15], v[14:15], v[204:205]
	v_lshlrev_b32_e32 v202, 16, v148
	v_and_b32_e32 v203, 0xffff0000, v148
	v_lshlrev_b32_e32 v204, 16, v149
	v_and_b32_e32 v205, 0xffff0000, v149
	v_pk_add_f32 v[8:9], v[8:9], v[202:203]
	v_pk_add_f32 v[10:11], v[10:11], v[204:205]
	v_cvt_pk_bf16_f32 v146, v12, v13
	v_cvt_pk_bf16_f32 v147, v14, v15
	v_cvt_pk_bf16_f32 v148, v8, v9
	v_cvt_pk_bf16_f32 v149, v10, v11
	v_pk_mul_f32 v[138:139], v[12:13], v[12:13]
	global_store_dwordx4 v207, v[146:149], s[10:11]
	v_pk_fma_f32 v[138:139], v[14:15], v[14:15], v[138:139]
	v_pk_fma_f32 v[138:139], v[8:9], v[8:9], v[138:139]
	v_pk_fma_f32 v[138:139], v[10:11], v[10:11], v[138:139]
	v_lshlrev_b32_e32 v202, 16, v150
	v_and_b32_e32 v203, 0xffff0000, v150
	v_lshlrev_b32_e32 v204, 16, v151
	v_and_b32_e32 v205, 0xffff0000, v151
	v_pk_add_f32 v[4:5], v[4:5], v[202:203]
	v_pk_add_f32 v[6:7], v[6:7], v[204:205]
	v_lshlrev_b32_e32 v202, 16, v152
	v_and_b32_e32 v203, 0xffff0000, v152
	v_lshlrev_b32_e32 v204, 16, v153
	v_and_b32_e32 v205, 0xffff0000, v153
	v_pk_add_f32 v[0:1], v[0:1], v[202:203]
	v_pk_add_f32 v[2:3], v[2:3], v[204:205]
	v_cvt_pk_bf16_f32 v150, v4, v5
	v_cvt_pk_bf16_f32 v151, v6, v7
	v_cvt_pk_bf16_f32 v152, v0, v1
	v_cvt_pk_bf16_f32 v153, v2, v3
	v_pk_fma_f32 v[138:139], v[4:5], v[4:5], v[138:139]
	global_store_dwordx4 v207, v[150:153], s[10:11] offset:256
	v_pk_fma_f32 v[138:139], v[6:7], v[6:7], v[138:139]
	v_pk_fma_f32 v[138:139], v[0:1], v[0:1], v[138:139]
	v_pk_fma_f32 v[138:139], v[2:3], v[2:3], v[138:139]
	v_add_f32_e32 v214, v138, v139
	v_add_u32_e32 v207, 0x8000, v207
	v_mov_b32_e32 v215, v214
	s_nop 1
	v_permlane16_swap_b32_e32 v214, v215
	s_nop 0
	v_add_f32_e32 v214, v214, v215
	v_mov_b32_e32 v215, v214
	s_nop 1
	v_permlane32_swap_b32_e32 v214, v215
	s_nop 0
	v_add_f32_e32 v214, v214, v215
	s_and_saveexec_b64 s[28:29], s[4:5]
	global_store_dword v210, v214, s[16:17] offset:3072
	s_mov_b64 exec, s[28:29]
	s_branch .LBB0_768

.LBB0_823:
	v_add_u32_e32 v206, 0x10000, v143
	s_add_u32 s26, s24, 0xfffc0080
	s_addc_u32 s27, s25, -1
	s_add_i32 s65, 0, 0x10000
	ds_read_b128 v[138:141], v206
	ds_read_b128 v[146:149], v206 offset:1024
	ds_read_b128 v[150:153], v206 offset:2048
	ds_read_b128 v[154:157], v206 offset:3072
	s_cmp_eq_u32 s51, 12
	s_cselect_b32 s29, s19, s27
	s_cselect_b32 s28, s38, s26
	s_cselect_b32 s27, s17, s50
	s_cselect_b32 s26, s39, s46
	s_add_i32 m0, s58, 0xc000
	ds_read_b128 v[158:161], v145
	ds_read_b128 v[162:165], v145 offset:1024
	ds_read_b128 v[166:169], v145 offset:2048
	ds_read_b128 v[170:173], v145 offset:3072
	ds_read_b128 v[174:177], v145 offset:4096
	ds_read_b128 v[178:181], v145 offset:5120
	ds_read_b128 v[182:185], v145 offset:6144
	ds_read_b128 v[186:189], v145 offset:7168
	global_load_lds_dwordx4 v134, s[24:25]
	s_add_i32 m0, s58, 0xe000
	s_nop 0
	global_load_lds_dwordx4 v136, s[24:25]
	s_waitcnt lgkmcnt(8)
	s_barrier
	s_waitcnt lgkmcnt(0)
	v_mfma_f32_16x16x32_bf16 v[124:127], v[138:141], v[158:161], v[124:127]
	v_mfma_f32_16x16x32_bf16 v[120:123], v[150:153], v[158:161], v[120:123]
	v_mfma_f32_16x16x32_bf16 v[108:111], v[138:141], v[166:169], v[108:111]
	v_mfma_f32_16x16x32_bf16 v[104:107], v[150:153], v[166:169], v[104:107]
	v_mfma_f32_16x16x32_bf16 v[92:95], v[138:141], v[174:177], v[92:95]
	v_mfma_f32_16x16x32_bf16 v[88:91], v[150:153], v[174:177], v[88:91]
	v_mfma_f32_16x16x32_bf16 v[76:79], v[138:141], v[182:185], v[76:79]
	v_mfma_f32_16x16x32_bf16 v[72:75], v[150:153], v[182:185], v[72:75]
	v_mfma_f32_16x16x32_bf16 v[124:127], v[146:149], v[162:165], v[124:127]
	v_mfma_f32_16x16x32_bf16 v[120:123], v[154:157], v[162:165], v[120:123]
	v_mfma_f32_16x16x32_bf16 v[108:111], v[146:149], v[170:173], v[108:111]
	v_mfma_f32_16x16x32_bf16 v[104:107], v[154:157], v[170:173], v[104:107]
	v_mfma_f32_16x16x32_bf16 v[92:95], v[146:149], v[178:181], v[92:95]
	v_mfma_f32_16x16x32_bf16 v[88:91], v[154:157], v[178:181], v[88:91]
	v_mfma_f32_16x16x32_bf16 v[76:79], v[146:149], v[186:189], v[76:79]
	v_mfma_f32_16x16x32_bf16 v[72:75], v[154:157], v[186:189], v[72:75]
	s_barrier
	s_add_i32 s68, 0, 0x14000
	s_add_i32 s65, s65, s57
	s_add_u32 s98, s26, s40
	s_addc_u32 s99, s27, s41
	s_mov_b32 m0, s65
	ds_read_b128 v[190:193], v206 offset:16384
	ds_read_b128 v[194:197], v206 offset:17408
	ds_read_b128 v[198:201], v206 offset:18432
	ds_read_b128 v[202:205], v206 offset:19456
	global_load_lds_dwordx4 v208, s[26:27]
	s_add_i32 m0, s65, 0x2000
	s_nop 0
	global_load_lds_dwordx4 v128, s[26:27]
	s_barrier
	s_waitcnt lgkmcnt(0)
	v_mfma_f32_16x16x32_bf16 v[116:119], v[190:193], v[158:161], v[116:119]
	v_mfma_f32_16x16x32_bf16 v[112:115], v[198:201], v[158:161], v[112:115]
	v_mfma_f32_16x16x32_bf16 v[100:103], v[190:193], v[166:169], v[100:103]
	v_mfma_f32_16x16x32_bf16 v[96:99], v[198:201], v[166:169], v[96:99]
	v_mfma_f32_16x16x32_bf16 v[84:87], v[190:193], v[174:177], v[84:87]
	v_mfma_f32_16x16x32_bf16 v[80:83], v[198:201], v[174:177], v[80:83]
	v_mfma_f32_16x16x32_bf16 v[68:71], v[190:193], v[182:185], v[68:71]
	v_mfma_f32_16x16x32_bf16 v[64:67], v[198:201], v[182:185], v[64:67]
	v_mfma_f32_16x16x32_bf16 v[116:119], v[194:197], v[162:165], v[116:119]
	v_mfma_f32_16x16x32_bf16 v[112:115], v[202:205], v[162:165], v[112:115]
	v_mfma_f32_16x16x32_bf16 v[100:103], v[194:197], v[170:173], v[100:103]
	v_mfma_f32_16x16x32_bf16 v[96:99], v[202:205], v[170:173], v[96:99]
	v_mfma_f32_16x16x32_bf16 v[84:87], v[194:197], v[178:181], v[84:87]
	v_mfma_f32_16x16x32_bf16 v[80:83], v[202:205], v[178:181], v[80:83]
	v_mfma_f32_16x16x32_bf16 v[68:71], v[194:197], v[186:189], v[68:71]
	v_mfma_f32_16x16x32_bf16 v[64:67], v[202:205], v[186:189], v[64:67]
	s_mov_b32 m0, s58
	s_add_u32 s100, s28, s40
	s_addc_u32 s101, s29, s41
	s_barrier
	ds_read_b128 v[158:161], v145 offset:16384
	ds_read_b128 v[162:165], v145 offset:17408
	ds_read_b128 v[166:169], v145 offset:18432
	ds_read_b128 v[170:173], v145 offset:19456
	ds_read_b128 v[174:177], v145 offset:20480
	ds_read_b128 v[178:181], v145 offset:21504
	ds_read_b128 v[182:185], v145 offset:22528
	ds_read_b128 v[186:189], v145 offset:23552
	global_load_lds_dwordx4 v132, s[28:29]
	s_mov_b32 m0, s59
	s_nop 0
	global_load_lds_dwordx4 v130, s[28:29]
	s_barrier
	s_waitcnt lgkmcnt(0)
	v_mfma_f32_16x16x32_bf16 v[60:63], v[138:141], v[158:161], v[60:63]
	v_mfma_f32_16x16x32_bf16 v[56:59], v[150:153], v[158:161], v[56:59]
	v_mfma_f32_16x16x32_bf16 v[44:47], v[138:141], v[166:169], v[44:47]
	v_mfma_f32_16x16x32_bf16 v[40:43], v[150:153], v[166:169], v[40:43]
	v_mfma_f32_16x16x32_bf16 v[28:31], v[138:141], v[174:177], v[28:31]
	v_mfma_f32_16x16x32_bf16 v[24:27], v[150:153], v[174:177], v[24:27]
	v_mfma_f32_16x16x32_bf16 v[12:15], v[138:141], v[182:185], v[12:15]
	v_mfma_f32_16x16x32_bf16 v[8:11], v[150:153], v[182:185], v[8:11]
	v_mfma_f32_16x16x32_bf16 v[60:63], v[146:149], v[162:165], v[60:63]
	v_mfma_f32_16x16x32_bf16 v[56:59], v[154:157], v[162:165], v[56:59]
	v_mfma_f32_16x16x32_bf16 v[44:47], v[146:149], v[170:173], v[44:47]
	v_mfma_f32_16x16x32_bf16 v[40:43], v[154:157], v[170:173], v[40:43]
	v_mfma_f32_16x16x32_bf16 v[28:31], v[146:149], v[178:181], v[28:31]
	v_mfma_f32_16x16x32_bf16 v[24:27], v[154:157], v[178:181], v[24:27]
	v_mfma_f32_16x16x32_bf16 v[12:15], v[146:149], v[186:189], v[12:15]
	v_mfma_f32_16x16x32_bf16 v[8:11], v[154:157], v[186:189], v[8:11]
	s_barrier
	s_add_u32 s66, s26, 0x40000
	s_addc_u32 s67, s27, 0
	s_add_i32 s65, s68, s57
	s_mov_b32 m0, s65
	s_nop 0
	global_load_lds_dwordx4 v208, s[66:67]
	s_add_i32 m0, s65, 0x2000
	s_nop 0
	global_load_lds_dwordx4 v128, s[66:67]
	s_waitcnt vmcnt(6)
	s_barrier
	v_mfma_f32_16x16x32_bf16 v[52:55], v[190:193], v[158:161], v[52:55]
	v_mfma_f32_16x16x32_bf16 v[48:51], v[198:201], v[158:161], v[48:51]
	v_mfma_f32_16x16x32_bf16 v[36:39], v[190:193], v[166:169], v[36:39]
	v_mfma_f32_16x16x32_bf16 v[32:35], v[198:201], v[166:169], v[32:35]
	v_mfma_f32_16x16x32_bf16 v[20:23], v[190:193], v[174:177], v[20:23]
	v_mfma_f32_16x16x32_bf16 v[16:19], v[198:201], v[174:177], v[16:19]
	v_mfma_f32_16x16x32_bf16 v[4:7], v[190:193], v[182:185], v[4:7]
	v_mfma_f32_16x16x32_bf16 v[0:3], v[198:201], v[182:185], v[0:3]
	v_mfma_f32_16x16x32_bf16 v[52:55], v[194:197], v[162:165], v[52:55]
	v_mfma_f32_16x16x32_bf16 v[48:51], v[202:205], v[162:165], v[48:51]
	v_mfma_f32_16x16x32_bf16 v[36:39], v[194:197], v[170:173], v[36:39]
	v_mfma_f32_16x16x32_bf16 v[32:35], v[202:205], v[170:173], v[32:35]
	v_mfma_f32_16x16x32_bf16 v[20:23], v[194:197], v[178:181], v[20:23]
	v_mfma_f32_16x16x32_bf16 v[16:19], v[202:205], v[178:181], v[16:19]
	v_mfma_f32_16x16x32_bf16 v[4:7], v[194:197], v[186:189], v[4:7]
	v_mfma_f32_16x16x32_bf16 v[0:3], v[202:205], v[186:189], v[0:3]
	s_add_i32 s65, 0, 0x18000
	s_barrier
	ds_read_b128 v[138:141], v206 offset:32768
	ds_read_b128 v[146:149], v206 offset:33792
	ds_read_b128 v[150:153], v206 offset:34816
	ds_read_b128 v[154:157], v206 offset:35840
	s_add_u32 s28, s28, 0x40000
	s_addc_u32 s29, s29, 0
	s_mov_b32 m0, s60
	ds_read_b128 v[158:161], v145 offset:32768
	ds_read_b128 v[162:165], v145 offset:33792
	ds_read_b128 v[166:169], v145 offset:34816
	ds_read_b128 v[170:173], v145 offset:35840
	ds_read_b128 v[174:177], v145 offset:36864
	ds_read_b128 v[178:181], v145 offset:37888
	ds_read_b128 v[182:185], v145 offset:38912
	ds_read_b128 v[186:189], v145 offset:39936
	global_load_lds_dwordx4 v132, s[28:29]
	s_mov_b32 m0, s61
	s_nop 0
	global_load_lds_dwordx4 v130, s[28:29]
	s_waitcnt lgkmcnt(8)
	s_barrier
	s_waitcnt lgkmcnt(0)
	v_mfma_f32_16x16x32_bf16 v[124:127], v[138:141], v[158:161], v[124:127]
	v_mfma_f32_16x16x32_bf16 v[120:123], v[150:153], v[158:161], v[120:123]
	v_mfma_f32_16x16x32_bf16 v[108:111], v[138:141], v[166:169], v[108:111]
	v_mfma_f32_16x16x32_bf16 v[104:107], v[150:153], v[166:169], v[104:107]
	v_mfma_f32_16x16x32_bf16 v[92:95], v[138:141], v[174:177], v[92:95]
	v_mfma_f32_16x16x32_bf16 v[88:91], v[150:153], v[174:177], v[88:91]
	v_mfma_f32_16x16x32_bf16 v[76:79], v[138:141], v[182:185], v[76:79]
	v_mfma_f32_16x16x32_bf16 v[72:75], v[150:153], v[182:185], v[72:75]
	v_mfma_f32_16x16x32_bf16 v[124:127], v[146:149], v[162:165], v[124:127]
	v_mfma_f32_16x16x32_bf16 v[120:123], v[154:157], v[162:165], v[120:123]
	v_mfma_f32_16x16x32_bf16 v[108:111], v[146:149], v[170:173], v[108:111]
	v_mfma_f32_16x16x32_bf16 v[104:107], v[154:157], v[170:173], v[104:107]
	v_mfma_f32_16x16x32_bf16 v[92:95], v[146:149], v[178:181], v[92:95]
	v_mfma_f32_16x16x32_bf16 v[88:91], v[154:157], v[178:181], v[88:91]
	v_mfma_f32_16x16x32_bf16 v[76:79], v[146:149], v[186:189], v[76:79]
	v_mfma_f32_16x16x32_bf16 v[72:75], v[154:157], v[186:189], v[72:75]
	s_barrier
	s_add_i32 s28, 0, 0x1c000
	s_add_i32 s29, s65, s57
	s_mov_b32 m0, s29
	ds_read_b128 v[190:193], v206 offset:49152
	ds_read_b128 v[194:197], v206 offset:50176
	ds_read_b128 v[198:201], v206 offset:51200
	ds_read_b128 v[202:205], v206 offset:52224
	global_load_lds_dwordx4 v208, s[98:99]
	s_add_i32 m0, s29, 0x2000
	s_nop 0
	global_load_lds_dwordx4 v128, s[98:99]
	s_barrier
	s_waitcnt lgkmcnt(0)
	v_mfma_f32_16x16x32_bf16 v[116:119], v[190:193], v[158:161], v[116:119]
	v_mfma_f32_16x16x32_bf16 v[112:115], v[198:201], v[158:161], v[112:115]
	v_mfma_f32_16x16x32_bf16 v[100:103], v[190:193], v[166:169], v[100:103]
	v_mfma_f32_16x16x32_bf16 v[96:99], v[198:201], v[166:169], v[96:99]
	v_mfma_f32_16x16x32_bf16 v[84:87], v[190:193], v[174:177], v[84:87]
	v_mfma_f32_16x16x32_bf16 v[80:83], v[198:201], v[174:177], v[80:83]
	v_mfma_f32_16x16x32_bf16 v[68:71], v[190:193], v[182:185], v[68:71]
	v_mfma_f32_16x16x32_bf16 v[64:67], v[198:201], v[182:185], v[64:67]
	v_mfma_f32_16x16x32_bf16 v[116:119], v[194:197], v[162:165], v[116:119]
	v_mfma_f32_16x16x32_bf16 v[112:115], v[202:205], v[162:165], v[112:115]
	v_mfma_f32_16x16x32_bf16 v[100:103], v[194:197], v[170:173], v[100:103]
	v_mfma_f32_16x16x32_bf16 v[96:99], v[202:205], v[170:173], v[96:99]
	v_mfma_f32_16x16x32_bf16 v[84:87], v[194:197], v[178:181], v[84:87]
	v_mfma_f32_16x16x32_bf16 v[80:83], v[202:205], v[178:181], v[80:83]
	v_mfma_f32_16x16x32_bf16 v[68:71], v[194:197], v[186:189], v[68:71]
	v_mfma_f32_16x16x32_bf16 v[64:67], v[202:205], v[186:189], v[64:67]
	s_mov_b32 m0, s62
	s_barrier
	ds_read_b128 v[158:161], v145 offset:49152
	ds_read_b128 v[162:165], v145 offset:50176
	ds_read_b128 v[166:169], v145 offset:51200
	ds_read_b128 v[170:173], v145 offset:52224
	ds_read_b128 v[174:177], v145 offset:53248
	ds_read_b128 v[178:181], v145 offset:54272
	ds_read_b128 v[182:185], v145 offset:55296
	ds_read_b128 v[186:189], v145 offset:56320
	global_load_lds_dwordx4 v132, s[100:101]
	s_mov_b32 m0, s63
	s_nop 0
	global_load_lds_dwordx4 v130, s[100:101]
	s_barrier
	s_waitcnt lgkmcnt(0)
	v_mfma_f32_16x16x32_bf16 v[60:63], v[138:141], v[158:161], v[60:63]
	v_mfma_f32_16x16x32_bf16 v[56:59], v[150:153], v[158:161], v[56:59]
	v_mfma_f32_16x16x32_bf16 v[44:47], v[138:141], v[166:169], v[44:47]
	v_mfma_f32_16x16x32_bf16 v[40:43], v[150:153], v[166:169], v[40:43]
	v_mfma_f32_16x16x32_bf16 v[28:31], v[138:141], v[174:177], v[28:31]
	v_mfma_f32_16x16x32_bf16 v[24:27], v[150:153], v[174:177], v[24:27]
	v_mfma_f32_16x16x32_bf16 v[12:15], v[138:141], v[182:185], v[12:15]
	v_mfma_f32_16x16x32_bf16 v[8:11], v[150:153], v[182:185], v[8:11]
	v_mfma_f32_16x16x32_bf16 v[60:63], v[146:149], v[162:165], v[60:63]
	v_mfma_f32_16x16x32_bf16 v[56:59], v[154:157], v[162:165], v[56:59]
	v_mfma_f32_16x16x32_bf16 v[44:47], v[146:149], v[170:173], v[44:47]
	v_mfma_f32_16x16x32_bf16 v[40:43], v[154:157], v[170:173], v[40:43]
	v_mfma_f32_16x16x32_bf16 v[28:31], v[146:149], v[178:181], v[28:31]
	v_mfma_f32_16x16x32_bf16 v[24:27], v[154:157], v[178:181], v[24:27]
	v_mfma_f32_16x16x32_bf16 v[12:15], v[146:149], v[186:189], v[12:15]
	v_mfma_f32_16x16x32_bf16 v[8:11], v[154:157], v[186:189], v[8:11]
	s_barrier
	s_add_u32 s26, s26, 0x40080
	s_addc_u32 s27, s27, 0
	s_add_i32 s28, s28, s57
	s_mov_b32 m0, s28
	s_nop 0
	global_load_lds_dwordx4 v208, s[26:27]
	s_add_i32 m0, s28, 0x2000
	s_nop 0
	global_load_lds_dwordx4 v128, s[26:27]
	s_waitcnt vmcnt(6)
	s_barrier
	v_mfma_f32_16x16x32_bf16 v[52:55], v[190:193], v[158:161], v[52:55]
	v_mfma_f32_16x16x32_bf16 v[48:51], v[198:201], v[158:161], v[48:51]
	v_mfma_f32_16x16x32_bf16 v[36:39], v[190:193], v[166:169], v[36:39]
	v_mfma_f32_16x16x32_bf16 v[32:35], v[198:201], v[166:169], v[32:35]
	v_mfma_f32_16x16x32_bf16 v[20:23], v[190:193], v[174:177], v[20:23]
	v_mfma_f32_16x16x32_bf16 v[16:19], v[198:201], v[174:177], v[16:19]
	v_mfma_f32_16x16x32_bf16 v[4:7], v[190:193], v[182:185], v[4:7]
	v_mfma_f32_16x16x32_bf16 v[0:3], v[198:201], v[182:185], v[0:3]
	v_mfma_f32_16x16x32_bf16 v[52:55], v[194:197], v[162:165], v[52:55]
	v_mfma_f32_16x16x32_bf16 v[48:51], v[202:205], v[162:165], v[48:51]
	v_mfma_f32_16x16x32_bf16 v[36:39], v[194:197], v[170:173], v[36:39]
	v_mfma_f32_16x16x32_bf16 v[32:35], v[202:205], v[170:173], v[32:35]
	v_mfma_f32_16x16x32_bf16 v[20:23], v[194:197], v[178:181], v[20:23]
	v_mfma_f32_16x16x32_bf16 v[16:19], v[202:205], v[178:181], v[16:19]
	v_mfma_f32_16x16x32_bf16 v[4:7], v[194:197], v[186:189], v[4:7]
	v_mfma_f32_16x16x32_bf16 v[0:3], v[202:205], v[186:189], v[0:3]
	s_add_i32 s51, s51, 2
	s_add_u32 s24, s24, 0x100
	s_addc_u32 s25, s25, 0
	s_add_u32 s46, s46, 0x100
	s_addc_u32 s50, s50, 0
	s_cmp_gt_u32 s51, 13
	s_barrier
	s_cbranch_scc0 .LBB0_823
	v_lshl_add_u32 v140, s35, 8, v142
	v_lshl_or_b32 v141, s34, 8, v144
	s_mov_b32 s34, s16
	s_mov_b32 s35, s18
	s_mov_b64 s[26:27], s[22:23]
	s_mov_b64 s[24:25], s[20:21]
	v_mbcnt_lo_u32_b32 v206, -1, 0
	v_mbcnt_hi_u32_b32 v206, -1, v206
	v_and_b32_e32 v206, 48, v206
	v_lshl_add_u32 v206, v140, 6, v206
	v_lshlrev_b32_e32 v207, 11, v140
	v_lshl_add_u32 v207, v141, 1, v207
	global_load_dwordx4 v[146:149], v206, s[14:15]
	global_load_dwordx4 v[150:153], v206, s[14:15] offset:1024
	global_load_dwordx4 v[154:157], v206, s[14:15] offset:2048
	global_load_dwordx4 v[158:161], v206, s[14:15] offset:3072
	v_add_u32_e32 v206, 0x2000, v206
	global_load_dwordx4 v[162:165], v206, s[14:15]
	global_load_dwordx4 v[166:169], v206, s[14:15] offset:1024
	global_load_dwordx4 v[170:173], v206, s[14:15] offset:2048
	global_load_dwordx4 v[174:177], v206, s[14:15] offset:3072
	s_waitcnt vmcnt(7)
	v_pk_add_f32 v[146:147], v[146:147], v[148:149]
	s_nop 0
	v_add_f32_e32 v214, v146, v147
	v_mov_b32_e32 v215, v214
	s_nop 1
	v_permlane16_swap_b32_e32 v214, v215
	s_nop 0
	v_add_f32_e32 v214, v214, v215
	v_mov_b32_e32 v215, v214
	s_nop 1
	v_permlane32_swap_b32_e32 v214, v215
	s_nop 0
	v_add_f32_e32 v214, v214, v215
	v_fmamk_f32 v214, v214, 0x3a800000, v248
	v_rsq_f32_e32 v178, v214
	s_nop 0
	v_pk_mul_f32 v[124:125], v[124:125], v[178:179] op_sel_hi:[1,0]
	v_pk_mul_f32 v[126:127], v[126:127], v[178:179] op_sel_hi:[1,0]
	v_pk_mul_f32 v[120:121], v[120:121], v[178:179] op_sel_hi:[1,0]
	v_pk_mul_f32 v[122:123], v[122:123], v[178:179] op_sel_hi:[1,0]
	v_cvt_pk_bf16_f32 v198, v124, v125
	v_cvt_pk_bf16_f32 v199, v126, v127
	v_cvt_pk_bf16_f32 v200, v120, v121
	v_cvt_pk_bf16_f32 v201, v122, v123
	global_store_dwordx4 v207, v[198:201], s[10:11]
	v_pk_mul_f32 v[116:117], v[116:117], v[178:179] op_sel_hi:[1,0]
	v_pk_mul_f32 v[118:119], v[118:119], v[178:179] op_sel_hi:[1,0]
	v_pk_mul_f32 v[112:113], v[112:113], v[178:179] op_sel_hi:[1,0]
	v_pk_mul_f32 v[114:115], v[114:115], v[178:179] op_sel_hi:[1,0]
	v_cvt_pk_bf16_f32 v202, v116, v117
	v_cvt_pk_bf16_f32 v203, v118, v119
	v_cvt_pk_bf16_f32 v204, v112, v113
	v_cvt_pk_bf16_f32 v205, v114, v115
	global_store_dwordx4 v207, v[202:205], s[10:11] offset:256
	v_add_u32_e32 v207, 0x8000, v207
	s_waitcnt vmcnt(8)
	v_pk_add_f32 v[150:151], v[150:151], v[152:153]
	s_nop 0
	v_add_f32_e32 v214, v150, v151
	v_mov_b32_e32 v215, v214
	s_nop 1
	v_permlane16_swap_b32_e32 v214, v215
	s_nop 0
	v_add_f32_e32 v214, v214, v215
	v_mov_b32_e32 v215, v214
	s_nop 1
	v_permlane32_swap_b32_e32 v214, v215
	s_nop 0
	v_add_f32_e32 v214, v214, v215
	v_fmamk_f32 v214, v214, 0x3a800000, v248
	v_rsq_f32_e32 v180, v214
	s_nop 0
	v_pk_mul_f32 v[108:109], v[108:109], v[180:181] op_sel_hi:[1,0]
	v_pk_mul_f32 v[110:111], v[110:111], v[180:181] op_sel_hi:[1,0]
	v_pk_mul_f32 v[104:105], v[104:105], v[180:181] op_sel_hi:[1,0]
	v_pk_mul_f32 v[106:107], v[106:107], v[180:181] op_sel_hi:[1,0]
	v_cvt_pk_bf16_f32 v198, v108, v109
	v_cvt_pk_bf16_f32 v199, v110, v111
	v_cvt_pk_bf16_f32 v200, v104, v105
	v_cvt_pk_bf16_f32 v201, v106, v107
	global_store_dwordx4 v207, v[198:201], s[10:11]
	v_pk_mul_f32 v[100:101], v[100:101], v[180:181] op_sel_hi:[1,0]
	v_pk_mul_f32 v[102:103], v[102:103], v[180:181] op_sel_hi:[1,0]
	v_pk_mul_f32 v[96:97], v[96:97], v[180:181] op_sel_hi:[1,0]
	v_pk_mul_f32 v[98:99], v[98:99], v[180:181] op_sel_hi:[1,0]
	v_cvt_pk_bf16_f32 v202, v100, v101
	v_cvt_pk_bf16_f32 v203, v102, v103
	v_cvt_pk_bf16_f32 v204, v96, v97
	v_cvt_pk_bf16_f32 v205, v98, v99
	global_store_dwordx4 v207, v[202:205], s[10:11] offset:256
	v_add_u32_e32 v207, 0x8000, v207
	s_waitcnt vmcnt(9)
	v_pk_add_f32 v[154:155], v[154:155], v[156:157]
	s_nop 0
	v_add_f32_e32 v214, v154, v155
	v_mov_b32_e32 v215, v214
	s_nop 1
	v_permlane16_swap_b32_e32 v214, v215
	s_nop 0
	v_add_f32_e32 v214, v214, v215
	v_mov_b32_e32 v215, v214
	s_nop 1
	v_permlane32_swap_b32_e32 v214, v215
	s_nop 0
	v_add_f32_e32 v214, v214, v215
	v_fmamk_f32 v214, v214, 0x3a800000, v248
	v_rsq_f32_e32 v182, v214
	s_nop 0
	v_pk_mul_f32 v[92:93], v[92:93], v[182:183] op_sel_hi:[1,0]
	v_pk_mul_f32 v[94:95], v[94:95], v[182:183] op_sel_hi:[1,0]
	v_pk_mul_f32 v[88:89], v[88:89], v[182:183] op_sel_hi:[1,0]
	v_pk_mul_f32 v[90:91], v[90:91], v[182:183] op_sel_hi:[1,0]
	v_cvt_pk_bf16_f32 v198, v92, v93
	v_cvt_pk_bf16_f32 v199, v94, v95
	v_cvt_pk_bf16_f32 v200, v88, v89
	v_cvt_pk_bf16_f32 v201, v90, v91
	global_store_dwordx4 v207, v[198:201], s[10:11]
	v_pk_mul_f32 v[84:85], v[84:85], v[182:183] op_sel_hi:[1,0]
	v_pk_mul_f32 v[86:87], v[86:87], v[182:183] op_sel_hi:[1,0]
	v_pk_mul_f32 v[80:81], v[80:81], v[182:183] op_sel_hi:[1,0]
	v_pk_mul_f32 v[82:83], v[82:83], v[182:183] op_sel_hi:[1,0]
	v_cvt_pk_bf16_f32 v202, v84, v85
	v_cvt_pk_bf16_f32 v203, v86, v87
	v_cvt_pk_bf16_f32 v204, v80, v81
	v_cvt_pk_bf16_f32 v205, v82, v83
	global_store_dwordx4 v207, v[202:205], s[10:11] offset:256
	v_add_u32_e32 v207, 0x8000, v207
	s_waitcnt vmcnt(10)
	v_pk_add_f32 v[158:159], v[158:159], v[160:161]
	s_nop 0
	v_add_f32_e32 v214, v158, v159
	v_mov_b32_e32 v215, v214
	s_nop 1
	v_permlane16_swap_b32_e32 v214, v215
	s_nop 0
	v_add_f32_e32 v214, v214, v215
	v_mov_b32_e32 v215, v214
	s_nop 1
	v_permlane32_swap_b32_e32 v214, v215
	s_nop 0
	v_add_f32_e32 v214, v214, v215
	v_fmamk_f32 v214, v214, 0x3a800000, v248
	v_rsq_f32_e32 v184, v214
	s_nop 0
	v_pk_mul_f32 v[76:77], v[76:77], v[184:185] op_sel_hi:[1,0]
	v_pk_mul_f32 v[78:79], v[78:79], v[184:185] op_sel_hi:[1,0]
	v_pk_mul_f32 v[72:73], v[72:73], v[184:185] op_sel_hi:[1,0]
	v_pk_mul_f32 v[74:75], v[74:75], v[184:185] op_sel_hi:[1,0]
	v_cvt_pk_bf16_f32 v198, v76, v77
	v_cvt_pk_bf16_f32 v199, v78, v79
	v_cvt_pk_bf16_f32 v200, v72, v73
	v_cvt_pk_bf16_f32 v201, v74, v75
	global_store_dwordx4 v207, v[198:201], s[10:11]
	v_pk_mul_f32 v[68:69], v[68:69], v[184:185] op_sel_hi:[1,0]
	v_pk_mul_f32 v[70:71], v[70:71], v[184:185] op_sel_hi:[1,0]
	v_pk_mul_f32 v[64:65], v[64:65], v[184:185] op_sel_hi:[1,0]
	v_pk_mul_f32 v[66:67], v[66:67], v[184:185] op_sel_hi:[1,0]
	v_cvt_pk_bf16_f32 v202, v68, v69
	v_cvt_pk_bf16_f32 v203, v70, v71
	v_cvt_pk_bf16_f32 v204, v64, v65
	v_cvt_pk_bf16_f32 v205, v66, v67
	global_store_dwordx4 v207, v[202:205], s[10:11] offset:256
	v_add_u32_e32 v207, 0x28000, v207
	s_waitcnt vmcnt(11)
	v_pk_add_f32 v[162:163], v[162:163], v[164:165]
	s_nop 0
	v_add_f32_e32 v214, v162, v163
	v_mov_b32_e32 v215, v214
	s_nop 1
	v_permlane16_swap_b32_e32 v214, v215
	s_nop 0
	v_add_f32_e32 v214, v214, v215
	v_mov_b32_e32 v215, v214
	s_nop 1
	v_permlane32_swap_b32_e32 v214, v215
	s_nop 0
	v_add_f32_e32 v214, v214, v215
	v_fmamk_f32 v214, v214, 0x3a800000, v248
	v_rsq_f32_e32 v186, v214
	s_nop 0
	v_pk_mul_f32 v[60:61], v[60:61], v[186:187] op_sel_hi:[1,0]
	v_pk_mul_f32 v[62:63], v[62:63], v[186:187] op_sel_hi:[1,0]
	v_pk_mul_f32 v[56:57], v[56:57], v[186:187] op_sel_hi:[1,0]
	v_pk_mul_f32 v[58:59], v[58:59], v[186:187] op_sel_hi:[1,0]
	v_cvt_pk_bf16_f32 v198, v60, v61
	v_cvt_pk_bf16_f32 v199, v62, v63
	v_cvt_pk_bf16_f32 v200, v56, v57
	v_cvt_pk_bf16_f32 v201, v58, v59
	global_store_dwordx4 v207, v[198:201], s[10:11]
	v_pk_mul_f32 v[52:53], v[52:53], v[186:187] op_sel_hi:[1,0]
	v_pk_mul_f32 v[54:55], v[54:55], v[186:187] op_sel_hi:[1,0]
	v_pk_mul_f32 v[48:49], v[48:49], v[186:187] op_sel_hi:[1,0]
	v_pk_mul_f32 v[50:51], v[50:51], v[186:187] op_sel_hi:[1,0]
	v_cvt_pk_bf16_f32 v202, v52, v53
	v_cvt_pk_bf16_f32 v203, v54, v55
	v_cvt_pk_bf16_f32 v204, v48, v49
	v_cvt_pk_bf16_f32 v205, v50, v51
	global_store_dwordx4 v207, v[202:205], s[10:11] offset:256
	v_add_u32_e32 v207, 0x8000, v207
	s_waitcnt vmcnt(12)
	v_pk_add_f32 v[166:167], v[166:167], v[168:169]
	s_nop 0
	v_add_f32_e32 v214, v166, v167
	v_mov_b32_e32 v215, v214
	s_nop 1
	v_permlane16_swap_b32_e32 v214, v215
	s_nop 0
	v_add_f32_e32 v214, v214, v215
	v_mov_b32_e32 v215, v214
	s_nop 1
	v_permlane32_swap_b32_e32 v214, v215
	s_nop 0
	v_add_f32_e32 v214, v214, v215
	v_fmamk_f32 v214, v214, 0x3a800000, v248
	v_rsq_f32_e32 v188, v214
	s_nop 0
	v_pk_mul_f32 v[44:45], v[44:45], v[188:189] op_sel_hi:[1,0]
	v_pk_mul_f32 v[46:47], v[46:47], v[188:189] op_sel_hi:[1,0]
	v_pk_mul_f32 v[40:41], v[40:41], v[188:189] op_sel_hi:[1,0]
	v_pk_mul_f32 v[42:43], v[42:43], v[188:189] op_sel_hi:[1,0]
	v_cvt_pk_bf16_f32 v198, v44, v45
	v_cvt_pk_bf16_f32 v199, v46, v47
	v_cvt_pk_bf16_f32 v200, v40, v41
	v_cvt_pk_bf16_f32 v201, v42, v43
	global_store_dwordx4 v207, v[198:201], s[10:11]
	v_pk_mul_f32 v[36:37], v[36:37], v[188:189] op_sel_hi:[1,0]
	v_pk_mul_f32 v[38:39], v[38:39], v[188:189] op_sel_hi:[1,0]
	v_pk_mul_f32 v[32:33], v[32:33], v[188:189] op_sel_hi:[1,0]
	v_pk_mul_f32 v[34:35], v[34:35], v[188:189] op_sel_hi:[1,0]
	v_cvt_pk_bf16_f32 v202, v36, v37
	v_cvt_pk_bf16_f32 v203, v38, v39
	v_cvt_pk_bf16_f32 v204, v32, v33
	v_cvt_pk_bf16_f32 v205, v34, v35
	global_store_dwordx4 v207, v[202:205], s[10:11] offset:256
	v_add_u32_e32 v207, 0x8000, v207
	s_waitcnt vmcnt(13)
	v_pk_add_f32 v[170:171], v[170:171], v[172:173]
	s_nop 0
	v_add_f32_e32 v214, v170, v171
	v_mov_b32_e32 v215, v214
	s_nop 1
	v_permlane16_swap_b32_e32 v214, v215
	s_nop 0
	v_add_f32_e32 v214, v214, v215
	v_mov_b32_e32 v215, v214
	s_nop 1
	v_permlane32_swap_b32_e32 v214, v215
	s_nop 0
	v_add_f32_e32 v214, v214, v215
	v_fmamk_f32 v214, v214, 0x3a800000, v248
	v_rsq_f32_e32 v190, v214
	s_nop 0
	v_pk_mul_f32 v[28:29], v[28:29], v[190:191] op_sel_hi:[1,0]
	v_pk_mul_f32 v[30:31], v[30:31], v[190:191] op_sel_hi:[1,0]
	v_pk_mul_f32 v[24:25], v[24:25], v[190:191] op_sel_hi:[1,0]
	v_pk_mul_f32 v[26:27], v[26:27], v[190:191] op_sel_hi:[1,0]
	v_cvt_pk_bf16_f32 v198, v28, v29
	v_cvt_pk_bf16_f32 v199, v30, v31
	v_cvt_pk_bf16_f32 v200, v24, v25
	v_cvt_pk_bf16_f32 v201, v26, v27
	global_store_dwordx4 v207, v[198:201], s[10:11]
	v_pk_mul_f32 v[20:21], v[20:21], v[190:191] op_sel_hi:[1,0]
	v_pk_mul_f32 v[22:23], v[22:23], v[190:191] op_sel_hi:[1,0]
	v_pk_mul_f32 v[16:17], v[16:17], v[190:191] op_sel_hi:[1,0]
	v_pk_mul_f32 v[18:19], v[18:19], v[190:191] op_sel_hi:[1,0]
	v_cvt_pk_bf16_f32 v202, v20, v21
	v_cvt_pk_bf16_f32 v203, v22, v23
	v_cvt_pk_bf16_f32 v204, v16, v17
	v_cvt_pk_bf16_f32 v205, v18, v19
	global_store_dwordx4 v207, v[202:205], s[10:11] offset:256
	v_add_u32_e32 v207, 0x8000, v207
	s_waitcnt vmcnt(14)
	v_pk_add_f32 v[174:175], v[174:175], v[176:177]
	s_nop 0
	v_add_f32_e32 v214, v174, v175
	v_mov_b32_e32 v215, v214
	s_nop 1
	v_permlane16_swap_b32_e32 v214, v215
	s_nop 0
	v_add_f32_e32 v214, v214, v215
	v_mov_b32_e32 v215, v214
	s_nop 1
	v_permlane32_swap_b32_e32 v214, v215
	s_nop 0
	v_add_f32_e32 v214, v214, v215
	v_fmamk_f32 v214, v214, 0x3a800000, v248
	v_rsq_f32_e32 v192, v214
	s_nop 0
	v_pk_mul_f32 v[12:13], v[12:13], v[192:193] op_sel_hi:[1,0]
	v_pk_mul_f32 v[14:15], v[14:15], v[192:193] op_sel_hi:[1,0]
	v_pk_mul_f32 v[8:9], v[8:9], v[192:193] op_sel_hi:[1,0]
	v_pk_mul_f32 v[10:11], v[10:11], v[192:193] op_sel_hi:[1,0]
	v_cvt_pk_bf16_f32 v198, v12, v13
	v_cvt_pk_bf16_f32 v199, v14, v15
	v_cvt_pk_bf16_f32 v200, v8, v9
	v_cvt_pk_bf16_f32 v201, v10, v11
	global_store_dwordx4 v207, v[198:201], s[10:11]
	v_pk_mul_f32 v[4:5], v[4:5], v[192:193] op_sel_hi:[1,0]
	v_pk_mul_f32 v[6:7], v[6:7], v[192:193] op_sel_hi:[1,0]
	v_pk_mul_f32 v[0:1], v[0:1], v[192:193] op_sel_hi:[1,0]
	v_pk_mul_f32 v[2:3], v[2:3], v[192:193] op_sel_hi:[1,0]
	v_cvt_pk_bf16_f32 v202, v4, v5
	v_cvt_pk_bf16_f32 v203, v6, v7
	v_cvt_pk_bf16_f32 v204, v0, v1
	v_cvt_pk_bf16_f32 v205, v2, v3
	global_store_dwordx4 v207, v[202:205], s[10:11] offset:256
	s_and_b64 vcc, exec, s[4:5]
	s_cbranch_vccz .LBB0_816
	s_waitcnt vmcnt(0)
	s_cmpk_gt_u32 s30, 0xff
	s_cbranch_scc1 .LBB0_827
	s_barrier

.LBB0_878:
	v_add_u32_e32 v206, 0x10000, v143
	s_add_u32 s26, s24, 0xfffc0080
	s_addc_u32 s27, s25, -1
	s_add_i32 s65, 0, 0x10000
	ds_read_b128 v[138:141], v206
	ds_read_b128 v[146:149], v206 offset:1024
	ds_read_b128 v[150:153], v206 offset:2048
	ds_read_b128 v[154:157], v206 offset:3072
	s_cmp_eq_u32 s64, 12
	s_cselect_b32 s29, s19, s27
	s_cselect_b32 s28, s39, s26
	s_cselect_b32 s27, s17, s63
	s_cselect_b32 s26, s61, s62
	s_add_i32 m0, s50, 0xc000
	ds_read_b128 v[158:161], v145
	ds_read_b128 v[162:165], v145 offset:1024
	ds_read_b128 v[166:169], v145 offset:2048
	ds_read_b128 v[170:173], v145 offset:3072
	ds_read_b128 v[174:177], v145 offset:4096
	ds_read_b128 v[178:181], v145 offset:5120
	ds_read_b128 v[182:185], v145 offset:6144
	ds_read_b128 v[186:189], v145 offset:7168
	global_load_lds_dwordx4 v134, s[24:25]
	s_add_i32 m0, s50, 0xe000
	s_nop 0
	global_load_lds_dwordx4 v136, s[24:25]
	s_waitcnt lgkmcnt(8)
	s_barrier
	s_waitcnt lgkmcnt(0)
	v_mfma_f32_16x16x32_bf16 v[124:127], v[138:141], v[158:161], v[124:127]
	v_mfma_f32_16x16x32_bf16 v[120:123], v[150:153], v[158:161], v[120:123]
	v_mfma_f32_16x16x32_bf16 v[108:111], v[138:141], v[166:169], v[108:111]
	v_mfma_f32_16x16x32_bf16 v[104:107], v[150:153], v[166:169], v[104:107]
	v_mfma_f32_16x16x32_bf16 v[92:95], v[138:141], v[174:177], v[92:95]
	v_mfma_f32_16x16x32_bf16 v[88:91], v[150:153], v[174:177], v[88:91]
	v_mfma_f32_16x16x32_bf16 v[76:79], v[138:141], v[182:185], v[76:79]
	v_mfma_f32_16x16x32_bf16 v[72:75], v[150:153], v[182:185], v[72:75]
	v_mfma_f32_16x16x32_bf16 v[124:127], v[146:149], v[162:165], v[124:127]
	v_mfma_f32_16x16x32_bf16 v[120:123], v[154:157], v[162:165], v[120:123]
	v_mfma_f32_16x16x32_bf16 v[108:111], v[146:149], v[170:173], v[108:111]
	v_mfma_f32_16x16x32_bf16 v[104:107], v[154:157], v[170:173], v[104:107]
	v_mfma_f32_16x16x32_bf16 v[92:95], v[146:149], v[178:181], v[92:95]
	v_mfma_f32_16x16x32_bf16 v[88:91], v[154:157], v[178:181], v[88:91]
	v_mfma_f32_16x16x32_bf16 v[76:79], v[146:149], v[186:189], v[76:79]
	v_mfma_f32_16x16x32_bf16 v[72:75], v[154:157], v[186:189], v[72:75]
	s_barrier
	s_add_i32 s68, 0, 0x14000
	s_add_i32 s65, s65, s47
	s_add_u32 s98, s26, s40
	s_addc_u32 s99, s27, s41
	s_mov_b32 m0, s65
	ds_read_b128 v[190:193], v206 offset:16384
	ds_read_b128 v[194:197], v206 offset:17408
	ds_read_b128 v[198:201], v206 offset:18432
	ds_read_b128 v[202:205], v206 offset:19456
	global_load_lds_dwordx4 v208, s[26:27]
	s_add_i32 m0, s65, 0x2000
	s_nop 0
	global_load_lds_dwordx4 v128, s[26:27]
	s_barrier
	s_waitcnt lgkmcnt(0)
	v_mfma_f32_16x16x32_bf16 v[116:119], v[190:193], v[158:161], v[116:119]
	v_mfma_f32_16x16x32_bf16 v[112:115], v[198:201], v[158:161], v[112:115]
	v_mfma_f32_16x16x32_bf16 v[100:103], v[190:193], v[166:169], v[100:103]
	v_mfma_f32_16x16x32_bf16 v[96:99], v[198:201], v[166:169], v[96:99]
	v_mfma_f32_16x16x32_bf16 v[84:87], v[190:193], v[174:177], v[84:87]
	v_mfma_f32_16x16x32_bf16 v[80:83], v[198:201], v[174:177], v[80:83]
	v_mfma_f32_16x16x32_bf16 v[68:71], v[190:193], v[182:185], v[68:71]
	v_mfma_f32_16x16x32_bf16 v[64:67], v[198:201], v[182:185], v[64:67]
	v_mfma_f32_16x16x32_bf16 v[116:119], v[194:197], v[162:165], v[116:119]
	v_mfma_f32_16x16x32_bf16 v[112:115], v[202:205], v[162:165], v[112:115]
	v_mfma_f32_16x16x32_bf16 v[100:103], v[194:197], v[170:173], v[100:103]
	v_mfma_f32_16x16x32_bf16 v[96:99], v[202:205], v[170:173], v[96:99]
	v_mfma_f32_16x16x32_bf16 v[84:87], v[194:197], v[178:181], v[84:87]
	v_mfma_f32_16x16x32_bf16 v[80:83], v[202:205], v[178:181], v[80:83]
	v_mfma_f32_16x16x32_bf16 v[68:71], v[194:197], v[186:189], v[68:71]
	v_mfma_f32_16x16x32_bf16 v[64:67], v[202:205], v[186:189], v[64:67]
	s_mov_b32 m0, s50
	s_add_u32 s100, s28, s40
	s_addc_u32 s101, s29, s41
	s_barrier
	ds_read_b128 v[158:161], v145 offset:16384
	ds_read_b128 v[162:165], v145 offset:17408
	ds_read_b128 v[166:169], v145 offset:18432
	ds_read_b128 v[170:173], v145 offset:19456
	ds_read_b128 v[174:177], v145 offset:20480
	ds_read_b128 v[178:181], v145 offset:21504
	ds_read_b128 v[182:185], v145 offset:22528
	ds_read_b128 v[186:189], v145 offset:23552
	global_load_lds_dwordx4 v132, s[28:29]
	s_mov_b32 m0, s51
	s_nop 0
	global_load_lds_dwordx4 v130, s[28:29]
	s_barrier
	s_waitcnt lgkmcnt(0)
	v_mfma_f32_16x16x32_bf16 v[60:63], v[138:141], v[158:161], v[60:63]
	v_mfma_f32_16x16x32_bf16 v[56:59], v[150:153], v[158:161], v[56:59]
	v_mfma_f32_16x16x32_bf16 v[44:47], v[138:141], v[166:169], v[44:47]
	v_mfma_f32_16x16x32_bf16 v[40:43], v[150:153], v[166:169], v[40:43]
	v_mfma_f32_16x16x32_bf16 v[28:31], v[138:141], v[174:177], v[28:31]
	v_mfma_f32_16x16x32_bf16 v[24:27], v[150:153], v[174:177], v[24:27]
	v_mfma_f32_16x16x32_bf16 v[12:15], v[138:141], v[182:185], v[12:15]
	v_mfma_f32_16x16x32_bf16 v[8:11], v[150:153], v[182:185], v[8:11]
	v_mfma_f32_16x16x32_bf16 v[60:63], v[146:149], v[162:165], v[60:63]
	v_mfma_f32_16x16x32_bf16 v[56:59], v[154:157], v[162:165], v[56:59]
	v_mfma_f32_16x16x32_bf16 v[44:47], v[146:149], v[170:173], v[44:47]
	v_mfma_f32_16x16x32_bf16 v[40:43], v[154:157], v[170:173], v[40:43]
	v_mfma_f32_16x16x32_bf16 v[28:31], v[146:149], v[178:181], v[28:31]
	v_mfma_f32_16x16x32_bf16 v[24:27], v[154:157], v[178:181], v[24:27]
	v_mfma_f32_16x16x32_bf16 v[12:15], v[146:149], v[186:189], v[12:15]
	v_mfma_f32_16x16x32_bf16 v[8:11], v[154:157], v[186:189], v[8:11]
	s_barrier
	s_add_u32 s66, s26, 0x40000
	s_addc_u32 s67, s27, 0
	s_add_i32 s65, s68, s47
	s_mov_b32 m0, s65
	s_nop 0
	global_load_lds_dwordx4 v208, s[66:67]
	s_add_i32 m0, s65, 0x2000
	s_nop 0
	global_load_lds_dwordx4 v128, s[66:67]
	s_waitcnt vmcnt(6)
	s_barrier
	v_mfma_f32_16x16x32_bf16 v[52:55], v[190:193], v[158:161], v[52:55]
	v_mfma_f32_16x16x32_bf16 v[48:51], v[198:201], v[158:161], v[48:51]
	v_mfma_f32_16x16x32_bf16 v[36:39], v[190:193], v[166:169], v[36:39]
	v_mfma_f32_16x16x32_bf16 v[32:35], v[198:201], v[166:169], v[32:35]
	v_mfma_f32_16x16x32_bf16 v[20:23], v[190:193], v[174:177], v[20:23]
	v_mfma_f32_16x16x32_bf16 v[16:19], v[198:201], v[174:177], v[16:19]
	v_mfma_f32_16x16x32_bf16 v[4:7], v[190:193], v[182:185], v[4:7]
	v_mfma_f32_16x16x32_bf16 v[0:3], v[198:201], v[182:185], v[0:3]
	v_mfma_f32_16x16x32_bf16 v[52:55], v[194:197], v[162:165], v[52:55]
	v_mfma_f32_16x16x32_bf16 v[48:51], v[202:205], v[162:165], v[48:51]
	v_mfma_f32_16x16x32_bf16 v[36:39], v[194:197], v[170:173], v[36:39]
	v_mfma_f32_16x16x32_bf16 v[32:35], v[202:205], v[170:173], v[32:35]
	v_mfma_f32_16x16x32_bf16 v[20:23], v[194:197], v[178:181], v[20:23]
	v_mfma_f32_16x16x32_bf16 v[16:19], v[202:205], v[178:181], v[16:19]
	v_mfma_f32_16x16x32_bf16 v[4:7], v[194:197], v[186:189], v[4:7]
	v_mfma_f32_16x16x32_bf16 v[0:3], v[202:205], v[186:189], v[0:3]
	s_add_i32 s65, 0, 0x18000
	s_barrier
	ds_read_b128 v[138:141], v206 offset:32768
	ds_read_b128 v[146:149], v206 offset:33792
	ds_read_b128 v[150:153], v206 offset:34816
	ds_read_b128 v[154:157], v206 offset:35840
	s_add_u32 s28, s28, 0x40000
	s_addc_u32 s29, s29, 0
	s_mov_b32 m0, s53
	ds_read_b128 v[158:161], v145 offset:32768
	ds_read_b128 v[162:165], v145 offset:33792
	ds_read_b128 v[166:169], v145 offset:34816
	ds_read_b128 v[170:173], v145 offset:35840
	ds_read_b128 v[174:177], v145 offset:36864
	ds_read_b128 v[178:181], v145 offset:37888
	ds_read_b128 v[182:185], v145 offset:38912
	ds_read_b128 v[186:189], v145 offset:39936
	global_load_lds_dwordx4 v132, s[28:29]
	s_mov_b32 m0, s56
	s_nop 0
	global_load_lds_dwordx4 v130, s[28:29]
	s_waitcnt lgkmcnt(8)
	s_barrier
	s_waitcnt lgkmcnt(0)
	v_mfma_f32_16x16x32_bf16 v[124:127], v[138:141], v[158:161], v[124:127]
	v_mfma_f32_16x16x32_bf16 v[120:123], v[150:153], v[158:161], v[120:123]
	v_mfma_f32_16x16x32_bf16 v[108:111], v[138:141], v[166:169], v[108:111]
	v_mfma_f32_16x16x32_bf16 v[104:107], v[150:153], v[166:169], v[104:107]
	v_mfma_f32_16x16x32_bf16 v[92:95], v[138:141], v[174:177], v[92:95]
	v_mfma_f32_16x16x32_bf16 v[88:91], v[150:153], v[174:177], v[88:91]
	v_mfma_f32_16x16x32_bf16 v[76:79], v[138:141], v[182:185], v[76:79]
	v_mfma_f32_16x16x32_bf16 v[72:75], v[150:153], v[182:185], v[72:75]
	v_mfma_f32_16x16x32_bf16 v[124:127], v[146:149], v[162:165], v[124:127]
	v_mfma_f32_16x16x32_bf16 v[120:123], v[154:157], v[162:165], v[120:123]
	v_mfma_f32_16x16x32_bf16 v[108:111], v[146:149], v[170:173], v[108:111]
	v_mfma_f32_16x16x32_bf16 v[104:107], v[154:157], v[170:173], v[104:107]
	v_mfma_f32_16x16x32_bf16 v[92:95], v[146:149], v[178:181], v[92:95]
	v_mfma_f32_16x16x32_bf16 v[88:91], v[154:157], v[178:181], v[88:91]
	v_mfma_f32_16x16x32_bf16 v[76:79], v[146:149], v[186:189], v[76:79]
	v_mfma_f32_16x16x32_bf16 v[72:75], v[154:157], v[186:189], v[72:75]
	s_barrier
	s_add_i32 s28, 0, 0x1c000
	s_add_i32 s29, s65, s47
	s_mov_b32 m0, s29
	ds_read_b128 v[190:193], v206 offset:49152
	ds_read_b128 v[194:197], v206 offset:50176
	ds_read_b128 v[198:201], v206 offset:51200
	ds_read_b128 v[202:205], v206 offset:52224
	global_load_lds_dwordx4 v208, s[98:99]
	s_add_i32 m0, s29, 0x2000
	s_nop 0
	global_load_lds_dwordx4 v128, s[98:99]
	s_barrier
	s_waitcnt lgkmcnt(0)
	v_mfma_f32_16x16x32_bf16 v[116:119], v[190:193], v[158:161], v[116:119]
	v_mfma_f32_16x16x32_bf16 v[112:115], v[198:201], v[158:161], v[112:115]
	v_mfma_f32_16x16x32_bf16 v[100:103], v[190:193], v[166:169], v[100:103]
	v_mfma_f32_16x16x32_bf16 v[96:99], v[198:201], v[166:169], v[96:99]
	v_mfma_f32_16x16x32_bf16 v[84:87], v[190:193], v[174:177], v[84:87]
	v_mfma_f32_16x16x32_bf16 v[80:83], v[198:201], v[174:177], v[80:83]
	v_mfma_f32_16x16x32_bf16 v[68:71], v[190:193], v[182:185], v[68:71]
	v_mfma_f32_16x16x32_bf16 v[64:67], v[198:201], v[182:185], v[64:67]
	v_mfma_f32_16x16x32_bf16 v[116:119], v[194:197], v[162:165], v[116:119]
	v_mfma_f32_16x16x32_bf16 v[112:115], v[202:205], v[162:165], v[112:115]
	v_mfma_f32_16x16x32_bf16 v[100:103], v[194:197], v[170:173], v[100:103]
	v_mfma_f32_16x16x32_bf16 v[96:99], v[202:205], v[170:173], v[96:99]
	v_mfma_f32_16x16x32_bf16 v[84:87], v[194:197], v[178:181], v[84:87]
	v_mfma_f32_16x16x32_bf16 v[80:83], v[202:205], v[178:181], v[80:83]
	v_mfma_f32_16x16x32_bf16 v[68:71], v[194:197], v[186:189], v[68:71]
	v_mfma_f32_16x16x32_bf16 v[64:67], v[202:205], v[186:189], v[64:67]
	s_mov_b32 m0, s58
	s_barrier
	ds_read_b128 v[158:161], v145 offset:49152
	ds_read_b128 v[162:165], v145 offset:50176
	ds_read_b128 v[166:169], v145 offset:51200
	ds_read_b128 v[170:173], v145 offset:52224
	ds_read_b128 v[174:177], v145 offset:53248
	ds_read_b128 v[178:181], v145 offset:54272
	ds_read_b128 v[182:185], v145 offset:55296
	ds_read_b128 v[186:189], v145 offset:56320
	global_load_lds_dwordx4 v132, s[100:101]
	s_mov_b32 m0, s59
	s_nop 0
	global_load_lds_dwordx4 v130, s[100:101]
	s_barrier
	s_waitcnt lgkmcnt(0)
	v_mfma_f32_16x16x32_bf16 v[60:63], v[138:141], v[158:161], v[60:63]
	v_mfma_f32_16x16x32_bf16 v[56:59], v[150:153], v[158:161], v[56:59]
	v_mfma_f32_16x16x32_bf16 v[44:47], v[138:141], v[166:169], v[44:47]
	v_mfma_f32_16x16x32_bf16 v[40:43], v[150:153], v[166:169], v[40:43]
	v_mfma_f32_16x16x32_bf16 v[28:31], v[138:141], v[174:177], v[28:31]
	v_mfma_f32_16x16x32_bf16 v[24:27], v[150:153], v[174:177], v[24:27]
	v_mfma_f32_16x16x32_bf16 v[12:15], v[138:141], v[182:185], v[12:15]
	v_mfma_f32_16x16x32_bf16 v[8:11], v[150:153], v[182:185], v[8:11]
	v_mfma_f32_16x16x32_bf16 v[60:63], v[146:149], v[162:165], v[60:63]
	v_mfma_f32_16x16x32_bf16 v[56:59], v[154:157], v[162:165], v[56:59]
	v_mfma_f32_16x16x32_bf16 v[44:47], v[146:149], v[170:173], v[44:47]
	v_mfma_f32_16x16x32_bf16 v[40:43], v[154:157], v[170:173], v[40:43]
	v_mfma_f32_16x16x32_bf16 v[28:31], v[146:149], v[178:181], v[28:31]
	v_mfma_f32_16x16x32_bf16 v[24:27], v[154:157], v[178:181], v[24:27]
	v_mfma_f32_16x16x32_bf16 v[12:15], v[146:149], v[186:189], v[12:15]
	v_mfma_f32_16x16x32_bf16 v[8:11], v[154:157], v[186:189], v[8:11]
	s_barrier
	s_add_u32 s26, s26, 0x40080
	s_addc_u32 s27, s27, 0
	s_add_i32 s28, s28, s47
	s_mov_b32 m0, s28
	s_nop 0
	global_load_lds_dwordx4 v208, s[26:27]
	s_add_i32 m0, s28, 0x2000
	s_nop 0
	global_load_lds_dwordx4 v128, s[26:27]
	s_waitcnt vmcnt(6)
	s_barrier
	v_mfma_f32_16x16x32_bf16 v[52:55], v[190:193], v[158:161], v[52:55]
	v_mfma_f32_16x16x32_bf16 v[48:51], v[198:201], v[158:161], v[48:51]
	v_mfma_f32_16x16x32_bf16 v[36:39], v[190:193], v[166:169], v[36:39]
	v_mfma_f32_16x16x32_bf16 v[32:35], v[198:201], v[166:169], v[32:35]
	v_mfma_f32_16x16x32_bf16 v[20:23], v[190:193], v[174:177], v[20:23]
	v_mfma_f32_16x16x32_bf16 v[16:19], v[198:201], v[174:177], v[16:19]
	v_mfma_f32_16x16x32_bf16 v[4:7], v[190:193], v[182:185], v[4:7]
	v_mfma_f32_16x16x32_bf16 v[0:3], v[198:201], v[182:185], v[0:3]
	v_mfma_f32_16x16x32_bf16 v[52:55], v[194:197], v[162:165], v[52:55]
	v_mfma_f32_16x16x32_bf16 v[48:51], v[202:205], v[162:165], v[48:51]
	v_mfma_f32_16x16x32_bf16 v[36:39], v[194:197], v[170:173], v[36:39]
	v_mfma_f32_16x16x32_bf16 v[32:35], v[202:205], v[170:173], v[32:35]
	v_mfma_f32_16x16x32_bf16 v[20:23], v[194:197], v[178:181], v[20:23]
	v_mfma_f32_16x16x32_bf16 v[16:19], v[202:205], v[178:181], v[16:19]
	v_mfma_f32_16x16x32_bf16 v[4:7], v[194:197], v[186:189], v[4:7]
	v_mfma_f32_16x16x32_bf16 v[0:3], v[202:205], v[186:189], v[0:3]
	s_add_i32 s64, s64, 2
	s_add_u32 s24, s24, 0x100
	s_addc_u32 s25, s25, 0
	s_add_u32 s62, s62, 0x100
	s_addc_u32 s63, s63, 0
	s_cmp_gt_u32 s64, 13
	s_barrier
	s_cbranch_scc0 .LBB0_878
	v_lshl_add_u32 v140, s38, 8, v142
	v_lshl_or_b32 v141, s36, 8, v144
	s_lshl_b32 s24, s36, 2
	s_ashr_i32 s25, s24, 31
	s_lshl_b32 s36, s57, 2
	v_lshlrev_b32_e32 v206, 11, v140
	v_lshl_add_u32 v206, v141, 1, v206
	v_lshl_add_u32 v210, v140, 6, s36
	v_lshl_add_u32 v210, s24, 2, v210
	v_mov_b32_e32 v207, v206
	global_load_dwordx4 v[146:149], v206, s[8:9]
	global_load_dwordx4 v[150:153], v206, s[8:9] offset:256
	v_add_u32_e32 v206, 0x8000, v206
	global_load_dwordx4 v[154:157], v206, s[8:9]
	global_load_dwordx4 v[158:161], v206, s[8:9] offset:256
	v_add_u32_e32 v206, 0x8000, v206
	global_load_dwordx4 v[162:165], v206, s[8:9]
	global_load_dwordx4 v[166:169], v206, s[8:9] offset:256
	v_add_u32_e32 v206, 0x8000, v206
	global_load_dwordx4 v[170:173], v206, s[8:9]
	global_load_dwordx4 v[174:177], v206, s[8:9] offset:256
	v_add_u32_e32 v206, 0x28000, v206
	global_load_dwordx4 v[178:181], v206, s[8:9]
	global_load_dwordx4 v[182:185], v206, s[8:9] offset:256
	v_add_u32_e32 v206, 0x8000, v206
	global_load_dwordx4 v[186:189], v206, s[8:9]
	global_load_dwordx4 v[190:193], v206, s[8:9] offset:256
	v_add_u32_e32 v206, 0x8000, v206
	global_load_dwordx4 v[194:197], v206, s[8:9]
	global_load_dwordx4 v[198:201], v206, s[8:9] offset:256
	v_add_u32_e32 v206, 0x8000, v206
	s_waitcnt vmcnt(12)
	v_lshlrev_b32_e32 v202, 16, v146
	v_and_b32_e32 v203, 0xffff0000, v146
	v_lshlrev_b32_e32 v204, 16, v147
	v_and_b32_e32 v205, 0xffff0000, v147
	v_pk_add_f32 v[124:125], v[124:125], v[202:203]
	v_pk_add_f32 v[126:127], v[126:127], v[204:205]
	v_lshlrev_b32_e32 v202, 16, v148
	v_and_b32_e32 v203, 0xffff0000, v148
	v_lshlrev_b32_e32 v204, 16, v149
	v_and_b32_e32 v205, 0xffff0000, v149
	v_pk_add_f32 v[120:121], v[120:121], v[202:203]
	v_pk_add_f32 v[122:123], v[122:123], v[204:205]
	v_cvt_pk_bf16_f32 v146, v124, v125
	v_cvt_pk_bf16_f32 v147, v126, v127
	v_cvt_pk_bf16_f32 v148, v120, v121
	v_cvt_pk_bf16_f32 v149, v122, v123
	v_pk_mul_f32 v[138:139], v[124:125], v[124:125]
	global_store_dwordx4 v207, v[146:149], s[8:9]
	v_pk_fma_f32 v[138:139], v[126:127], v[126:127], v[138:139]
	v_pk_fma_f32 v[138:139], v[120:121], v[120:121], v[138:139]
	v_pk_fma_f32 v[138:139], v[122:123], v[122:123], v[138:139]
	v_lshlrev_b32_e32 v202, 16, v150
	v_and_b32_e32 v203, 0xffff0000, v150
	v_lshlrev_b32_e32 v204, 16, v151
	v_and_b32_e32 v205, 0xffff0000, v151
	v_pk_add_f32 v[116:117], v[116:117], v[202:203]
	v_pk_add_f32 v[118:119], v[118:119], v[204:205]
	v_lshlrev_b32_e32 v202, 16, v152
	v_and_b32_e32 v203, 0xffff0000, v152
	v_lshlrev_b32_e32 v204, 16, v153
	v_and_b32_e32 v205, 0xffff0000, v153
	v_pk_add_f32 v[112:113], v[112:113], v[202:203]
	v_pk_add_f32 v[114:115], v[114:115], v[204:205]
	v_cvt_pk_bf16_f32 v150, v116, v117
	v_cvt_pk_bf16_f32 v151, v118, v119
	v_cvt_pk_bf16_f32 v152, v112, v113
	v_cvt_pk_bf16_f32 v153, v114, v115
	v_pk_fma_f32 v[138:139], v[116:117], v[116:117], v[138:139]
	global_store_dwordx4 v207, v[150:153], s[8:9] offset:256
	v_pk_fma_f32 v[138:139], v[118:119], v[118:119], v[138:139]
	v_pk_fma_f32 v[138:139], v[112:113], v[112:113], v[138:139]
	v_pk_fma_f32 v[138:139], v[114:115], v[114:115], v[138:139]
	v_add_f32_e32 v214, v138, v139
	v_add_u32_e32 v207, 0x8000, v207
	v_mov_b32_e32 v215, v214
	s_nop 1
	v_permlane16_swap_b32_e32 v214, v215
	s_nop 0
	v_add_f32_e32 v214, v214, v215
	v_mov_b32_e32 v215, v214
	s_nop 1
	v_permlane32_swap_b32_e32 v214, v215
	s_nop 0
	v_add_f32_e32 v214, v214, v215
	s_and_saveexec_b64 s[26:27], s[4:5]
	global_store_dword v210, v214, s[14:15]
	s_mov_b64 exec, s[26:27]
	global_load_dwordx4 v[146:149], v206, s[8:9]
	global_load_dwordx4 v[150:153], v206, s[8:9] offset:256
	s_waitcnt vmcnt(15)
	v_lshlrev_b32_e32 v202, 16, v154
	v_and_b32_e32 v203, 0xffff0000, v154
	v_lshlrev_b32_e32 v204, 16, v155
	v_and_b32_e32 v205, 0xffff0000, v155
	v_pk_add_f32 v[108:109], v[108:109], v[202:203]
	v_pk_add_f32 v[110:111], v[110:111], v[204:205]
	v_lshlrev_b32_e32 v202, 16, v156
	v_and_b32_e32 v203, 0xffff0000, v156
	v_lshlrev_b32_e32 v204, 16, v157
	v_and_b32_e32 v205, 0xffff0000, v157
	v_pk_add_f32 v[104:105], v[104:105], v[202:203]
	v_pk_add_f32 v[106:107], v[106:107], v[204:205]
	v_cvt_pk_bf16_f32 v154, v108, v109
	v_cvt_pk_bf16_f32 v155, v110, v111
	v_cvt_pk_bf16_f32 v156, v104, v105
	v_cvt_pk_bf16_f32 v157, v106, v107
	v_pk_mul_f32 v[138:139], v[108:109], v[108:109]
	global_store_dwordx4 v207, v[154:157], s[8:9]
	v_pk_fma_f32 v[138:139], v[110:111], v[110:111], v[138:139]
	v_pk_fma_f32 v[138:139], v[104:105], v[104:105], v[138:139]
	v_pk_fma_f32 v[138:139], v[106:107], v[106:107], v[138:139]
	v_lshlrev_b32_e32 v202, 16, v158
	v_and_b32_e32 v203, 0xffff0000, v158
	v_lshlrev_b32_e32 v204, 16, v159
	v_and_b32_e32 v205, 0xffff0000, v159
	v_pk_add_f32 v[100:101], v[100:101], v[202:203]
	v_pk_add_f32 v[102:103], v[102:103], v[204:205]
	v_lshlrev_b32_e32 v202, 16, v160
	v_and_b32_e32 v203, 0xffff0000, v160
	v_lshlrev_b32_e32 v204, 16, v161
	v_and_b32_e32 v205, 0xffff0000, v161
	v_pk_add_f32 v[96:97], v[96:97], v[202:203]
	v_pk_add_f32 v[98:99], v[98:99], v[204:205]
	v_cvt_pk_bf16_f32 v158, v100, v101
	v_cvt_pk_bf16_f32 v159, v102, v103
	v_cvt_pk_bf16_f32 v160, v96, v97
	v_cvt_pk_bf16_f32 v161, v98, v99
	v_pk_fma_f32 v[138:139], v[100:101], v[100:101], v[138:139]
	global_store_dwordx4 v207, v[158:161], s[8:9] offset:256
	v_pk_fma_f32 v[138:139], v[102:103], v[102:103], v[138:139]
	v_pk_fma_f32 v[138:139], v[96:97], v[96:97], v[138:139]
	v_pk_fma_f32 v[138:139], v[98:99], v[98:99], v[138:139]
	v_add_f32_e32 v214, v138, v139
	v_add_u32_e32 v207, 0x8000, v207
	v_mov_b32_e32 v215, v214
	s_nop 1
	v_permlane16_swap_b32_e32 v214, v215
	s_nop 0
	v_add_f32_e32 v214, v214, v215
	v_mov_b32_e32 v215, v214
	s_nop 1
	v_permlane32_swap_b32_e32 v214, v215
	s_nop 0
	v_add_f32_e32 v214, v214, v215
	s_and_saveexec_b64 s[26:27], s[4:5]
	global_store_dword v210, v214, s[14:15] offset:1024
	s_mov_b64 exec, s[26:27]
	s_waitcnt vmcnt(16)
	v_lshlrev_b32_e32 v202, 16, v162
	v_and_b32_e32 v203, 0xffff0000, v162
	v_lshlrev_b32_e32 v204, 16, v163
	v_and_b32_e32 v205, 0xffff0000, v163
	v_pk_add_f32 v[92:93], v[92:93], v[202:203]
	v_pk_add_f32 v[94:95], v[94:95], v[204:205]
	v_lshlrev_b32_e32 v202, 16, v164
	v_and_b32_e32 v203, 0xffff0000, v164
	v_lshlrev_b32_e32 v204, 16, v165
	v_and_b32_e32 v205, 0xffff0000, v165
	v_pk_add_f32 v[88:89], v[88:89], v[202:203]
	v_pk_add_f32 v[90:91], v[90:91], v[204:205]
	v_cvt_pk_bf16_f32 v162, v92, v93
	v_cvt_pk_bf16_f32 v163, v94, v95
	v_cvt_pk_bf16_f32 v164, v88, v89
	v_cvt_pk_bf16_f32 v165, v90, v91
	v_pk_mul_f32 v[138:139], v[92:93], v[92:93]
	global_store_dwordx4 v207, v[162:165], s[8:9]
	v_pk_fma_f32 v[138:139], v[94:95], v[94:95], v[138:139]
	v_pk_fma_f32 v[138:139], v[88:89], v[88:89], v[138:139]
	v_pk_fma_f32 v[138:139], v[90:91], v[90:91], v[138:139]
	v_lshlrev_b32_e32 v202, 16, v166
	v_and_b32_e32 v203, 0xffff0000, v166
	v_lshlrev_b32_e32 v204, 16, v167
	v_and_b32_e32 v205, 0xffff0000, v167
	v_pk_add_f32 v[84:85], v[84:85], v[202:203]
	v_pk_add_f32 v[86:87], v[86:87], v[204:205]
	v_lshlrev_b32_e32 v202, 16, v168
	v_and_b32_e32 v203, 0xffff0000, v168
	v_lshlrev_b32_e32 v204, 16, v169
	v_and_b32_e32 v205, 0xffff0000, v169
	v_pk_add_f32 v[80:81], v[80:81], v[202:203]
	v_pk_add_f32 v[82:83], v[82:83], v[204:205]
	v_cvt_pk_bf16_f32 v166, v84, v85
	v_cvt_pk_bf16_f32 v167, v86, v87
	v_cvt_pk_bf16_f32 v168, v80, v81
	v_cvt_pk_bf16_f32 v169, v82, v83
	v_pk_fma_f32 v[138:139], v[84:85], v[84:85], v[138:139]
	global_store_dwordx4 v207, v[166:169], s[8:9] offset:256
	v_pk_fma_f32 v[138:139], v[86:87], v[86:87], v[138:139]
	v_pk_fma_f32 v[138:139], v[80:81], v[80:81], v[138:139]
	v_pk_fma_f32 v[138:139], v[82:83], v[82:83], v[138:139]
	v_add_f32_e32 v214, v138, v139
	v_add_u32_e32 v207, 0x8000, v207
	v_mov_b32_e32 v215, v214
	s_nop 1
	v_permlane16_swap_b32_e32 v214, v215
	s_nop 0
	v_add_f32_e32 v214, v214, v215
	v_mov_b32_e32 v215, v214
	s_nop 1
	v_permlane32_swap_b32_e32 v214, v215
	s_nop 0
	v_add_f32_e32 v214, v214, v215
	s_and_saveexec_b64 s[26:27], s[4:5]
	global_store_dword v210, v214, s[14:15] offset:2048
	s_mov_b64 exec, s[26:27]
	s_waitcnt vmcnt(17)
	v_lshlrev_b32_e32 v202, 16, v170
	v_and_b32_e32 v203, 0xffff0000, v170
	v_lshlrev_b32_e32 v204, 16, v171
	v_and_b32_e32 v205, 0xffff0000, v171
	v_pk_add_f32 v[76:77], v[76:77], v[202:203]
	v_pk_add_f32 v[78:79], v[78:79], v[204:205]
	v_lshlrev_b32_e32 v202, 16, v172
	v_and_b32_e32 v203, 0xffff0000, v172
	v_lshlrev_b32_e32 v204, 16, v173
	v_and_b32_e32 v205, 0xffff0000, v173
	v_pk_add_f32 v[72:73], v[72:73], v[202:203]
	v_pk_add_f32 v[74:75], v[74:75], v[204:205]
	v_cvt_pk_bf16_f32 v170, v76, v77
	v_cvt_pk_bf16_f32 v171, v78, v79
	v_cvt_pk_bf16_f32 v172, v72, v73
	v_cvt_pk_bf16_f32 v173, v74, v75
	v_pk_mul_f32 v[138:139], v[76:77], v[76:77]
	global_store_dwordx4 v207, v[170:173], s[8:9]
	v_pk_fma_f32 v[138:139], v[78:79], v[78:79], v[138:139]
	v_pk_fma_f32 v[138:139], v[72:73], v[72:73], v[138:139]
	v_pk_fma_f32 v[138:139], v[74:75], v[74:75], v[138:139]
	v_lshlrev_b32_e32 v202, 16, v174
	v_and_b32_e32 v203, 0xffff0000, v174
	v_lshlrev_b32_e32 v204, 16, v175
	v_and_b32_e32 v205, 0xffff0000, v175
	v_pk_add_f32 v[68:69], v[68:69], v[202:203]
	v_pk_add_f32 v[70:71], v[70:71], v[204:205]
	v_lshlrev_b32_e32 v202, 16, v176
	v_and_b32_e32 v203, 0xffff0000, v176
	v_lshlrev_b32_e32 v204, 16, v177
	v_and_b32_e32 v205, 0xffff0000, v177
	v_pk_add_f32 v[64:65], v[64:65], v[202:203]
	v_pk_add_f32 v[66:67], v[66:67], v[204:205]
	v_cvt_pk_bf16_f32 v174, v68, v69
	v_cvt_pk_bf16_f32 v175, v70, v71
	v_cvt_pk_bf16_f32 v176, v64, v65
	v_cvt_pk_bf16_f32 v177, v66, v67
	v_pk_fma_f32 v[138:139], v[68:69], v[68:69], v[138:139]
	global_store_dwordx4 v207, v[174:177], s[8:9] offset:256
	v_pk_fma_f32 v[138:139], v[70:71], v[70:71], v[138:139]
	v_pk_fma_f32 v[138:139], v[64:65], v[64:65], v[138:139]
	v_pk_fma_f32 v[138:139], v[66:67], v[66:67], v[138:139]
	v_add_f32_e32 v214, v138, v139
	v_add_u32_e32 v207, 0x28000, v207
	v_mov_b32_e32 v215, v214
	s_nop 1
	v_permlane16_swap_b32_e32 v214, v215
	s_nop 0
	v_add_f32_e32 v214, v214, v215
	v_mov_b32_e32 v215, v214
	s_nop 1
	v_permlane32_swap_b32_e32 v214, v215
	s_nop 0
	v_add_f32_e32 v214, v214, v215
	s_and_saveexec_b64 s[26:27], s[4:5]
	global_store_dword v210, v214, s[14:15] offset:3072
	s_mov_b64 exec, s[26:27]
	v_add_u32_e32 v210, 0x2000, v210
	s_waitcnt vmcnt(18)
	v_lshlrev_b32_e32 v202, 16, v178
	v_and_b32_e32 v203, 0xffff0000, v178
	v_lshlrev_b32_e32 v204, 16, v179
	v_and_b32_e32 v205, 0xffff0000, v179
	v_pk_add_f32 v[60:61], v[60:61], v[202:203]
	v_pk_add_f32 v[62:63], v[62:63], v[204:205]
	v_lshlrev_b32_e32 v202, 16, v180
	v_and_b32_e32 v203, 0xffff0000, v180
	v_lshlrev_b32_e32 v204, 16, v181
	v_and_b32_e32 v205, 0xffff0000, v181
	v_pk_add_f32 v[56:57], v[56:57], v[202:203]
	v_pk_add_f32 v[58:59], v[58:59], v[204:205]
	v_cvt_pk_bf16_f32 v178, v60, v61
	v_cvt_pk_bf16_f32 v179, v62, v63
	v_cvt_pk_bf16_f32 v180, v56, v57
	v_cvt_pk_bf16_f32 v181, v58, v59
	v_pk_mul_f32 v[138:139], v[60:61], v[60:61]
	global_store_dwordx4 v207, v[178:181], s[8:9]
	v_pk_fma_f32 v[138:139], v[62:63], v[62:63], v[138:139]
	v_pk_fma_f32 v[138:139], v[56:57], v[56:57], v[138:139]
	v_pk_fma_f32 v[138:139], v[58:59], v[58:59], v[138:139]
	v_lshlrev_b32_e32 v202, 16, v182
	v_and_b32_e32 v203, 0xffff0000, v182
	v_lshlrev_b32_e32 v204, 16, v183
	v_and_b32_e32 v205, 0xffff0000, v183
	v_pk_add_f32 v[52:53], v[52:53], v[202:203]
	v_pk_add_f32 v[54:55], v[54:55], v[204:205]
	v_lshlrev_b32_e32 v202, 16, v184
	v_and_b32_e32 v203, 0xffff0000, v184
	v_lshlrev_b32_e32 v204, 16, v185
	v_and_b32_e32 v205, 0xffff0000, v185
	v_pk_add_f32 v[48:49], v[48:49], v[202:203]
	v_pk_add_f32 v[50:51], v[50:51], v[204:205]
	v_cvt_pk_bf16_f32 v182, v52, v53
	v_cvt_pk_bf16_f32 v183, v54, v55
	v_cvt_pk_bf16_f32 v184, v48, v49
	v_cvt_pk_bf16_f32 v185, v50, v51
	v_pk_fma_f32 v[138:139], v[52:53], v[52:53], v[138:139]
	global_store_dwordx4 v207, v[182:185], s[8:9] offset:256
	v_pk_fma_f32 v[138:139], v[54:55], v[54:55], v[138:139]
	v_pk_fma_f32 v[138:139], v[48:49], v[48:49], v[138:139]
	v_pk_fma_f32 v[138:139], v[50:51], v[50:51], v[138:139]
	v_add_f32_e32 v214, v138, v139
	v_add_u32_e32 v207, 0x8000, v207
	v_mov_b32_e32 v215, v214
	s_nop 1
	v_permlane16_swap_b32_e32 v214, v215
	s_nop 0
	v_add_f32_e32 v214, v214, v215
	v_mov_b32_e32 v215, v214
	s_nop 1
	v_permlane32_swap_b32_e32 v214, v215
	s_nop 0
	v_add_f32_e32 v214, v214, v215
	s_and_saveexec_b64 s[26:27], s[4:5]
	global_store_dword v210, v214, s[14:15]
	s_mov_b64 exec, s[26:27]
	s_waitcnt vmcnt(19)
	v_lshlrev_b32_e32 v202, 16, v186
	v_and_b32_e32 v203, 0xffff0000, v186
	v_lshlrev_b32_e32 v204, 16, v187
	v_and_b32_e32 v205, 0xffff0000, v187
	v_pk_add_f32 v[44:45], v[44:45], v[202:203]
	v_pk_add_f32 v[46:47], v[46:47], v[204:205]
	v_lshlrev_b32_e32 v202, 16, v188
	v_and_b32_e32 v203, 0xffff0000, v188
	v_lshlrev_b32_e32 v204, 16, v189
	v_and_b32_e32 v205, 0xffff0000, v189
	v_pk_add_f32 v[40:41], v[40:41], v[202:203]
	v_pk_add_f32 v[42:43], v[42:43], v[204:205]
	v_cvt_pk_bf16_f32 v186, v44, v45
	v_cvt_pk_bf16_f32 v187, v46, v47
	v_cvt_pk_bf16_f32 v188, v40, v41
	v_cvt_pk_bf16_f32 v189, v42, v43
	v_pk_mul_f32 v[138:139], v[44:45], v[44:45]
	global_store_dwordx4 v207, v[186:189], s[8:9]
	v_pk_fma_f32 v[138:139], v[46:47], v[46:47], v[138:139]
	v_pk_fma_f32 v[138:139], v[40:41], v[40:41], v[138:139]
	v_pk_fma_f32 v[138:139], v[42:43], v[42:43], v[138:139]
	v_lshlrev_b32_e32 v202, 16, v190
	v_and_b32_e32 v203, 0xffff0000, v190
	v_lshlrev_b32_e32 v204, 16, v191
	v_and_b32_e32 v205, 0xffff0000, v191
	v_pk_add_f32 v[36:37], v[36:37], v[202:203]
	v_pk_add_f32 v[38:39], v[38:39], v[204:205]
	v_lshlrev_b32_e32 v202, 16, v192
	v_and_b32_e32 v203, 0xffff0000, v192
	v_lshlrev_b32_e32 v204, 16, v193
	v_and_b32_e32 v205, 0xffff0000, v193
	v_pk_add_f32 v[32:33], v[32:33], v[202:203]
	v_pk_add_f32 v[34:35], v[34:35], v[204:205]
	v_cvt_pk_bf16_f32 v190, v36, v37
	v_cvt_pk_bf16_f32 v191, v38, v39
	v_cvt_pk_bf16_f32 v192, v32, v33
	v_cvt_pk_bf16_f32 v193, v34, v35
	v_pk_fma_f32 v[138:139], v[36:37], v[36:37], v[138:139]
	global_store_dwordx4 v207, v[190:193], s[8:9] offset:256
	v_pk_fma_f32 v[138:139], v[38:39], v[38:39], v[138:139]
	v_pk_fma_f32 v[138:139], v[32:33], v[32:33], v[138:139]
	v_pk_fma_f32 v[138:139], v[34:35], v[34:35], v[138:139]
	v_add_f32_e32 v214, v138, v139
	v_add_u32_e32 v207, 0x8000, v207
	v_mov_b32_e32 v215, v214
	s_nop 1
	v_permlane16_swap_b32_e32 v214, v215
	s_nop 0
	v_add_f32_e32 v214, v214, v215
	v_mov_b32_e32 v215, v214
	s_nop 1
	v_permlane32_swap_b32_e32 v214, v215
	s_nop 0
	v_add_f32_e32 v214, v214, v215
	s_and_saveexec_b64 s[26:27], s[4:5]
	global_store_dword v210, v214, s[14:15] offset:1024
	s_mov_b64 exec, s[26:27]
	s_waitcnt vmcnt(20)
	v_lshlrev_b32_e32 v202, 16, v194
	v_and_b32_e32 v203, 0xffff0000, v194
	v_lshlrev_b32_e32 v204, 16, v195
	v_and_b32_e32 v205, 0xffff0000, v195
	v_pk_add_f32 v[28:29], v[28:29], v[202:203]
	v_pk_add_f32 v[30:31], v[30:31], v[204:205]
	v_lshlrev_b32_e32 v202, 16, v196
	v_and_b32_e32 v203, 0xffff0000, v196
	v_lshlrev_b32_e32 v204, 16, v197
	v_and_b32_e32 v205, 0xffff0000, v197
	v_pk_add_f32 v[24:25], v[24:25], v[202:203]
	v_pk_add_f32 v[26:27], v[26:27], v[204:205]
	v_cvt_pk_bf16_f32 v194, v28, v29
	v_cvt_pk_bf16_f32 v195, v30, v31
	v_cvt_pk_bf16_f32 v196, v24, v25
	v_cvt_pk_bf16_f32 v197, v26, v27
	v_pk_mul_f32 v[138:139], v[28:29], v[28:29]
	global_store_dwordx4 v207, v[194:197], s[8:9]
	v_pk_fma_f32 v[138:139], v[30:31], v[30:31], v[138:139]
	v_pk_fma_f32 v[138:139], v[24:25], v[24:25], v[138:139]
	v_pk_fma_f32 v[138:139], v[26:27], v[26:27], v[138:139]
	v_lshlrev_b32_e32 v202, 16, v198
	v_and_b32_e32 v203, 0xffff0000, v198
	v_lshlrev_b32_e32 v204, 16, v199
	v_and_b32_e32 v205, 0xffff0000, v199
	v_pk_add_f32 v[20:21], v[20:21], v[202:203]
	v_pk_add_f32 v[22:23], v[22:23], v[204:205]
	v_lshlrev_b32_e32 v202, 16, v200
	v_and_b32_e32 v203, 0xffff0000, v200
	v_lshlrev_b32_e32 v204, 16, v201
	v_and_b32_e32 v205, 0xffff0000, v201
	v_pk_add_f32 v[16:17], v[16:17], v[202:203]
	v_pk_add_f32 v[18:19], v[18:19], v[204:205]
	v_cvt_pk_bf16_f32 v198, v20, v21
	v_cvt_pk_bf16_f32 v199, v22, v23
	v_cvt_pk_bf16_f32 v200, v16, v17
	v_cvt_pk_bf16_f32 v201, v18, v19
	v_pk_fma_f32 v[138:139], v[20:21], v[20:21], v[138:139]
	global_store_dwordx4 v207, v[198:201], s[8:9] offset:256
	v_pk_fma_f32 v[138:139], v[22:23], v[22:23], v[138:139]
	v_pk_fma_f32 v[138:139], v[16:17], v[16:17], v[138:139]
	v_pk_fma_f32 v[138:139], v[18:19], v[18:19], v[138:139]
	v_add_f32_e32 v214, v138, v139
	v_add_u32_e32 v207, 0x8000, v207
	v_mov_b32_e32 v215, v214
	s_nop 1
	v_permlane16_swap_b32_e32 v214, v215
	s_nop 0
	v_add_f32_e32 v214, v214, v215
	v_mov_b32_e32 v215, v214
	s_nop 1
	v_permlane32_swap_b32_e32 v214, v215
	s_nop 0
	v_add_f32_e32 v214, v214, v215
	s_and_saveexec_b64 s[26:27], s[4:5]
	global_store_dword v210, v214, s[14:15] offset:2048
	s_mov_b64 exec, s[26:27]
	s_waitcnt vmcnt(18)
	v_lshlrev_b32_e32 v202, 16, v146
	v_and_b32_e32 v203, 0xffff0000, v146
	v_lshlrev_b32_e32 v204, 16, v147
	v_and_b32_e32 v205, 0xffff0000, v147
	v_pk_add_f32 v[12:13], v[12:13], v[202:203]
	v_pk_add_f32 v[14:15], v[14:15], v[204:205]
	v_lshlrev_b32_e32 v202, 16, v148
	v_and_b32_e32 v203, 0xffff0000, v148
	v_lshlrev_b32_e32 v204, 16, v149
	v_and_b32_e32 v205, 0xffff0000, v149
	v_pk_add_f32 v[8:9], v[8:9], v[202:203]
	v_pk_add_f32 v[10:11], v[10:11], v[204:205]
	v_cvt_pk_bf16_f32 v146, v12, v13
	v_cvt_pk_bf16_f32 v147, v14, v15
	v_cvt_pk_bf16_f32 v148, v8, v9
	v_cvt_pk_bf16_f32 v149, v10, v11
	v_pk_mul_f32 v[138:139], v[12:13], v[12:13]
	global_store_dwordx4 v207, v[146:149], s[8:9]
	v_pk_fma_f32 v[138:139], v[14:15], v[14:15], v[138:139]
	v_pk_fma_f32 v[138:139], v[8:9], v[8:9], v[138:139]
	v_pk_fma_f32 v[138:139], v[10:11], v[10:11], v[138:139]
	v_lshlrev_b32_e32 v202, 16, v150
	v_and_b32_e32 v203, 0xffff0000, v150
	v_lshlrev_b32_e32 v204, 16, v151
	v_and_b32_e32 v205, 0xffff0000, v151
	v_pk_add_f32 v[4:5], v[4:5], v[202:203]
	v_pk_add_f32 v[6:7], v[6:7], v[204:205]
	v_lshlrev_b32_e32 v202, 16, v152
	v_and_b32_e32 v203, 0xffff0000, v152
	v_lshlrev_b32_e32 v204, 16, v153
	v_and_b32_e32 v205, 0xffff0000, v153
	v_pk_add_f32 v[0:1], v[0:1], v[202:203]
	v_pk_add_f32 v[2:3], v[2:3], v[204:205]
	v_cvt_pk_bf16_f32 v150, v4, v5
	v_cvt_pk_bf16_f32 v151, v6, v7
	v_cvt_pk_bf16_f32 v152, v0, v1
	v_cvt_pk_bf16_f32 v153, v2, v3
	v_pk_fma_f32 v[138:139], v[4:5], v[4:5], v[138:139]
	global_store_dwordx4 v207, v[150:153], s[8:9] offset:256
	v_pk_fma_f32 v[138:139], v[6:7], v[6:7], v[138:139]
	v_pk_fma_f32 v[138:139], v[0:1], v[0:1], v[138:139]
	v_pk_fma_f32 v[138:139], v[2:3], v[2:3], v[138:139]
	v_add_f32_e32 v214, v138, v139
	v_add_u32_e32 v207, 0x8000, v207
	v_mov_b32_e32 v215, v214
	s_nop 1
	v_permlane16_swap_b32_e32 v214, v215
	s_nop 0
	v_add_f32_e32 v214, v214, v215
	v_mov_b32_e32 v215, v214
	s_nop 1
	v_permlane32_swap_b32_e32 v214, v215
	s_nop 0
	v_add_f32_e32 v214, v214, v215
	s_and_saveexec_b64 s[26:27], s[4:5]
	global_store_dword v210, v214, s[14:15] offset:3072
	s_mov_b64 exec, s[26:27]
	s_branch .LBB0_870

.LBB0_921:
	v_add_u32_e32 v192, 0x10000, v253
	s_add_u32 s8, s6, 0xfffe0080
	s_addc_u32 s9, s7, -1
	s_add_i32 s84, 0, 0x10000
	ds_read_b128 v[128:131], v192
	ds_read_b128 v[132:135], v192 offset:1024
	ds_read_b128 v[136:139], v192 offset:2048
	ds_read_b128 v[140:143], v192 offset:3072
	s_cmp_eq_u32 s73, 12
	s_cselect_b32 s11, s15, s9
	s_cselect_b32 s10, s39, s8
	s_cselect_b32 s9, s65, vcc_hi
	s_cselect_b32 s8, s67, vcc_lo
	s_add_i32 m0, s46, 0xc000
	ds_read_b128 v[144:147], v251
	ds_read_b128 v[148:151], v251 offset:1024
	ds_read_b128 v[152:155], v251 offset:2048
	ds_read_b128 v[156:159], v251 offset:3072
	ds_read_b128 v[160:163], v251 offset:4096
	ds_read_b128 v[164:167], v251 offset:5120
	ds_read_b128 v[168:171], v251 offset:6144
	ds_read_b128 v[172:175], v251 offset:7168
	global_load_lds_dwordx4 v220, s[6:7]
	s_add_i32 m0, s46, 0xe000
	s_nop 0
	global_load_lds_dwordx4 v222, s[6:7]
	s_waitcnt lgkmcnt(8)
	s_barrier
	s_waitcnt lgkmcnt(0)
	v_mfma_f32_16x16x32_bf16 v[124:127], v[128:131], v[144:147], v[124:127]
	v_mfma_f32_16x16x32_bf16 v[120:123], v[136:139], v[144:147], v[120:123]
	v_mfma_f32_16x16x32_bf16 v[92:95], v[128:131], v[152:155], v[92:95]
	v_mfma_f32_16x16x32_bf16 v[44:47], v[136:139], v[152:155], v[44:47]
	v_mfma_f32_16x16x32_bf16 v[84:87], v[128:131], v[160:163], v[84:87]
	v_mfma_f32_16x16x32_bf16 v[40:43], v[136:139], v[160:163], v[40:43]
	v_mfma_f32_16x16x32_bf16 v[76:79], v[128:131], v[168:171], v[76:79]
	v_mfma_f32_16x16x32_bf16 v[36:39], v[136:139], v[168:171], v[36:39]
	v_mfma_f32_16x16x32_bf16 v[124:127], v[132:135], v[148:151], v[124:127]
	v_mfma_f32_16x16x32_bf16 v[120:123], v[140:143], v[148:151], v[120:123]
	v_mfma_f32_16x16x32_bf16 v[92:95], v[132:135], v[156:159], v[92:95]
	v_mfma_f32_16x16x32_bf16 v[44:47], v[140:143], v[156:159], v[44:47]
	v_mfma_f32_16x16x32_bf16 v[84:87], v[132:135], v[164:167], v[84:87]
	v_mfma_f32_16x16x32_bf16 v[40:43], v[140:143], v[164:167], v[40:43]
	v_mfma_f32_16x16x32_bf16 v[76:79], v[132:135], v[172:175], v[76:79]
	v_mfma_f32_16x16x32_bf16 v[36:39], v[140:143], v[172:175], v[36:39]
	s_barrier
	s_add_i32 s86, 0, 0x14000
	s_add_i32 s84, s84, s88
	s_add_u32 s98, s8, s40
	s_addc_u32 s99, s9, s41
	s_mov_b32 m0, s84
	ds_read_b128 v[176:179], v192 offset:16384
	ds_read_b128 v[180:183], v192 offset:17408
	ds_read_b128 v[184:187], v192 offset:18432
	ds_read_b128 v[188:191], v192 offset:19456
	global_load_lds_dwordx4 v208, s[8:9]
	s_add_i32 m0, s84, 0x2000
	s_nop 0
	global_load_lds_dwordx4 v214, s[8:9]
	s_barrier
	s_waitcnt lgkmcnt(0)
	v_mfma_f32_16x16x32_bf16 v[116:119], v[176:179], v[144:147], v[116:119]
	v_mfma_f32_16x16x32_bf16 v[112:115], v[184:187], v[144:147], v[112:115]
	v_mfma_f32_16x16x32_bf16 v[88:91], v[176:179], v[152:155], v[88:91]
	v_mfma_f32_16x16x32_bf16 v[32:35], v[184:187], v[152:155], v[32:35]
	v_mfma_f32_16x16x32_bf16 v[80:83], v[176:179], v[160:163], v[80:83]
	v_mfma_f32_16x16x32_bf16 v[28:31], v[184:187], v[160:163], v[28:31]
	v_mfma_f32_16x16x32_bf16 v[72:75], v[176:179], v[168:171], v[72:75]
	v_mfma_f32_16x16x32_bf16 v[24:27], v[184:187], v[168:171], v[24:27]
	v_mfma_f32_16x16x32_bf16 v[116:119], v[180:183], v[148:151], v[116:119]
	v_mfma_f32_16x16x32_bf16 v[112:115], v[188:191], v[148:151], v[112:115]
	v_mfma_f32_16x16x32_bf16 v[88:91], v[180:183], v[156:159], v[88:91]
	v_mfma_f32_16x16x32_bf16 v[32:35], v[188:191], v[156:159], v[32:35]
	v_mfma_f32_16x16x32_bf16 v[80:83], v[180:183], v[164:167], v[80:83]
	v_mfma_f32_16x16x32_bf16 v[28:31], v[188:191], v[164:167], v[28:31]
	v_mfma_f32_16x16x32_bf16 v[72:75], v[180:183], v[172:175], v[72:75]
	v_mfma_f32_16x16x32_bf16 v[24:27], v[188:191], v[172:175], v[24:27]
	s_mov_b32 m0, s46
	s_add_u32 s100, s10, s40
	s_addc_u32 s101, s11, s41
	s_barrier
	ds_read_b128 v[144:147], v251 offset:16384
	ds_read_b128 v[148:151], v251 offset:17408
	ds_read_b128 v[152:155], v251 offset:18432
	ds_read_b128 v[156:159], v251 offset:19456
	ds_read_b128 v[160:163], v251 offset:20480
	ds_read_b128 v[164:167], v251 offset:21504
	ds_read_b128 v[168:171], v251 offset:22528
	ds_read_b128 v[172:175], v251 offset:23552
	global_load_lds_dwordx4 v218, s[10:11]
	s_mov_b32 m0, s50
	s_nop 0
	global_load_lds_dwordx4 v216, s[10:11]
	s_barrier
	s_waitcnt lgkmcnt(0)
	v_mfma_f32_16x16x32_bf16 v[68:71], v[128:131], v[144:147], v[68:71]
	v_mfma_f32_16x16x32_bf16 v[20:23], v[136:139], v[144:147], v[20:23]
	v_mfma_f32_16x16x32_bf16 v[64:67], v[128:131], v[152:155], v[64:67]
	v_mfma_f32_16x16x32_bf16 v[16:19], v[136:139], v[152:155], v[16:19]
	v_mfma_f32_16x16x32_bf16 v[60:63], v[128:131], v[160:163], v[60:63]
	v_mfma_f32_16x16x32_bf16 v[12:15], v[136:139], v[160:163], v[12:15]
	v_mfma_f32_16x16x32_bf16 v[108:111], v[128:131], v[168:171], v[108:111]
	v_mfma_f32_16x16x32_bf16 v[104:107], v[136:139], v[168:171], v[104:107]
	v_mfma_f32_16x16x32_bf16 v[68:71], v[132:135], v[148:151], v[68:71]
	v_mfma_f32_16x16x32_bf16 v[20:23], v[140:143], v[148:151], v[20:23]
	v_mfma_f32_16x16x32_bf16 v[64:67], v[132:135], v[156:159], v[64:67]
	v_mfma_f32_16x16x32_bf16 v[16:19], v[140:143], v[156:159], v[16:19]
	v_mfma_f32_16x16x32_bf16 v[60:63], v[132:135], v[164:167], v[60:63]
	v_mfma_f32_16x16x32_bf16 v[12:15], v[140:143], v[164:167], v[12:15]
	v_mfma_f32_16x16x32_bf16 v[108:111], v[132:135], v[172:175], v[108:111]
	v_mfma_f32_16x16x32_bf16 v[104:107], v[140:143], v[172:175], v[104:107]
	s_barrier
	s_add_u32 s84, s8, 0x40000
	s_addc_u32 s85, s9, 0
	s_add_i32 s86, s86, s88
	s_mov_b32 m0, s86
	s_nop 0
	global_load_lds_dwordx4 v208, s[84:85]
	s_add_i32 m0, s86, 0x2000
	s_nop 0
	global_load_lds_dwordx4 v214, s[84:85]
	s_waitcnt vmcnt(6)
	s_barrier
	v_mfma_f32_16x16x32_bf16 v[56:59], v[176:179], v[144:147], v[56:59]
	v_mfma_f32_16x16x32_bf16 v[8:11], v[184:187], v[144:147], v[8:11]
	v_mfma_f32_16x16x32_bf16 v[52:55], v[176:179], v[152:155], v[52:55]
	v_mfma_f32_16x16x32_bf16 v[4:7], v[184:187], v[152:155], v[4:7]
	v_mfma_f32_16x16x32_bf16 v[48:51], v[176:179], v[160:163], v[48:51]
	v_mfma_f32_16x16x32_bf16 v[0:3], v[184:187], v[160:163], v[0:3]
	v_mfma_f32_16x16x32_bf16 v[100:103], v[176:179], v[168:171], v[100:103]
	v_mfma_f32_16x16x32_bf16 v[96:99], v[184:187], v[168:171], v[96:99]
	v_mfma_f32_16x16x32_bf16 v[56:59], v[180:183], v[148:151], v[56:59]
	v_mfma_f32_16x16x32_bf16 v[8:11], v[188:191], v[148:151], v[8:11]
	v_mfma_f32_16x16x32_bf16 v[52:55], v[180:183], v[156:159], v[52:55]
	v_mfma_f32_16x16x32_bf16 v[4:7], v[188:191], v[156:159], v[4:7]
	v_mfma_f32_16x16x32_bf16 v[48:51], v[180:183], v[164:167], v[48:51]
	v_mfma_f32_16x16x32_bf16 v[0:3], v[188:191], v[164:167], v[0:3]
	v_mfma_f32_16x16x32_bf16 v[100:103], v[180:183], v[172:175], v[100:103]
	v_mfma_f32_16x16x32_bf16 v[96:99], v[188:191], v[172:175], v[96:99]
	s_add_i32 s84, 0, 0x18000
	s_barrier
	ds_read_b128 v[128:131], v192 offset:32768
	ds_read_b128 v[132:135], v192 offset:33792
	ds_read_b128 v[136:139], v192 offset:34816
	ds_read_b128 v[140:143], v192 offset:35840
	s_add_u32 s10, s10, 0x20000
	s_addc_u32 s11, s11, 0
	s_mov_b32 m0, s51
	ds_read_b128 v[144:147], v251 offset:32768
	ds_read_b128 v[148:151], v251 offset:33792
	ds_read_b128 v[152:155], v251 offset:34816
	ds_read_b128 v[156:159], v251 offset:35840
	ds_read_b128 v[160:163], v251 offset:36864
	ds_read_b128 v[164:167], v251 offset:37888
	ds_read_b128 v[168:171], v251 offset:38912
	ds_read_b128 v[172:175], v251 offset:39936
	global_load_lds_dwordx4 v218, s[10:11]
	s_mov_b32 m0, s34
	s_nop 0
	global_load_lds_dwordx4 v216, s[10:11]
	s_waitcnt lgkmcnt(8)
	s_barrier
	s_waitcnt lgkmcnt(0)
	v_mfma_f32_16x16x32_bf16 v[124:127], v[128:131], v[144:147], v[124:127]
	v_mfma_f32_16x16x32_bf16 v[120:123], v[136:139], v[144:147], v[120:123]
	v_mfma_f32_16x16x32_bf16 v[92:95], v[128:131], v[152:155], v[92:95]
	v_mfma_f32_16x16x32_bf16 v[44:47], v[136:139], v[152:155], v[44:47]
	v_mfma_f32_16x16x32_bf16 v[84:87], v[128:131], v[160:163], v[84:87]
	v_mfma_f32_16x16x32_bf16 v[40:43], v[136:139], v[160:163], v[40:43]
	v_mfma_f32_16x16x32_bf16 v[76:79], v[128:131], v[168:171], v[76:79]
	v_mfma_f32_16x16x32_bf16 v[36:39], v[136:139], v[168:171], v[36:39]
	v_mfma_f32_16x16x32_bf16 v[124:127], v[132:135], v[148:151], v[124:127]
	v_mfma_f32_16x16x32_bf16 v[120:123], v[140:143], v[148:151], v[120:123]
	v_mfma_f32_16x16x32_bf16 v[92:95], v[132:135], v[156:159], v[92:95]
	v_mfma_f32_16x16x32_bf16 v[44:47], v[140:143], v[156:159], v[44:47]
	v_mfma_f32_16x16x32_bf16 v[84:87], v[132:135], v[164:167], v[84:87]
	v_mfma_f32_16x16x32_bf16 v[40:43], v[140:143], v[164:167], v[40:43]
	v_mfma_f32_16x16x32_bf16 v[76:79], v[132:135], v[172:175], v[76:79]
	v_mfma_f32_16x16x32_bf16 v[36:39], v[140:143], v[172:175], v[36:39]
	s_barrier
	s_add_i32 s10, 0, 0x1c000
	s_add_i32 s11, s84, s88
	s_mov_b32 m0, s11
	ds_read_b128 v[176:179], v192 offset:49152
	ds_read_b128 v[180:183], v192 offset:50176
	ds_read_b128 v[184:187], v192 offset:51200
	ds_read_b128 v[188:191], v192 offset:52224
	global_load_lds_dwordx4 v208, s[98:99]
	s_add_i32 m0, s11, 0x2000
	s_nop 0
	global_load_lds_dwordx4 v214, s[98:99]
	s_barrier
	s_waitcnt lgkmcnt(0)
	v_mfma_f32_16x16x32_bf16 v[116:119], v[176:179], v[144:147], v[116:119]
	v_mfma_f32_16x16x32_bf16 v[112:115], v[184:187], v[144:147], v[112:115]
	v_mfma_f32_16x16x32_bf16 v[88:91], v[176:179], v[152:155], v[88:91]
	v_mfma_f32_16x16x32_bf16 v[32:35], v[184:187], v[152:155], v[32:35]
	v_mfma_f32_16x16x32_bf16 v[80:83], v[176:179], v[160:163], v[80:83]
	v_mfma_f32_16x16x32_bf16 v[28:31], v[184:187], v[160:163], v[28:31]
	v_mfma_f32_16x16x32_bf16 v[72:75], v[176:179], v[168:171], v[72:75]
	v_mfma_f32_16x16x32_bf16 v[24:27], v[184:187], v[168:171], v[24:27]
	v_mfma_f32_16x16x32_bf16 v[116:119], v[180:183], v[148:151], v[116:119]
	v_mfma_f32_16x16x32_bf16 v[112:115], v[188:191], v[148:151], v[112:115]
	v_mfma_f32_16x16x32_bf16 v[88:91], v[180:183], v[156:159], v[88:91]
	v_mfma_f32_16x16x32_bf16 v[32:35], v[188:191], v[156:159], v[32:35]
	v_mfma_f32_16x16x32_bf16 v[80:83], v[180:183], v[164:167], v[80:83]
	v_mfma_f32_16x16x32_bf16 v[28:31], v[188:191], v[164:167], v[28:31]
	v_mfma_f32_16x16x32_bf16 v[72:75], v[180:183], v[172:175], v[72:75]
	v_mfma_f32_16x16x32_bf16 v[24:27], v[188:191], v[172:175], v[24:27]
	s_mov_b32 m0, s92
	s_barrier
	ds_read_b128 v[144:147], v251 offset:49152
	ds_read_b128 v[148:151], v251 offset:50176
	ds_read_b128 v[152:155], v251 offset:51200
	ds_read_b128 v[156:159], v251 offset:52224
	ds_read_b128 v[160:163], v251 offset:53248
	ds_read_b128 v[164:167], v251 offset:54272
	ds_read_b128 v[168:171], v251 offset:55296
	ds_read_b128 v[172:175], v251 offset:56320
	global_load_lds_dwordx4 v218, s[100:101]
	s_mov_b32 m0, s93
	s_nop 0
	global_load_lds_dwordx4 v216, s[100:101]
	s_barrier
	s_waitcnt lgkmcnt(0)
	v_mfma_f32_16x16x32_bf16 v[68:71], v[128:131], v[144:147], v[68:71]
	v_mfma_f32_16x16x32_bf16 v[20:23], v[136:139], v[144:147], v[20:23]
	v_mfma_f32_16x16x32_bf16 v[64:67], v[128:131], v[152:155], v[64:67]
	v_mfma_f32_16x16x32_bf16 v[16:19], v[136:139], v[152:155], v[16:19]
	v_mfma_f32_16x16x32_bf16 v[60:63], v[128:131], v[160:163], v[60:63]
	v_mfma_f32_16x16x32_bf16 v[12:15], v[136:139], v[160:163], v[12:15]
	v_mfma_f32_16x16x32_bf16 v[108:111], v[128:131], v[168:171], v[108:111]
	v_mfma_f32_16x16x32_bf16 v[104:107], v[136:139], v[168:171], v[104:107]
	v_mfma_f32_16x16x32_bf16 v[68:71], v[132:135], v[148:151], v[68:71]
	v_mfma_f32_16x16x32_bf16 v[20:23], v[140:143], v[148:151], v[20:23]
	v_mfma_f32_16x16x32_bf16 v[64:67], v[132:135], v[156:159], v[64:67]
	v_mfma_f32_16x16x32_bf16 v[16:19], v[140:143], v[156:159], v[16:19]
	v_mfma_f32_16x16x32_bf16 v[60:63], v[132:135], v[164:167], v[60:63]
	v_mfma_f32_16x16x32_bf16 v[12:15], v[140:143], v[164:167], v[12:15]
	v_mfma_f32_16x16x32_bf16 v[108:111], v[132:135], v[172:175], v[108:111]
	v_mfma_f32_16x16x32_bf16 v[104:107], v[140:143], v[172:175], v[104:107]
	s_barrier
	s_add_u32 s8, s8, 0x40080
	s_addc_u32 s9, s9, 0
	s_add_i32 s10, s10, s88
	s_mov_b32 m0, s10
	s_nop 0
	global_load_lds_dwordx4 v208, s[8:9]
	s_add_i32 m0, s10, 0x2000
	s_nop 0
	global_load_lds_dwordx4 v214, s[8:9]
	s_waitcnt vmcnt(6)
	s_barrier
	v_mfma_f32_16x16x32_bf16 v[56:59], v[176:179], v[144:147], v[56:59]
	v_mfma_f32_16x16x32_bf16 v[8:11], v[184:187], v[144:147], v[8:11]
	v_mfma_f32_16x16x32_bf16 v[52:55], v[176:179], v[152:155], v[52:55]
	v_mfma_f32_16x16x32_bf16 v[4:7], v[184:187], v[152:155], v[4:7]
	v_mfma_f32_16x16x32_bf16 v[48:51], v[176:179], v[160:163], v[48:51]
	v_mfma_f32_16x16x32_bf16 v[0:3], v[184:187], v[160:163], v[0:3]
	v_mfma_f32_16x16x32_bf16 v[100:103], v[176:179], v[168:171], v[100:103]
	v_mfma_f32_16x16x32_bf16 v[96:99], v[184:187], v[168:171], v[96:99]
	v_mfma_f32_16x16x32_bf16 v[56:59], v[180:183], v[148:151], v[56:59]
	v_mfma_f32_16x16x32_bf16 v[8:11], v[188:191], v[148:151], v[8:11]
	v_mfma_f32_16x16x32_bf16 v[52:55], v[180:183], v[156:159], v[52:55]
	v_mfma_f32_16x16x32_bf16 v[4:7], v[188:191], v[156:159], v[4:7]
	v_mfma_f32_16x16x32_bf16 v[48:51], v[180:183], v[164:167], v[48:51]
	v_mfma_f32_16x16x32_bf16 v[0:3], v[188:191], v[164:167], v[0:3]
	v_mfma_f32_16x16x32_bf16 v[100:103], v[180:183], v[172:175], v[100:103]
	v_mfma_f32_16x16x32_bf16 v[96:99], v[188:191], v[172:175], v[96:99]
	s_add_i32 s73, s73, 2
	s_add_u32 s6, s6, 0x100
	s_addc_u32 s7, s7, 0
	s_add_u32 vcc_lo, vcc_lo, 0x100
	s_addc_u32 vcc_hi, vcc_hi, 0
	s_cmp_gt_u32 s73, 13
	s_barrier
	s_cbranch_scc0 .LBB0_921
	s_lshl_b32 s6, s38, 8
	v_mov_b32_e32 v250, v210
	v_mov_b32_e32 v254, v249
	s_add_i32 s6, s6, s90
	v_mov_b64_e32 v[242:243], s[44:45]
	v_add_u32_e32 v234, s6, v254
	v_ashrrev_i32_e32 v235, 31, v234
	v_mbcnt_lo_u32_b32 v212, -1, 0
	v_mbcnt_hi_u32_b32 v212, -1, v212
	v_lshlrev_b32_e32 v244, 6, v234
	v_and_b32_e32 v212, 48, v212
	v_add_u32_e32 v212, v244, v212
	v_add_u32_e32 v213, 0x1000, v212
	v_add_u32_e32 v245, 0x1000, v244
	global_load_dwordx4 v[192:195], v212, s[20:21]
	global_load_dwordx4 v[196:199], v212, s[20:21] offset:1024
	global_load_dwordx4 v[200:203], v213, s[20:21] offset:2048
	global_load_dwordx4 v[204:207], v213, s[20:21] offset:3072
	global_load_dwordx4 v[160:163], v244, s[20:21] offset:2096
	global_load_dwordx4 v[164:167], v244, s[20:21] offset:2080
	global_load_dwordx4 v[176:179], v244, s[20:21] offset:2064
	global_load_dwordx4 v[180:183], v244, s[20:21] offset:2048
	global_load_dwordx4 v[168:171], v244, s[20:21] offset:3120
	global_load_dwordx4 v[172:175], v244, s[20:21] offset:3104
	global_load_dwordx4 v[184:187], v244, s[20:21] offset:3088
	global_load_dwordx4 v[188:191], v244, s[20:21] offset:3072
	global_load_dwordx4 v[144:147], v245, s[20:21] offset:48
	global_load_dwordx4 v[148:151], v245, s[20:21] offset:32
	global_load_dwordx4 v[152:155], v245, s[20:21] offset:16
	global_load_dwordx4 v[156:159], v245, s[20:21]
	global_load_dwordx4 v[128:131], v245, s[20:21] offset:1072
	global_load_dwordx4 v[132:135], v245, s[20:21] offset:1056
	global_load_dwordx4 v[136:139], v245, s[20:21] offset:1040
	global_load_dwordx4 v[140:143], v245, s[20:21] offset:1024
	v_add_u32_e32 v236, 16, v234
	v_ashrrev_i32_e32 v237, 31, v236
	v_add_u32_e32 v238, 32, v234
	v_ashrrev_i32_e32 v239, 31, v238
	v_add_u32_e32 v232, 48, v234
	v_ashrrev_i32_e32 v233, 31, v232
	v_add_u32_e32 v230, 64, v234
	v_ashrrev_i32_e32 v231, 31, v230
	v_add_u32_e32 v228, 0x50, v234
	v_ashrrev_i32_e32 v229, 31, v228
	v_add_u32_e32 v224, 0x60, v234
	v_ashrrev_i32_e32 v225, 31, v224
	v_add_u32_e32 v226, 0x70, v234
	v_ashrrev_i32_e32 v227, 31, v226
	s_lshl_b32 s14, s14, 7
	s_or_b32 s14, s14, s35
	s_waitcnt vmcnt(16)
	v_pk_add_f32 v[192:193], v[192:193], v[194:195]
	s_nop 0
	v_add_f32_e32 v246, v192, v193
	v_mov_b32_e32 v247, v246
	s_nop 1
	v_permlane16_swap_b32_e32 v246, v247
	s_nop 0
	v_add_f32_e32 v246, v246, v247
	v_mov_b32_e32 v247, v246
	s_nop 1
	v_permlane32_swap_b32_e32 v246, v247
	s_nop 0
	v_add_f32_e32 v193, v246, v247
	v_pk_add_f32 v[196:197], v[196:197], v[198:199]
	s_nop 0
	v_add_f32_e32 v246, v196, v197
	v_mov_b32_e32 v247, v246
	s_nop 1
	v_permlane16_swap_b32_e32 v246, v247
	s_nop 0
	v_add_f32_e32 v246, v246, v247
	v_mov_b32_e32 v247, v246
	s_nop 1
	v_permlane32_swap_b32_e32 v246, v247
	s_nop 0
	v_add_f32_e32 v192, v246, v247
	v_pk_add_f32 v[200:201], v[200:201], v[202:203]
	s_nop 0
	v_add_f32_e32 v246, v200, v201
	v_mov_b32_e32 v247, v246
	s_nop 1
	v_permlane16_swap_b32_e32 v246, v247
	s_nop 0
	v_add_f32_e32 v246, v246, v247
	v_mov_b32_e32 v247, v246
	s_nop 1
	v_permlane32_swap_b32_e32 v246, v247
	s_nop 0
	v_add_f32_e32 v197, v246, v247
	v_pk_add_f32 v[204:205], v[204:205], v[206:207]
	s_nop 0
	v_add_f32_e32 v246, v204, v205
	v_mov_b32_e32 v247, v246
	s_nop 1
	v_permlane16_swap_b32_e32 v246, v247
	s_nop 0
	v_add_f32_e32 v246, v246, v247
	v_mov_b32_e32 v247, v246
	s_nop 1
	v_permlane32_swap_b32_e32 v246, v247
	s_nop 0
	v_add_f32_e32 v196, v246, v247
	s_nop 0
	v_pk_fma_f32 v[240:241], v[192:193], s[42:43], v[242:243] op_sel_hi:[1,0,0]
	v_pk_fma_f32 v[202:203], v[196:197], s[42:43], v[242:243] op_sel_hi:[1,0,0]
	v_cmp_gt_f32_e64 s[6:7], s97, v240
	v_cmp_gt_f32_e32 vcc, s97, v241
	s_waitcnt vmcnt(0)
	v_lshl_add_u32 v192, v250, 3, s14
	v_add_u32_e32 v193, -14, v254
	v_cmp_gt_f32_e64 s[8:9], s97, v203
	v_cmp_gt_f32_e64 s[10:11], s97, v202
	v_cmp_lt_u32_e64 s[14:15], -13, v193
	v_ashrrev_i32_e32 v193, 31, v192
	s_and_saveexec_b64 s[86:87], s[14:15]
	s_xor_b64 s[14:15], exec, s[86:87]
	s_or_saveexec_b64 s[14:15], s[14:15]
	v_mul_f32_e32 v194, 0x4b800000, v241
	v_cndmask_b32_e32 v194, v241, v194, vcc
	v_rsq_f32_e32 v194, v194
	s_nop 0
	v_mul_f32_e32 v195, 0x45800000, v194
	v_cndmask_b32_e32 v204, v194, v195, vcc
	v_pk_mul_f32 v[196:197], v[118:119], v[204:205] op_sel_hi:[1,0]
	v_mul_f32_e32 v118, 0x4b800000, v202
	v_cndmask_b32_e64 v118, v202, v118, s[10:11]
	v_rsq_f32_e32 v118, v118
	v_pk_mul_f32 v[200:201], v[116:117], v[204:205] op_sel_hi:[1,0]
	v_pk_mul_f32 v[194:195], v[126:127], v[204:205] op_sel_hi:[1,0]
	v_pk_mul_f32 v[198:199], v[124:125], v[204:205] op_sel_hi:[1,0]
	v_mul_f32_e32 v116, 0x45800000, v118
	v_cndmask_b32_e64 v116, v118, v116, s[10:11]
	v_pk_mul_f32 v[122:123], v[122:123], v[204:205] op_sel_hi:[1,0]
	v_pk_mul_f32 v[120:121], v[120:121], v[204:205] op_sel_hi:[1,0]
	v_pk_mul_f32 v[114:115], v[114:115], v[204:205] op_sel_hi:[1,0]
	v_pk_mul_f32 v[112:113], v[112:113], v[204:205] op_sel_hi:[1,0]
	v_pk_mul_f32 v[110:111], v[110:111], v[116:117] op_sel_hi:[1,0]
	v_pk_mul_f32 v[108:109], v[108:109], v[116:117] op_sel_hi:[1,0]
	v_pk_mul_f32 v[106:107], v[106:107], v[116:117] op_sel_hi:[1,0]
	v_pk_mul_f32 v[104:105], v[104:105], v[116:117] op_sel_hi:[1,0]
	v_pk_mul_f32 v[102:103], v[102:103], v[116:117] op_sel_hi:[1,0]
	v_pk_mul_f32 v[100:101], v[100:101], v[116:117] op_sel_hi:[1,0]
	v_pk_mul_f32 v[98:99], v[98:99], v[116:117] op_sel_hi:[1,0]
	v_pk_mul_f32 v[96:97], v[96:97], v[116:117] op_sel_hi:[1,0]
	s_xor_b64 exec, exec, s[14:15]
	s_cbranch_execz .LBB0_917
	v_add_u32_e32 v116, -12, v254
	v_cmp_gt_i32_e64 s[10:11], 2, v254
	s_lshl_b32 s38, s38, 3
	s_add_i32 s38, s38, s91
	v_cndmask_b32_e64 v116, v116, v254, s[10:11]
	v_add_u32_e32 v126, s38, v116
	v_mov_b64_e32 v[124:125], s[22:23]
	s_movk_i32 s38, 0x5800
	v_mad_i64_i32 v[124:125], s[38:39], v126, s38, v[124:125]
	v_cndmask_b32_e64 v119, v111, v195, s[10:11]
	v_cndmask_b32_e64 v118, v110, v194, s[10:11]
	v_cndmask_b32_e64 v117, v109, v199, s[10:11]
	v_cndmask_b32_e64 v116, v108, v198, s[10:11]
	v_lshl_add_u64 v[124:125], v[192:193], 2, v[124:125]
	s_mov_b64 s[38:39], 0x2c00
	global_store_dwordx4 v[124:125], v[116:119], off
	v_lshl_add_u64 v[126:127], v[124:125], 0, s[38:39]
	s_movk_i32 s38, 0x2000
	v_cndmask_b32_e64 v119, v107, v123, s[10:11]
	v_cndmask_b32_e64 v118, v106, v122, s[10:11]
	v_cndmask_b32_e64 v117, v105, v121, s[10:11]
	v_cndmask_b32_e64 v116, v104, v120, s[10:11]
	global_store_dwordx4 v[124:125], v[116:119], off offset:16
	v_add_co_u32_e32 v124, vcc, s38, v124
	s_nop 0
	v_cndmask_b32_e64 v119, v103, v197, s[10:11]
	v_cndmask_b32_e64 v118, v102, v196, s[10:11]
	v_cndmask_b32_e64 v117, v101, v201, s[10:11]
	v_cndmask_b32_e64 v116, v100, v200, s[10:11]
	v_addc_co_u32_e32 v125, vcc, 0, v125, vcc
	global_store_dwordx4 v[124:125], v[116:119], off offset:3072
	s_nop 1
	v_cndmask_b32_e64 v119, v99, v115, s[10:11]
	v_cndmask_b32_e64 v118, v98, v114, s[10:11]
	v_cndmask_b32_e64 v117, v97, v113, s[10:11]
	v_cndmask_b32_e64 v116, v96, v112, s[10:11]
	global_store_dwordx4 v[126:127], v[116:119], off offset:16
	s_branch .LBB0_917

.LBB0_998:
	v_add_u32_e32 v143, 0x10000, v145
	s_add_u32 s20, s10, 0x100
	s_addc_u32 s21, s11, 0
	s_add_i32 s60, 0, 0x10000
	ds_read_b128 v[138:141], v143
	ds_read_b128 v[148:151], v143 offset:1024
	ds_read_b128 v[152:155], v143 offset:2048
	ds_read_b128 v[156:159], v143 offset:3072
	s_cmp_eq_u32 s59, 40
	s_cselect_b32 s25, s7, s21
	s_cselect_b32 s24, s6, s20
	s_cselect_b32 s23, s9, s58
	s_cselect_b32 s22, s8, s57
	s_add_i32 m0, s34, 0xc000
	ds_read_b128 v[160:163], v147
	ds_read_b128 v[164:167], v147 offset:1024
	ds_read_b128 v[168:171], v147 offset:2048
	ds_read_b128 v[172:175], v147 offset:3072
	ds_read_b128 v[176:179], v147 offset:4096
	ds_read_b128 v[180:183], v147 offset:5120
	ds_read_b128 v[184:187], v147 offset:6144
	ds_read_b128 v[188:191], v147 offset:7168
	global_load_lds_dwordx4 v134, s[10:11]
	s_add_i32 m0, s34, 0xe000
	s_nop 0
	global_load_lds_dwordx4 v136, s[10:11]
	s_waitcnt lgkmcnt(8)
	s_barrier
	s_waitcnt lgkmcnt(0)
	v_mfma_f32_16x16x32_bf16 v[124:127], v[138:141], v[160:163], v[124:127]
	v_mfma_f32_16x16x32_bf16 v[120:123], v[152:155], v[160:163], v[120:123]
	v_mfma_f32_16x16x32_bf16 v[108:111], v[138:141], v[168:171], v[108:111]
	v_mfma_f32_16x16x32_bf16 v[104:107], v[152:155], v[168:171], v[104:107]
	v_mfma_f32_16x16x32_bf16 v[92:95], v[138:141], v[176:179], v[92:95]
	v_mfma_f32_16x16x32_bf16 v[88:91], v[152:155], v[176:179], v[88:91]
	v_mfma_f32_16x16x32_bf16 v[76:79], v[138:141], v[184:187], v[76:79]
	v_mfma_f32_16x16x32_bf16 v[72:75], v[152:155], v[184:187], v[72:75]
	v_mfma_f32_16x16x32_bf16 v[124:127], v[148:151], v[164:167], v[124:127]
	v_mfma_f32_16x16x32_bf16 v[120:123], v[156:159], v[164:167], v[120:123]
	v_mfma_f32_16x16x32_bf16 v[108:111], v[148:151], v[172:175], v[108:111]
	v_mfma_f32_16x16x32_bf16 v[104:107], v[156:159], v[172:175], v[104:107]
	v_mfma_f32_16x16x32_bf16 v[92:95], v[148:151], v[180:183], v[92:95]
	v_mfma_f32_16x16x32_bf16 v[88:91], v[156:159], v[180:183], v[88:91]
	v_mfma_f32_16x16x32_bf16 v[76:79], v[148:151], v[188:191], v[76:79]
	v_mfma_f32_16x16x32_bf16 v[72:75], v[156:159], v[188:191], v[72:75]
	s_barrier
	s_add_i32 s61, 0, 0x14000
	s_add_i32 s10, s60, s27
	ds_read_b128 v[192:195], v143 offset:16384
	ds_read_b128 v[196:199], v143 offset:17408
	ds_read_b128 v[200:203], v143 offset:18432
	ds_read_b128 v[204:207], v143 offset:19456
	s_add_u32 s98, s22, s40
	s_addc_u32 s99, s23, s41
	s_mov_b32 m0, s10
	s_nop 0
	global_load_lds_dwordx4 v208, s[22:23]
	s_add_i32 m0, s10, 0x2000
	s_nop 0
	global_load_lds_dwordx4 v128, s[22:23]
	s_barrier
	s_waitcnt lgkmcnt(0)
	v_mfma_f32_16x16x32_bf16 v[116:119], v[192:195], v[160:163], v[116:119]
	v_mfma_f32_16x16x32_bf16 v[112:115], v[200:203], v[160:163], v[112:115]
	v_mfma_f32_16x16x32_bf16 v[100:103], v[192:195], v[168:171], v[100:103]
	v_mfma_f32_16x16x32_bf16 v[96:99], v[200:203], v[168:171], v[96:99]
	v_mfma_f32_16x16x32_bf16 v[84:87], v[192:195], v[176:179], v[84:87]
	v_mfma_f32_16x16x32_bf16 v[80:83], v[200:203], v[176:179], v[80:83]
	v_mfma_f32_16x16x32_bf16 v[68:71], v[192:195], v[184:187], v[68:71]
	v_mfma_f32_16x16x32_bf16 v[64:67], v[200:203], v[184:187], v[64:67]
	v_mfma_f32_16x16x32_bf16 v[116:119], v[196:199], v[164:167], v[116:119]
	v_mfma_f32_16x16x32_bf16 v[112:115], v[204:207], v[164:167], v[112:115]
	v_mfma_f32_16x16x32_bf16 v[100:103], v[196:199], v[172:175], v[100:103]
	v_mfma_f32_16x16x32_bf16 v[96:99], v[204:207], v[172:175], v[96:99]
	v_mfma_f32_16x16x32_bf16 v[84:87], v[196:199], v[180:183], v[84:87]
	v_mfma_f32_16x16x32_bf16 v[80:83], v[204:207], v[180:183], v[80:83]
	v_mfma_f32_16x16x32_bf16 v[68:71], v[196:199], v[188:191], v[68:71]
	v_mfma_f32_16x16x32_bf16 v[64:67], v[204:207], v[188:191], v[64:67]
	s_mov_b32 m0, s34
	s_add_u32 s100, s24, s40
	s_addc_u32 s101, s25, s41
	s_barrier
	ds_read_b128 v[160:163], v147 offset:16384
	ds_read_b128 v[164:167], v147 offset:17408
	ds_read_b128 v[168:171], v147 offset:18432
	ds_read_b128 v[172:175], v147 offset:19456
	ds_read_b128 v[176:179], v147 offset:20480
	ds_read_b128 v[180:183], v147 offset:21504
	ds_read_b128 v[184:187], v147 offset:22528
	ds_read_b128 v[188:191], v147 offset:23552
	global_load_lds_dwordx4 v132, s[24:25]
	s_mov_b32 m0, s35
	s_nop 0
	global_load_lds_dwordx4 v130, s[24:25]
	s_barrier
	s_waitcnt lgkmcnt(0)
	v_mfma_f32_16x16x32_bf16 v[60:63], v[138:141], v[160:163], v[60:63]
	v_mfma_f32_16x16x32_bf16 v[56:59], v[152:155], v[160:163], v[56:59]
	v_mfma_f32_16x16x32_bf16 v[44:47], v[138:141], v[168:171], v[44:47]
	v_mfma_f32_16x16x32_bf16 v[40:43], v[152:155], v[168:171], v[40:43]
	v_mfma_f32_16x16x32_bf16 v[28:31], v[138:141], v[176:179], v[28:31]
	v_mfma_f32_16x16x32_bf16 v[24:27], v[152:155], v[176:179], v[24:27]
	v_mfma_f32_16x16x32_bf16 v[12:15], v[138:141], v[184:187], v[12:15]
	v_mfma_f32_16x16x32_bf16 v[8:11], v[152:155], v[184:187], v[8:11]
	v_mfma_f32_16x16x32_bf16 v[60:63], v[148:151], v[164:167], v[60:63]
	v_mfma_f32_16x16x32_bf16 v[56:59], v[156:159], v[164:167], v[56:59]
	v_mfma_f32_16x16x32_bf16 v[44:47], v[148:151], v[172:175], v[44:47]
	v_mfma_f32_16x16x32_bf16 v[40:43], v[156:159], v[172:175], v[40:43]
	v_mfma_f32_16x16x32_bf16 v[28:31], v[148:151], v[180:183], v[28:31]
	v_mfma_f32_16x16x32_bf16 v[24:27], v[156:159], v[180:183], v[24:27]
	v_mfma_f32_16x16x32_bf16 v[12:15], v[148:151], v[188:191], v[12:15]
	v_mfma_f32_16x16x32_bf16 v[8:11], v[156:159], v[188:191], v[8:11]
	s_barrier
	s_add_u32 s10, s22, 0xb0000
	s_addc_u32 s11, s23, 0
	s_add_i32 s60, s61, s27
	s_mov_b32 m0, s60
	s_nop 0
	global_load_lds_dwordx4 v208, s[10:11]
	s_add_i32 m0, s60, 0x2000
	s_nop 0
	global_load_lds_dwordx4 v128, s[10:11]
	s_waitcnt vmcnt(6)
	s_barrier
	v_mfma_f32_16x16x32_bf16 v[52:55], v[192:195], v[160:163], v[52:55]
	v_mfma_f32_16x16x32_bf16 v[48:51], v[200:203], v[160:163], v[48:51]
	v_mfma_f32_16x16x32_bf16 v[36:39], v[192:195], v[168:171], v[36:39]
	v_mfma_f32_16x16x32_bf16 v[32:35], v[200:203], v[168:171], v[32:35]
	v_mfma_f32_16x16x32_bf16 v[20:23], v[192:195], v[176:179], v[20:23]
	v_mfma_f32_16x16x32_bf16 v[16:19], v[200:203], v[176:179], v[16:19]
	v_mfma_f32_16x16x32_bf16 v[4:7], v[192:195], v[184:187], v[4:7]
	v_mfma_f32_16x16x32_bf16 v[0:3], v[200:203], v[184:187], v[0:3]
	v_mfma_f32_16x16x32_bf16 v[52:55], v[196:199], v[164:167], v[52:55]
	v_mfma_f32_16x16x32_bf16 v[48:51], v[204:207], v[164:167], v[48:51]
	v_mfma_f32_16x16x32_bf16 v[36:39], v[196:199], v[172:175], v[36:39]
	v_mfma_f32_16x16x32_bf16 v[32:35], v[204:207], v[172:175], v[32:35]
	v_mfma_f32_16x16x32_bf16 v[20:23], v[196:199], v[180:183], v[20:23]
	v_mfma_f32_16x16x32_bf16 v[16:19], v[204:207], v[180:183], v[16:19]
	v_mfma_f32_16x16x32_bf16 v[4:7], v[196:199], v[188:191], v[4:7]
	v_mfma_f32_16x16x32_bf16 v[0:3], v[204:207], v[188:191], v[0:3]
	s_add_i32 s60, 0, 0x18000
	s_barrier
	ds_read_b128 v[138:141], v143 offset:32768
	ds_read_b128 v[148:151], v143 offset:33792
	ds_read_b128 v[152:155], v143 offset:34816
	ds_read_b128 v[156:159], v143 offset:35840
	s_add_u32 s10, s24, 0xb0000
	s_addc_u32 s11, s25, 0
	s_mov_b32 m0, s36
	ds_read_b128 v[160:163], v147 offset:32768
	ds_read_b128 v[164:167], v147 offset:33792
	ds_read_b128 v[168:171], v147 offset:34816
	ds_read_b128 v[172:175], v147 offset:35840
	ds_read_b128 v[176:179], v147 offset:36864
	ds_read_b128 v[180:183], v147 offset:37888
	ds_read_b128 v[184:187], v147 offset:38912
	ds_read_b128 v[188:191], v147 offset:39936
	global_load_lds_dwordx4 v132, s[10:11]
	s_mov_b32 m0, s46
	s_nop 0
	global_load_lds_dwordx4 v130, s[10:11]
	s_waitcnt lgkmcnt(8)
	s_barrier
	s_waitcnt lgkmcnt(0)
	v_mfma_f32_16x16x32_bf16 v[124:127], v[138:141], v[160:163], v[124:127]
	v_mfma_f32_16x16x32_bf16 v[120:123], v[152:155], v[160:163], v[120:123]
	v_mfma_f32_16x16x32_bf16 v[108:111], v[138:141], v[168:171], v[108:111]
	v_mfma_f32_16x16x32_bf16 v[104:107], v[152:155], v[168:171], v[104:107]
	v_mfma_f32_16x16x32_bf16 v[92:95], v[138:141], v[176:179], v[92:95]
	v_mfma_f32_16x16x32_bf16 v[88:91], v[152:155], v[176:179], v[88:91]
	v_mfma_f32_16x16x32_bf16 v[76:79], v[138:141], v[184:187], v[76:79]
	v_mfma_f32_16x16x32_bf16 v[72:75], v[152:155], v[184:187], v[72:75]
	v_mfma_f32_16x16x32_bf16 v[124:127], v[148:151], v[164:167], v[124:127]
	v_mfma_f32_16x16x32_bf16 v[120:123], v[156:159], v[164:167], v[120:123]
	v_mfma_f32_16x16x32_bf16 v[108:111], v[148:151], v[172:175], v[108:111]
	v_mfma_f32_16x16x32_bf16 v[104:107], v[156:159], v[172:175], v[104:107]
	v_mfma_f32_16x16x32_bf16 v[92:95], v[148:151], v[180:183], v[92:95]
	v_mfma_f32_16x16x32_bf16 v[88:91], v[156:159], v[180:183], v[88:91]
	v_mfma_f32_16x16x32_bf16 v[76:79], v[148:151], v[188:191], v[76:79]
	v_mfma_f32_16x16x32_bf16 v[72:75], v[156:159], v[188:191], v[72:75]
	s_barrier
	s_add_i32 s24, 0, 0x1c000
	s_add_i32 s10, s60, s27
	s_mov_b32 m0, s10
	ds_read_b128 v[192:195], v143 offset:49152
	ds_read_b128 v[196:199], v143 offset:50176
	ds_read_b128 v[200:203], v143 offset:51200
	ds_read_b128 v[204:207], v143 offset:52224
	global_load_lds_dwordx4 v208, s[98:99]
	s_add_i32 m0, s10, 0x2000
	s_nop 0
	global_load_lds_dwordx4 v128, s[98:99]
	s_barrier
	s_waitcnt lgkmcnt(0)
	v_mfma_f32_16x16x32_bf16 v[116:119], v[192:195], v[160:163], v[116:119]
	v_mfma_f32_16x16x32_bf16 v[112:115], v[200:203], v[160:163], v[112:115]
	v_mfma_f32_16x16x32_bf16 v[100:103], v[192:195], v[168:171], v[100:103]
	v_mfma_f32_16x16x32_bf16 v[96:99], v[200:203], v[168:171], v[96:99]
	v_mfma_f32_16x16x32_bf16 v[84:87], v[192:195], v[176:179], v[84:87]
	v_mfma_f32_16x16x32_bf16 v[80:83], v[200:203], v[176:179], v[80:83]
	v_mfma_f32_16x16x32_bf16 v[68:71], v[192:195], v[184:187], v[68:71]
	v_mfma_f32_16x16x32_bf16 v[64:67], v[200:203], v[184:187], v[64:67]
	v_mfma_f32_16x16x32_bf16 v[116:119], v[196:199], v[164:167], v[116:119]
	v_mfma_f32_16x16x32_bf16 v[112:115], v[204:207], v[164:167], v[112:115]
	v_mfma_f32_16x16x32_bf16 v[100:103], v[196:199], v[172:175], v[100:103]
	v_mfma_f32_16x16x32_bf16 v[96:99], v[204:207], v[172:175], v[96:99]
	v_mfma_f32_16x16x32_bf16 v[84:87], v[196:199], v[180:183], v[84:87]
	v_mfma_f32_16x16x32_bf16 v[80:83], v[204:207], v[180:183], v[80:83]
	v_mfma_f32_16x16x32_bf16 v[68:71], v[196:199], v[188:191], v[68:71]
	v_mfma_f32_16x16x32_bf16 v[64:67], v[204:207], v[188:191], v[64:67]
	s_mov_b32 m0, s50
	s_barrier
	ds_read_b128 v[160:163], v147 offset:49152
	ds_read_b128 v[164:167], v147 offset:50176
	ds_read_b128 v[168:171], v147 offset:51200
	ds_read_b128 v[172:175], v147 offset:52224
	ds_read_b128 v[176:179], v147 offset:53248
	ds_read_b128 v[180:183], v147 offset:54272
	ds_read_b128 v[184:187], v147 offset:55296
	ds_read_b128 v[188:191], v147 offset:56320
	global_load_lds_dwordx4 v132, s[100:101]
	s_mov_b32 m0, s51
	s_nop 0
	global_load_lds_dwordx4 v130, s[100:101]
	s_barrier
	s_waitcnt lgkmcnt(0)
	v_mfma_f32_16x16x32_bf16 v[60:63], v[138:141], v[160:163], v[60:63]
	v_mfma_f32_16x16x32_bf16 v[56:59], v[152:155], v[160:163], v[56:59]
	v_mfma_f32_16x16x32_bf16 v[44:47], v[138:141], v[168:171], v[44:47]
	v_mfma_f32_16x16x32_bf16 v[40:43], v[152:155], v[168:171], v[40:43]
	v_mfma_f32_16x16x32_bf16 v[28:31], v[138:141], v[176:179], v[28:31]
	v_mfma_f32_16x16x32_bf16 v[24:27], v[152:155], v[176:179], v[24:27]
	v_mfma_f32_16x16x32_bf16 v[12:15], v[138:141], v[184:187], v[12:15]
	v_mfma_f32_16x16x32_bf16 v[8:11], v[152:155], v[184:187], v[8:11]
	v_mfma_f32_16x16x32_bf16 v[60:63], v[148:151], v[164:167], v[60:63]
	v_mfma_f32_16x16x32_bf16 v[56:59], v[156:159], v[164:167], v[56:59]
	v_mfma_f32_16x16x32_bf16 v[44:47], v[148:151], v[172:175], v[44:47]
	v_mfma_f32_16x16x32_bf16 v[40:43], v[156:159], v[172:175], v[40:43]
	v_mfma_f32_16x16x32_bf16 v[28:31], v[148:151], v[180:183], v[28:31]
	v_mfma_f32_16x16x32_bf16 v[24:27], v[156:159], v[180:183], v[24:27]
	v_mfma_f32_16x16x32_bf16 v[12:15], v[148:151], v[188:191], v[12:15]
	v_mfma_f32_16x16x32_bf16 v[8:11], v[156:159], v[188:191], v[8:11]
	s_barrier
	s_add_u32 s10, s22, 0xb0080
	s_addc_u32 s11, s23, 0
	s_add_i32 s22, s24, s27
	s_mov_b32 m0, s22
	s_nop 0
	global_load_lds_dwordx4 v208, s[10:11]
	s_add_i32 m0, s22, 0x2000
	s_nop 0
	global_load_lds_dwordx4 v128, s[10:11]
	s_waitcnt vmcnt(6)
	s_barrier
	v_mfma_f32_16x16x32_bf16 v[52:55], v[192:195], v[160:163], v[52:55]
	v_mfma_f32_16x16x32_bf16 v[48:51], v[200:203], v[160:163], v[48:51]
	v_mfma_f32_16x16x32_bf16 v[36:39], v[192:195], v[168:171], v[36:39]
	v_mfma_f32_16x16x32_bf16 v[32:35], v[200:203], v[168:171], v[32:35]
	v_mfma_f32_16x16x32_bf16 v[20:23], v[192:195], v[176:179], v[20:23]
	v_mfma_f32_16x16x32_bf16 v[16:19], v[200:203], v[176:179], v[16:19]
	v_mfma_f32_16x16x32_bf16 v[4:7], v[192:195], v[184:187], v[4:7]
	v_mfma_f32_16x16x32_bf16 v[0:3], v[200:203], v[184:187], v[0:3]
	v_mfma_f32_16x16x32_bf16 v[52:55], v[196:199], v[164:167], v[52:55]
	v_mfma_f32_16x16x32_bf16 v[48:51], v[204:207], v[164:167], v[48:51]
	v_mfma_f32_16x16x32_bf16 v[36:39], v[196:199], v[172:175], v[36:39]
	v_mfma_f32_16x16x32_bf16 v[32:35], v[204:207], v[172:175], v[32:35]
	v_mfma_f32_16x16x32_bf16 v[20:23], v[196:199], v[180:183], v[20:23]
	v_mfma_f32_16x16x32_bf16 v[16:19], v[204:207], v[180:183], v[16:19]
	v_mfma_f32_16x16x32_bf16 v[4:7], v[196:199], v[188:191], v[4:7]
	v_mfma_f32_16x16x32_bf16 v[0:3], v[204:207], v[188:191], v[0:3]
	s_add_i32 s59, s59, 2
	s_add_u32 s57, s57, 0x100
	s_addc_u32 s58, s58, 0
	s_cmp_gt_u32 s59, 41
	s_mov_b64 s[10:11], s[20:21]
	s_barrier
	s_cbranch_scc0 .LBB0_998
	v_lshl_add_u32 v142, s39, 8, v144
	v_lshl_or_b32 v143, s38, 8, v146
	s_and_b64 vcc, exec, s[4:5]
	s_mov_b32 s38, s53
	s_mov_b32 s39, s56
	s_mov_b64 s[20:21], s[8:9]
	s_mov_b64 s[10:11], s[6:7]
	v_lshl_add_u32 v210, v142, 10, v143
	v_lshlrev_b32_e32 v211, 2, v210
	v_lshlrev_b32_e32 v210, 1, v210
	global_load_dwordx4 v[148:151], v210, s[14:15]
	global_load_dwordx4 v[152:155], v210, s[14:15] offset:256
	v_add_u32_e32 v210, 0x8000, v210
	global_load_dwordx4 v[156:159], v210, s[14:15]
	global_load_dwordx4 v[160:163], v210, s[14:15] offset:256
	v_add_u32_e32 v210, 0x8000, v210
	global_load_dwordx4 v[164:167], v210, s[14:15]
	global_load_dwordx4 v[168:171], v210, s[14:15] offset:256
	v_add_u32_e32 v210, 0x8000, v210
	global_load_dwordx4 v[172:175], v210, s[14:15]
	global_load_dwordx4 v[176:179], v210, s[14:15] offset:256
	v_add_u32_e32 v210, 0x28000, v210
	global_load_dwordx4 v[180:183], v210, s[14:15]
	global_load_dwordx4 v[184:187], v210, s[14:15] offset:256
	v_add_u32_e32 v210, 0x8000, v210
	global_load_dwordx4 v[188:191], v210, s[14:15]
	global_load_dwordx4 v[192:195], v210, s[14:15] offset:256
	v_add_u32_e32 v210, 0x8000, v210
	global_load_dwordx4 v[196:199], v210, s[14:15]
	global_load_dwordx4 v[200:203], v210, s[14:15] offset:256
	v_add_u32_e32 v210, 0x8000, v210
	s_waitcnt vmcnt(12)
	v_lshlrev_b32_e32 v204, 16, v148
	v_and_b32_e32 v205, 0xffff0000, v148
	v_lshlrev_b32_e32 v206, 16, v149
	v_and_b32_e32 v207, 0xffff0000, v149
	v_pk_add_f32 v[124:125], v[124:125], v[204:205]
	v_pk_add_f32 v[126:127], v[126:127], v[206:207]
	v_lshlrev_b32_e32 v204, 16, v150
	v_and_b32_e32 v205, 0xffff0000, v150
	v_lshlrev_b32_e32 v206, 16, v151
	v_and_b32_e32 v207, 0xffff0000, v151
	v_pk_add_f32 v[120:121], v[120:121], v[204:205]
	v_pk_add_f32 v[122:123], v[122:123], v[206:207]
	global_store_dwordx4 v211, v[124:127], s[16:17]
	global_store_dwordx4 v211, v[120:123], s[16:17] offset:16
	v_lshlrev_b32_e32 v204, 16, v152
	v_and_b32_e32 v205, 0xffff0000, v152
	v_lshlrev_b32_e32 v206, 16, v153
	v_and_b32_e32 v207, 0xffff0000, v153
	v_pk_add_f32 v[116:117], v[116:117], v[204:205]
	v_pk_add_f32 v[118:119], v[118:119], v[206:207]
	v_lshlrev_b32_e32 v204, 16, v154
	v_and_b32_e32 v205, 0xffff0000, v154
	v_lshlrev_b32_e32 v206, 16, v155
	v_and_b32_e32 v207, 0xffff0000, v155
	v_pk_add_f32 v[112:113], v[112:113], v[204:205]
	v_pk_add_f32 v[114:115], v[114:115], v[206:207]
	global_store_dwordx4 v211, v[116:119], s[16:17] offset:512
	global_store_dwordx4 v211, v[112:115], s[16:17] offset:528
	v_add_u32_e32 v211, 0x10000, v211
	global_load_dwordx4 v[148:151], v210, s[14:15]
	global_load_dwordx4 v[152:155], v210, s[14:15] offset:256
	s_waitcnt vmcnt(16)
	v_lshlrev_b32_e32 v204, 16, v156
	v_and_b32_e32 v205, 0xffff0000, v156
	v_lshlrev_b32_e32 v206, 16, v157
	v_and_b32_e32 v207, 0xffff0000, v157
	v_pk_add_f32 v[108:109], v[108:109], v[204:205]
	v_pk_add_f32 v[110:111], v[110:111], v[206:207]
	v_lshlrev_b32_e32 v204, 16, v158
	v_and_b32_e32 v205, 0xffff0000, v158
	v_lshlrev_b32_e32 v206, 16, v159
	v_and_b32_e32 v207, 0xffff0000, v159
	v_pk_add_f32 v[104:105], v[104:105], v[204:205]
	v_pk_add_f32 v[106:107], v[106:107], v[206:207]
	global_store_dwordx4 v211, v[108:111], s[16:17]
	global_store_dwordx4 v211, v[104:107], s[16:17] offset:16
	v_lshlrev_b32_e32 v204, 16, v160
	v_and_b32_e32 v205, 0xffff0000, v160
	v_lshlrev_b32_e32 v206, 16, v161
	v_and_b32_e32 v207, 0xffff0000, v161
	v_pk_add_f32 v[100:101], v[100:101], v[204:205]
	v_pk_add_f32 v[102:103], v[102:103], v[206:207]
	v_lshlrev_b32_e32 v204, 16, v162
	v_and_b32_e32 v205, 0xffff0000, v162
	v_lshlrev_b32_e32 v206, 16, v163
	v_and_b32_e32 v207, 0xffff0000, v163
	v_pk_add_f32 v[96:97], v[96:97], v[204:205]
	v_pk_add_f32 v[98:99], v[98:99], v[206:207]
	global_store_dwordx4 v211, v[100:103], s[16:17] offset:512
	global_store_dwordx4 v211, v[96:99], s[16:17] offset:528
	v_add_u32_e32 v211, 0x10000, v211
	s_waitcnt vmcnt(18)
	v_lshlrev_b32_e32 v204, 16, v164
	v_and_b32_e32 v205, 0xffff0000, v164
	v_lshlrev_b32_e32 v206, 16, v165
	v_and_b32_e32 v207, 0xffff0000, v165
	v_pk_add_f32 v[92:93], v[92:93], v[204:205]
	v_pk_add_f32 v[94:95], v[94:95], v[206:207]
	v_lshlrev_b32_e32 v204, 16, v166
	v_and_b32_e32 v205, 0xffff0000, v166
	v_lshlrev_b32_e32 v206, 16, v167
	v_and_b32_e32 v207, 0xffff0000, v167
	v_pk_add_f32 v[88:89], v[88:89], v[204:205]
	v_pk_add_f32 v[90:91], v[90:91], v[206:207]
	global_store_dwordx4 v211, v[92:95], s[16:17]
	global_store_dwordx4 v211, v[88:91], s[16:17] offset:16
	v_lshlrev_b32_e32 v204, 16, v168
	v_and_b32_e32 v205, 0xffff0000, v168
	v_lshlrev_b32_e32 v206, 16, v169
	v_and_b32_e32 v207, 0xffff0000, v169
	v_pk_add_f32 v[84:85], v[84:85], v[204:205]
	v_pk_add_f32 v[86:87], v[86:87], v[206:207]
	v_lshlrev_b32_e32 v204, 16, v170
	v_and_b32_e32 v205, 0xffff0000, v170
	v_lshlrev_b32_e32 v206, 16, v171
	v_and_b32_e32 v207, 0xffff0000, v171
	v_pk_add_f32 v[80:81], v[80:81], v[204:205]
	v_pk_add_f32 v[82:83], v[82:83], v[206:207]
	global_store_dwordx4 v211, v[84:87], s[16:17] offset:512
	global_store_dwordx4 v211, v[80:83], s[16:17] offset:528
	v_add_u32_e32 v211, 0x10000, v211
	s_waitcnt vmcnt(20)
	v_lshlrev_b32_e32 v204, 16, v172
	v_and_b32_e32 v205, 0xffff0000, v172
	v_lshlrev_b32_e32 v206, 16, v173
	v_and_b32_e32 v207, 0xffff0000, v173
	v_pk_add_f32 v[76:77], v[76:77], v[204:205]
	v_pk_add_f32 v[78:79], v[78:79], v[206:207]
	v_lshlrev_b32_e32 v204, 16, v174
	v_and_b32_e32 v205, 0xffff0000, v174
	v_lshlrev_b32_e32 v206, 16, v175
	v_and_b32_e32 v207, 0xffff0000, v175
	v_pk_add_f32 v[72:73], v[72:73], v[204:205]
	v_pk_add_f32 v[74:75], v[74:75], v[206:207]
	global_store_dwordx4 v211, v[76:79], s[16:17]
	global_store_dwordx4 v211, v[72:75], s[16:17] offset:16
	v_lshlrev_b32_e32 v204, 16, v176
	v_and_b32_e32 v205, 0xffff0000, v176
	v_lshlrev_b32_e32 v206, 16, v177
	v_and_b32_e32 v207, 0xffff0000, v177
	v_pk_add_f32 v[68:69], v[68:69], v[204:205]
	v_pk_add_f32 v[70:71], v[70:71], v[206:207]
	v_lshlrev_b32_e32 v204, 16, v178
	v_and_b32_e32 v205, 0xffff0000, v178
	v_lshlrev_b32_e32 v206, 16, v179
	v_and_b32_e32 v207, 0xffff0000, v179
	v_pk_add_f32 v[64:65], v[64:65], v[204:205]
	v_pk_add_f32 v[66:67], v[66:67], v[206:207]
	global_store_dwordx4 v211, v[68:71], s[16:17] offset:512
	global_store_dwordx4 v211, v[64:67], s[16:17] offset:528
	v_add_u32_e32 v211, 0x50000, v211
	s_waitcnt vmcnt(22)
	v_lshlrev_b32_e32 v204, 16, v180
	v_and_b32_e32 v205, 0xffff0000, v180
	v_lshlrev_b32_e32 v206, 16, v181
	v_and_b32_e32 v207, 0xffff0000, v181
	v_pk_add_f32 v[60:61], v[60:61], v[204:205]
	v_pk_add_f32 v[62:63], v[62:63], v[206:207]
	v_lshlrev_b32_e32 v204, 16, v182
	v_and_b32_e32 v205, 0xffff0000, v182
	v_lshlrev_b32_e32 v206, 16, v183
	v_and_b32_e32 v207, 0xffff0000, v183
	v_pk_add_f32 v[56:57], v[56:57], v[204:205]
	v_pk_add_f32 v[58:59], v[58:59], v[206:207]
	global_store_dwordx4 v211, v[60:63], s[16:17]
	global_store_dwordx4 v211, v[56:59], s[16:17] offset:16
	v_lshlrev_b32_e32 v204, 16, v184
	v_and_b32_e32 v205, 0xffff0000, v184
	v_lshlrev_b32_e32 v206, 16, v185
	v_and_b32_e32 v207, 0xffff0000, v185
	v_pk_add_f32 v[52:53], v[52:53], v[204:205]
	v_pk_add_f32 v[54:55], v[54:55], v[206:207]
	v_lshlrev_b32_e32 v204, 16, v186
	v_and_b32_e32 v205, 0xffff0000, v186
	v_lshlrev_b32_e32 v206, 16, v187
	v_and_b32_e32 v207, 0xffff0000, v187
	v_pk_add_f32 v[48:49], v[48:49], v[204:205]
	v_pk_add_f32 v[50:51], v[50:51], v[206:207]
	global_store_dwordx4 v211, v[52:55], s[16:17] offset:512
	global_store_dwordx4 v211, v[48:51], s[16:17] offset:528
	v_add_u32_e32 v211, 0x10000, v211
	s_waitcnt vmcnt(24)
	v_lshlrev_b32_e32 v204, 16, v188
	v_and_b32_e32 v205, 0xffff0000, v188
	v_lshlrev_b32_e32 v206, 16, v189
	v_and_b32_e32 v207, 0xffff0000, v189
	v_pk_add_f32 v[44:45], v[44:45], v[204:205]
	v_pk_add_f32 v[46:47], v[46:47], v[206:207]
	v_lshlrev_b32_e32 v204, 16, v190
	v_and_b32_e32 v205, 0xffff0000, v190
	v_lshlrev_b32_e32 v206, 16, v191
	v_and_b32_e32 v207, 0xffff0000, v191
	v_pk_add_f32 v[40:41], v[40:41], v[204:205]
	v_pk_add_f32 v[42:43], v[42:43], v[206:207]
	global_store_dwordx4 v211, v[44:47], s[16:17]
	global_store_dwordx4 v211, v[40:43], s[16:17] offset:16
	v_lshlrev_b32_e32 v204, 16, v192
	v_and_b32_e32 v205, 0xffff0000, v192
	v_lshlrev_b32_e32 v206, 16, v193
	v_and_b32_e32 v207, 0xffff0000, v193
	v_pk_add_f32 v[36:37], v[36:37], v[204:205]
	v_pk_add_f32 v[38:39], v[38:39], v[206:207]
	v_lshlrev_b32_e32 v204, 16, v194
	v_and_b32_e32 v205, 0xffff0000, v194
	v_lshlrev_b32_e32 v206, 16, v195
	v_and_b32_e32 v207, 0xffff0000, v195
	v_pk_add_f32 v[32:33], v[32:33], v[204:205]
	v_pk_add_f32 v[34:35], v[34:35], v[206:207]
	global_store_dwordx4 v211, v[36:39], s[16:17] offset:512
	global_store_dwordx4 v211, v[32:35], s[16:17] offset:528
	v_add_u32_e32 v211, 0x10000, v211
	s_waitcnt vmcnt(26)
	v_lshlrev_b32_e32 v204, 16, v196
	v_and_b32_e32 v205, 0xffff0000, v196
	v_lshlrev_b32_e32 v206, 16, v197
	v_and_b32_e32 v207, 0xffff0000, v197
	v_pk_add_f32 v[28:29], v[28:29], v[204:205]
	v_pk_add_f32 v[30:31], v[30:31], v[206:207]
	v_lshlrev_b32_e32 v204, 16, v198
	v_and_b32_e32 v205, 0xffff0000, v198
	v_lshlrev_b32_e32 v206, 16, v199
	v_and_b32_e32 v207, 0xffff0000, v199
	v_pk_add_f32 v[24:25], v[24:25], v[204:205]
	v_pk_add_f32 v[26:27], v[26:27], v[206:207]
	global_store_dwordx4 v211, v[28:31], s[16:17]
	global_store_dwordx4 v211, v[24:27], s[16:17] offset:16
	v_lshlrev_b32_e32 v204, 16, v200
	v_and_b32_e32 v205, 0xffff0000, v200
	v_lshlrev_b32_e32 v206, 16, v201
	v_and_b32_e32 v207, 0xffff0000, v201
	v_pk_add_f32 v[20:21], v[20:21], v[204:205]
	v_pk_add_f32 v[22:23], v[22:23], v[206:207]
	v_lshlrev_b32_e32 v204, 16, v202
	v_and_b32_e32 v205, 0xffff0000, v202
	v_lshlrev_b32_e32 v206, 16, v203
	v_and_b32_e32 v207, 0xffff0000, v203
	v_pk_add_f32 v[16:17], v[16:17], v[204:205]
	v_pk_add_f32 v[18:19], v[18:19], v[206:207]
	global_store_dwordx4 v211, v[20:23], s[16:17] offset:512
	global_store_dwordx4 v211, v[16:19], s[16:17] offset:528
	v_add_u32_e32 v211, 0x10000, v211
	s_waitcnt vmcnt(24)
	v_lshlrev_b32_e32 v204, 16, v148
	v_and_b32_e32 v205, 0xffff0000, v148
	v_lshlrev_b32_e32 v206, 16, v149
	v_and_b32_e32 v207, 0xffff0000, v149
	v_pk_add_f32 v[12:13], v[12:13], v[204:205]
	v_pk_add_f32 v[14:15], v[14:15], v[206:207]
	v_lshlrev_b32_e32 v204, 16, v150
	v_and_b32_e32 v205, 0xffff0000, v150
	v_lshlrev_b32_e32 v206, 16, v151
	v_and_b32_e32 v207, 0xffff0000, v151
	v_pk_add_f32 v[8:9], v[8:9], v[204:205]
	v_pk_add_f32 v[10:11], v[10:11], v[206:207]
	global_store_dwordx4 v211, v[12:15], s[16:17]
	global_store_dwordx4 v211, v[8:11], s[16:17] offset:16
	v_lshlrev_b32_e32 v204, 16, v152
	v_and_b32_e32 v205, 0xffff0000, v152
	v_lshlrev_b32_e32 v206, 16, v153
	v_and_b32_e32 v207, 0xffff0000, v153
	v_pk_add_f32 v[4:5], v[4:5], v[204:205]
	v_pk_add_f32 v[6:7], v[6:7], v[206:207]
	v_lshlrev_b32_e32 v204, 16, v154
	v_and_b32_e32 v205, 0xffff0000, v154
	v_lshlrev_b32_e32 v206, 16, v155
	v_and_b32_e32 v207, 0xffff0000, v155
	v_pk_add_f32 v[0:1], v[0:1], v[204:205]
	v_pk_add_f32 v[2:3], v[2:3], v[206:207]
	global_store_dwordx4 v211, v[4:7], s[16:17] offset:512
	global_store_dwordx4 v211, v[0:3], s[16:17] offset:528
	v_add_u32_e32 v211, 0x10000, v211
	s_cbranch_vccz .LBB0_987
	s_waitcnt vmcnt(0)
	s_cmpk_gt_u32 s26, 0xff
	s_cbranch_scc1 .LBB0_1002
	s_barrier

.LBB0_1021:
	v_add_u32_e32 v206, 0x10000, v143
	s_add_u32 s22, s20, 0x100
	s_addc_u32 s23, s21, 0
	s_add_i32 s62, 0, 0x10000
	ds_read_b128 v[138:141], v206
	ds_read_b128 v[146:149], v206 offset:1024
	ds_read_b128 v[150:153], v206 offset:2048
	ds_read_b128 v[154:157], v206 offset:3072
	s_cmp_eq_u32 s61, 40
	s_cselect_b32 s27, s9, s23
	s_cselect_b32 s26, s8, s22
	s_cselect_b32 s25, s11, s60
	s_cselect_b32 s24, s10, s39
	s_add_i32 m0, s46, 0xc000
	ds_read_b128 v[158:161], v145
	ds_read_b128 v[162:165], v145 offset:1024
	ds_read_b128 v[166:169], v145 offset:2048
	ds_read_b128 v[170:173], v145 offset:3072
	ds_read_b128 v[174:177], v145 offset:4096
	ds_read_b128 v[178:181], v145 offset:5120
	ds_read_b128 v[182:185], v145 offset:6144
	ds_read_b128 v[186:189], v145 offset:7168
	global_load_lds_dwordx4 v134, s[20:21]
	s_add_i32 m0, s46, 0xe000
	s_nop 0
	global_load_lds_dwordx4 v136, s[20:21]
	s_waitcnt lgkmcnt(8)
	s_barrier
	s_waitcnt lgkmcnt(0)
	v_mfma_f32_16x16x32_bf16 v[124:127], v[138:141], v[158:161], v[124:127]
	v_mfma_f32_16x16x32_bf16 v[120:123], v[150:153], v[158:161], v[120:123]
	v_mfma_f32_16x16x32_bf16 v[108:111], v[138:141], v[166:169], v[108:111]
	v_mfma_f32_16x16x32_bf16 v[104:107], v[150:153], v[166:169], v[104:107]
	v_mfma_f32_16x16x32_bf16 v[92:95], v[138:141], v[174:177], v[92:95]
	v_mfma_f32_16x16x32_bf16 v[88:91], v[150:153], v[174:177], v[88:91]
	v_mfma_f32_16x16x32_bf16 v[76:79], v[138:141], v[182:185], v[76:79]
	v_mfma_f32_16x16x32_bf16 v[72:75], v[150:153], v[182:185], v[72:75]
	v_mfma_f32_16x16x32_bf16 v[124:127], v[146:149], v[162:165], v[124:127]
	v_mfma_f32_16x16x32_bf16 v[120:123], v[154:157], v[162:165], v[120:123]
	v_mfma_f32_16x16x32_bf16 v[108:111], v[146:149], v[170:173], v[108:111]
	v_mfma_f32_16x16x32_bf16 v[104:107], v[154:157], v[170:173], v[104:107]
	v_mfma_f32_16x16x32_bf16 v[92:95], v[146:149], v[178:181], v[92:95]
	v_mfma_f32_16x16x32_bf16 v[88:91], v[154:157], v[178:181], v[88:91]
	v_mfma_f32_16x16x32_bf16 v[76:79], v[146:149], v[186:189], v[76:79]
	v_mfma_f32_16x16x32_bf16 v[72:75], v[154:157], v[186:189], v[72:75]
	s_barrier
	s_add_i32 s63, 0, 0x14000
	s_add_i32 s20, s62, s35
	s_add_u32 s98, s24, s40
	s_addc_u32 s99, s25, s41
	s_mov_b32 m0, s20
	ds_read_b128 v[190:193], v206 offset:16384
	ds_read_b128 v[194:197], v206 offset:17408
	ds_read_b128 v[198:201], v206 offset:18432
	ds_read_b128 v[202:205], v206 offset:19456
	global_load_lds_dwordx4 v208, s[24:25]
	s_add_i32 m0, s20, 0x2000
	s_nop 0
	global_load_lds_dwordx4 v128, s[24:25]
	s_barrier
	s_waitcnt lgkmcnt(0)
	v_mfma_f32_16x16x32_bf16 v[116:119], v[190:193], v[158:161], v[116:119]
	v_mfma_f32_16x16x32_bf16 v[112:115], v[198:201], v[158:161], v[112:115]
	v_mfma_f32_16x16x32_bf16 v[100:103], v[190:193], v[166:169], v[100:103]
	v_mfma_f32_16x16x32_bf16 v[96:99], v[198:201], v[166:169], v[96:99]
	v_mfma_f32_16x16x32_bf16 v[84:87], v[190:193], v[174:177], v[84:87]
	v_mfma_f32_16x16x32_bf16 v[80:83], v[198:201], v[174:177], v[80:83]
	v_mfma_f32_16x16x32_bf16 v[68:71], v[190:193], v[182:185], v[68:71]
	v_mfma_f32_16x16x32_bf16 v[64:67], v[198:201], v[182:185], v[64:67]
	v_mfma_f32_16x16x32_bf16 v[116:119], v[194:197], v[162:165], v[116:119]
	v_mfma_f32_16x16x32_bf16 v[112:115], v[202:205], v[162:165], v[112:115]
	v_mfma_f32_16x16x32_bf16 v[100:103], v[194:197], v[170:173], v[100:103]
	v_mfma_f32_16x16x32_bf16 v[96:99], v[202:205], v[170:173], v[96:99]
	v_mfma_f32_16x16x32_bf16 v[84:87], v[194:197], v[178:181], v[84:87]
	v_mfma_f32_16x16x32_bf16 v[80:83], v[202:205], v[178:181], v[80:83]
	v_mfma_f32_16x16x32_bf16 v[68:71], v[194:197], v[186:189], v[68:71]
	v_mfma_f32_16x16x32_bf16 v[64:67], v[202:205], v[186:189], v[64:67]
	s_mov_b32 m0, s46
	s_add_u32 s100, s26, s40
	s_addc_u32 s101, s27, s41
	s_barrier
	ds_read_b128 v[158:161], v145 offset:16384
	ds_read_b128 v[162:165], v145 offset:17408
	ds_read_b128 v[166:169], v145 offset:18432
	ds_read_b128 v[170:173], v145 offset:19456
	ds_read_b128 v[174:177], v145 offset:20480
	ds_read_b128 v[178:181], v145 offset:21504
	ds_read_b128 v[182:185], v145 offset:22528
	ds_read_b128 v[186:189], v145 offset:23552
	global_load_lds_dwordx4 v132, s[26:27]
	s_mov_b32 m0, s47
	s_nop 0
	global_load_lds_dwordx4 v130, s[26:27]
	s_barrier
	s_waitcnt lgkmcnt(0)
	v_mfma_f32_16x16x32_bf16 v[60:63], v[138:141], v[158:161], v[60:63]
	v_mfma_f32_16x16x32_bf16 v[56:59], v[150:153], v[158:161], v[56:59]
	v_mfma_f32_16x16x32_bf16 v[44:47], v[138:141], v[166:169], v[44:47]
	v_mfma_f32_16x16x32_bf16 v[40:43], v[150:153], v[166:169], v[40:43]
	v_mfma_f32_16x16x32_bf16 v[28:31], v[138:141], v[174:177], v[28:31]
	v_mfma_f32_16x16x32_bf16 v[24:27], v[150:153], v[174:177], v[24:27]
	v_mfma_f32_16x16x32_bf16 v[12:15], v[138:141], v[182:185], v[12:15]
	v_mfma_f32_16x16x32_bf16 v[8:11], v[150:153], v[182:185], v[8:11]
	v_mfma_f32_16x16x32_bf16 v[60:63], v[146:149], v[162:165], v[60:63]
	v_mfma_f32_16x16x32_bf16 v[56:59], v[154:157], v[162:165], v[56:59]
	v_mfma_f32_16x16x32_bf16 v[44:47], v[146:149], v[170:173], v[44:47]
	v_mfma_f32_16x16x32_bf16 v[40:43], v[154:157], v[170:173], v[40:43]
	v_mfma_f32_16x16x32_bf16 v[28:31], v[146:149], v[178:181], v[28:31]
	v_mfma_f32_16x16x32_bf16 v[24:27], v[154:157], v[178:181], v[24:27]
	v_mfma_f32_16x16x32_bf16 v[12:15], v[146:149], v[186:189], v[12:15]
	v_mfma_f32_16x16x32_bf16 v[8:11], v[154:157], v[186:189], v[8:11]
	s_barrier
	s_add_u32 s20, s24, 0xb0000
	s_addc_u32 s21, s25, 0
	s_add_i32 s62, s63, s35
	s_mov_b32 m0, s62
	s_nop 0
	global_load_lds_dwordx4 v208, s[20:21]
	s_add_i32 m0, s62, 0x2000
	s_nop 0
	global_load_lds_dwordx4 v128, s[20:21]
	s_waitcnt vmcnt(6)
	s_barrier
	v_mfma_f32_16x16x32_bf16 v[52:55], v[190:193], v[158:161], v[52:55]
	v_mfma_f32_16x16x32_bf16 v[48:51], v[198:201], v[158:161], v[48:51]
	v_mfma_f32_16x16x32_bf16 v[36:39], v[190:193], v[166:169], v[36:39]
	v_mfma_f32_16x16x32_bf16 v[32:35], v[198:201], v[166:169], v[32:35]
	v_mfma_f32_16x16x32_bf16 v[20:23], v[190:193], v[174:177], v[20:23]
	v_mfma_f32_16x16x32_bf16 v[16:19], v[198:201], v[174:177], v[16:19]
	v_mfma_f32_16x16x32_bf16 v[4:7], v[190:193], v[182:185], v[4:7]
	v_mfma_f32_16x16x32_bf16 v[0:3], v[198:201], v[182:185], v[0:3]
	v_mfma_f32_16x16x32_bf16 v[52:55], v[194:197], v[162:165], v[52:55]
	v_mfma_f32_16x16x32_bf16 v[48:51], v[202:205], v[162:165], v[48:51]
	v_mfma_f32_16x16x32_bf16 v[36:39], v[194:197], v[170:173], v[36:39]
	v_mfma_f32_16x16x32_bf16 v[32:35], v[202:205], v[170:173], v[32:35]
	v_mfma_f32_16x16x32_bf16 v[20:23], v[194:197], v[178:181], v[20:23]
	v_mfma_f32_16x16x32_bf16 v[16:19], v[202:205], v[178:181], v[16:19]
	v_mfma_f32_16x16x32_bf16 v[4:7], v[194:197], v[186:189], v[4:7]
	v_mfma_f32_16x16x32_bf16 v[0:3], v[202:205], v[186:189], v[0:3]
	s_add_i32 s62, 0, 0x18000
	s_barrier
	ds_read_b128 v[138:141], v206 offset:32768
	ds_read_b128 v[146:149], v206 offset:33792
	ds_read_b128 v[150:153], v206 offset:34816
	ds_read_b128 v[154:157], v206 offset:35840
	s_add_u32 s20, s26, 0xb0000
	s_addc_u32 s21, s27, 0
	s_mov_b32 m0, s50
	ds_read_b128 v[158:161], v145 offset:32768
	ds_read_b128 v[162:165], v145 offset:33792
	ds_read_b128 v[166:169], v145 offset:34816
	ds_read_b128 v[170:173], v145 offset:35840
	ds_read_b128 v[174:177], v145 offset:36864
	ds_read_b128 v[178:181], v145 offset:37888
	ds_read_b128 v[182:185], v145 offset:38912
	ds_read_b128 v[186:189], v145 offset:39936
	global_load_lds_dwordx4 v132, s[20:21]
	s_mov_b32 m0, s51
	s_nop 0
	global_load_lds_dwordx4 v130, s[20:21]
	s_waitcnt lgkmcnt(8)
	s_barrier
	s_waitcnt lgkmcnt(0)
	v_mfma_f32_16x16x32_bf16 v[124:127], v[138:141], v[158:161], v[124:127]
	v_mfma_f32_16x16x32_bf16 v[120:123], v[150:153], v[158:161], v[120:123]
	v_mfma_f32_16x16x32_bf16 v[108:111], v[138:141], v[166:169], v[108:111]
	v_mfma_f32_16x16x32_bf16 v[104:107], v[150:153], v[166:169], v[104:107]
	v_mfma_f32_16x16x32_bf16 v[92:95], v[138:141], v[174:177], v[92:95]
	v_mfma_f32_16x16x32_bf16 v[88:91], v[150:153], v[174:177], v[88:91]
	v_mfma_f32_16x16x32_bf16 v[76:79], v[138:141], v[182:185], v[76:79]
	v_mfma_f32_16x16x32_bf16 v[72:75], v[150:153], v[182:185], v[72:75]
	v_mfma_f32_16x16x32_bf16 v[124:127], v[146:149], v[162:165], v[124:127]
	v_mfma_f32_16x16x32_bf16 v[120:123], v[154:157], v[162:165], v[120:123]
	v_mfma_f32_16x16x32_bf16 v[108:111], v[146:149], v[170:173], v[108:111]
	v_mfma_f32_16x16x32_bf16 v[104:107], v[154:157], v[170:173], v[104:107]
	v_mfma_f32_16x16x32_bf16 v[92:95], v[146:149], v[178:181], v[92:95]
	v_mfma_f32_16x16x32_bf16 v[88:91], v[154:157], v[178:181], v[88:91]
	v_mfma_f32_16x16x32_bf16 v[76:79], v[146:149], v[186:189], v[76:79]
	v_mfma_f32_16x16x32_bf16 v[72:75], v[154:157], v[186:189], v[72:75]
	s_barrier
	s_add_i32 s26, 0, 0x1c000
	s_add_i32 s20, s62, s35
	s_mov_b32 m0, s20
	ds_read_b128 v[190:193], v206 offset:49152
	ds_read_b128 v[194:197], v206 offset:50176
	ds_read_b128 v[198:201], v206 offset:51200
	ds_read_b128 v[202:205], v206 offset:52224
	global_load_lds_dwordx4 v208, s[98:99]
	s_add_i32 m0, s20, 0x2000
	s_nop 0
	global_load_lds_dwordx4 v128, s[98:99]
	s_barrier
	s_waitcnt lgkmcnt(0)
	v_mfma_f32_16x16x32_bf16 v[116:119], v[190:193], v[158:161], v[116:119]
	v_mfma_f32_16x16x32_bf16 v[112:115], v[198:201], v[158:161], v[112:115]
	v_mfma_f32_16x16x32_bf16 v[100:103], v[190:193], v[166:169], v[100:103]
	v_mfma_f32_16x16x32_bf16 v[96:99], v[198:201], v[166:169], v[96:99]
	v_mfma_f32_16x16x32_bf16 v[84:87], v[190:193], v[174:177], v[84:87]
	v_mfma_f32_16x16x32_bf16 v[80:83], v[198:201], v[174:177], v[80:83]
	v_mfma_f32_16x16x32_bf16 v[68:71], v[190:193], v[182:185], v[68:71]
	v_mfma_f32_16x16x32_bf16 v[64:67], v[198:201], v[182:185], v[64:67]
	v_mfma_f32_16x16x32_bf16 v[116:119], v[194:197], v[162:165], v[116:119]
	v_mfma_f32_16x16x32_bf16 v[112:115], v[202:205], v[162:165], v[112:115]
	v_mfma_f32_16x16x32_bf16 v[100:103], v[194:197], v[170:173], v[100:103]
	v_mfma_f32_16x16x32_bf16 v[96:99], v[202:205], v[170:173], v[96:99]
	v_mfma_f32_16x16x32_bf16 v[84:87], v[194:197], v[178:181], v[84:87]
	v_mfma_f32_16x16x32_bf16 v[80:83], v[202:205], v[178:181], v[80:83]
	v_mfma_f32_16x16x32_bf16 v[68:71], v[194:197], v[186:189], v[68:71]
	v_mfma_f32_16x16x32_bf16 v[64:67], v[202:205], v[186:189], v[64:67]
	s_mov_b32 m0, s53
	s_barrier
	ds_read_b128 v[158:161], v145 offset:49152
	ds_read_b128 v[162:165], v145 offset:50176
	ds_read_b128 v[166:169], v145 offset:51200
	ds_read_b128 v[170:173], v145 offset:52224
	ds_read_b128 v[174:177], v145 offset:53248
	ds_read_b128 v[178:181], v145 offset:54272
	ds_read_b128 v[182:185], v145 offset:55296
	ds_read_b128 v[186:189], v145 offset:56320
	global_load_lds_dwordx4 v132, s[100:101]
	s_mov_b32 m0, s56
	s_nop 0
	global_load_lds_dwordx4 v130, s[100:101]
	s_barrier
	s_waitcnt lgkmcnt(0)
	v_mfma_f32_16x16x32_bf16 v[60:63], v[138:141], v[158:161], v[60:63]
	v_mfma_f32_16x16x32_bf16 v[56:59], v[150:153], v[158:161], v[56:59]
	v_mfma_f32_16x16x32_bf16 v[44:47], v[138:141], v[166:169], v[44:47]
	v_mfma_f32_16x16x32_bf16 v[40:43], v[150:153], v[166:169], v[40:43]
	v_mfma_f32_16x16x32_bf16 v[28:31], v[138:141], v[174:177], v[28:31]
	v_mfma_f32_16x16x32_bf16 v[24:27], v[150:153], v[174:177], v[24:27]
	v_mfma_f32_16x16x32_bf16 v[12:15], v[138:141], v[182:185], v[12:15]
	v_mfma_f32_16x16x32_bf16 v[8:11], v[150:153], v[182:185], v[8:11]
	v_mfma_f32_16x16x32_bf16 v[60:63], v[146:149], v[162:165], v[60:63]
	v_mfma_f32_16x16x32_bf16 v[56:59], v[154:157], v[162:165], v[56:59]
	v_mfma_f32_16x16x32_bf16 v[44:47], v[146:149], v[170:173], v[44:47]
	v_mfma_f32_16x16x32_bf16 v[40:43], v[154:157], v[170:173], v[40:43]
	v_mfma_f32_16x16x32_bf16 v[28:31], v[146:149], v[178:181], v[28:31]
	v_mfma_f32_16x16x32_bf16 v[24:27], v[154:157], v[178:181], v[24:27]
	v_mfma_f32_16x16x32_bf16 v[12:15], v[146:149], v[186:189], v[12:15]
	v_mfma_f32_16x16x32_bf16 v[8:11], v[154:157], v[186:189], v[8:11]
	s_barrier
	s_add_u32 s20, s24, 0xb0080
	s_addc_u32 s21, s25, 0
	s_add_i32 s24, s26, s35
	s_mov_b32 m0, s24
	s_nop 0
	global_load_lds_dwordx4 v208, s[20:21]
	s_add_i32 m0, s24, 0x2000
	s_nop 0
	global_load_lds_dwordx4 v128, s[20:21]
	s_waitcnt vmcnt(6)
	s_barrier
	v_mfma_f32_16x16x32_bf16 v[52:55], v[190:193], v[158:161], v[52:55]
	v_mfma_f32_16x16x32_bf16 v[48:51], v[198:201], v[158:161], v[48:51]
	v_mfma_f32_16x16x32_bf16 v[36:39], v[190:193], v[166:169], v[36:39]
	v_mfma_f32_16x16x32_bf16 v[32:35], v[198:201], v[166:169], v[32:35]
	v_mfma_f32_16x16x32_bf16 v[20:23], v[190:193], v[174:177], v[20:23]
	v_mfma_f32_16x16x32_bf16 v[16:19], v[198:201], v[174:177], v[16:19]
	v_mfma_f32_16x16x32_bf16 v[4:7], v[190:193], v[182:185], v[4:7]
	v_mfma_f32_16x16x32_bf16 v[0:3], v[198:201], v[182:185], v[0:3]
	v_mfma_f32_16x16x32_bf16 v[52:55], v[194:197], v[162:165], v[52:55]
	v_mfma_f32_16x16x32_bf16 v[48:51], v[202:205], v[162:165], v[48:51]
	v_mfma_f32_16x16x32_bf16 v[36:39], v[194:197], v[170:173], v[36:39]
	v_mfma_f32_16x16x32_bf16 v[32:35], v[202:205], v[170:173], v[32:35]
	v_mfma_f32_16x16x32_bf16 v[20:23], v[194:197], v[178:181], v[20:23]
	v_mfma_f32_16x16x32_bf16 v[16:19], v[202:205], v[178:181], v[16:19]
	v_mfma_f32_16x16x32_bf16 v[4:7], v[194:197], v[186:189], v[4:7]
	v_mfma_f32_16x16x32_bf16 v[0:3], v[202:205], v[186:189], v[0:3]
	s_add_i32 s61, s61, 2
	s_add_u32 s39, s39, 0x100
	s_addc_u32 s60, s60, 0
	s_cmp_gt_u32 s61, 41
	s_mov_b64 s[20:21], s[22:23]
	s_barrier
	s_cbranch_scc0 .LBB0_1021
	v_lshl_add_u32 v140, s38, 8, v142
	v_lshl_or_b32 v141, s36, 8, v144
	s_lshl_b32 s20, s36, 2
	s_ashr_i32 s21, s20, 31
	s_lshl_b32 s36, s52, 2
	v_lshlrev_b32_e32 v206, 11, v140
	v_lshl_add_u32 v206, v141, 1, v206
	v_lshl_add_u32 v210, v140, 6, s36
	v_lshl_add_u32 v210, s20, 2, v210
	v_mov_b32_e32 v207, v206
	global_load_dwordx4 v[146:149], v206, s[14:15]
	global_load_dwordx4 v[150:153], v206, s[14:15] offset:256
	v_add_u32_e32 v206, 0x8000, v206
	global_load_dwordx4 v[154:157], v206, s[14:15]
	global_load_dwordx4 v[158:161], v206, s[14:15] offset:256
	v_add_u32_e32 v206, 0x8000, v206
	global_load_dwordx4 v[162:165], v206, s[14:15]
	global_load_dwordx4 v[166:169], v206, s[14:15] offset:256
	v_add_u32_e32 v206, 0x8000, v206
	global_load_dwordx4 v[170:173], v206, s[14:15]
	global_load_dwordx4 v[174:177], v206, s[14:15] offset:256
	v_add_u32_e32 v206, 0x28000, v206
	global_load_dwordx4 v[178:181], v206, s[14:15]
	global_load_dwordx4 v[182:185], v206, s[14:15] offset:256
	v_add_u32_e32 v206, 0x8000, v206
	global_load_dwordx4 v[186:189], v206, s[14:15]
	global_load_dwordx4 v[190:193], v206, s[14:15] offset:256
	v_add_u32_e32 v206, 0x8000, v206
	global_load_dwordx4 v[194:197], v206, s[14:15]
	global_load_dwordx4 v[198:201], v206, s[14:15] offset:256
	v_add_u32_e32 v206, 0x8000, v206
	s_waitcnt vmcnt(12)
	v_lshlrev_b32_e32 v202, 16, v146
	v_and_b32_e32 v203, 0xffff0000, v146
	v_lshlrev_b32_e32 v204, 16, v147
	v_and_b32_e32 v205, 0xffff0000, v147
	v_pk_add_f32 v[124:125], v[124:125], v[202:203]
	v_pk_add_f32 v[126:127], v[126:127], v[204:205]
	v_lshlrev_b32_e32 v202, 16, v148
	v_and_b32_e32 v203, 0xffff0000, v148
	v_lshlrev_b32_e32 v204, 16, v149
	v_and_b32_e32 v205, 0xffff0000, v149
	v_pk_add_f32 v[120:121], v[120:121], v[202:203]
	v_pk_add_f32 v[122:123], v[122:123], v[204:205]
	v_cvt_pk_bf16_f32 v146, v124, v125
	v_cvt_pk_bf16_f32 v147, v126, v127
	v_cvt_pk_bf16_f32 v148, v120, v121
	v_cvt_pk_bf16_f32 v149, v122, v123
	v_pk_mul_f32 v[138:139], v[124:125], v[124:125]
	global_store_dwordx4 v207, v[146:149], s[14:15]
	v_pk_fma_f32 v[138:139], v[126:127], v[126:127], v[138:139]
	v_pk_fma_f32 v[138:139], v[120:121], v[120:121], v[138:139]
	v_pk_fma_f32 v[138:139], v[122:123], v[122:123], v[138:139]
	v_lshlrev_b32_e32 v202, 16, v150
	v_and_b32_e32 v203, 0xffff0000, v150
	v_lshlrev_b32_e32 v204, 16, v151
	v_and_b32_e32 v205, 0xffff0000, v151
	v_pk_add_f32 v[116:117], v[116:117], v[202:203]
	v_pk_add_f32 v[118:119], v[118:119], v[204:205]
	v_lshlrev_b32_e32 v202, 16, v152
	v_and_b32_e32 v203, 0xffff0000, v152
	v_lshlrev_b32_e32 v204, 16, v153
	v_and_b32_e32 v205, 0xffff0000, v153
	v_pk_add_f32 v[112:113], v[112:113], v[202:203]
	v_pk_add_f32 v[114:115], v[114:115], v[204:205]
	v_cvt_pk_bf16_f32 v150, v116, v117
	v_cvt_pk_bf16_f32 v151, v118, v119
	v_cvt_pk_bf16_f32 v152, v112, v113
	v_cvt_pk_bf16_f32 v153, v114, v115
	v_pk_fma_f32 v[138:139], v[116:117], v[116:117], v[138:139]
	global_store_dwordx4 v207, v[150:153], s[14:15] offset:256
	v_pk_fma_f32 v[138:139], v[118:119], v[118:119], v[138:139]
	v_pk_fma_f32 v[138:139], v[112:113], v[112:113], v[138:139]
	v_pk_fma_f32 v[138:139], v[114:115], v[114:115], v[138:139]
	v_add_f32_e32 v214, v138, v139
	v_add_u32_e32 v207, 0x8000, v207
	v_mov_b32_e32 v215, v214
	s_nop 1
	v_permlane16_swap_b32_e32 v214, v215
	s_nop 0
	v_add_f32_e32 v214, v214, v215
	v_mov_b32_e32 v215, v214
	s_nop 1
	v_permlane32_swap_b32_e32 v214, v215
	s_nop 0
	v_add_f32_e32 v214, v214, v215
	s_and_saveexec_b64 s[22:23], s[4:5]
	global_store_dword v210, v214, s[16:17]
	s_mov_b64 exec, s[22:23]
	global_load_dwordx4 v[146:149], v206, s[14:15]
	global_load_dwordx4 v[150:153], v206, s[14:15] offset:256
	s_waitcnt vmcnt(15)
	v_lshlrev_b32_e32 v202, 16, v154
	v_and_b32_e32 v203, 0xffff0000, v154
	v_lshlrev_b32_e32 v204, 16, v155
	v_and_b32_e32 v205, 0xffff0000, v155
	v_pk_add_f32 v[108:109], v[108:109], v[202:203]
	v_pk_add_f32 v[110:111], v[110:111], v[204:205]
	v_lshlrev_b32_e32 v202, 16, v156
	v_and_b32_e32 v203, 0xffff0000, v156
	v_lshlrev_b32_e32 v204, 16, v157
	v_and_b32_e32 v205, 0xffff0000, v157
	v_pk_add_f32 v[104:105], v[104:105], v[202:203]
	v_pk_add_f32 v[106:107], v[106:107], v[204:205]
	v_cvt_pk_bf16_f32 v154, v108, v109
	v_cvt_pk_bf16_f32 v155, v110, v111
	v_cvt_pk_bf16_f32 v156, v104, v105
	v_cvt_pk_bf16_f32 v157, v106, v107
	v_pk_mul_f32 v[138:139], v[108:109], v[108:109]
	global_store_dwordx4 v207, v[154:157], s[14:15]
	v_pk_fma_f32 v[138:139], v[110:111], v[110:111], v[138:139]
	v_pk_fma_f32 v[138:139], v[104:105], v[104:105], v[138:139]
	v_pk_fma_f32 v[138:139], v[106:107], v[106:107], v[138:139]
	v_lshlrev_b32_e32 v202, 16, v158
	v_and_b32_e32 v203, 0xffff0000, v158
	v_lshlrev_b32_e32 v204, 16, v159
	v_and_b32_e32 v205, 0xffff0000, v159
	v_pk_add_f32 v[100:101], v[100:101], v[202:203]
	v_pk_add_f32 v[102:103], v[102:103], v[204:205]
	v_lshlrev_b32_e32 v202, 16, v160
	v_and_b32_e32 v203, 0xffff0000, v160
	v_lshlrev_b32_e32 v204, 16, v161
	v_and_b32_e32 v205, 0xffff0000, v161
	v_pk_add_f32 v[96:97], v[96:97], v[202:203]
	v_pk_add_f32 v[98:99], v[98:99], v[204:205]
	v_cvt_pk_bf16_f32 v158, v100, v101
	v_cvt_pk_bf16_f32 v159, v102, v103
	v_cvt_pk_bf16_f32 v160, v96, v97
	v_cvt_pk_bf16_f32 v161, v98, v99
	v_pk_fma_f32 v[138:139], v[100:101], v[100:101], v[138:139]
	global_store_dwordx4 v207, v[158:161], s[14:15] offset:256
	v_pk_fma_f32 v[138:139], v[102:103], v[102:103], v[138:139]
	v_pk_fma_f32 v[138:139], v[96:97], v[96:97], v[138:139]
	v_pk_fma_f32 v[138:139], v[98:99], v[98:99], v[138:139]
	v_add_f32_e32 v214, v138, v139
	v_add_u32_e32 v207, 0x8000, v207
	v_mov_b32_e32 v215, v214
	s_nop 1
	v_permlane16_swap_b32_e32 v214, v215
	s_nop 0
	v_add_f32_e32 v214, v214, v215
	v_mov_b32_e32 v215, v214
	s_nop 1
	v_permlane32_swap_b32_e32 v214, v215
	s_nop 0
	v_add_f32_e32 v214, v214, v215
	s_and_saveexec_b64 s[22:23], s[4:5]
	global_store_dword v210, v214, s[16:17] offset:1024
	s_mov_b64 exec, s[22:23]
	s_waitcnt vmcnt(16)
	v_lshlrev_b32_e32 v202, 16, v162
	v_and_b32_e32 v203, 0xffff0000, v162
	v_lshlrev_b32_e32 v204, 16, v163
	v_and_b32_e32 v205, 0xffff0000, v163
	v_pk_add_f32 v[92:93], v[92:93], v[202:203]
	v_pk_add_f32 v[94:95], v[94:95], v[204:205]
	v_lshlrev_b32_e32 v202, 16, v164
	v_and_b32_e32 v203, 0xffff0000, v164
	v_lshlrev_b32_e32 v204, 16, v165
	v_and_b32_e32 v205, 0xffff0000, v165
	v_pk_add_f32 v[88:89], v[88:89], v[202:203]
	v_pk_add_f32 v[90:91], v[90:91], v[204:205]
	v_cvt_pk_bf16_f32 v162, v92, v93
	v_cvt_pk_bf16_f32 v163, v94, v95
	v_cvt_pk_bf16_f32 v164, v88, v89
	v_cvt_pk_bf16_f32 v165, v90, v91
	v_pk_mul_f32 v[138:139], v[92:93], v[92:93]
	global_store_dwordx4 v207, v[162:165], s[14:15]
	v_pk_fma_f32 v[138:139], v[94:95], v[94:95], v[138:139]
	v_pk_fma_f32 v[138:139], v[88:89], v[88:89], v[138:139]
	v_pk_fma_f32 v[138:139], v[90:91], v[90:91], v[138:139]
	v_lshlrev_b32_e32 v202, 16, v166
	v_and_b32_e32 v203, 0xffff0000, v166
	v_lshlrev_b32_e32 v204, 16, v167
	v_and_b32_e32 v205, 0xffff0000, v167
	v_pk_add_f32 v[84:85], v[84:85], v[202:203]
	v_pk_add_f32 v[86:87], v[86:87], v[204:205]
	v_lshlrev_b32_e32 v202, 16, v168
	v_and_b32_e32 v203, 0xffff0000, v168
	v_lshlrev_b32_e32 v204, 16, v169
	v_and_b32_e32 v205, 0xffff0000, v169
	v_pk_add_f32 v[80:81], v[80:81], v[202:203]
	v_pk_add_f32 v[82:83], v[82:83], v[204:205]
	v_cvt_pk_bf16_f32 v166, v84, v85
	v_cvt_pk_bf16_f32 v167, v86, v87
	v_cvt_pk_bf16_f32 v168, v80, v81
	v_cvt_pk_bf16_f32 v169, v82, v83
	v_pk_fma_f32 v[138:139], v[84:85], v[84:85], v[138:139]
	global_store_dwordx4 v207, v[166:169], s[14:15] offset:256
	v_pk_fma_f32 v[138:139], v[86:87], v[86:87], v[138:139]
	v_pk_fma_f32 v[138:139], v[80:81], v[80:81], v[138:139]
	v_pk_fma_f32 v[138:139], v[82:83], v[82:83], v[138:139]
	v_add_f32_e32 v214, v138, v139
	v_add_u32_e32 v207, 0x8000, v207
	v_mov_b32_e32 v215, v214
	s_nop 1
	v_permlane16_swap_b32_e32 v214, v215
	s_nop 0
	v_add_f32_e32 v214, v214, v215
	v_mov_b32_e32 v215, v214
	s_nop 1
	v_permlane32_swap_b32_e32 v214, v215
	s_nop 0
	v_add_f32_e32 v214, v214, v215
	s_and_saveexec_b64 s[22:23], s[4:5]
	global_store_dword v210, v214, s[16:17] offset:2048
	s_mov_b64 exec, s[22:23]
	s_waitcnt vmcnt(17)
	v_lshlrev_b32_e32 v202, 16, v170
	v_and_b32_e32 v203, 0xffff0000, v170
	v_lshlrev_b32_e32 v204, 16, v171
	v_and_b32_e32 v205, 0xffff0000, v171
	v_pk_add_f32 v[76:77], v[76:77], v[202:203]
	v_pk_add_f32 v[78:79], v[78:79], v[204:205]
	v_lshlrev_b32_e32 v202, 16, v172
	v_and_b32_e32 v203, 0xffff0000, v172
	v_lshlrev_b32_e32 v204, 16, v173
	v_and_b32_e32 v205, 0xffff0000, v173
	v_pk_add_f32 v[72:73], v[72:73], v[202:203]
	v_pk_add_f32 v[74:75], v[74:75], v[204:205]
	v_cvt_pk_bf16_f32 v170, v76, v77
	v_cvt_pk_bf16_f32 v171, v78, v79
	v_cvt_pk_bf16_f32 v172, v72, v73
	v_cvt_pk_bf16_f32 v173, v74, v75
	v_pk_mul_f32 v[138:139], v[76:77], v[76:77]
	global_store_dwordx4 v207, v[170:173], s[14:15]
	v_pk_fma_f32 v[138:139], v[78:79], v[78:79], v[138:139]
	v_pk_fma_f32 v[138:139], v[72:73], v[72:73], v[138:139]
	v_pk_fma_f32 v[138:139], v[74:75], v[74:75], v[138:139]
	v_lshlrev_b32_e32 v202, 16, v174
	v_and_b32_e32 v203, 0xffff0000, v174
	v_lshlrev_b32_e32 v204, 16, v175
	v_and_b32_e32 v205, 0xffff0000, v175
	v_pk_add_f32 v[68:69], v[68:69], v[202:203]
	v_pk_add_f32 v[70:71], v[70:71], v[204:205]
	v_lshlrev_b32_e32 v202, 16, v176
	v_and_b32_e32 v203, 0xffff0000, v176
	v_lshlrev_b32_e32 v204, 16, v177
	v_and_b32_e32 v205, 0xffff0000, v177
	v_pk_add_f32 v[64:65], v[64:65], v[202:203]
	v_pk_add_f32 v[66:67], v[66:67], v[204:205]
	v_cvt_pk_bf16_f32 v174, v68, v69
	v_cvt_pk_bf16_f32 v175, v70, v71
	v_cvt_pk_bf16_f32 v176, v64, v65
	v_cvt_pk_bf16_f32 v177, v66, v67
	v_pk_fma_f32 v[138:139], v[68:69], v[68:69], v[138:139]
	global_store_dwordx4 v207, v[174:177], s[14:15] offset:256
	v_pk_fma_f32 v[138:139], v[70:71], v[70:71], v[138:139]
	v_pk_fma_f32 v[138:139], v[64:65], v[64:65], v[138:139]
	v_pk_fma_f32 v[138:139], v[66:67], v[66:67], v[138:139]
	v_add_f32_e32 v214, v138, v139
	v_add_u32_e32 v207, 0x28000, v207
	v_mov_b32_e32 v215, v214
	s_nop 1
	v_permlane16_swap_b32_e32 v214, v215
	s_nop 0
	v_add_f32_e32 v214, v214, v215
	v_mov_b32_e32 v215, v214
	s_nop 1
	v_permlane32_swap_b32_e32 v214, v215
	s_nop 0
	v_add_f32_e32 v214, v214, v215
	s_and_saveexec_b64 s[22:23], s[4:5]
	global_store_dword v210, v214, s[16:17] offset:3072
	s_mov_b64 exec, s[22:23]
	v_add_u32_e32 v210, 0x2000, v210
	s_waitcnt vmcnt(18)
	v_lshlrev_b32_e32 v202, 16, v178
	v_and_b32_e32 v203, 0xffff0000, v178
	v_lshlrev_b32_e32 v204, 16, v179
	v_and_b32_e32 v205, 0xffff0000, v179
	v_pk_add_f32 v[60:61], v[60:61], v[202:203]
	v_pk_add_f32 v[62:63], v[62:63], v[204:205]
	v_lshlrev_b32_e32 v202, 16, v180
	v_and_b32_e32 v203, 0xffff0000, v180
	v_lshlrev_b32_e32 v204, 16, v181
	v_and_b32_e32 v205, 0xffff0000, v181
	v_pk_add_f32 v[56:57], v[56:57], v[202:203]
	v_pk_add_f32 v[58:59], v[58:59], v[204:205]
	v_cvt_pk_bf16_f32 v178, v60, v61
	v_cvt_pk_bf16_f32 v179, v62, v63
	v_cvt_pk_bf16_f32 v180, v56, v57
	v_cvt_pk_bf16_f32 v181, v58, v59
	v_pk_mul_f32 v[138:139], v[60:61], v[60:61]
	global_store_dwordx4 v207, v[178:181], s[14:15]
	v_pk_fma_f32 v[138:139], v[62:63], v[62:63], v[138:139]
	v_pk_fma_f32 v[138:139], v[56:57], v[56:57], v[138:139]
	v_pk_fma_f32 v[138:139], v[58:59], v[58:59], v[138:139]
	v_lshlrev_b32_e32 v202, 16, v182
	v_and_b32_e32 v203, 0xffff0000, v182
	v_lshlrev_b32_e32 v204, 16, v183
	v_and_b32_e32 v205, 0xffff0000, v183
	v_pk_add_f32 v[52:53], v[52:53], v[202:203]
	v_pk_add_f32 v[54:55], v[54:55], v[204:205]
	v_lshlrev_b32_e32 v202, 16, v184
	v_and_b32_e32 v203, 0xffff0000, v184
	v_lshlrev_b32_e32 v204, 16, v185
	v_and_b32_e32 v205, 0xffff0000, v185
	v_pk_add_f32 v[48:49], v[48:49], v[202:203]
	v_pk_add_f32 v[50:51], v[50:51], v[204:205]
	v_cvt_pk_bf16_f32 v182, v52, v53
	v_cvt_pk_bf16_f32 v183, v54, v55
	v_cvt_pk_bf16_f32 v184, v48, v49
	v_cvt_pk_bf16_f32 v185, v50, v51
	v_pk_fma_f32 v[138:139], v[52:53], v[52:53], v[138:139]
	global_store_dwordx4 v207, v[182:185], s[14:15] offset:256
	v_pk_fma_f32 v[138:139], v[54:55], v[54:55], v[138:139]
	v_pk_fma_f32 v[138:139], v[48:49], v[48:49], v[138:139]
	v_pk_fma_f32 v[138:139], v[50:51], v[50:51], v[138:139]
	v_add_f32_e32 v214, v138, v139
	v_add_u32_e32 v207, 0x8000, v207
	v_mov_b32_e32 v215, v214
	s_nop 1
	v_permlane16_swap_b32_e32 v214, v215
	s_nop 0
	v_add_f32_e32 v214, v214, v215
	v_mov_b32_e32 v215, v214
	s_nop 1
	v_permlane32_swap_b32_e32 v214, v215
	s_nop 0
	v_add_f32_e32 v214, v214, v215
	s_and_saveexec_b64 s[22:23], s[4:5]
	global_store_dword v210, v214, s[16:17]
	s_mov_b64 exec, s[22:23]
	s_waitcnt vmcnt(19)
	v_lshlrev_b32_e32 v202, 16, v186
	v_and_b32_e32 v203, 0xffff0000, v186
	v_lshlrev_b32_e32 v204, 16, v187
	v_and_b32_e32 v205, 0xffff0000, v187
	v_pk_add_f32 v[44:45], v[44:45], v[202:203]
	v_pk_add_f32 v[46:47], v[46:47], v[204:205]
	v_lshlrev_b32_e32 v202, 16, v188
	v_and_b32_e32 v203, 0xffff0000, v188
	v_lshlrev_b32_e32 v204, 16, v189
	v_and_b32_e32 v205, 0xffff0000, v189
	v_pk_add_f32 v[40:41], v[40:41], v[202:203]
	v_pk_add_f32 v[42:43], v[42:43], v[204:205]
	v_cvt_pk_bf16_f32 v186, v44, v45
	v_cvt_pk_bf16_f32 v187, v46, v47
	v_cvt_pk_bf16_f32 v188, v40, v41
	v_cvt_pk_bf16_f32 v189, v42, v43
	v_pk_mul_f32 v[138:139], v[44:45], v[44:45]
	global_store_dwordx4 v207, v[186:189], s[14:15]
	v_pk_fma_f32 v[138:139], v[46:47], v[46:47], v[138:139]
	v_pk_fma_f32 v[138:139], v[40:41], v[40:41], v[138:139]
	v_pk_fma_f32 v[138:139], v[42:43], v[42:43], v[138:139]
	v_lshlrev_b32_e32 v202, 16, v190
	v_and_b32_e32 v203, 0xffff0000, v190
	v_lshlrev_b32_e32 v204, 16, v191
	v_and_b32_e32 v205, 0xffff0000, v191
	v_pk_add_f32 v[36:37], v[36:37], v[202:203]
	v_pk_add_f32 v[38:39], v[38:39], v[204:205]
	v_lshlrev_b32_e32 v202, 16, v192
	v_and_b32_e32 v203, 0xffff0000, v192
	v_lshlrev_b32_e32 v204, 16, v193
	v_and_b32_e32 v205, 0xffff0000, v193
	v_pk_add_f32 v[32:33], v[32:33], v[202:203]
	v_pk_add_f32 v[34:35], v[34:35], v[204:205]
	v_cvt_pk_bf16_f32 v190, v36, v37
	v_cvt_pk_bf16_f32 v191, v38, v39
	v_cvt_pk_bf16_f32 v192, v32, v33
	v_cvt_pk_bf16_f32 v193, v34, v35
	v_pk_fma_f32 v[138:139], v[36:37], v[36:37], v[138:139]
	global_store_dwordx4 v207, v[190:193], s[14:15] offset:256
	v_pk_fma_f32 v[138:139], v[38:39], v[38:39], v[138:139]
	v_pk_fma_f32 v[138:139], v[32:33], v[32:33], v[138:139]
	v_pk_fma_f32 v[138:139], v[34:35], v[34:35], v[138:139]
	v_add_f32_e32 v214, v138, v139
	v_add_u32_e32 v207, 0x8000, v207
	v_mov_b32_e32 v215, v214
	s_nop 1
	v_permlane16_swap_b32_e32 v214, v215
	s_nop 0
	v_add_f32_e32 v214, v214, v215
	v_mov_b32_e32 v215, v214
	s_nop 1
	v_permlane32_swap_b32_e32 v214, v215
	s_nop 0
	v_add_f32_e32 v214, v214, v215
	s_and_saveexec_b64 s[22:23], s[4:5]
	global_store_dword v210, v214, s[16:17] offset:1024
	s_mov_b64 exec, s[22:23]
	s_waitcnt vmcnt(20)
	v_lshlrev_b32_e32 v202, 16, v194
	v_and_b32_e32 v203, 0xffff0000, v194
	v_lshlrev_b32_e32 v204, 16, v195
	v_and_b32_e32 v205, 0xffff0000, v195
	v_pk_add_f32 v[28:29], v[28:29], v[202:203]
	v_pk_add_f32 v[30:31], v[30:31], v[204:205]
	v_lshlrev_b32_e32 v202, 16, v196
	v_and_b32_e32 v203, 0xffff0000, v196
	v_lshlrev_b32_e32 v204, 16, v197
	v_and_b32_e32 v205, 0xffff0000, v197
	v_pk_add_f32 v[24:25], v[24:25], v[202:203]
	v_pk_add_f32 v[26:27], v[26:27], v[204:205]
	v_cvt_pk_bf16_f32 v194, v28, v29
	v_cvt_pk_bf16_f32 v195, v30, v31
	v_cvt_pk_bf16_f32 v196, v24, v25
	v_cvt_pk_bf16_f32 v197, v26, v27
	v_pk_mul_f32 v[138:139], v[28:29], v[28:29]
	global_store_dwordx4 v207, v[194:197], s[14:15]
	v_pk_fma_f32 v[138:139], v[30:31], v[30:31], v[138:139]
	v_pk_fma_f32 v[138:139], v[24:25], v[24:25], v[138:139]
	v_pk_fma_f32 v[138:139], v[26:27], v[26:27], v[138:139]
	v_lshlrev_b32_e32 v202, 16, v198
	v_and_b32_e32 v203, 0xffff0000, v198
	v_lshlrev_b32_e32 v204, 16, v199
	v_and_b32_e32 v205, 0xffff0000, v199
	v_pk_add_f32 v[20:21], v[20:21], v[202:203]
	v_pk_add_f32 v[22:23], v[22:23], v[204:205]
	v_lshlrev_b32_e32 v202, 16, v200
	v_and_b32_e32 v203, 0xffff0000, v200
	v_lshlrev_b32_e32 v204, 16, v201
	v_and_b32_e32 v205, 0xffff0000, v201
	v_pk_add_f32 v[16:17], v[16:17], v[202:203]
	v_pk_add_f32 v[18:19], v[18:19], v[204:205]
	v_cvt_pk_bf16_f32 v198, v20, v21
	v_cvt_pk_bf16_f32 v199, v22, v23
	v_cvt_pk_bf16_f32 v200, v16, v17
	v_cvt_pk_bf16_f32 v201, v18, v19
	v_pk_fma_f32 v[138:139], v[20:21], v[20:21], v[138:139]
	global_store_dwordx4 v207, v[198:201], s[14:15] offset:256
	v_pk_fma_f32 v[138:139], v[22:23], v[22:23], v[138:139]
	v_pk_fma_f32 v[138:139], v[16:17], v[16:17], v[138:139]
	v_pk_fma_f32 v[138:139], v[18:19], v[18:19], v[138:139]
	v_add_f32_e32 v214, v138, v139
	v_add_u32_e32 v207, 0x8000, v207
	v_mov_b32_e32 v215, v214
	s_nop 1
	v_permlane16_swap_b32_e32 v214, v215
	s_nop 0
	v_add_f32_e32 v214, v214, v215
	v_mov_b32_e32 v215, v214
	s_nop 1
	v_permlane32_swap_b32_e32 v214, v215
	s_nop 0
	v_add_f32_e32 v214, v214, v215
	s_and_saveexec_b64 s[22:23], s[4:5]
	global_store_dword v210, v214, s[16:17] offset:2048
	s_mov_b64 exec, s[22:23]
	s_waitcnt vmcnt(18)
	v_lshlrev_b32_e32 v202, 16, v146
	v_and_b32_e32 v203, 0xffff0000, v146
	v_lshlrev_b32_e32 v204, 16, v147
	v_and_b32_e32 v205, 0xffff0000, v147
	v_pk_add_f32 v[12:13], v[12:13], v[202:203]
	v_pk_add_f32 v[14:15], v[14:15], v[204:205]
	v_lshlrev_b32_e32 v202, 16, v148
	v_and_b32_e32 v203, 0xffff0000, v148
	v_lshlrev_b32_e32 v204, 16, v149
	v_and_b32_e32 v205, 0xffff0000, v149
	v_pk_add_f32 v[8:9], v[8:9], v[202:203]
	v_pk_add_f32 v[10:11], v[10:11], v[204:205]
	v_cvt_pk_bf16_f32 v146, v12, v13
	v_cvt_pk_bf16_f32 v147, v14, v15
	v_cvt_pk_bf16_f32 v148, v8, v9
	v_cvt_pk_bf16_f32 v149, v10, v11
	v_pk_mul_f32 v[138:139], v[12:13], v[12:13]
	global_store_dwordx4 v207, v[146:149], s[14:15]
	v_pk_fma_f32 v[138:139], v[14:15], v[14:15], v[138:139]
	v_pk_fma_f32 v[138:139], v[8:9], v[8:9], v[138:139]
	v_pk_fma_f32 v[138:139], v[10:11], v[10:11], v[138:139]
	v_lshlrev_b32_e32 v202, 16, v150
	v_and_b32_e32 v203, 0xffff0000, v150
	v_lshlrev_b32_e32 v204, 16, v151
	v_and_b32_e32 v205, 0xffff0000, v151
	v_pk_add_f32 v[4:5], v[4:5], v[202:203]
	v_pk_add_f32 v[6:7], v[6:7], v[204:205]
	v_lshlrev_b32_e32 v202, 16, v152
	v_and_b32_e32 v203, 0xffff0000, v152
	v_lshlrev_b32_e32 v204, 16, v153
	v_and_b32_e32 v205, 0xffff0000, v153
	v_pk_add_f32 v[0:1], v[0:1], v[202:203]
	v_pk_add_f32 v[2:3], v[2:3], v[204:205]
	v_cvt_pk_bf16_f32 v150, v4, v5
	v_cvt_pk_bf16_f32 v151, v6, v7
	v_cvt_pk_bf16_f32 v152, v0, v1
	v_cvt_pk_bf16_f32 v153, v2, v3
	v_pk_fma_f32 v[138:139], v[4:5], v[4:5], v[138:139]
	global_store_dwordx4 v207, v[150:153], s[14:15] offset:256
	v_pk_fma_f32 v[138:139], v[6:7], v[6:7], v[138:139]
	v_pk_fma_f32 v[138:139], v[0:1], v[0:1], v[138:139]
	v_pk_fma_f32 v[138:139], v[2:3], v[2:3], v[138:139]
	v_add_f32_e32 v214, v138, v139
	v_add_u32_e32 v207, 0x8000, v207
	v_mov_b32_e32 v215, v214
	s_nop 1
	v_permlane16_swap_b32_e32 v214, v215
	s_nop 0
	v_add_f32_e32 v214, v214, v215
	v_mov_b32_e32 v215, v214
	s_nop 1
	v_permlane32_swap_b32_e32 v214, v215
	s_nop 0
	v_add_f32_e32 v214, v214, v215
	s_and_saveexec_b64 s[22:23], s[4:5]
	global_store_dword v210, v214, s[16:17] offset:3072
	s_mov_b64 exec, s[22:23]
	s_branch .LBB0_1009
